# all flat stores issued as global stores (vmcnt only): LDS waits in the GEMM and attention loops no longer wait on earlier output stores
# baseline (speedup 1.0000x reference)
; __device__ __forceinline__ void phase_mod(const Tab tb, unsigned char* lds_g) {
;     ...
;     for (int item = blockIdx.x; item < DEPTH * 96; item += gridDim.x) {
;         const int l = item / 96, cgp = item % 96;
;         const float* W = in2 + (size_t)l * DM * 6 * DM + (size_t)(kg * 128) * (6 * DM) + cgp * 128 + 4 * cl;
;         f32x4 acc = {0.f, 0.f, 0.f, 0.f};
; #pragma unroll 8
;         for (int kk = 0; kk < 128; ++kk) { const f32x4 w = __builtin_nontemporal_load((const f32x4*)(W + (size_t)kk * (6 * DM))); acc += w * condL[kg * 128 + kk]; }
;         red[kg * 32 + cl] = acc;
;         __syncthreads();
;         if (tid < 128) { float s = 0.f; const float* rf = (const float*)red;
;             for (int g = 0; g < 16; ++g) s += rf[g * 128 + tid];
;             mod[l * 6 * DM + cgp * 128 + tid] = s + in3[l * 6 * DM + cgp * 128 + tid]; }
.LBB0_101:
	v_lshl_add_u64 v[44:45], v[10:11], 0, s[10:11]
	v_add_co_u32_e32 v20, vcc, s12, v44
	flat_load_dwordx4 v[16:19], v[44:45] nt
	s_nop 0
	v_addc_co_u32_e32 v21, vcc, 0, v45, vcc
	v_add_co_u32_e32 v32, vcc, s13, v44
	flat_load_dwordx4 v[20:23], v[20:21] nt
	s_nop 0
	v_addc_co_u32_e32 v33, vcc, 0, v45, vcc
	v_add_co_u32_e32 v34, vcc, s14, v44
	s_add_u32 s10, s10, 0x60000
	s_nop 0
	v_addc_co_u32_e32 v35, vcc, 0, v45, vcc
	v_add_co_u32_e32 v40, vcc, s15, v44
	flat_load_dwordx4 v[24:27], v[32:33] nt
	flat_load_dwordx4 v[28:31], v[34:35] nt
	v_addc_co_u32_e32 v41, vcc, 0, v45, vcc
	v_add_co_u32_e32 v42, vcc, s16, v44
	s_addc_u32 s11, s11, 0
	s_nop 0
	v_addc_co_u32_e32 v43, vcc, 0, v45, vcc
	v_add_co_u32_e32 v46, vcc, s17, v44
	flat_load_dwordx4 v[32:35], v[40:41] nt
	flat_load_dwordx4 v[36:39], v[42:43] nt
	v_addc_co_u32_e32 v47, vcc, 0, v45, vcc
	v_add_co_u32_e32 v44, vcc, s18, v44
	flat_load_dwordx4 v[40:43], v[46:47] nt
	s_nop 0
	v_addc_co_u32_e32 v45, vcc, 0, v45, vcc
	flat_load_dwordx4 v[44:47], v[44:45] nt
	ds_read_b128 v[48:51], v15
	ds_read_b128 v[52:55], v15 offset:16
	v_add_u32_e32 v15, 32, v15
	s_cmp_eq_u32 s10, 0x600000
	s_waitcnt lgkmcnt(0)
	v_mov_b32_e32 v56, v51
	v_mov_b32_e32 v58, v55
	s_waitcnt vmcnt(0)
	v_pk_fma_f32 v[2:3], v[18:19], v[48:49], v[2:3] op_sel_hi:[1,0,1]
	v_pk_fma_f32 v[0:1], v[16:17], v[48:49], v[0:1] op_sel_hi:[1,0,1]
	v_pk_fma_f32 v[2:3], v[22:23], v[48:49], v[2:3] op_sel:[0,1,0]
	v_pk_fma_f32 v[0:1], v[20:21], v[48:49], v[0:1] op_sel:[0,1,0]
	v_pk_fma_f32 v[2:3], v[26:27], v[50:51], v[2:3] op_sel_hi:[1,0,1]
	v_pk_fma_f32 v[0:1], v[24:25], v[50:51], v[0:1] op_sel_hi:[1,0,1]
	v_pk_fma_f32 v[2:3], v[30:31], v[56:57], v[2:3] op_sel_hi:[1,0,1]
	v_pk_fma_f32 v[0:1], v[28:29], v[56:57], v[0:1] op_sel_hi:[1,0,1]
	v_pk_fma_f32 v[2:3], v[34:35], v[52:53], v[2:3] op_sel_hi:[1,0,1]
	v_pk_fma_f32 v[0:1], v[32:33], v[52:53], v[0:1] op_sel_hi:[1,0,1]
	v_pk_fma_f32 v[2:3], v[38:39], v[52:53], v[2:3] op_sel:[0,1,0]
	v_pk_fma_f32 v[0:1], v[36:37], v[52:53], v[0:1] op_sel:[0,1,0]
	v_pk_fma_f32 v[2:3], v[42:43], v[54:55], v[2:3] op_sel_hi:[1,0,1]
	v_pk_fma_f32 v[0:1], v[40:41], v[54:55], v[0:1] op_sel_hi:[1,0,1]
	v_pk_fma_f32 v[2:3], v[46:47], v[58:59], v[2:3] op_sel_hi:[1,0,1]
	v_pk_fma_f32 v[0:1], v[44:45], v[58:59], v[0:1] op_sel_hi:[1,0,1]
	s_cbranch_scc0 .LBB0_101
	ds_write_b128 v12, v[0:3] offset:8192
	s_waitcnt lgkmcnt(0)
	s_barrier
	s_and_saveexec_b64 s[10:11], s[0:1]
	s_cbranch_execz .LBB0_99
	s_mul_i32 s9, s20, 0x3000
	s_add_i32 s9, s9, s8
	v_add_u32_e32 v0, s9, v4
	v_ashrrev_i32_e32 v1, 31, v0
	v_lshlrev_b64 v[0:1], 2, v[0:1]
	v_lshl_add_u64 v[2:3], s[24:25], 0, v[0:1]
	flat_load_dword v15, v[2:3]
	ds_read2st64_b32 v[2:3], v14 offset0:32 offset1:34
	ds_read2st64_b32 v[10:11], v14 offset0:36 offset1:38
	ds_read2st64_b32 v[16:17], v14 offset0:40 offset1:42
	ds_read2st64_b32 v[18:19], v14 offset0:44 offset1:46
	ds_read2st64_b32 v[20:21], v14 offset0:48 offset1:50
	ds_read2st64_b32 v[22:23], v14 offset0:52 offset1:54
	ds_read2st64_b32 v[24:25], v14 offset0:56 offset1:58
	ds_read2st64_b32 v[26:27], v14 offset0:60 offset1:62
	s_waitcnt lgkmcnt(0)
	v_add_f32_e32 v2, 0, v2
	v_add_f32_e32 v2, v2, v3
	v_add_f32_e32 v2, v2, v10
	v_add_f32_e32 v2, v2, v11
	v_add_f32_e32 v2, v2, v16
	v_add_f32_e32 v2, v2, v17
	v_add_f32_e32 v2, v2, v18
	v_add_f32_e32 v2, v2, v19
	v_add_f32_e32 v2, v2, v20
	v_add_f32_e32 v2, v2, v21
	v_add_f32_e32 v2, v2, v22
	v_add_f32_e32 v2, v2, v23
	v_add_f32_e32 v2, v2, v24
	v_add_f32_e32 v2, v2, v25
	v_add_f32_e32 v2, v2, v26
	v_add_f32_e32 v2, v2, v27
	v_lshl_add_u64 v[0:1], s[6:7], 0, v[0:1]
	s_waitcnt vmcnt(0)
	v_add_f32_e32 v2, v2, v15
	global_store_dword v[0:1], v2, off
	s_branch .LBB0_99

; __device__ __forceinline__ unsigned cvt_pk_bf16(float lo, float hi) { unsigned r; asm volatile("v_cvt_pk_bf16_f32 %0, %1, %2" : "=v"(r) : "v"(lo), "v"(hi)); return r; }
; template <int PERMT>
; __device__ __forceinline__ int dst_row(int n) {
;     ...
;     if (PERMT == 3) { if (n < C_KR || n >= C_KR + 64) return n; const int j = n - C_KR; return C_KR + 2 * (j & 31) + (j >> 5); }
; template <int PERMT>
; __device__ __forceinline__ void transpose_job(const float* __restrict__ src, bf16_t* __restrict__ dst, int K, int N, int Npad, const float* __restrict__ kscale, unsigned char* lds_g, int first, int stride) {
;     ...
;           for (int i = 0; i < 8; ++i) { const int k = k0 + kk + 8 * i; if (kscale) v[i] = v[i] * kscale[k];
;               float* tp = T + (kk + 8 * i) * 257 + 4 * n4; tp[0] = v[i][0]; tp[1] = v[i][1]; tp[2] = v[i][2]; tp[3] = v[i][3]; } }
;         __syncthreads();
;         { const int n = tid >> 1, ks = tid & 1;
;           if (n0 + n < N) { bf16_t* dp = dst + (size_t)dst_row<PERMT>(n0 + n) * K + k0 + 32 * ks;
; #pragma unroll
;             for (int eb = 0; eb < 4; ++eb) { float v[8];
; #pragma unroll
;               for (int e = 0; e < 8; ++e) v[e] = T[(32 * ks + 8 * eb + e) * 257 + n];
;               u32x4 w; w.x = cvt_pk_bf16(v[0], v[1]); w.y = cvt_pk_bf16(v[2], v[3]); w.z = cvt_pk_bf16(v[4], v[5]); w.w = cvt_pk_bf16(v[6], v[7]);
;               *(u32x4*)(dp + 8 * eb) = w; } } }
.LBB0_178:
	s_or_b64 exec, exec, s[44:45]
	s_waitcnt vmcnt(0) lgkmcnt(0)
	ds_write2_b32 v47, v12, v13 offset1:1
	ds_write2_b32 v47, v14, v15 offset0:2 offset1:3
	v_add_u32_e32 v12, 0x2020, v47
	ds_write2_b32 v12, v8, v9 offset1:1
	v_add_u32_e32 v8, 0x2028, v47
	ds_write2_b32 v8, v10, v11 offset1:1
	v_add_u32_e32 v8, 0x4040, v47
	ds_write2_b32 v8, v20, v21 offset1:1
	v_add_u32_e32 v8, 0x4048, v47
	ds_write2_b32 v8, v22, v23 offset1:1
	v_add_u32_e32 v8, 0x6060, v47
	ds_write2_b32 v8, v16, v17 offset1:1
	v_add_u32_e32 v8, 0x6068, v47
	ds_write2_b32 v8, v18, v19 offset1:1
	v_add_u32_e32 v8, 0x8080, v47
	ds_write2_b32 v8, v28, v29 offset1:1
	v_add_u32_e32 v8, 0x8088, v47
	ds_write2_b32 v8, v30, v31 offset1:1
	v_add_u32_e32 v8, 0xa0a0, v47
	ds_write2_b32 v8, v24, v25 offset1:1
	v_add_u32_e32 v8, 0xa0a8, v47
	ds_write2_b32 v8, v26, v27 offset1:1
	v_add_u32_e32 v8, 0xc0c0, v47
	ds_write2_b32 v8, v36, v37 offset1:1
	v_add_u32_e32 v8, 0xc0c8, v47
	ds_write2_b32 v8, v38, v39 offset1:1
	v_add_u32_e32 v8, 0xe0e0, v47
	ds_write2_b32 v8, v32, v33 offset1:1
	v_add_u32_e32 v8, 0xe0e8, v47
	ds_write2_b32 v8, v34, v35 offset1:1
	v_add_u32_e32 v8, s40, v46
	v_cmp_gt_i32_e32 vcc, s64, v8
	s_waitcnt lgkmcnt(0)
	s_barrier
	s_and_saveexec_b64 s[40:41], vcc
	s_cbranch_execz .LBB0_161
	v_add_u32_e32 v10, 0xfffff700, v8
	v_lshlrev_b32_e32 v11, 1, v8
	v_and_b32_e32 v11, 62, v11
	v_lshrrev_b32_e32 v10, 5, v10
	s_movk_i32 s45, 0x900
	v_add_u32_e32 v9, 0xfffff6c0, v8
	v_or3_b32 v10, v10, v11, s45
	s_movk_i32 s45, 0xffc0
	v_cmp_gt_u32_e32 vcc, s45, v9
	s_sub_i32 s44, 0, s50
	s_add_i32 s44, s48, s44
	v_cndmask_b32_e32 v8, v10, v8, vcc
	ds_read_b32 v10, v48 offset:1028
	ds_read_b32 v11, v48 offset:3084
	ds_read_b32 v14, v48 offset:5140
	ds_read_b32 v15, v48 offset:7196
	ds_read_b32 v16, v48 offset:6168
	ds_read_b32 v17, v48 offset:4112
	ds_read_b32 v18, v48 offset:2056
	ds_read_b32 v19, v48
	v_ashrrev_i32_e32 v9, 31, v8
	v_lshlrev_b64 v[8:9], 12, v[8:9]
	v_lshl_add_u64 v[12:13], s[0:1], 0, v[8:9]
	s_waitcnt lgkmcnt(0)
	v_cvt_pk_bf16_f32 v8, v19, v10
	v_cvt_pk_bf16_f32 v9, v18, v11
	v_cvt_pk_bf16_f32 v10, v17, v14
	v_cvt_pk_bf16_f32 v11, v16, v15
	ds_read_b32 v14, v48 offset:9252
	ds_read_b32 v15, v48 offset:11308
	ds_read_b32 v16, v48 offset:13364
	ds_read_b32 v17, v48 offset:15420
	ds_read_b32 v18, v48 offset:14392
	ds_read_b32 v19, v48 offset:12336
	ds_read_b32 v20, v48 offset:10280
	ds_read_b32 v21, v48 offset:8224
	s_ashr_i32 s45, s44, 31
	v_lshl_add_u64 v[12:13], s[44:45], 1, v[12:13]
	v_mov_b32_e32 v43, v0
	v_lshl_add_u64 v[12:13], v[12:13], 0, v[42:43]
	global_store_dwordx4 v[12:13], v[8:11], off
	s_waitcnt lgkmcnt(0)
	s_nop 0
	v_cvt_pk_bf16_f32 v8, v21, v14
	v_cvt_pk_bf16_f32 v9, v20, v15
	v_cvt_pk_bf16_f32 v10, v19, v16
	v_cvt_pk_bf16_f32 v11, v18, v17
	ds_read_b32 v14, v48 offset:17476
	ds_read_b32 v15, v48 offset:18504
	ds_read_b32 v16, v48 offset:23644
	ds_read_b32 v17, v48 offset:21588
	ds_read_b32 v18, v48 offset:19532
	ds_read_b32 v19, v48 offset:16448
	ds_read_b32 v20, v48 offset:20560
	ds_read_b32 v21, v48 offset:22616
	global_store_dwordx4 v[12:13], v[8:11], off offset:16
	s_waitcnt lgkmcnt(0)
	s_nop 0
	v_cvt_pk_bf16_f32 v8, v19, v14
	v_cvt_pk_bf16_f32 v9, v15, v18
	v_cvt_pk_bf16_f32 v10, v20, v17
	v_cvt_pk_bf16_f32 v11, v21, v16
	ds_read_b32 v14, v48 offset:25700
	ds_read_b32 v15, v48 offset:26728
	ds_read_b32 v16, v48 offset:31868
	ds_read_b32 v17, v48 offset:29812
	ds_read_b32 v18, v48 offset:27756
	ds_read_b32 v19, v48 offset:24672
	ds_read_b32 v20, v48 offset:28784
	ds_read_b32 v21, v48 offset:30840
	global_store_dwordx4 v[12:13], v[8:11], off offset:32
	s_waitcnt lgkmcnt(0)
	s_nop 0
	v_cvt_pk_bf16_f32 v8, v19, v14
	v_cvt_pk_bf16_f32 v9, v15, v18
	v_cvt_pk_bf16_f32 v10, v20, v17
	v_cvt_pk_bf16_f32 v11, v21, v16
	global_store_dwordx4 v[12:13], v[8:11], off offset:48
	s_branch .LBB0_161

; template <int PERMT>
; __device__ __forceinline__ void transpose_job(const float* __restrict__ src, bf16_t* __restrict__ dst, int K, int N, int Npad, const float* __restrict__ kscale, unsigned char* lds_g, int first, int stride) {
;     ...
;     const size_t nz = (size_t)(Npad - N) * K / 8;
;     for (size_t i = (size_t)blockIdx.x * NTHREADS + tid; i < nz; i += (size_t)gridDim.x * NTHREADS) *(u32x4*)(dst + (size_t)N * K + i * 8) = (u32x4){0u, 0u, 0u, 0u};
.LBB0_182:
	v_lshl_add_u64 v[8:9], v[8:9], 0, s[6:7]
	v_cmp_lt_u64_e32 vcc, s[34:35], v[8:9]
	global_store_dwordx4 v[2:3], v[4:7], off
	s_or_b64 s[40:41], vcc, s[40:41]
	v_lshl_add_u64 v[2:3], v[2:3], 0, s[8:9]
	s_andn2_b64 exec, exec, s[40:41]
	s_cbranch_execnz .LBB0_182

; __device__ __forceinline__ unsigned cvt_pk_bf16(float lo, float hi) { unsigned r; asm volatile("v_cvt_pk_bf16_f32 %0, %1, %2" : "=v"(r) : "v"(lo), "v"(hi)); return r; }
; template <int PERMT>
; __device__ __forceinline__ void transpose_job(const float* __restrict__ src, bf16_t* __restrict__ dst, int K, int N, int Npad, const float* __restrict__ kscale, unsigned char* lds_g, int first, int stride) {
;     ...
;         { const int n = tid >> 1, ks = tid & 1;
;           if (n0 + n < N) { bf16_t* dp = dst + (size_t)dst_row<PERMT>(n0 + n) * K + k0 + 32 * ks;
; #pragma unroll
;             for (int eb = 0; eb < 4; ++eb) { float v[8];
; #pragma unroll
;               for (int e = 0; e < 8; ++e) v[e] = T[(32 * ks + 8 * eb + e) * 257 + n];
;               u32x4 w; w.x = cvt_pk_bf16(v[0], v[1]); w.y = cvt_pk_bf16(v[2], v[3]); w.z = cvt_pk_bf16(v[4], v[5]); w.w = cvt_pk_bf16(v[6], v[7]);
;               *(u32x4*)(dp + 8 * eb) = w; } } }
.LBB0_185:
	s_or_b64 exec, exec, s[50:51]
	ds_read_b32 v1, v58 offset:1028
	ds_read_b32 v9, v58 offset:3084
	ds_read_b32 v10, v58 offset:5140
	ds_read_b32 v11, v58 offset:7196
	ds_read_b32 v12, v58 offset:6168
	ds_read_b32 v13, v58 offset:4112
	ds_read_b32 v14, v58 offset:2056
	ds_read_b32 v8, v58
	s_sub_i32 s50, 0, s92
	v_ashrrev_i32_e32 v3, 31, v2
	s_add_i32 s50, s90, s50
	v_lshlrev_b64 v[2:3], 10, v[2:3]
	s_waitcnt lgkmcnt(0)
	v_cvt_pk_bf16_f32 v8, v8, v1
	v_cvt_pk_bf16_f32 v9, v14, v9
	v_cvt_pk_bf16_f32 v10, v13, v10
	v_cvt_pk_bf16_f32 v11, v12, v11
	ds_read_b32 v1, v58 offset:9252
	ds_read_b32 v12, v58 offset:11308
	ds_read_b32 v13, v58 offset:13364
	ds_read_b32 v14, v58 offset:15420
	ds_read_b32 v15, v58 offset:14392
	ds_read_b32 v16, v58 offset:12336
	ds_read_b32 v17, v58 offset:10280
	ds_read_b32 v18, v58 offset:8224
	v_lshl_add_u64 v[2:3], s[44:45], 0, v[2:3]
	s_ashr_i32 s51, s50, 31
	v_lshl_add_u64 v[2:3], s[50:51], 1, v[2:3]
	v_mov_b32_e32 v49, v0
	v_lshl_add_u64 v[2:3], v[2:3], 0, v[48:49]
	global_store_dwordx4 v[2:3], v[8:11], off
	s_waitcnt lgkmcnt(0)
	s_nop 0
	v_cvt_pk_bf16_f32 v8, v18, v1
	v_cvt_pk_bf16_f32 v9, v17, v12
	v_cvt_pk_bf16_f32 v10, v16, v13
	v_cvt_pk_bf16_f32 v11, v15, v14
	ds_read_b32 v1, v58 offset:17476
	ds_read_b32 v12, v58 offset:18504
	ds_read_b32 v13, v58 offset:23644
	ds_read_b32 v14, v58 offset:21588
	ds_read_b32 v15, v58 offset:19532
	ds_read_b32 v16, v58 offset:16448
	ds_read_b32 v17, v58 offset:20560
	ds_read_b32 v18, v58 offset:22616
	global_store_dwordx4 v[2:3], v[8:11], off offset:16
	s_waitcnt lgkmcnt(0)
	s_nop 0
	v_cvt_pk_bf16_f32 v8, v16, v1
	v_cvt_pk_bf16_f32 v9, v12, v15
	v_cvt_pk_bf16_f32 v10, v17, v14
	v_cvt_pk_bf16_f32 v11, v18, v13
	ds_read_b32 v1, v58 offset:25700
	ds_read_b32 v12, v58 offset:26728
	ds_read_b32 v13, v58 offset:31868
	ds_read_b32 v14, v58 offset:29812
	ds_read_b32 v15, v58 offset:27756
	ds_read_b32 v16, v58 offset:24672
	ds_read_b32 v17, v58 offset:28784
	ds_read_b32 v18, v58 offset:30840
	global_store_dwordx4 v[2:3], v[8:11], off offset:32
	s_waitcnt lgkmcnt(0)
	s_nop 0
	v_cvt_pk_bf16_f32 v8, v16, v1
	v_cvt_pk_bf16_f32 v9, v12, v15
	v_cvt_pk_bf16_f32 v10, v17, v14
	v_cvt_pk_bf16_f32 v11, v18, v13
	global_store_dwordx4 v[2:3], v[8:11], off offset:48

; template <int PERMT>
; __device__ __forceinline__ void transpose_job(const float* __restrict__ src, bf16_t* __restrict__ dst, int K, int N, int Npad, const float* __restrict__ kscale, unsigned char* lds_g, int first, int stride) {
;     ...
;     const size_t nz = (size_t)(Npad - N) * K / 8;
;     for (size_t i = (size_t)blockIdx.x * NTHREADS + tid; i < nz; i += (size_t)gridDim.x * NTHREADS) *(u32x4*)(dst + (size_t)N * K + i * 8) = (u32x4){0u, 0u, 0u, 0u};
.LBB0_224:
	v_lshl_add_u64 v[2:3], v[2:3], 0, s[6:7]
	v_cmp_lt_u64_e32 vcc, s[38:39], v[2:3]
	global_store_dwordx4 v[8:9], v[4:7], off
	s_or_b64 s[44:45], vcc, s[44:45]
	v_lshl_add_u64 v[8:9], v[8:9], 0, s[8:9]
	s_andn2_b64 exec, exec, s[44:45]
	s_cbranch_execnz .LBB0_224

; __device__ __forceinline__ unsigned cvt_pk_bf16(float lo, float hi) { unsigned r; asm volatile("v_cvt_pk_bf16_f32 %0, %1, %2" : "=v"(r) : "v"(lo), "v"(hi)); return r; }
; template <int PERMT>
; __device__ __forceinline__ void transpose_job(const float* __restrict__ src, bf16_t* __restrict__ dst, int K, int N, int Npad, const float* __restrict__ kscale, unsigned char* lds_g, int first, int stride) {
;     ...
;           for (int i = 0; i < 8; ++i) { const int k = k0 + kk + 8 * i; if (kscale) v[i] = v[i] * kscale[k];
;               float* tp = T + (kk + 8 * i) * 257 + 4 * n4; tp[0] = v[i][0]; tp[1] = v[i][1]; tp[2] = v[i][2]; tp[3] = v[i][3]; } }
;         __syncthreads();
;         { const int n = tid >> 1, ks = tid & 1;
;           if (n0 + n < N) { bf16_t* dp = dst + (size_t)dst_row<PERMT>(n0 + n) * K + k0 + 32 * ks;
; #pragma unroll
;             for (int eb = 0; eb < 4; ++eb) { float v[8];
; #pragma unroll
;               for (int e = 0; e < 8; ++e) v[e] = T[(32 * ks + 8 * eb + e) * 257 + n];
;               u32x4 w; w.x = cvt_pk_bf16(v[0], v[1]); w.y = cvt_pk_bf16(v[2], v[3]); w.z = cvt_pk_bf16(v[4], v[5]); w.w = cvt_pk_bf16(v[6], v[7]);
;               *(u32x4*)(dp + 8 * eb) = w; } } }
.LBB0_256:
	v_add_u32_e32 v1, 0xc0c0, v58
	ds_write2_b32 v1, v20, v21 offset1:1
	v_add_u32_e32 v1, 0xc0c8, v58
	ds_write2_b32 v1, v2, v3 offset1:1
	v_add_u32_e32 v1, 0xe0e0, v58
	v_add_u32_e32 v2, s50, v56
	ds_write2_b32 v1, v16, v17 offset1:1
	v_add_u32_e32 v1, 0xe0e8, v58
	v_cmp_gt_i32_e32 vcc, s77, v2
	ds_write2_b32 v1, v18, v19 offset1:1
	s_waitcnt lgkmcnt(0)
	s_barrier
	s_and_saveexec_b64 s[0:1], vcc
	s_cbranch_execz .LBB0_227
	ds_read_b32 v1, v57 offset:1028
	ds_read_b32 v9, v57 offset:3084
	ds_read_b32 v10, v57 offset:5140
	ds_read_b32 v11, v57 offset:7196
	ds_read_b32 v12, v57 offset:6168
	ds_read_b32 v13, v57 offset:4112
	ds_read_b32 v14, v57 offset:2056
	ds_read_b32 v8, v57
	s_sub_i32 s50, 0, s50
	v_ashrrev_i32_e32 v3, 31, v2
	s_add_i32 s50, s88, s50
	v_lshlrev_b64 v[2:3], 9, v[2:3]
	s_waitcnt lgkmcnt(0)
	v_cvt_pk_bf16_f32 v8, v8, v1
	v_cvt_pk_bf16_f32 v9, v14, v9
	v_cvt_pk_bf16_f32 v10, v13, v10
	v_cvt_pk_bf16_f32 v11, v12, v11
	ds_read_b32 v1, v57 offset:9252
	ds_read_b32 v12, v57 offset:11308
	ds_read_b32 v13, v57 offset:13364
	ds_read_b32 v14, v57 offset:15420
	ds_read_b32 v15, v57 offset:14392
	ds_read_b32 v16, v57 offset:12336
	ds_read_b32 v17, v57 offset:10280
	ds_read_b32 v18, v57 offset:8224
	v_lshl_add_u64 v[2:3], s[44:45], 0, v[2:3]
	s_ashr_i32 s51, s50, 31
	v_lshl_add_u64 v[2:3], s[50:51], 1, v[2:3]
	v_mov_b32_e32 v47, v0
	v_lshl_add_u64 v[2:3], v[2:3], 0, v[46:47]
	global_store_dwordx4 v[2:3], v[8:11], off
	s_waitcnt lgkmcnt(0)
	s_nop 0
	v_cvt_pk_bf16_f32 v8, v18, v1
	v_cvt_pk_bf16_f32 v9, v17, v12
	v_cvt_pk_bf16_f32 v10, v16, v13
	v_cvt_pk_bf16_f32 v11, v15, v14
	ds_read_b32 v1, v57 offset:17476
	ds_read_b32 v12, v57 offset:18504
	ds_read_b32 v13, v57 offset:23644
	ds_read_b32 v14, v57 offset:21588
	ds_read_b32 v15, v57 offset:19532
	ds_read_b32 v16, v57 offset:16448
	ds_read_b32 v17, v57 offset:20560
	ds_read_b32 v18, v57 offset:22616
	global_store_dwordx4 v[2:3], v[8:11], off offset:16
	s_waitcnt lgkmcnt(0)
	s_nop 0
	v_cvt_pk_bf16_f32 v8, v16, v1
	v_cvt_pk_bf16_f32 v9, v12, v15
	v_cvt_pk_bf16_f32 v10, v17, v14
	v_cvt_pk_bf16_f32 v11, v18, v13
	ds_read_b32 v1, v57 offset:25700
	ds_read_b32 v12, v57 offset:26728
	ds_read_b32 v13, v57 offset:31868
	ds_read_b32 v14, v57 offset:29812
	ds_read_b32 v15, v57 offset:27756
	ds_read_b32 v16, v57 offset:24672
	ds_read_b32 v17, v57 offset:28784
	ds_read_b32 v18, v57 offset:30840
	global_store_dwordx4 v[2:3], v[8:11], off offset:32
	s_waitcnt lgkmcnt(0)
	s_nop 0
	v_cvt_pk_bf16_f32 v8, v16, v1
	v_cvt_pk_bf16_f32 v9, v12, v15
	v_cvt_pk_bf16_f32 v10, v17, v14
	v_cvt_pk_bf16_f32 v11, v18, v13
	global_store_dwordx4 v[2:3], v[8:11], off offset:48
	s_branch .LBB0_227

; __device__ __forceinline__ unsigned cvt_pk_bf16(float lo, float hi) { unsigned r; asm volatile("v_cvt_pk_bf16_f32 %0, %1, %2" : "=v"(r) : "v"(lo), "v"(hi)); return r; }
; template <int PERMT>
; __device__ __forceinline__ void transpose_job(const float* __restrict__ src, bf16_t* __restrict__ dst, int K, int N, int Npad, const float* __restrict__ kscale, unsigned char* lds_g, int first, int stride) {
;     ...
;           for (int i = 0; i < 8; ++i) { const int k = k0 + kk + 8 * i; if (kscale) v[i] = v[i] * kscale[k];
;               float* tp = T + (kk + 8 * i) * 257 + 4 * n4; tp[0] = v[i][0]; tp[1] = v[i][1]; tp[2] = v[i][2]; tp[3] = v[i][3]; } }
;         __syncthreads();
;         { const int n = tid >> 1, ks = tid & 1;
;           if (n0 + n < N) { bf16_t* dp = dst + (size_t)dst_row<PERMT>(n0 + n) * K + k0 + 32 * ks;
; #pragma unroll
;             for (int eb = 0; eb < 4; ++eb) { float v[8];
; #pragma unroll
;               for (int e = 0; e < 8; ++e) v[e] = T[(32 * ks + 8 * eb + e) * 257 + n];
;               u32x4 w; w.x = cvt_pk_bf16(v[0], v[1]); w.y = cvt_pk_bf16(v[2], v[3]); w.z = cvt_pk_bf16(v[4], v[5]); w.w = cvt_pk_bf16(v[6], v[7]);
;               *(u32x4*)(dp + 8 * eb) = w; } } }
.LBB0_294:
	v_add_u32_e32 v1, 0xc0c0, v58
	ds_write2_b32 v1, v20, v21 offset1:1
	v_add_u32_e32 v1, 0xc0c8, v58
	ds_write2_b32 v1, v2, v3 offset1:1
	v_add_u32_e32 v1, 0xe0e0, v58
	v_add_u32_e32 v2, s50, v56
	ds_write2_b32 v1, v12, v13 offset1:1
	v_add_u32_e32 v1, 0xe0e8, v58
	v_cmp_gt_i32_e32 vcc, s80, v2
	ds_write2_b32 v1, v14, v15 offset1:1
	s_waitcnt lgkmcnt(0)
	s_barrier
	s_and_saveexec_b64 s[0:1], vcc
	s_cbranch_execz .LBB0_265
	ds_read_b32 v1, v57 offset:1028
	ds_read_b32 v9, v57 offset:3084
	ds_read_b32 v10, v57 offset:5140
	ds_read_b32 v11, v57 offset:7196
	ds_read_b32 v12, v57 offset:6168
	ds_read_b32 v13, v57 offset:4112
	ds_read_b32 v14, v57 offset:2056
	ds_read_b32 v8, v57
	s_sub_i32 s50, 0, s90
	v_ashrrev_i32_e32 v3, 31, v2
	s_add_i32 s50, s88, s50
	v_lshlrev_b64 v[2:3], 12, v[2:3]
	s_waitcnt lgkmcnt(0)
	v_cvt_pk_bf16_f32 v8, v8, v1
	v_cvt_pk_bf16_f32 v9, v14, v9
	v_cvt_pk_bf16_f32 v10, v13, v10
	v_cvt_pk_bf16_f32 v11, v12, v11
	ds_read_b32 v1, v57 offset:9252
	ds_read_b32 v12, v57 offset:11308
	ds_read_b32 v13, v57 offset:13364
	ds_read_b32 v14, v57 offset:15420
	ds_read_b32 v15, v57 offset:14392
	ds_read_b32 v16, v57 offset:12336
	ds_read_b32 v17, v57 offset:10280
	ds_read_b32 v18, v57 offset:8224
	v_lshl_add_u64 v[2:3], s[44:45], 0, v[2:3]
	s_ashr_i32 s51, s50, 31
	v_lshl_add_u64 v[2:3], s[50:51], 1, v[2:3]
	v_mov_b32_e32 v47, v0
	v_lshl_add_u64 v[2:3], v[2:3], 0, v[46:47]
	global_store_dwordx4 v[2:3], v[8:11], off
	s_waitcnt lgkmcnt(0)
	s_nop 0
	v_cvt_pk_bf16_f32 v8, v18, v1
	v_cvt_pk_bf16_f32 v9, v17, v12
	v_cvt_pk_bf16_f32 v10, v16, v13
	v_cvt_pk_bf16_f32 v11, v15, v14
	ds_read_b32 v1, v57 offset:17476
	ds_read_b32 v12, v57 offset:18504
	ds_read_b32 v13, v57 offset:23644
	ds_read_b32 v14, v57 offset:21588
	ds_read_b32 v15, v57 offset:19532
	ds_read_b32 v16, v57 offset:16448
	ds_read_b32 v17, v57 offset:20560
	ds_read_b32 v18, v57 offset:22616
	global_store_dwordx4 v[2:3], v[8:11], off offset:16
	s_waitcnt lgkmcnt(0)
	s_nop 0
	v_cvt_pk_bf16_f32 v8, v16, v1
	v_cvt_pk_bf16_f32 v9, v12, v15
	v_cvt_pk_bf16_f32 v10, v17, v14
	v_cvt_pk_bf16_f32 v11, v18, v13
	ds_read_b32 v1, v57 offset:25700
	ds_read_b32 v12, v57 offset:26728
	ds_read_b32 v13, v57 offset:31868
	ds_read_b32 v14, v57 offset:29812
	ds_read_b32 v15, v57 offset:27756
	ds_read_b32 v16, v57 offset:24672
	ds_read_b32 v17, v57 offset:28784
	ds_read_b32 v18, v57 offset:30840
	global_store_dwordx4 v[2:3], v[8:11], off offset:32
	s_waitcnt lgkmcnt(0)
	s_nop 0
	v_cvt_pk_bf16_f32 v8, v16, v1
	v_cvt_pk_bf16_f32 v9, v12, v15
	v_cvt_pk_bf16_f32 v10, v17, v14
	v_cvt_pk_bf16_f32 v11, v18, v13
	global_store_dwordx4 v[2:3], v[8:11], off offset:48
	s_branch .LBB0_265

; __device__ __forceinline__ unsigned cvt_pk_bf16(float lo, float hi) { unsigned r; asm volatile("v_cvt_pk_bf16_f32 %0, %1, %2" : "=v"(r) : "v"(lo), "v"(hi)); return r; }
; template <int PERMT>
; __device__ __forceinline__ void transpose_job(const float* __restrict__ src, bf16_t* __restrict__ dst, int K, int N, int Npad, const float* __restrict__ kscale, unsigned char* lds_g, int first, int stride) {
;     ...
;         { const int n = tid >> 1, ks = tid & 1;
;           if (n0 + n < N) { bf16_t* dp = dst + (size_t)dst_row<PERMT>(n0 + n) * K + k0 + 32 * ks;
; #pragma unroll
;             for (int eb = 0; eb < 4; ++eb) { float v[8];
; #pragma unroll
;               for (int e = 0; e < 8; ++e) v[e] = T[(32 * ks + 8 * eb + e) * 257 + n];
;               u32x4 w; w.x = cvt_pk_bf16(v[0], v[1]); w.y = cvt_pk_bf16(v[2], v[3]); w.z = cvt_pk_bf16(v[4], v[5]); w.w = cvt_pk_bf16(v[6], v[7]);
;               *(u32x4*)(dp + 8 * eb) = w; } } }
.LBB0_303:
	s_or_b64 exec, exec, s[46:47]
	ds_read_b32 v9, v16 offset:1028
	ds_read_b32 v17, v16 offset:3084
	ds_read_b32 v20, v16 offset:5140
	ds_read_b32 v21, v16 offset:7196
	ds_read_b32 v22, v16 offset:6168
	ds_read_b32 v23, v16 offset:4112
	ds_read_b32 v19, v16 offset:2056
	ds_read_b32 v18, v16
	s_sub_i32 s46, 0, s50
	v_ashrrev_i32_e32 v11, 31, v10
	s_add_i32 s46, s48, s46
	v_lshlrev_b64 v[10:11], 12, v[10:11]
	s_waitcnt lgkmcnt(0)
	v_cvt_pk_bf16_f32 v18, v18, v9
	v_cvt_pk_bf16_f32 v19, v19, v17
	v_cvt_pk_bf16_f32 v20, v23, v20
	v_cvt_pk_bf16_f32 v21, v22, v21
	ds_read_b32 v17, v16 offset:9252
	ds_read_b32 v22, v16 offset:11308
	ds_read_b32 v23, v16 offset:13364
	ds_read_b32 v24, v16 offset:15420
	ds_read_b32 v25, v16 offset:14392
	ds_read_b32 v26, v16 offset:12336
	ds_read_b32 v27, v16 offset:10280
	ds_read_b32 v28, v16 offset:8224
	v_lshl_add_u64 v[10:11], s[42:43], 0, v[10:11]
	s_ashr_i32 s47, s46, 31
	v_lshl_add_u64 v[10:11], s[46:47], 1, v[10:11]
	v_mov_b32_e32 v9, v0
	v_lshl_add_u64 v[10:11], v[10:11], 0, v[8:9]
	global_store_dwordx4 v[10:11], v[18:21], off
	s_waitcnt lgkmcnt(0)
	s_nop 0
	v_cvt_pk_bf16_f32 v18, v28, v17
	v_cvt_pk_bf16_f32 v19, v27, v22
	v_cvt_pk_bf16_f32 v20, v26, v23
	v_cvt_pk_bf16_f32 v21, v25, v24
	ds_read_b32 v9, v16 offset:17476
	ds_read_b32 v17, v16 offset:18504
	ds_read_b32 v22, v16 offset:23644
	ds_read_b32 v23, v16 offset:21588
	ds_read_b32 v24, v16 offset:19532
	ds_read_b32 v25, v16 offset:16448
	ds_read_b32 v26, v16 offset:20560
	ds_read_b32 v27, v16 offset:22616
	global_store_dwordx4 v[10:11], v[18:21], off offset:16
	s_waitcnt lgkmcnt(0)
	s_nop 0
	v_cvt_pk_bf16_f32 v18, v25, v9
	v_cvt_pk_bf16_f32 v19, v17, v24
	v_cvt_pk_bf16_f32 v20, v26, v23
	v_cvt_pk_bf16_f32 v21, v27, v22
	ds_read_b32 v9, v16 offset:25700
	ds_read_b32 v17, v16 offset:26728
	ds_read_b32 v22, v16 offset:31868
	ds_read_b32 v23, v16 offset:29812
	ds_read_b32 v24, v16 offset:27756
	ds_read_b32 v25, v16 offset:24672
	ds_read_b32 v26, v16 offset:28784
	ds_read_b32 v27, v16 offset:30840
	global_store_dwordx4 v[10:11], v[18:21], off offset:32
	s_waitcnt lgkmcnt(0)
	s_nop 0
	v_cvt_pk_bf16_f32 v18, v25, v9
	v_cvt_pk_bf16_f32 v19, v17, v24
	v_cvt_pk_bf16_f32 v20, v26, v23
	v_cvt_pk_bf16_f32 v21, v27, v22
	global_store_dwordx4 v[10:11], v[18:21], off offset:48

; __device__ __forceinline__ unsigned cvt_pk_bf16(float lo, float hi) { unsigned r; asm volatile("v_cvt_pk_bf16_f32 %0, %1, %2" : "=v"(r) : "v"(lo), "v"(hi)); return r; }
; template <int PERMT>
; __device__ __forceinline__ void transpose_job(const float* __restrict__ src, bf16_t* __restrict__ dst, int K, int N, int Npad, const float* __restrict__ kscale, unsigned char* lds_g, int first, int stride) {
;     ...
;           for (int i = 0; i < 8; ++i) { const int k = k0 + kk + 8 * i; if (kscale) v[i] = v[i] * kscale[k];
;               float* tp = T + (kk + 8 * i) * 257 + 4 * n4; tp[0] = v[i][0]; tp[1] = v[i][1]; tp[2] = v[i][2]; tp[3] = v[i][3]; } }
;         __syncthreads();
;         { const int n = tid >> 1, ks = tid & 1;
;           if (n0 + n < N) { bf16_t* dp = dst + (size_t)dst_row<PERMT>(n0 + n) * K + k0 + 32 * ks;
; #pragma unroll
;             for (int eb = 0; eb < 4; ++eb) { float v[8];
; #pragma unroll
;               for (int e = 0; e < 8; ++e) v[e] = T[(32 * ks + 8 * eb + e) * 257 + n];
;               u32x4 w; w.x = cvt_pk_bf16(v[0], v[1]); w.y = cvt_pk_bf16(v[2], v[3]); w.z = cvt_pk_bf16(v[4], v[5]); w.w = cvt_pk_bf16(v[6], v[7]);
;               *(u32x4*)(dp + 8 * eb) = w; } } }
.LBB0_329:
	s_or_b64 exec, exec, s[46:47]
	s_waitcnt vmcnt(0) lgkmcnt(0)
	ds_write2_b32 v48, v12, v13 offset1:1
	ds_write2_b32 v48, v14, v15 offset0:2 offset1:3
	v_add_u32_e32 v12, 0x2020, v48
	ds_write2_b32 v12, v8, v9 offset1:1
	v_add_u32_e32 v8, 0x2028, v48
	ds_write2_b32 v8, v10, v11 offset1:1
	v_add_u32_e32 v8, 0x4040, v48
	ds_write2_b32 v8, v20, v21 offset1:1
	v_add_u32_e32 v8, 0x4048, v48
	ds_write2_b32 v8, v22, v23 offset1:1
	v_add_u32_e32 v8, 0x6060, v48
	ds_write2_b32 v8, v16, v17 offset1:1
	v_add_u32_e32 v8, 0x6068, v48
	ds_write2_b32 v8, v18, v19 offset1:1
	v_add_u32_e32 v8, 0x8080, v48
	ds_write2_b32 v8, v28, v29 offset1:1
	v_add_u32_e32 v8, 0x8088, v48
	ds_write2_b32 v8, v30, v31 offset1:1
	v_add_u32_e32 v8, 0xa0a0, v48
	ds_write2_b32 v8, v24, v25 offset1:1
	v_add_u32_e32 v8, 0xa0a8, v48
	ds_write2_b32 v8, v26, v27 offset1:1
	v_add_u32_e32 v8, 0xc0c0, v48
	ds_write2_b32 v8, v36, v37 offset1:1
	v_add_u32_e32 v8, 0xc0c8, v48
	ds_write2_b32 v8, v38, v39 offset1:1
	v_add_u32_e32 v8, 0xe0e0, v48
	ds_write2_b32 v8, v32, v33 offset1:1
	v_add_u32_e32 v8, 0xe0e8, v48
	ds_write2_b32 v8, v34, v35 offset1:1
	v_add_u32_e32 v8, s44, v47
	v_cmp_gt_i32_e32 vcc, s80, v8
	s_waitcnt lgkmcnt(0)
	s_barrier
	s_and_saveexec_b64 s[44:45], vcc
	s_cbranch_execz .LBB0_312
	ds_read_b32 v9, v49 offset:1028
	ds_read_b32 v14, v49 offset:3084
	ds_read_b32 v15, v49 offset:5140
	ds_read_b32 v16, v49 offset:7196
	ds_read_b32 v17, v49 offset:6168
	ds_read_b32 v18, v49 offset:4112
	ds_read_b32 v19, v49 offset:2056
	ds_read_b32 v20, v49
	v_mov_b64_e32 v[10:11], s[0:1]
	v_mad_i64_i32 v[12:13], s[46:47], v8, s83, v[10:11]
	s_ashr_i32 s43, s42, 31
	s_waitcnt lgkmcnt(0)
	v_cvt_pk_bf16_f32 v8, v20, v9
	v_cvt_pk_bf16_f32 v9, v19, v14
	v_cvt_pk_bf16_f32 v10, v18, v15
	v_cvt_pk_bf16_f32 v11, v17, v16
	ds_read_b32 v14, v49 offset:9252
	ds_read_b32 v15, v49 offset:11308
	ds_read_b32 v16, v49 offset:13364
	ds_read_b32 v17, v49 offset:15420
	ds_read_b32 v18, v49 offset:14392
	ds_read_b32 v19, v49 offset:12336
	ds_read_b32 v20, v49 offset:10280
	ds_read_b32 v21, v49 offset:8224
	v_lshl_add_u64 v[12:13], s[42:43], 1, v[12:13]
	v_mov_b32_e32 v41, v0
	v_lshl_add_u64 v[12:13], v[12:13], 0, v[40:41]
	global_store_dwordx4 v[12:13], v[8:11], off
	s_waitcnt lgkmcnt(0)
	s_nop 0
	v_cvt_pk_bf16_f32 v8, v21, v14
	v_cvt_pk_bf16_f32 v9, v20, v15
	v_cvt_pk_bf16_f32 v10, v19, v16
	v_cvt_pk_bf16_f32 v11, v18, v17
	ds_read_b32 v14, v49 offset:17476
	ds_read_b32 v15, v49 offset:18504
	ds_read_b32 v16, v49 offset:23644
	ds_read_b32 v17, v49 offset:21588
	ds_read_b32 v18, v49 offset:19532
	ds_read_b32 v19, v49 offset:16448
	ds_read_b32 v20, v49 offset:20560
	ds_read_b32 v21, v49 offset:22616
	global_store_dwordx4 v[12:13], v[8:11], off offset:16
	s_waitcnt lgkmcnt(0)
	s_nop 0
	v_cvt_pk_bf16_f32 v8, v19, v14
	v_cvt_pk_bf16_f32 v9, v15, v18
	v_cvt_pk_bf16_f32 v10, v20, v17
	v_cvt_pk_bf16_f32 v11, v21, v16
	ds_read_b32 v14, v49 offset:25700
	ds_read_b32 v15, v49 offset:26728
	ds_read_b32 v16, v49 offset:31868
	ds_read_b32 v17, v49 offset:29812
	ds_read_b32 v18, v49 offset:27756
	ds_read_b32 v19, v49 offset:24672
	ds_read_b32 v20, v49 offset:28784
	ds_read_b32 v21, v49 offset:30840
	global_store_dwordx4 v[12:13], v[8:11], off offset:32
	s_waitcnt lgkmcnt(0)
	s_nop 0
	v_cvt_pk_bf16_f32 v8, v19, v14
	v_cvt_pk_bf16_f32 v9, v15, v18
	v_cvt_pk_bf16_f32 v10, v20, v17
	v_cvt_pk_bf16_f32 v11, v21, v16
	global_store_dwordx4 v[12:13], v[8:11], off offset:48
	s_branch .LBB0_312

; __device__ __forceinline__ u32x4 pack8(const f32x4 v0, const f32x4 v1) { u32x4 w; w.x = cvt_pk_bf16(v0[0], v0[1]); w.y = cvt_pk_bf16(v0[2], v0[3]); w.z = cvt_pk_bf16(v1[0], v1[1]); w.w = cvt_pk_bf16(v1[2], v1[3]); return w; }
; __device__ __forceinline__ int otid() { int t = threadIdx.x; asm volatile("" : "+v"(t)); return t; }
; __device__ __forceinline__ void modulate_rows(const float* __restrict__ x, const float* __restrict__ sc, const float* __restrict__ sh, bf16_t* __restrict__ u) {
;     const size_t n8 = (size_t)S * DM / 8;
;     for (size_t i = (size_t)blockIdx.x * NTHREADS + otid(); i < n8; i += (size_t)gridDim.x * NTHREADS) {
;         const int col = (int)((i * 8) % DM);
;         const f32x4 x0 = *(const f32x4*)(x + i * 8), x1 = *(const f32x4*)(x + i * 8 + 4);
;         const f32x4 s0 = *(const f32x4*)(sc + col) + 1.0f, s1 = *(const f32x4*)(sc + col + 4) + 1.0f;
;         const f32x4 h0 = *(const f32x4*)(sh + col), h1 = *(const f32x4*)(sh + col + 4);
;         *(u32x4*)(u + i * 8) = pg8::pack8(x0 * s0 + h0, x1 * s1 + h1);
;     }
.LBB0_333:
	v_lshlrev_b32_e32 v8, 2, v6
	v_and_b32_e32 v8, 0x1fe0, v8
	v_lshl_add_u64 v[34:35], s[4:5], 0, v[8:9]
	flat_load_dwordx4 v[10:13], v[4:5]
	flat_load_dwordx4 v[14:17], v[4:5] offset:16
	v_lshl_add_u64 v[36:37], s[12:13], 0, v[8:9]
	flat_load_dwordx4 v[18:21], v[34:35]
	flat_load_dwordx4 v[22:25], v[34:35] offset:16
	flat_load_dwordx4 v[26:29], v[36:37]
	flat_load_dwordx4 v[30:33], v[36:37] offset:16
	v_lshl_add_u64 v[0:1], v[0:1], 0, s[6:7]
	v_cmp_lt_u64_e32 vcc, s[18:19], v[0:1]
	v_lshl_add_u64 v[4:5], v[4:5], 0, s[14:15]
	v_lshl_add_u64 v[6:7], v[6:7], 0, s[10:11]
	s_or_b64 s[16:17], vcc, s[16:17]
	s_waitcnt vmcnt(0) lgkmcnt(0)
	v_pk_add_f32 v[20:21], v[20:21], 1.0 op_sel_hi:[1,0]
	v_pk_add_f32 v[18:19], v[18:19], 1.0 op_sel_hi:[1,0]
	v_pk_add_f32 v[24:25], v[24:25], 1.0 op_sel_hi:[1,0]
	v_pk_add_f32 v[22:23], v[22:23], 1.0 op_sel_hi:[1,0]
	v_pk_fma_f32 v[12:13], v[12:13], v[20:21], v[28:29]
	v_pk_fma_f32 v[10:11], v[10:11], v[18:19], v[26:27]
	v_pk_fma_f32 v[16:17], v[16:17], v[24:25], v[32:33]
	v_pk_fma_f32 v[14:15], v[14:15], v[22:23], v[30:31]
	v_cvt_pk_bf16_f32 v10, v10, v11
	v_cvt_pk_bf16_f32 v11, v12, v13
	s_nop 0
	v_cvt_pk_bf16_f32 v12, v14, v15
	v_cvt_pk_bf16_f32 v13, v16, v17
	global_store_dwordx4 v[2:3], v[10:13], off
	v_lshl_add_u64 v[2:3], v[2:3], 0, s[8:9]
	s_andn2_b64 exec, exec, s[16:17]
	s_cbranch_execnz .LBB0_333

; __device__ __forceinline__ int otid() { int t = threadIdx.x; asm volatile("" : "+v"(t)); return t; }
; __device__ __forceinline__ void rope_table(float* __restrict__ rope) {
;     for (int i = blockIdx.x * NTHREADS + otid(); i < S * 32; i += gridDim.x * NTHREADS) {
;         const int pos = i >> 5, j = i & 31;
;         const float inv = exp2f(-(float)j * (13.287712379549449f / 32.0f));
;         const float ang = (float)pos * inv;
;         const double rev = (double)ang * 0.15915494309189535;
;         const double fr = rev - floor(rev);
;         const float ar = (float)(fr * 6.283185307179586);
;         rope[(size_t)pos * 64 + j] = cosf(ar); rope[(size_t)pos * 64 + 32 + j] = sinf(ar);
;     }
.LBB0_336:
	s_or_b64 exec, exec, s[0:1]
	v_mul_f32_e32 v16, v15, v15
	v_fmamk_f32 v17, v16, 0xb94c1982, v9
	v_fmaak_f32 v17, v16, v17, 0xbe2aaa9d
	v_mul_f32_e32 v17, v16, v17
	v_fmac_f32_e32 v15, v15, v17
	v_fmamk_f32 v17, v16, 0x37d75334, v10
	v_fmaak_f32 v17, v16, v17, 0x3d2aabf7
	v_fmaak_f32 v17, v16, v17, 0xbf000004
	v_fma_f32 v16, v16, v17, 1.0
	v_and_b32_e32 v17, 1, v0
	v_lshlrev_b32_e32 v0, 30, v0
	v_cmp_eq_u32_e64 s[0:1], 0, v17
	v_and_b32_e32 v0, 0x80000000, v0
	v_xor_b32_e32 v13, v14, v13
	v_cndmask_b32_e64 v15, v16, v15, s[0:1]
	v_xor_b32_e32 v0, v13, v0
	v_xor_b32_e32 v0, v0, v15
	v_add_u32_e32 v6, s20, v6
	v_cndmask_b32_e32 v0, v12, v0, vcc
	v_cmp_lt_i32_e32 vcc, s36, v6
	s_or_b64 s[12:13], vcc, s[12:13]
	global_store_dword v[4:5], v0, off offset:128
	s_andn2_b64 exec, exec, s[12:13]
	s_cbranch_execz .LBB0_345

; __device__ __forceinline__ void rope_table(float* __restrict__ rope) {
;     ...
;         const double rev = (double)ang * 0.15915494309189535;
;         const double fr = rev - floor(rev);
;         const float ar = (float)(fr * 6.283185307179586);
;         rope[(size_t)pos * 64 + j] = cosf(ar); rope[(size_t)pos * 64 + 32 + j] = sinf(ar);
.LBB0_339:
	s_andn2_saveexec_b64 s[0:1], s[18:19]
	v_mul_f32_e64 v0, |v13|, s30
	v_rndne_f32_e32 v15, v0
	v_cvt_i32_f32_e32 v0, v15
	v_fma_f32 v5, v15, s31, |v13|
	v_fmac_f32_e32 v5, 0xb3a22168, v15
	v_fmac_f32_e32 v5, 0xa7c234c4, v15
	s_or_b64 exec, exec, s[0:1]
	v_mul_f32_e32 v15, v5, v5
	v_fmamk_f32 v16, v15, 0xb94c1982, v9
	v_fmaak_f32 v16, v15, v16, 0xbe2aaa9d
	v_mul_f32_e32 v16, v15, v16
	v_fmac_f32_e32 v5, v5, v16
	v_fmamk_f32 v16, v15, 0x37d75334, v10
	v_fmaak_f32 v16, v15, v16, 0x3d2aabf7
	v_fmaak_f32 v16, v15, v16, 0xbf000004
	v_fma_f32 v15, v15, v16, 1.0
	v_and_b32_e32 v16, 1, v0
	v_cmp_eq_u32_e32 vcc, 0, v16
	v_lshlrev_b32_e32 v0, 30, v0
	s_nop 0
	v_cndmask_b32_e64 v5, -v5, v15, vcc
	v_bitop3_b32 v0, v0, v5, s34 bitop3:0x6c
	v_ashrrev_i32_e32 v5, 31, v4
	v_cmp_class_f32_e64 vcc, v13, s35
	v_lshlrev_b64 v[4:5], 8, v[4:5]
	v_lshl_add_u64 v[4:5], v[2:3], 0, v[4:5]
	v_cndmask_b32_e32 v0, v12, v0, vcc
	global_store_dword v[4:5], v0, off
	s_and_saveexec_b64 s[0:1], s[8:9]
	s_xor_b64 s[18:19], exec, s[0:1]
	s_cbranch_execz .LBB0_343
	v_lshrrev_b32_e32 v0, 23, v14
	v_add_u32_e32 v0, 0xffffff88, v0
	v_cmp_lt_u32_e64 s[0:1], 63, v0
	s_nop 1
	v_cndmask_b32_e64 v15, 0, v7, s[0:1]
	v_add_u32_e32 v0, v15, v0
	v_cmp_lt_u32_e64 s[4:5], 31, v0
	s_nop 1
	v_cndmask_b32_e64 v15, 0, v11, s[4:5]
	v_add_u32_e32 v0, v15, v0
	v_cmp_lt_u32_e64 s[6:7], 31, v0
	s_nop 1
	v_cndmask_b32_e64 v15, 0, v11, s[6:7]
	v_add_u32_e32 v15, v15, v0
	v_and_b32_e32 v0, 0x7fffff, v14
	v_or_b32_e32 v28, 0x800000, v0
	v_mad_u64_u32 v[16:17], s[8:9], v28, s22, 0
	v_mov_b32_e32 v0, v17
	v_mad_u64_u32 v[18:19], s[8:9], v28, s23, v[0:1]
	v_mov_b32_e32 v0, v19
	v_mad_u64_u32 v[20:21], s[8:9], v28, s24, v[0:1]
	v_mov_b32_e32 v0, v21
	v_mad_u64_u32 v[22:23], s[8:9], v28, s25, v[0:1]
	v_mov_b32_e32 v0, v23
	v_mad_u64_u32 v[24:25], s[8:9], v28, s26, v[0:1]
	v_mov_b32_e32 v0, v25
	v_mad_u64_u32 v[26:27], s[8:9], v28, s27, v[0:1]
	v_mov_b32_e32 v0, v27
	v_mad_u64_u32 v[28:29], s[8:9], v28, s28, v[0:1]
	v_cndmask_b32_e64 v17, v26, v22, s[0:1]
	v_cndmask_b32_e64 v0, v28, v24, s[0:1]
	v_cndmask_b32_e64 v21, v29, v26, s[0:1]
	v_cndmask_b32_e64 v19, v0, v17, s[4:5]
	v_cndmask_b32_e64 v0, v21, v0, s[4:5]
	v_cndmask_b32_e64 v21, v24, v20, s[0:1]
	v_cndmask_b32_e64 v17, v17, v21, s[4:5]
	v_sub_u32_e32 v23, 32, v15
	v_cmp_eq_u32_e64 s[8:9], 0, v15
	v_cndmask_b32_e64 v15, v22, v18, s[0:1]
	v_cndmask_b32_e64 v0, v0, v19, s[6:7]
	v_cndmask_b32_e64 v19, v19, v17, s[6:7]
	v_cndmask_b32_e64 v18, v21, v15, s[4:5]
	v_alignbit_b32 v24, v0, v19, v23
	v_cndmask_b32_e64 v17, v17, v18, s[6:7]
	v_cndmask_b32_e64 v0, v24, v0, s[8:9]
	v_alignbit_b32 v21, v19, v17, v23
	v_cndmask_b32_e64 v16, v20, v16, s[0:1]
	v_cndmask_b32_e64 v19, v21, v19, s[8:9]
	v_bfe_u32 v24, v0, 29, 1
	v_cndmask_b32_e64 v15, v15, v16, s[4:5]
	v_alignbit_b32 v21, v0, v19, 30
	v_sub_u32_e32 v25, 0, v24
	v_cndmask_b32_e64 v15, v18, v15, s[6:7]
	v_xor_b32_e32 v21, v21, v25
	v_alignbit_b32 v16, v17, v15, v23
	v_cndmask_b32_e64 v16, v16, v17, s[8:9]
	v_ffbh_u32_e32 v18, v21
	v_alignbit_b32 v17, v19, v16, 30
	v_min_u32_e32 v18, 32, v18
	v_alignbit_b32 v15, v16, v15, 30
	v_xor_b32_e32 v17, v17, v25
	v_sub_u32_e32 v19, 31, v18
	v_xor_b32_e32 v15, v15, v25
	v_alignbit_b32 v20, v21, v17, v19
	v_alignbit_b32 v15, v17, v15, v19
	v_alignbit_b32 v16, v20, v15, 9
	v_ffbh_u32_e32 v17, v16
	v_min_u32_e32 v17, 32, v17
	v_lshrrev_b32_e32 v22, 29, v0
	v_not_b32_e32 v19, v17
	v_alignbit_b32 v15, v16, v15, v19
	v_lshlrev_b32_e32 v16, 31, v22
	v_or_b32_e32 v19, 0x33000000, v16
	v_add_lshl_u32 v17, v17, v18, 23
	v_lshrrev_b32_e32 v15, 9, v15
	v_sub_u32_e32 v17, v19, v17
	v_or_b32_e32 v16, 0.5, v16
	v_lshlrev_b32_e32 v18, 23, v18
	v_or_b32_e32 v15, v17, v15
	v_lshrrev_b32_e32 v17, 9, v20
	v_sub_u32_e32 v16, v16, v18
	v_or_b32_e32 v16, v17, v16
	v_mul_f32_e32 v17, 0x3fc90fda, v16
	v_fma_f32 v18, v16, s29, -v17
	v_fmac_f32_e32 v18, 0x33a22168, v16
	v_fmac_f32_e32 v18, 0x3fc90fda, v15
	v_lshrrev_b32_e32 v0, 30, v0
	v_add_f32_e32 v15, v17, v18
	v_add_u32_e32 v0, v24, v0

; __device__ __forceinline__ u32x4 pack8(const f32x4 v0, const f32x4 v1) { u32x4 w; w.x = cvt_pk_bf16(v0[0], v0[1]); w.y = cvt_pk_bf16(v0[2], v0[3]); w.z = cvt_pk_bf16(v1[0], v1[1]); w.w = cvt_pk_bf16(v1[2], v1[3]); return w; }
;     __device__ __forceinline__ void operator()(const f32x4 (&acc)[2][2][4][2], const Unit& u, int wr, int wc, int fr, int fq) const {
;         const int row0 = u.pm * BM + wr * 64 + fr, col0 = u.pn * BM + wc * 32 + 8 * fq;
; #pragma unroll
;         for (int ai = 0; ai < 2; ++ai)
; #pragma unroll
;             for (int m = 0; m < 4; ++m) { const int row = row0 + ai * HALF + m * 16; bf16_t* rowp = O + (size_t)row * ldc + col0; float sq = 0.f;
; #pragma unroll
;                 for (int bj = 0; bj < 2; ++bj) { const u32x4 w = pack8(acc[ai][bj][m][0], acc[ai][bj][m][1]); *(u32x4*)(rowp + bj * HALF) = w;
; #pragma unroll
;                     for (int e = 0; e < 4; ++e) { const float lo = __uint_as_float(w[e] << 16), hi = __uint_as_float(w[e] & 0xffff0000u); sq += lo * lo + hi * hi; } }
;                 if (u.pn >= 6 && u.pn <= 8) { sq += __shfl_xor(sq, 16); sq += __shfl_xor(sq, 32); if (fq == 0) ssq[((size_t)row * 3 + (u.pn - 6)) * 4 + wc] = sq; }
.LBB0_416:
	v_lshl_or_b32 v150, s69, 8, v156
	v_lshl_add_u32 v152, s34, 8, v154
	v_mov_b64_e32 v[130:131], s[20:21]
	s_movk_i32 s8, 0x1e00
	s_add_i32 s68, s69, -6
	v_ashrrev_i32_e32 v151, 31, v150
	v_mad_i64_i32 v[130:131], s[8:9], v152, s8, v[130:131]
	s_cmp_lt_u32 s68, 3
	v_ashrrev_i32_e32 v153, 31, v152
	v_lshl_add_u64 v[158:159], v[150:151], 1, v[130:131]
	s_cselect_b64 s[34:35], -1, 0
	s_cmp_gt_u32 s68, 2
	v_cvt_pk_bf16_f32 v130, v118, v119
	v_cvt_pk_bf16_f32 v131, v120, v121
	v_cvt_pk_bf16_f32 v132, v114, v115
	v_cvt_pk_bf16_f32 v133, v116, v117
	global_store_dwordx4 v[158:159], v[130:133], off
	v_cvt_pk_bf16_f32 v126, v126, v127
	v_cvt_pk_bf16_f32 v127, v128, v129
	v_cvt_pk_bf16_f32 v128, v122, v123
	v_cvt_pk_bf16_f32 v129, v124, v125
	global_store_dwordx4 v[158:159], v[126:129], off offset:256
	s_cbranch_scc1 .LBB0_420
	v_and_b32_e32 v122, 0xffff0000, v130
	v_lshlrev_b32_e32 v0, 16, v130
	v_mul_f32_e32 v122, v122, v122
	v_and_b32_e32 v123, 0xffff0000, v131
	v_fmac_f32_e32 v122, v0, v0
	v_lshlrev_b32_e32 v0, 16, v131
	v_mul_f32_e32 v123, v123, v123
	v_fmac_f32_e32 v123, v0, v0
	v_add_f32_e32 v0, v122, v123
	v_and_b32_e32 v123, 0xffff0000, v132
	v_lshlrev_b32_e32 v122, 16, v132
	v_mul_f32_e32 v123, v123, v123
	v_fmac_f32_e32 v123, v122, v122
	v_add_f32_e32 v0, v0, v123
	v_and_b32_e32 v123, 0xffff0000, v133
	v_lshlrev_b32_e32 v122, 16, v133
	v_mul_f32_e32 v123, v123, v123
	v_fmac_f32_e32 v123, v122, v122
	v_add_f32_e32 v0, v0, v123
	v_and_b32_e32 v123, 0xffff0000, v126
	v_lshlrev_b32_e32 v122, 16, v126
	v_mul_f32_e32 v123, v123, v123
	v_fmac_f32_e32 v123, v122, v122
	v_add_f32_e32 v0, v0, v123
	v_and_b32_e32 v123, 0xffff0000, v127
	v_lshlrev_b32_e32 v122, 16, v127
	v_mul_f32_e32 v123, v123, v123
	v_fmac_f32_e32 v123, v122, v122
	v_add_f32_e32 v0, v0, v123
	v_and_b32_e32 v123, 0xffff0000, v128
	v_lshlrev_b32_e32 v122, 16, v128
	v_mul_f32_e32 v123, v123, v123
	v_fmac_f32_e32 v123, v122, v122
	v_add_f32_e32 v0, v0, v123
	v_and_b32_e32 v123, 0xffff0000, v129
	v_lshlrev_b32_e32 v122, 16, v129
	v_mul_f32_e32 v123, v123, v123
	v_fmac_f32_e32 v123, v122, v122
	v_add_f32_e32 v0, v0, v123
	v_and_b32_e32 v123, 64, v221
	v_xor_b32_e32 v122, 16, v221
	v_add_u32_e32 v123, 64, v123
	v_cmp_lt_i32_e32 vcc, v122, v123
	s_nop 1
	v_cndmask_b32_e32 v122, v221, v122, vcc
	v_lshlrev_b32_e32 v122, 2, v122
	ds_bpermute_b32 v122, v122, v0
	s_waitcnt lgkmcnt(0)
	v_add_f32_e32 v0, v0, v122
	v_xor_b32_e32 v122, 32, v221
	v_cmp_lt_i32_e32 vcc, v122, v123
	s_nop 1
	v_cndmask_b32_e32 v122, v221, v122, vcc
	v_lshlrev_b32_e32 v122, 2, v122
	ds_bpermute_b32 v122, v122, v0
	s_and_saveexec_b64 s[8:9], s[4:5]
	s_cbranch_execz .LBB0_419
	s_waitcnt lgkmcnt(0)
	v_add_f32_e32 v124, v0, v122
	v_mov_b32_e32 v0, s68
	v_mad_i64_i32 v[122:123], s[10:11], v152, 3, v[0:1]
	v_lshl_add_u64 v[122:123], v[122:123], 4, s[28:29]
	global_store_dword v[122:123], v124, off

; __device__ __forceinline__ u32x4 pack8(const f32x4 v0, const f32x4 v1) { u32x4 w; w.x = cvt_pk_bf16(v0[0], v0[1]); w.y = cvt_pk_bf16(v0[2], v0[3]); w.z = cvt_pk_bf16(v1[0], v1[1]); w.w = cvt_pk_bf16(v1[2], v1[3]); return w; }
;     __device__ __forceinline__ void operator()(const f32x4 (&acc)[2][2][4][2], const Unit& u, int wr, int wc, int fr, int fq) const {
;     ...
;             for (int m = 0; m < 4; ++m) { const int row = row0 + ai * HALF + m * 16; bf16_t* rowp = O + (size_t)row * ldc + col0; float sq = 0.f;
; #pragma unroll
;                 for (int bj = 0; bj < 2; ++bj) { const u32x4 w = pack8(acc[ai][bj][m][0], acc[ai][bj][m][1]); *(u32x4*)(rowp + bj * HALF) = w;
; #pragma unroll
;                     for (int e = 0; e < 4; ++e) { const float lo = __uint_as_float(w[e] << 16), hi = __uint_as_float(w[e] & 0xffff0000u); sq += lo * lo + hi * hi; } }
;                 if (u.pn >= 6 && u.pn <= 8) { sq += __shfl_xor(sq, 16); sq += __shfl_xor(sq, 32); if (fq == 0) ssq[((size_t)row * 3 + (u.pn - 6)) * 4 + wc] = sq; }
;                 if (u.pn == 9 && wc < 2) { const int ib = wc * 16 + 4 * fq; const f32x4 v0 = acc[ai][0][m][0], v1 = acc[ai][0][m][1];
;                     const f32x4 c = *(const f32x4*)(rope + (size_t)row * 64 + ib), sn = *(const f32x4*)(rope + (size_t)row * 64 + 32 + ib);
;                     f32x4 a, b;
;                     a[0] = v0[0] * c[0] - v0[1] * sn[0]; a[1] = v0[1] * c[0] + v0[0] * sn[0];
;                     a[2] = v0[2] * c[1] - v0[3] * sn[1]; a[3] = v0[3] * c[1] + v0[2] * sn[1];
;                     b[0] = v1[0] * c[2] - v1[1] * sn[2]; b[1] = v1[1] * c[2] + v1[0] * sn[2];
;                     b[2] = v1[2] * c[3] - v1[3] * sn[3]; b[3] = v1[3] * c[3] + v1[2] * sn[3];
;                     const u32x4 w = pack8(a, b);
; #pragma unroll
;                     for (int h = 0; h < 6; ++h) *(u32x4*)(Kb + (size_t)row * ldk + 192 * h + 128 + wc * 32 + 8 * fq) = w; }
.LBB0_420:
	s_cmp_eq_u32 s69, 9
	s_cselect_b64 s[8:9], -1, 0
	s_and_b64 s[10:11], s[8:9], s[26:27]
	v_cndmask_b32_e64 v0, 0, 1, s[10:11]
	v_cmp_ne_u32_e64 s[8:9], 1, v0
	s_andn2_b64 vcc, exec, s[10:11]
	s_cbranch_vccnz .LBB0_422
	s_waitcnt lgkmcnt(0)
	v_lshlrev_b64 v[122:123], 8, v[152:153]
	v_lshl_add_u64 v[126:127], v[142:143], 0, v[122:123]
	flat_load_dwordx4 v[122:125], v[126:127]
	s_nop 0
	flat_load_dwordx4 v[126:129], v[126:127] offset:128
	s_waitcnt vmcnt(0) lgkmcnt(0)
	v_mov_b32_e32 v130, v122
	v_mov_b32_e32 v131, v126
	v_pk_mul_f32 v[130:131], v[118:119], v[130:131]
	s_nop 0
	v_sub_f32_e32 v0, v130, v131
	v_mov_b32_e32 v130, v126
	v_mov_b32_e32 v131, v122
	v_pk_mul_f32 v[118:119], v[118:119], v[130:131]
	v_mov_b32_e32 v126, v123
	v_add_f32_e32 v130, v119, v118
	v_pk_mul_f32 v[118:119], v[120:121], v[126:127]
	v_mov_b32_e32 v122, v127
	v_sub_f32_e32 v126, v118, v119
	v_pk_mul_f32 v[118:119], v[120:121], v[122:123]
	s_nop 0
	v_add_f32_e32 v120, v119, v118
	v_mov_b32_e32 v118, v124
	v_mov_b32_e32 v119, v128
	v_pk_mul_f32 v[118:119], v[114:115], v[118:119]
	s_nop 0
	v_sub_f32_e32 v121, v118, v119
	v_mov_b32_e32 v118, v128
	v_mov_b32_e32 v119, v124
	v_pk_mul_f32 v[114:115], v[114:115], v[118:119]
	v_mov_b32_e32 v128, v125
	v_add_f32_e32 v118, v115, v114
	v_pk_mul_f32 v[114:115], v[116:117], v[128:129]
	v_mov_b32_e32 v124, v129
	v_sub_f32_e32 v119, v114, v115
	v_pk_mul_f32 v[114:115], v[116:117], v[124:125]
	s_nop 0
	v_add_f32_e32 v117, v115, v114
	v_cvt_pk_bf16_f32 v114, v0, v130
	v_cvt_pk_bf16_f32 v115, v126, v120
	v_cvt_pk_bf16_f32 v116, v121, v118
	v_cvt_pk_bf16_f32 v117, v119, v117
	v_mad_i64_i32 v[118:119], s[10:11], v152, s87, v[144:145]
	global_store_dwordx4 v[118:119], v[114:117], off offset:256
	global_store_dwordx4 v[118:119], v[114:117], off offset:640
	global_store_dwordx4 v[118:119], v[114:117], off offset:1024
	global_store_dwordx4 v[118:119], v[114:117], off offset:1408
	global_store_dwordx4 v[118:119], v[114:117], off offset:1792
	global_store_dwordx4 v[118:119], v[114:117], off offset:2176
.LBB0_422:
	v_or_b32_e32 v118, 16, v152
	s_nop 0
	v_mov_b64_e32 v[114:115], s[20:21]
	s_movk_i32 s10, 0x1e00
	v_mad_i64_i32 v[114:115], s[10:11], v118, s10, v[114:115]
	v_cndmask_b32_e64 v0, 0, 1, s[34:35]
	v_ashrrev_i32_e32 v119, 31, v118
	v_lshl_add_u64 v[120:121], v[150:151], 1, v[114:115]
	v_cmp_ne_u32_e64 s[10:11], 1, v0
	s_andn2_b64 vcc, exec, s[34:35]
	v_cvt_pk_bf16_f32 v114, v102, v103
	v_cvt_pk_bf16_f32 v115, v104, v105
	v_cvt_pk_bf16_f32 v116, v98, v99
	v_cvt_pk_bf16_f32 v117, v100, v101
	global_store_dwordx4 v[120:121], v[114:117], off
	v_cvt_pk_bf16_f32 v110, v110, v111
	v_cvt_pk_bf16_f32 v111, v112, v113
	v_cvt_pk_bf16_f32 v112, v106, v107
	v_cvt_pk_bf16_f32 v113, v108, v109
	global_store_dwordx4 v[120:121], v[110:113], off offset:256
	s_cbranch_vccnz .LBB0_426
	v_and_b32_e32 v106, 0xffff0000, v114
	v_lshlrev_b32_e32 v0, 16, v114
	v_mul_f32_e32 v106, v106, v106
	v_and_b32_e32 v107, 0xffff0000, v115
	v_fmac_f32_e32 v106, v0, v0
	v_lshlrev_b32_e32 v0, 16, v115
	v_mul_f32_e32 v107, v107, v107
	v_fmac_f32_e32 v107, v0, v0
	v_add_f32_e32 v0, v106, v107
	v_and_b32_e32 v107, 0xffff0000, v116
	v_lshlrev_b32_e32 v106, 16, v116
	v_mul_f32_e32 v107, v107, v107
	v_fmac_f32_e32 v107, v106, v106
	v_add_f32_e32 v0, v0, v107
	v_and_b32_e32 v107, 0xffff0000, v117
	v_lshlrev_b32_e32 v106, 16, v117
	v_mul_f32_e32 v107, v107, v107
	v_fmac_f32_e32 v107, v106, v106
	v_add_f32_e32 v0, v0, v107
	v_and_b32_e32 v107, 0xffff0000, v110
	v_lshlrev_b32_e32 v106, 16, v110
	v_mul_f32_e32 v107, v107, v107
	v_fmac_f32_e32 v107, v106, v106
	v_add_f32_e32 v0, v0, v107
	v_and_b32_e32 v107, 0xffff0000, v111
	v_lshlrev_b32_e32 v106, 16, v111
	v_mul_f32_e32 v107, v107, v107
	v_fmac_f32_e32 v107, v106, v106
	v_add_f32_e32 v0, v0, v107
	v_and_b32_e32 v107, 0xffff0000, v112
	v_lshlrev_b32_e32 v106, 16, v112
	v_mul_f32_e32 v107, v107, v107
	v_fmac_f32_e32 v107, v106, v106
	v_add_f32_e32 v0, v0, v107
	v_and_b32_e32 v107, 0xffff0000, v113
	v_lshlrev_b32_e32 v106, 16, v113
	v_mul_f32_e32 v107, v107, v107
	v_fmac_f32_e32 v107, v106, v106
	v_add_f32_e32 v0, v0, v107
	v_and_b32_e32 v107, 64, v221
	v_xor_b32_e32 v106, 16, v221
	v_add_u32_e32 v107, 64, v107
	v_cmp_lt_i32_e32 vcc, v106, v107
	s_nop 1
	v_cndmask_b32_e32 v106, v221, v106, vcc
	v_lshlrev_b32_e32 v106, 2, v106
	ds_bpermute_b32 v106, v106, v0
	s_waitcnt lgkmcnt(0)
	v_add_f32_e32 v0, v0, v106
	v_xor_b32_e32 v106, 32, v221
	v_cmp_lt_i32_e32 vcc, v106, v107
	s_nop 1
	v_cndmask_b32_e32 v106, v221, v106, vcc
	v_lshlrev_b32_e32 v106, 2, v106
	ds_bpermute_b32 v106, v106, v0
	s_and_saveexec_b64 s[34:35], s[4:5]
	s_cbranch_execz .LBB0_425
	s_waitcnt lgkmcnt(0)
	v_add_f32_e32 v108, v0, v106
	v_mov_b32_e32 v0, s68
	v_mad_i64_i32 v[106:107], s[60:61], v118, 3, v[0:1]
	v_lshl_add_u64 v[106:107], v[106:107], 4, s[28:29]
	global_store_dword v[106:107], v108, off

; __device__ __forceinline__ u32x4 pack8(const f32x4 v0, const f32x4 v1) { u32x4 w; w.x = cvt_pk_bf16(v0[0], v0[1]); w.y = cvt_pk_bf16(v0[2], v0[3]); w.z = cvt_pk_bf16(v1[0], v1[1]); w.w = cvt_pk_bf16(v1[2], v1[3]); return w; }
;     __device__ __forceinline__ void operator()(const f32x4 (&acc)[2][2][4][2], const Unit& u, int wr, int wc, int fr, int fq) const {
;     ...
;             for (int m = 0; m < 4; ++m) { const int row = row0 + ai * HALF + m * 16; bf16_t* rowp = O + (size_t)row * ldc + col0; float sq = 0.f;
; #pragma unroll
;                 for (int bj = 0; bj < 2; ++bj) { const u32x4 w = pack8(acc[ai][bj][m][0], acc[ai][bj][m][1]); *(u32x4*)(rowp + bj * HALF) = w;
; #pragma unroll
;                     for (int e = 0; e < 4; ++e) { const float lo = __uint_as_float(w[e] << 16), hi = __uint_as_float(w[e] & 0xffff0000u); sq += lo * lo + hi * hi; } }
;                 if (u.pn >= 6 && u.pn <= 8) { sq += __shfl_xor(sq, 16); sq += __shfl_xor(sq, 32); if (fq == 0) ssq[((size_t)row * 3 + (u.pn - 6)) * 4 + wc] = sq; }
;                 if (u.pn == 9 && wc < 2) { const int ib = wc * 16 + 4 * fq; const f32x4 v0 = acc[ai][0][m][0], v1 = acc[ai][0][m][1];
;                     const f32x4 c = *(const f32x4*)(rope + (size_t)row * 64 + ib), sn = *(const f32x4*)(rope + (size_t)row * 64 + 32 + ib);
;                     f32x4 a, b;
;                     a[0] = v0[0] * c[0] - v0[1] * sn[0]; a[1] = v0[1] * c[0] + v0[0] * sn[0];
;                     a[2] = v0[2] * c[1] - v0[3] * sn[1]; a[3] = v0[3] * c[1] + v0[2] * sn[1];
;                     b[0] = v1[0] * c[2] - v1[1] * sn[2]; b[1] = v1[1] * c[2] + v1[0] * sn[2];
;                     b[2] = v1[2] * c[3] - v1[3] * sn[3]; b[3] = v1[3] * c[3] + v1[2] * sn[3];
;                     const u32x4 w = pack8(a, b);
; #pragma unroll
;                     for (int h = 0; h < 6; ++h) *(u32x4*)(Kb + (size_t)row * ldk + 192 * h + 128 + wc * 32 + 8 * fq) = w; }
.LBB0_426:
	s_and_b64 vcc, exec, s[8:9]
	s_cbranch_vccnz .LBB0_428
	s_waitcnt lgkmcnt(0)
	v_lshlrev_b64 v[106:107], 8, v[118:119]
	v_lshl_add_u64 v[110:111], v[142:143], 0, v[106:107]
	flat_load_dwordx4 v[106:109], v[110:111]
	s_nop 0
	flat_load_dwordx4 v[110:113], v[110:111] offset:128
	s_waitcnt vmcnt(0) lgkmcnt(0)
	v_mov_b32_e32 v114, v106
	v_mov_b32_e32 v115, v110
	v_pk_mul_f32 v[114:115], v[102:103], v[114:115]
	s_nop 0
	v_sub_f32_e32 v0, v114, v115
	v_mov_b32_e32 v114, v110
	v_mov_b32_e32 v115, v106
	v_pk_mul_f32 v[102:103], v[102:103], v[114:115]
	v_mov_b32_e32 v110, v107
	v_add_f32_e32 v114, v103, v102
	v_pk_mul_f32 v[102:103], v[104:105], v[110:111]
	v_mov_b32_e32 v106, v111
	v_sub_f32_e32 v110, v102, v103
	v_pk_mul_f32 v[102:103], v[104:105], v[106:107]
	s_nop 0
	v_add_f32_e32 v104, v103, v102
	v_mov_b32_e32 v102, v108
	v_mov_b32_e32 v103, v112
	v_pk_mul_f32 v[102:103], v[98:99], v[102:103]
	s_nop 0
	v_sub_f32_e32 v105, v102, v103
	v_mov_b32_e32 v102, v112
	v_mov_b32_e32 v103, v108
	v_pk_mul_f32 v[98:99], v[98:99], v[102:103]
	v_mov_b32_e32 v112, v109
	v_add_f32_e32 v102, v99, v98
	v_pk_mul_f32 v[98:99], v[100:101], v[112:113]
	v_mov_b32_e32 v108, v113
	v_sub_f32_e32 v103, v98, v99
	v_pk_mul_f32 v[98:99], v[100:101], v[108:109]
	s_nop 0
	v_add_f32_e32 v101, v99, v98
	v_cvt_pk_bf16_f32 v98, v0, v114
	v_cvt_pk_bf16_f32 v99, v110, v104
	v_cvt_pk_bf16_f32 v100, v105, v102
	v_cvt_pk_bf16_f32 v101, v103, v101
	v_mad_i64_i32 v[102:103], s[34:35], v118, s87, v[144:145]
	global_store_dwordx4 v[102:103], v[98:101], off offset:256
	global_store_dwordx4 v[102:103], v[98:101], off offset:640
	global_store_dwordx4 v[102:103], v[98:101], off offset:1024
	global_store_dwordx4 v[102:103], v[98:101], off offset:1408
	global_store_dwordx4 v[102:103], v[98:101], off offset:1792
	global_store_dwordx4 v[102:103], v[98:101], off offset:2176
.LBB0_428:
	v_or_b32_e32 v102, 32, v152
	s_nop 0
	v_mov_b64_e32 v[98:99], s[20:21]
	s_movk_i32 s34, 0x1e00
	v_mad_i64_i32 v[98:99], s[34:35], v102, s34, v[98:99]
	v_ashrrev_i32_e32 v103, 31, v102
	v_lshl_add_u64 v[104:105], v[150:151], 1, v[98:99]
	s_and_b64 vcc, exec, s[10:11]
	v_cvt_pk_bf16_f32 v98, v86, v87
	v_cvt_pk_bf16_f32 v99, v88, v89
	v_cvt_pk_bf16_f32 v100, v82, v83
	v_cvt_pk_bf16_f32 v101, v84, v85
	global_store_dwordx4 v[104:105], v[98:101], off
	v_cvt_pk_bf16_f32 v94, v94, v95
	v_cvt_pk_bf16_f32 v95, v96, v97
	v_cvt_pk_bf16_f32 v96, v90, v91
	v_cvt_pk_bf16_f32 v97, v92, v93
	global_store_dwordx4 v[104:105], v[94:97], off offset:256
	s_cbranch_vccnz .LBB0_432
	v_and_b32_e32 v90, 0xffff0000, v98
	v_lshlrev_b32_e32 v0, 16, v98
	v_mul_f32_e32 v90, v90, v90
	v_and_b32_e32 v91, 0xffff0000, v99
	v_fmac_f32_e32 v90, v0, v0
	v_lshlrev_b32_e32 v0, 16, v99
	v_mul_f32_e32 v91, v91, v91
	v_fmac_f32_e32 v91, v0, v0
	v_add_f32_e32 v0, v90, v91
	v_and_b32_e32 v91, 0xffff0000, v100
	v_lshlrev_b32_e32 v90, 16, v100
	v_mul_f32_e32 v91, v91, v91
	v_fmac_f32_e32 v91, v90, v90
	v_add_f32_e32 v0, v0, v91
	v_and_b32_e32 v91, 0xffff0000, v101
	v_lshlrev_b32_e32 v90, 16, v101
	v_mul_f32_e32 v91, v91, v91
	v_fmac_f32_e32 v91, v90, v90
	v_add_f32_e32 v0, v0, v91
	v_and_b32_e32 v91, 0xffff0000, v94
	v_lshlrev_b32_e32 v90, 16, v94
	v_mul_f32_e32 v91, v91, v91
	v_fmac_f32_e32 v91, v90, v90
	v_add_f32_e32 v0, v0, v91
	v_and_b32_e32 v91, 0xffff0000, v95
	v_lshlrev_b32_e32 v90, 16, v95
	v_mul_f32_e32 v91, v91, v91
	v_fmac_f32_e32 v91, v90, v90
	v_add_f32_e32 v0, v0, v91
	v_and_b32_e32 v91, 0xffff0000, v96
	v_lshlrev_b32_e32 v90, 16, v96
	v_mul_f32_e32 v91, v91, v91
	v_fmac_f32_e32 v91, v90, v90
	v_add_f32_e32 v0, v0, v91
	v_and_b32_e32 v91, 0xffff0000, v97
	v_lshlrev_b32_e32 v90, 16, v97
	v_mul_f32_e32 v91, v91, v91
	v_fmac_f32_e32 v91, v90, v90
	v_add_f32_e32 v0, v0, v91
	v_and_b32_e32 v91, 64, v221
	v_xor_b32_e32 v90, 16, v221
	v_add_u32_e32 v91, 64, v91
	v_cmp_lt_i32_e32 vcc, v90, v91
	s_nop 1
	v_cndmask_b32_e32 v90, v221, v90, vcc
	v_lshlrev_b32_e32 v90, 2, v90
	ds_bpermute_b32 v90, v90, v0
	s_waitcnt lgkmcnt(0)
	v_add_f32_e32 v0, v0, v90
	v_xor_b32_e32 v90, 32, v221
	v_cmp_lt_i32_e32 vcc, v90, v91
	s_nop 1
	v_cndmask_b32_e32 v90, v221, v90, vcc
	v_lshlrev_b32_e32 v90, 2, v90
	ds_bpermute_b32 v90, v90, v0
	s_and_saveexec_b64 s[34:35], s[4:5]
	s_cbranch_execz .LBB0_431
	s_waitcnt lgkmcnt(0)
	v_add_f32_e32 v92, v0, v90
	v_mov_b32_e32 v0, s68
	v_mad_i64_i32 v[90:91], s[60:61], v102, 3, v[0:1]
	v_lshl_add_u64 v[90:91], v[90:91], 4, s[28:29]
	global_store_dword v[90:91], v92, off

; __device__ __forceinline__ u32x4 pack8(const f32x4 v0, const f32x4 v1) { u32x4 w; w.x = cvt_pk_bf16(v0[0], v0[1]); w.y = cvt_pk_bf16(v0[2], v0[3]); w.z = cvt_pk_bf16(v1[0], v1[1]); w.w = cvt_pk_bf16(v1[2], v1[3]); return w; }
;     __device__ __forceinline__ void operator()(const f32x4 (&acc)[2][2][4][2], const Unit& u, int wr, int wc, int fr, int fq) const {
;     ...
;             for (int m = 0; m < 4; ++m) { const int row = row0 + ai * HALF + m * 16; bf16_t* rowp = O + (size_t)row * ldc + col0; float sq = 0.f;
; #pragma unroll
;                 for (int bj = 0; bj < 2; ++bj) { const u32x4 w = pack8(acc[ai][bj][m][0], acc[ai][bj][m][1]); *(u32x4*)(rowp + bj * HALF) = w;
; #pragma unroll
;                     for (int e = 0; e < 4; ++e) { const float lo = __uint_as_float(w[e] << 16), hi = __uint_as_float(w[e] & 0xffff0000u); sq += lo * lo + hi * hi; } }
;                 if (u.pn >= 6 && u.pn <= 8) { sq += __shfl_xor(sq, 16); sq += __shfl_xor(sq, 32); if (fq == 0) ssq[((size_t)row * 3 + (u.pn - 6)) * 4 + wc] = sq; }
;                 if (u.pn == 9 && wc < 2) { const int ib = wc * 16 + 4 * fq; const f32x4 v0 = acc[ai][0][m][0], v1 = acc[ai][0][m][1];
;                     const f32x4 c = *(const f32x4*)(rope + (size_t)row * 64 + ib), sn = *(const f32x4*)(rope + (size_t)row * 64 + 32 + ib);
;                     f32x4 a, b;
;                     a[0] = v0[0] * c[0] - v0[1] * sn[0]; a[1] = v0[1] * c[0] + v0[0] * sn[0];
;                     a[2] = v0[2] * c[1] - v0[3] * sn[1]; a[3] = v0[3] * c[1] + v0[2] * sn[1];
;                     b[0] = v1[0] * c[2] - v1[1] * sn[2]; b[1] = v1[1] * c[2] + v1[0] * sn[2];
;                     b[2] = v1[2] * c[3] - v1[3] * sn[3]; b[3] = v1[3] * c[3] + v1[2] * sn[3];
;                     const u32x4 w = pack8(a, b);
; #pragma unroll
;                     for (int h = 0; h < 6; ++h) *(u32x4*)(Kb + (size_t)row * ldk + 192 * h + 128 + wc * 32 + 8 * fq) = w; }
.LBB0_432:
	s_and_b64 vcc, exec, s[8:9]
	s_cbranch_vccnz .LBB0_434
	s_waitcnt lgkmcnt(0)
	v_lshlrev_b64 v[90:91], 8, v[102:103]
	v_lshl_add_u64 v[94:95], v[142:143], 0, v[90:91]
	flat_load_dwordx4 v[90:93], v[94:95]
	s_nop 0
	flat_load_dwordx4 v[94:97], v[94:95] offset:128
	s_waitcnt vmcnt(0) lgkmcnt(0)
	v_mov_b32_e32 v98, v90
	v_mov_b32_e32 v99, v94
	v_pk_mul_f32 v[98:99], v[86:87], v[98:99]
	s_nop 0
	v_sub_f32_e32 v0, v98, v99
	v_mov_b32_e32 v98, v94
	v_mov_b32_e32 v99, v90
	v_pk_mul_f32 v[86:87], v[86:87], v[98:99]
	v_mov_b32_e32 v94, v91
	v_add_f32_e32 v98, v87, v86
	v_pk_mul_f32 v[86:87], v[88:89], v[94:95]
	v_mov_b32_e32 v90, v95
	v_sub_f32_e32 v94, v86, v87
	v_pk_mul_f32 v[86:87], v[88:89], v[90:91]
	s_nop 0
	v_add_f32_e32 v88, v87, v86
	v_mov_b32_e32 v86, v92
	v_mov_b32_e32 v87, v96
	v_pk_mul_f32 v[86:87], v[82:83], v[86:87]
	s_nop 0
	v_sub_f32_e32 v89, v86, v87
	v_mov_b32_e32 v86, v96
	v_mov_b32_e32 v87, v92
	v_pk_mul_f32 v[82:83], v[82:83], v[86:87]
	v_mov_b32_e32 v96, v93
	v_add_f32_e32 v86, v83, v82
	v_pk_mul_f32 v[82:83], v[84:85], v[96:97]
	v_mov_b32_e32 v92, v97
	v_sub_f32_e32 v87, v82, v83
	v_pk_mul_f32 v[82:83], v[84:85], v[92:93]
	s_nop 0
	v_add_f32_e32 v85, v83, v82
	v_cvt_pk_bf16_f32 v82, v0, v98
	v_cvt_pk_bf16_f32 v83, v94, v88
	v_cvt_pk_bf16_f32 v84, v89, v86
	v_cvt_pk_bf16_f32 v85, v87, v85
	v_mad_i64_i32 v[86:87], s[34:35], v102, s87, v[144:145]
	global_store_dwordx4 v[86:87], v[82:85], off offset:256
	global_store_dwordx4 v[86:87], v[82:85], off offset:640
	global_store_dwordx4 v[86:87], v[82:85], off offset:1024
	global_store_dwordx4 v[86:87], v[82:85], off offset:1408
	global_store_dwordx4 v[86:87], v[82:85], off offset:1792
	global_store_dwordx4 v[86:87], v[82:85], off offset:2176
.LBB0_434:
	v_or_b32_e32 v86, 48, v152
	s_nop 0
	v_mov_b64_e32 v[82:83], s[20:21]
	s_movk_i32 s34, 0x1e00
	v_mad_i64_i32 v[82:83], s[34:35], v86, s34, v[82:83]
	v_ashrrev_i32_e32 v87, 31, v86
	v_lshl_add_u64 v[88:89], v[150:151], 1, v[82:83]
	s_and_b64 vcc, exec, s[10:11]
	v_cvt_pk_bf16_f32 v82, v70, v71
	v_cvt_pk_bf16_f32 v83, v72, v73
	v_cvt_pk_bf16_f32 v84, v66, v67
	v_cvt_pk_bf16_f32 v85, v68, v69
	global_store_dwordx4 v[88:89], v[82:85], off
	v_cvt_pk_bf16_f32 v78, v78, v79
	v_cvt_pk_bf16_f32 v79, v80, v81
	v_cvt_pk_bf16_f32 v80, v74, v75
	v_cvt_pk_bf16_f32 v81, v76, v77
	global_store_dwordx4 v[88:89], v[78:81], off offset:256
	s_cbranch_vccnz .LBB0_438
	v_and_b32_e32 v74, 0xffff0000, v82
	v_lshlrev_b32_e32 v0, 16, v82
	v_mul_f32_e32 v74, v74, v74
	v_and_b32_e32 v75, 0xffff0000, v83
	v_fmac_f32_e32 v74, v0, v0
	v_lshlrev_b32_e32 v0, 16, v83
	v_mul_f32_e32 v75, v75, v75
	v_fmac_f32_e32 v75, v0, v0
	v_add_f32_e32 v0, v74, v75
	v_and_b32_e32 v75, 0xffff0000, v84
	v_lshlrev_b32_e32 v74, 16, v84
	v_mul_f32_e32 v75, v75, v75
	v_fmac_f32_e32 v75, v74, v74
	v_add_f32_e32 v0, v0, v75
	v_and_b32_e32 v75, 0xffff0000, v85
	v_lshlrev_b32_e32 v74, 16, v85
	v_mul_f32_e32 v75, v75, v75
	v_fmac_f32_e32 v75, v74, v74
	v_add_f32_e32 v0, v0, v75
	v_and_b32_e32 v75, 0xffff0000, v78
	v_lshlrev_b32_e32 v74, 16, v78
	v_mul_f32_e32 v75, v75, v75
	v_fmac_f32_e32 v75, v74, v74
	v_add_f32_e32 v0, v0, v75
	v_and_b32_e32 v75, 0xffff0000, v79
	v_lshlrev_b32_e32 v74, 16, v79
	v_mul_f32_e32 v75, v75, v75
	v_fmac_f32_e32 v75, v74, v74
	v_add_f32_e32 v0, v0, v75
	v_and_b32_e32 v75, 0xffff0000, v80
	v_lshlrev_b32_e32 v74, 16, v80
	v_mul_f32_e32 v75, v75, v75
	v_fmac_f32_e32 v75, v74, v74
	v_add_f32_e32 v0, v0, v75
	v_and_b32_e32 v75, 0xffff0000, v81
	v_lshlrev_b32_e32 v74, 16, v81
	v_mul_f32_e32 v75, v75, v75
	v_fmac_f32_e32 v75, v74, v74
	v_add_f32_e32 v0, v0, v75
	v_and_b32_e32 v75, 64, v221
	v_xor_b32_e32 v74, 16, v221
	v_add_u32_e32 v75, 64, v75
	v_cmp_lt_i32_e32 vcc, v74, v75
	s_nop 1
	v_cndmask_b32_e32 v74, v221, v74, vcc
	v_lshlrev_b32_e32 v74, 2, v74
	ds_bpermute_b32 v74, v74, v0
	s_waitcnt lgkmcnt(0)
	v_add_f32_e32 v0, v0, v74
	v_xor_b32_e32 v74, 32, v221
	v_cmp_lt_i32_e32 vcc, v74, v75
	s_nop 1
	v_cndmask_b32_e32 v74, v221, v74, vcc
	v_lshlrev_b32_e32 v74, 2, v74
	ds_bpermute_b32 v74, v74, v0
	s_and_saveexec_b64 s[34:35], s[4:5]
	s_cbranch_execz .LBB0_437
	s_waitcnt lgkmcnt(0)
	v_add_f32_e32 v76, v0, v74
	v_mov_b32_e32 v0, s68
	v_mad_i64_i32 v[74:75], s[60:61], v86, 3, v[0:1]
	v_lshl_add_u64 v[74:75], v[74:75], 4, s[28:29]
	global_store_dword v[74:75], v76, off

; __device__ __forceinline__ u32x4 pack8(const f32x4 v0, const f32x4 v1) { u32x4 w; w.x = cvt_pk_bf16(v0[0], v0[1]); w.y = cvt_pk_bf16(v0[2], v0[3]); w.z = cvt_pk_bf16(v1[0], v1[1]); w.w = cvt_pk_bf16(v1[2], v1[3]); return w; }
;     __device__ __forceinline__ void operator()(const f32x4 (&acc)[2][2][4][2], const Unit& u, int wr, int wc, int fr, int fq) const {
;     ...
;             for (int m = 0; m < 4; ++m) { const int row = row0 + ai * HALF + m * 16; bf16_t* rowp = O + (size_t)row * ldc + col0; float sq = 0.f;
; #pragma unroll
;                 for (int bj = 0; bj < 2; ++bj) { const u32x4 w = pack8(acc[ai][bj][m][0], acc[ai][bj][m][1]); *(u32x4*)(rowp + bj * HALF) = w;
; #pragma unroll
;                     for (int e = 0; e < 4; ++e) { const float lo = __uint_as_float(w[e] << 16), hi = __uint_as_float(w[e] & 0xffff0000u); sq += lo * lo + hi * hi; } }
;                 if (u.pn >= 6 && u.pn <= 8) { sq += __shfl_xor(sq, 16); sq += __shfl_xor(sq, 32); if (fq == 0) ssq[((size_t)row * 3 + (u.pn - 6)) * 4 + wc] = sq; }
;                 if (u.pn == 9 && wc < 2) { const int ib = wc * 16 + 4 * fq; const f32x4 v0 = acc[ai][0][m][0], v1 = acc[ai][0][m][1];
;                     const f32x4 c = *(const f32x4*)(rope + (size_t)row * 64 + ib), sn = *(const f32x4*)(rope + (size_t)row * 64 + 32 + ib);
;                     f32x4 a, b;
;                     a[0] = v0[0] * c[0] - v0[1] * sn[0]; a[1] = v0[1] * c[0] + v0[0] * sn[0];
;                     a[2] = v0[2] * c[1] - v0[3] * sn[1]; a[3] = v0[3] * c[1] + v0[2] * sn[1];
;                     b[0] = v1[0] * c[2] - v1[1] * sn[2]; b[1] = v1[1] * c[2] + v1[0] * sn[2];
;                     b[2] = v1[2] * c[3] - v1[3] * sn[3]; b[3] = v1[3] * c[3] + v1[2] * sn[3];
;                     const u32x4 w = pack8(a, b);
; #pragma unroll
;                     for (int h = 0; h < 6; ++h) *(u32x4*)(Kb + (size_t)row * ldk + 192 * h + 128 + wc * 32 + 8 * fq) = w; }
.LBB0_438:
	s_and_b64 vcc, exec, s[8:9]
	s_cbranch_vccnz .LBB0_440
	s_waitcnt lgkmcnt(0)
	v_lshlrev_b64 v[74:75], 8, v[86:87]
	v_lshl_add_u64 v[78:79], v[142:143], 0, v[74:75]
	flat_load_dwordx4 v[74:77], v[78:79]
	s_nop 0
	flat_load_dwordx4 v[78:81], v[78:79] offset:128
	s_waitcnt vmcnt(0) lgkmcnt(0)
	v_mov_b32_e32 v82, v74
	v_mov_b32_e32 v83, v78
	v_pk_mul_f32 v[82:83], v[70:71], v[82:83]
	s_nop 0
	v_sub_f32_e32 v0, v82, v83
	v_mov_b32_e32 v82, v78
	v_mov_b32_e32 v83, v74
	v_pk_mul_f32 v[70:71], v[70:71], v[82:83]
	v_mov_b32_e32 v78, v75
	v_add_f32_e32 v82, v71, v70
	v_pk_mul_f32 v[70:71], v[72:73], v[78:79]
	v_mov_b32_e32 v74, v79
	v_sub_f32_e32 v78, v70, v71
	v_pk_mul_f32 v[70:71], v[72:73], v[74:75]
	s_nop 0
	v_add_f32_e32 v72, v71, v70
	v_mov_b32_e32 v70, v76
	v_mov_b32_e32 v71, v80
	v_pk_mul_f32 v[70:71], v[66:67], v[70:71]
	s_nop 0
	v_sub_f32_e32 v73, v70, v71
	v_mov_b32_e32 v70, v80
	v_mov_b32_e32 v71, v76
	v_pk_mul_f32 v[66:67], v[66:67], v[70:71]
	v_mov_b32_e32 v80, v77
	v_add_f32_e32 v70, v67, v66
	v_pk_mul_f32 v[66:67], v[68:69], v[80:81]
	v_mov_b32_e32 v76, v81
	v_sub_f32_e32 v71, v66, v67
	v_pk_mul_f32 v[66:67], v[68:69], v[76:77]
	s_nop 0
	v_add_f32_e32 v69, v67, v66
	v_cvt_pk_bf16_f32 v66, v0, v82
	v_cvt_pk_bf16_f32 v67, v78, v72
	v_cvt_pk_bf16_f32 v68, v73, v70
	v_cvt_pk_bf16_f32 v69, v71, v69
	v_mad_i64_i32 v[70:71], s[34:35], v86, s87, v[144:145]
	global_store_dwordx4 v[70:71], v[66:69], off offset:256
	global_store_dwordx4 v[70:71], v[66:69], off offset:640
	global_store_dwordx4 v[70:71], v[66:69], off offset:1024
	global_store_dwordx4 v[70:71], v[66:69], off offset:1408
	global_store_dwordx4 v[70:71], v[66:69], off offset:1792
	global_store_dwordx4 v[70:71], v[66:69], off offset:2176
.LBB0_440:
	v_add_u32_e32 v70, 0x80, v152
	s_nop 0
	v_mov_b64_e32 v[66:67], s[20:21]
	s_movk_i32 s34, 0x1e00
	v_mad_i64_i32 v[66:67], s[34:35], v70, s34, v[66:67]
	v_ashrrev_i32_e32 v71, 31, v70
	v_lshl_add_u64 v[72:73], v[150:151], 1, v[66:67]
	s_and_b64 vcc, exec, s[10:11]
	v_cvt_pk_bf16_f32 v66, v54, v55
	v_cvt_pk_bf16_f32 v67, v56, v57
	v_cvt_pk_bf16_f32 v68, v50, v51
	v_cvt_pk_bf16_f32 v69, v52, v53
	global_store_dwordx4 v[72:73], v[66:69], off
	v_cvt_pk_bf16_f32 v62, v62, v63
	v_cvt_pk_bf16_f32 v63, v64, v65
	v_cvt_pk_bf16_f32 v64, v58, v59
	v_cvt_pk_bf16_f32 v65, v60, v61
	global_store_dwordx4 v[72:73], v[62:65], off offset:256
	s_cbranch_vccnz .LBB0_444
	v_and_b32_e32 v58, 0xffff0000, v66
	v_lshlrev_b32_e32 v0, 16, v66
	v_mul_f32_e32 v58, v58, v58
	v_and_b32_e32 v59, 0xffff0000, v67
	v_fmac_f32_e32 v58, v0, v0
	v_lshlrev_b32_e32 v0, 16, v67
	v_mul_f32_e32 v59, v59, v59
	v_fmac_f32_e32 v59, v0, v0
	v_add_f32_e32 v0, v58, v59
	v_and_b32_e32 v59, 0xffff0000, v68
	v_lshlrev_b32_e32 v58, 16, v68
	v_mul_f32_e32 v59, v59, v59
	v_fmac_f32_e32 v59, v58, v58
	v_add_f32_e32 v0, v0, v59
	v_and_b32_e32 v59, 0xffff0000, v69
	v_lshlrev_b32_e32 v58, 16, v69
	v_mul_f32_e32 v59, v59, v59
	v_fmac_f32_e32 v59, v58, v58
	v_add_f32_e32 v0, v0, v59
	v_and_b32_e32 v59, 0xffff0000, v62
	v_lshlrev_b32_e32 v58, 16, v62
	v_mul_f32_e32 v59, v59, v59
	v_fmac_f32_e32 v59, v58, v58
	v_add_f32_e32 v0, v0, v59
	v_and_b32_e32 v59, 0xffff0000, v63
	v_lshlrev_b32_e32 v58, 16, v63
	v_mul_f32_e32 v59, v59, v59
	v_fmac_f32_e32 v59, v58, v58
	v_add_f32_e32 v0, v0, v59
	v_and_b32_e32 v59, 0xffff0000, v64
	v_lshlrev_b32_e32 v58, 16, v64
	v_mul_f32_e32 v59, v59, v59
	v_fmac_f32_e32 v59, v58, v58
	v_add_f32_e32 v0, v0, v59
	v_and_b32_e32 v59, 0xffff0000, v65
	v_lshlrev_b32_e32 v58, 16, v65
	v_mul_f32_e32 v59, v59, v59
	v_fmac_f32_e32 v59, v58, v58
	v_add_f32_e32 v0, v0, v59
	v_and_b32_e32 v59, 64, v221
	v_xor_b32_e32 v58, 16, v221
	v_add_u32_e32 v59, 64, v59
	v_cmp_lt_i32_e32 vcc, v58, v59
	s_nop 1
	v_cndmask_b32_e32 v58, v221, v58, vcc
	v_lshlrev_b32_e32 v58, 2, v58
	ds_bpermute_b32 v58, v58, v0
	s_waitcnt lgkmcnt(0)
	v_add_f32_e32 v0, v0, v58
	v_xor_b32_e32 v58, 32, v221
	v_cmp_lt_i32_e32 vcc, v58, v59
	s_nop 1
	v_cndmask_b32_e32 v58, v221, v58, vcc
	v_lshlrev_b32_e32 v58, 2, v58
	ds_bpermute_b32 v58, v58, v0
	s_and_saveexec_b64 s[34:35], s[4:5]
	s_cbranch_execz .LBB0_443
	s_waitcnt lgkmcnt(0)
	v_add_f32_e32 v60, v0, v58
	v_mov_b32_e32 v0, s68
	v_mad_i64_i32 v[58:59], s[60:61], v70, 3, v[0:1]
	v_lshl_add_u64 v[58:59], v[58:59], 4, s[28:29]
	global_store_dword v[58:59], v60, off

; __device__ __forceinline__ u32x4 pack8(const f32x4 v0, const f32x4 v1) { u32x4 w; w.x = cvt_pk_bf16(v0[0], v0[1]); w.y = cvt_pk_bf16(v0[2], v0[3]); w.z = cvt_pk_bf16(v1[0], v1[1]); w.w = cvt_pk_bf16(v1[2], v1[3]); return w; }
;     __device__ __forceinline__ void operator()(const f32x4 (&acc)[2][2][4][2], const Unit& u, int wr, int wc, int fr, int fq) const {
;     ...
;             for (int m = 0; m < 4; ++m) { const int row = row0 + ai * HALF + m * 16; bf16_t* rowp = O + (size_t)row * ldc + col0; float sq = 0.f;
; #pragma unroll
;                 for (int bj = 0; bj < 2; ++bj) { const u32x4 w = pack8(acc[ai][bj][m][0], acc[ai][bj][m][1]); *(u32x4*)(rowp + bj * HALF) = w;
; #pragma unroll
;                     for (int e = 0; e < 4; ++e) { const float lo = __uint_as_float(w[e] << 16), hi = __uint_as_float(w[e] & 0xffff0000u); sq += lo * lo + hi * hi; } }
;                 if (u.pn >= 6 && u.pn <= 8) { sq += __shfl_xor(sq, 16); sq += __shfl_xor(sq, 32); if (fq == 0) ssq[((size_t)row * 3 + (u.pn - 6)) * 4 + wc] = sq; }
;                 if (u.pn == 9 && wc < 2) { const int ib = wc * 16 + 4 * fq; const f32x4 v0 = acc[ai][0][m][0], v1 = acc[ai][0][m][1];
;                     const f32x4 c = *(const f32x4*)(rope + (size_t)row * 64 + ib), sn = *(const f32x4*)(rope + (size_t)row * 64 + 32 + ib);
;                     f32x4 a, b;
;                     a[0] = v0[0] * c[0] - v0[1] * sn[0]; a[1] = v0[1] * c[0] + v0[0] * sn[0];
;                     a[2] = v0[2] * c[1] - v0[3] * sn[1]; a[3] = v0[3] * c[1] + v0[2] * sn[1];
;                     b[0] = v1[0] * c[2] - v1[1] * sn[2]; b[1] = v1[1] * c[2] + v1[0] * sn[2];
;                     b[2] = v1[2] * c[3] - v1[3] * sn[3]; b[3] = v1[3] * c[3] + v1[2] * sn[3];
;                     const u32x4 w = pack8(a, b);
; #pragma unroll
;                     for (int h = 0; h < 6; ++h) *(u32x4*)(Kb + (size_t)row * ldk + 192 * h + 128 + wc * 32 + 8 * fq) = w; }
.LBB0_444:
	s_and_b64 vcc, exec, s[8:9]
	s_cbranch_vccnz .LBB0_446
	s_waitcnt lgkmcnt(0)
	v_lshlrev_b64 v[58:59], 8, v[70:71]
	v_lshl_add_u64 v[62:63], v[142:143], 0, v[58:59]
	flat_load_dwordx4 v[58:61], v[62:63]
	s_nop 0
	flat_load_dwordx4 v[62:65], v[62:63] offset:128
	s_waitcnt vmcnt(0) lgkmcnt(0)
	v_mov_b32_e32 v66, v58
	v_mov_b32_e32 v67, v62
	v_pk_mul_f32 v[66:67], v[54:55], v[66:67]
	s_nop 0
	v_sub_f32_e32 v0, v66, v67
	v_mov_b32_e32 v66, v62
	v_mov_b32_e32 v67, v58
	v_pk_mul_f32 v[54:55], v[54:55], v[66:67]
	v_mov_b32_e32 v62, v59
	v_add_f32_e32 v66, v55, v54
	v_pk_mul_f32 v[54:55], v[56:57], v[62:63]
	v_mov_b32_e32 v58, v63
	v_sub_f32_e32 v62, v54, v55
	v_pk_mul_f32 v[54:55], v[56:57], v[58:59]
	s_nop 0
	v_add_f32_e32 v56, v55, v54
	v_mov_b32_e32 v54, v60
	v_mov_b32_e32 v55, v64
	v_pk_mul_f32 v[54:55], v[50:51], v[54:55]
	s_nop 0
	v_sub_f32_e32 v57, v54, v55
	v_mov_b32_e32 v54, v64
	v_mov_b32_e32 v55, v60
	v_pk_mul_f32 v[50:51], v[50:51], v[54:55]
	v_mov_b32_e32 v64, v61
	v_add_f32_e32 v54, v51, v50
	v_pk_mul_f32 v[50:51], v[52:53], v[64:65]
	v_mov_b32_e32 v60, v65
	v_sub_f32_e32 v55, v50, v51
	v_pk_mul_f32 v[50:51], v[52:53], v[60:61]
	s_nop 0
	v_add_f32_e32 v53, v51, v50
	v_cvt_pk_bf16_f32 v50, v0, v66
	v_cvt_pk_bf16_f32 v51, v62, v56
	v_cvt_pk_bf16_f32 v52, v57, v54
	v_cvt_pk_bf16_f32 v53, v55, v53
	v_mad_i64_i32 v[54:55], s[34:35], v70, s87, v[144:145]
	global_store_dwordx4 v[54:55], v[50:53], off offset:256
	global_store_dwordx4 v[54:55], v[50:53], off offset:640
	global_store_dwordx4 v[54:55], v[50:53], off offset:1024
	global_store_dwordx4 v[54:55], v[50:53], off offset:1408
	global_store_dwordx4 v[54:55], v[50:53], off offset:1792
	global_store_dwordx4 v[54:55], v[50:53], off offset:2176
.LBB0_446:
	v_add_u32_e32 v54, 0x90, v152
	s_nop 0
	v_mov_b64_e32 v[50:51], s[20:21]
	s_movk_i32 s34, 0x1e00
	v_mad_i64_i32 v[50:51], s[34:35], v54, s34, v[50:51]
	v_ashrrev_i32_e32 v55, 31, v54
	v_lshl_add_u64 v[56:57], v[150:151], 1, v[50:51]
	s_and_b64 vcc, exec, s[10:11]
	v_cvt_pk_bf16_f32 v50, v38, v39
	v_cvt_pk_bf16_f32 v51, v40, v41
	v_cvt_pk_bf16_f32 v52, v34, v35
	v_cvt_pk_bf16_f32 v53, v36, v37
	global_store_dwordx4 v[56:57], v[50:53], off
	v_cvt_pk_bf16_f32 v46, v46, v47
	v_cvt_pk_bf16_f32 v47, v48, v49
	v_cvt_pk_bf16_f32 v48, v42, v43
	v_cvt_pk_bf16_f32 v49, v44, v45
	global_store_dwordx4 v[56:57], v[46:49], off offset:256
	s_cbranch_vccnz .LBB0_450
	v_and_b32_e32 v42, 0xffff0000, v50
	v_lshlrev_b32_e32 v0, 16, v50
	v_mul_f32_e32 v42, v42, v42
	v_and_b32_e32 v43, 0xffff0000, v51
	v_fmac_f32_e32 v42, v0, v0
	v_lshlrev_b32_e32 v0, 16, v51
	v_mul_f32_e32 v43, v43, v43
	v_fmac_f32_e32 v43, v0, v0
	v_add_f32_e32 v0, v42, v43
	v_and_b32_e32 v43, 0xffff0000, v52
	v_lshlrev_b32_e32 v42, 16, v52
	v_mul_f32_e32 v43, v43, v43
	v_fmac_f32_e32 v43, v42, v42
	v_add_f32_e32 v0, v0, v43
	v_and_b32_e32 v43, 0xffff0000, v53
	v_lshlrev_b32_e32 v42, 16, v53
	v_mul_f32_e32 v43, v43, v43
	v_fmac_f32_e32 v43, v42, v42
	v_add_f32_e32 v0, v0, v43
	v_and_b32_e32 v43, 0xffff0000, v46
	v_lshlrev_b32_e32 v42, 16, v46
	v_mul_f32_e32 v43, v43, v43
	v_fmac_f32_e32 v43, v42, v42
	v_add_f32_e32 v0, v0, v43
	v_and_b32_e32 v43, 0xffff0000, v47
	v_lshlrev_b32_e32 v42, 16, v47
	v_mul_f32_e32 v43, v43, v43
	v_fmac_f32_e32 v43, v42, v42
	v_add_f32_e32 v0, v0, v43
	v_and_b32_e32 v43, 0xffff0000, v48
	v_lshlrev_b32_e32 v42, 16, v48
	v_mul_f32_e32 v43, v43, v43
	v_fmac_f32_e32 v43, v42, v42
	v_add_f32_e32 v0, v0, v43
	v_and_b32_e32 v43, 0xffff0000, v49
	v_lshlrev_b32_e32 v42, 16, v49
	v_mul_f32_e32 v43, v43, v43
	v_fmac_f32_e32 v43, v42, v42
	v_add_f32_e32 v0, v0, v43
	v_and_b32_e32 v43, 64, v221
	v_xor_b32_e32 v42, 16, v221
	v_add_u32_e32 v43, 64, v43
	v_cmp_lt_i32_e32 vcc, v42, v43
	s_nop 1
	v_cndmask_b32_e32 v42, v221, v42, vcc
	v_lshlrev_b32_e32 v42, 2, v42
	ds_bpermute_b32 v42, v42, v0
	s_waitcnt lgkmcnt(0)
	v_add_f32_e32 v0, v0, v42
	v_xor_b32_e32 v42, 32, v221
	v_cmp_lt_i32_e32 vcc, v42, v43
	s_nop 1
	v_cndmask_b32_e32 v42, v221, v42, vcc
	v_lshlrev_b32_e32 v42, 2, v42
	ds_bpermute_b32 v42, v42, v0
	s_and_saveexec_b64 s[34:35], s[4:5]
	s_cbranch_execz .LBB0_449
	s_waitcnt lgkmcnt(0)
	v_add_f32_e32 v44, v0, v42
	v_mov_b32_e32 v0, s68
	v_mad_i64_i32 v[42:43], s[60:61], v54, 3, v[0:1]
	v_lshl_add_u64 v[42:43], v[42:43], 4, s[28:29]
	global_store_dword v[42:43], v44, off

; __device__ __forceinline__ u32x4 pack8(const f32x4 v0, const f32x4 v1) { u32x4 w; w.x = cvt_pk_bf16(v0[0], v0[1]); w.y = cvt_pk_bf16(v0[2], v0[3]); w.z = cvt_pk_bf16(v1[0], v1[1]); w.w = cvt_pk_bf16(v1[2], v1[3]); return w; }
;     __device__ __forceinline__ void operator()(const f32x4 (&acc)[2][2][4][2], const Unit& u, int wr, int wc, int fr, int fq) const {
;     ...
;             for (int m = 0; m < 4; ++m) { const int row = row0 + ai * HALF + m * 16; bf16_t* rowp = O + (size_t)row * ldc + col0; float sq = 0.f;
; #pragma unroll
;                 for (int bj = 0; bj < 2; ++bj) { const u32x4 w = pack8(acc[ai][bj][m][0], acc[ai][bj][m][1]); *(u32x4*)(rowp + bj * HALF) = w;
; #pragma unroll
;                     for (int e = 0; e < 4; ++e) { const float lo = __uint_as_float(w[e] << 16), hi = __uint_as_float(w[e] & 0xffff0000u); sq += lo * lo + hi * hi; } }
;                 if (u.pn >= 6 && u.pn <= 8) { sq += __shfl_xor(sq, 16); sq += __shfl_xor(sq, 32); if (fq == 0) ssq[((size_t)row * 3 + (u.pn - 6)) * 4 + wc] = sq; }
;                 if (u.pn == 9 && wc < 2) { const int ib = wc * 16 + 4 * fq; const f32x4 v0 = acc[ai][0][m][0], v1 = acc[ai][0][m][1];
;                     const f32x4 c = *(const f32x4*)(rope + (size_t)row * 64 + ib), sn = *(const f32x4*)(rope + (size_t)row * 64 + 32 + ib);
;                     f32x4 a, b;
;                     a[0] = v0[0] * c[0] - v0[1] * sn[0]; a[1] = v0[1] * c[0] + v0[0] * sn[0];
;                     a[2] = v0[2] * c[1] - v0[3] * sn[1]; a[3] = v0[3] * c[1] + v0[2] * sn[1];
;                     b[0] = v1[0] * c[2] - v1[1] * sn[2]; b[1] = v1[1] * c[2] + v1[0] * sn[2];
;                     b[2] = v1[2] * c[3] - v1[3] * sn[3]; b[3] = v1[3] * c[3] + v1[2] * sn[3];
;                     const u32x4 w = pack8(a, b);
; #pragma unroll
;                     for (int h = 0; h < 6; ++h) *(u32x4*)(Kb + (size_t)row * ldk + 192 * h + 128 + wc * 32 + 8 * fq) = w; }
.LBB0_450:
	s_and_b64 vcc, exec, s[8:9]
	s_cbranch_vccnz .LBB0_452
	s_waitcnt lgkmcnt(0)
	v_lshlrev_b64 v[42:43], 8, v[54:55]
	v_lshl_add_u64 v[46:47], v[142:143], 0, v[42:43]
	flat_load_dwordx4 v[42:45], v[46:47]
	s_nop 0
	flat_load_dwordx4 v[46:49], v[46:47] offset:128
	s_waitcnt vmcnt(0) lgkmcnt(0)
	v_mov_b32_e32 v50, v42
	v_mov_b32_e32 v51, v46
	v_pk_mul_f32 v[50:51], v[38:39], v[50:51]
	s_nop 0
	v_sub_f32_e32 v0, v50, v51
	v_mov_b32_e32 v50, v46
	v_mov_b32_e32 v51, v42
	v_pk_mul_f32 v[38:39], v[38:39], v[50:51]
	v_mov_b32_e32 v46, v43
	v_add_f32_e32 v50, v39, v38
	v_pk_mul_f32 v[38:39], v[40:41], v[46:47]
	v_mov_b32_e32 v42, v47
	v_sub_f32_e32 v46, v38, v39
	v_pk_mul_f32 v[38:39], v[40:41], v[42:43]
	s_nop 0
	v_add_f32_e32 v40, v39, v38
	v_mov_b32_e32 v38, v44
	v_mov_b32_e32 v39, v48
	v_pk_mul_f32 v[38:39], v[34:35], v[38:39]
	s_nop 0
	v_sub_f32_e32 v41, v38, v39
	v_mov_b32_e32 v38, v48
	v_mov_b32_e32 v39, v44
	v_pk_mul_f32 v[34:35], v[34:35], v[38:39]
	v_mov_b32_e32 v48, v45
	v_add_f32_e32 v38, v35, v34
	v_pk_mul_f32 v[34:35], v[36:37], v[48:49]
	v_mov_b32_e32 v44, v49
	v_sub_f32_e32 v39, v34, v35
	v_pk_mul_f32 v[34:35], v[36:37], v[44:45]
	s_nop 0
	v_add_f32_e32 v37, v35, v34
	v_cvt_pk_bf16_f32 v34, v0, v50
	v_cvt_pk_bf16_f32 v35, v46, v40
	v_cvt_pk_bf16_f32 v36, v41, v38
	v_cvt_pk_bf16_f32 v37, v39, v37
	v_mad_i64_i32 v[38:39], s[34:35], v54, s87, v[144:145]
	global_store_dwordx4 v[38:39], v[34:37], off offset:256
	global_store_dwordx4 v[38:39], v[34:37], off offset:640
	global_store_dwordx4 v[38:39], v[34:37], off offset:1024
	global_store_dwordx4 v[38:39], v[34:37], off offset:1408
	global_store_dwordx4 v[38:39], v[34:37], off offset:1792
	global_store_dwordx4 v[38:39], v[34:37], off offset:2176
.LBB0_452:
	v_add_u32_e32 v38, 0xa0, v152
	s_nop 0
	v_mov_b64_e32 v[34:35], s[20:21]
	s_movk_i32 s34, 0x1e00
	v_mad_i64_i32 v[34:35], s[34:35], v38, s34, v[34:35]
	v_ashrrev_i32_e32 v39, 31, v38
	v_lshl_add_u64 v[40:41], v[150:151], 1, v[34:35]
	s_and_b64 vcc, exec, s[10:11]
	v_cvt_pk_bf16_f32 v34, v22, v23
	v_cvt_pk_bf16_f32 v35, v24, v25
	v_cvt_pk_bf16_f32 v36, v18, v19
	v_cvt_pk_bf16_f32 v37, v20, v21
	global_store_dwordx4 v[40:41], v[34:37], off
	v_cvt_pk_bf16_f32 v30, v30, v31
	v_cvt_pk_bf16_f32 v31, v32, v33
	v_cvt_pk_bf16_f32 v32, v26, v27
	v_cvt_pk_bf16_f32 v33, v28, v29
	global_store_dwordx4 v[40:41], v[30:33], off offset:256
	s_cbranch_vccnz .LBB0_456
	v_and_b32_e32 v26, 0xffff0000, v34
	v_lshlrev_b32_e32 v0, 16, v34
	v_mul_f32_e32 v26, v26, v26
	v_and_b32_e32 v27, 0xffff0000, v35
	v_fmac_f32_e32 v26, v0, v0
	v_lshlrev_b32_e32 v0, 16, v35
	v_mul_f32_e32 v27, v27, v27
	v_fmac_f32_e32 v27, v0, v0
	v_add_f32_e32 v0, v26, v27
	v_and_b32_e32 v27, 0xffff0000, v36
	v_lshlrev_b32_e32 v26, 16, v36
	v_mul_f32_e32 v27, v27, v27
	v_fmac_f32_e32 v27, v26, v26
	v_add_f32_e32 v0, v0, v27
	v_and_b32_e32 v27, 0xffff0000, v37
	v_lshlrev_b32_e32 v26, 16, v37
	v_mul_f32_e32 v27, v27, v27
	v_fmac_f32_e32 v27, v26, v26
	v_add_f32_e32 v0, v0, v27
	v_and_b32_e32 v27, 0xffff0000, v30
	v_lshlrev_b32_e32 v26, 16, v30
	v_mul_f32_e32 v27, v27, v27
	v_fmac_f32_e32 v27, v26, v26
	v_add_f32_e32 v0, v0, v27
	v_and_b32_e32 v27, 0xffff0000, v31
	v_lshlrev_b32_e32 v26, 16, v31
	v_mul_f32_e32 v27, v27, v27
	v_fmac_f32_e32 v27, v26, v26
	v_add_f32_e32 v0, v0, v27
	v_and_b32_e32 v27, 0xffff0000, v32
	v_lshlrev_b32_e32 v26, 16, v32
	v_mul_f32_e32 v27, v27, v27
	v_fmac_f32_e32 v27, v26, v26
	v_add_f32_e32 v0, v0, v27
	v_and_b32_e32 v27, 0xffff0000, v33
	v_lshlrev_b32_e32 v26, 16, v33
	v_mul_f32_e32 v27, v27, v27
	v_fmac_f32_e32 v27, v26, v26
	v_add_f32_e32 v0, v0, v27
	v_and_b32_e32 v27, 64, v221
	v_xor_b32_e32 v26, 16, v221
	v_add_u32_e32 v27, 64, v27
	v_cmp_lt_i32_e32 vcc, v26, v27
	s_nop 1
	v_cndmask_b32_e32 v26, v221, v26, vcc
	v_lshlrev_b32_e32 v26, 2, v26
	ds_bpermute_b32 v26, v26, v0
	s_waitcnt lgkmcnt(0)
	v_add_f32_e32 v0, v0, v26
	v_xor_b32_e32 v26, 32, v221
	v_cmp_lt_i32_e32 vcc, v26, v27
	s_nop 1
	v_cndmask_b32_e32 v26, v221, v26, vcc
	v_lshlrev_b32_e32 v26, 2, v26
	ds_bpermute_b32 v26, v26, v0
	s_and_saveexec_b64 s[34:35], s[4:5]
	s_cbranch_execz .LBB0_455
	s_waitcnt lgkmcnt(0)
	v_add_f32_e32 v28, v0, v26
	v_mov_b32_e32 v0, s68
	v_mad_i64_i32 v[26:27], s[60:61], v38, 3, v[0:1]
	v_lshl_add_u64 v[26:27], v[26:27], 4, s[28:29]
	global_store_dword v[26:27], v28, off

; __device__ __forceinline__ u32x4 pack8(const f32x4 v0, const f32x4 v1) { u32x4 w; w.x = cvt_pk_bf16(v0[0], v0[1]); w.y = cvt_pk_bf16(v0[2], v0[3]); w.z = cvt_pk_bf16(v1[0], v1[1]); w.w = cvt_pk_bf16(v1[2], v1[3]); return w; }
;     __device__ __forceinline__ void operator()(const f32x4 (&acc)[2][2][4][2], const Unit& u, int wr, int wc, int fr, int fq) const {
;     ...
;             for (int m = 0; m < 4; ++m) { const int row = row0 + ai * HALF + m * 16; bf16_t* rowp = O + (size_t)row * ldc + col0; float sq = 0.f;
; #pragma unroll
;                 for (int bj = 0; bj < 2; ++bj) { const u32x4 w = pack8(acc[ai][bj][m][0], acc[ai][bj][m][1]); *(u32x4*)(rowp + bj * HALF) = w;
; #pragma unroll
;                     for (int e = 0; e < 4; ++e) { const float lo = __uint_as_float(w[e] << 16), hi = __uint_as_float(w[e] & 0xffff0000u); sq += lo * lo + hi * hi; } }
;                 if (u.pn >= 6 && u.pn <= 8) { sq += __shfl_xor(sq, 16); sq += __shfl_xor(sq, 32); if (fq == 0) ssq[((size_t)row * 3 + (u.pn - 6)) * 4 + wc] = sq; }
;                 if (u.pn == 9 && wc < 2) { const int ib = wc * 16 + 4 * fq; const f32x4 v0 = acc[ai][0][m][0], v1 = acc[ai][0][m][1];
;                     const f32x4 c = *(const f32x4*)(rope + (size_t)row * 64 + ib), sn = *(const f32x4*)(rope + (size_t)row * 64 + 32 + ib);
;                     f32x4 a, b;
;                     a[0] = v0[0] * c[0] - v0[1] * sn[0]; a[1] = v0[1] * c[0] + v0[0] * sn[0];
;                     a[2] = v0[2] * c[1] - v0[3] * sn[1]; a[3] = v0[3] * c[1] + v0[2] * sn[1];
;                     b[0] = v1[0] * c[2] - v1[1] * sn[2]; b[1] = v1[1] * c[2] + v1[0] * sn[2];
;                     b[2] = v1[2] * c[3] - v1[3] * sn[3]; b[3] = v1[3] * c[3] + v1[2] * sn[3];
;                     const u32x4 w = pack8(a, b);
; #pragma unroll
;                     for (int h = 0; h < 6; ++h) *(u32x4*)(Kb + (size_t)row * ldk + 192 * h + 128 + wc * 32 + 8 * fq) = w; }
.LBB0_456:
	s_and_b64 vcc, exec, s[8:9]
	s_cbranch_vccnz .LBB0_458
	s_waitcnt lgkmcnt(0)
	v_lshlrev_b64 v[26:27], 8, v[38:39]
	v_lshl_add_u64 v[30:31], v[142:143], 0, v[26:27]
	flat_load_dwordx4 v[26:29], v[30:31]
	s_nop 0
	flat_load_dwordx4 v[30:33], v[30:31] offset:128
	s_waitcnt vmcnt(0) lgkmcnt(0)
	v_mov_b32_e32 v34, v26
	v_mov_b32_e32 v35, v30
	v_pk_mul_f32 v[34:35], v[22:23], v[34:35]
	s_nop 0
	v_sub_f32_e32 v0, v34, v35
	v_mov_b32_e32 v34, v30
	v_mov_b32_e32 v35, v26
	v_pk_mul_f32 v[22:23], v[22:23], v[34:35]
	v_mov_b32_e32 v30, v27
	v_add_f32_e32 v34, v23, v22
	v_pk_mul_f32 v[22:23], v[24:25], v[30:31]
	v_mov_b32_e32 v26, v31
	v_sub_f32_e32 v30, v22, v23
	v_pk_mul_f32 v[22:23], v[24:25], v[26:27]
	s_nop 0
	v_add_f32_e32 v24, v23, v22
	v_mov_b32_e32 v22, v28
	v_mov_b32_e32 v23, v32
	v_pk_mul_f32 v[22:23], v[18:19], v[22:23]
	s_nop 0
	v_sub_f32_e32 v25, v22, v23
	v_mov_b32_e32 v22, v32
	v_mov_b32_e32 v23, v28
	v_pk_mul_f32 v[18:19], v[18:19], v[22:23]
	v_mov_b32_e32 v32, v29
	v_add_f32_e32 v22, v19, v18
	v_pk_mul_f32 v[18:19], v[20:21], v[32:33]
	v_mov_b32_e32 v28, v33
	v_sub_f32_e32 v23, v18, v19
	v_pk_mul_f32 v[18:19], v[20:21], v[28:29]
	s_nop 0
	v_add_f32_e32 v21, v19, v18
	v_cvt_pk_bf16_f32 v18, v0, v34
	v_cvt_pk_bf16_f32 v19, v30, v24
	v_cvt_pk_bf16_f32 v20, v25, v22
	v_cvt_pk_bf16_f32 v21, v23, v21
	v_mad_i64_i32 v[22:23], s[34:35], v38, s87, v[144:145]
	global_store_dwordx4 v[22:23], v[18:21], off offset:256
	global_store_dwordx4 v[22:23], v[18:21], off offset:640
	global_store_dwordx4 v[22:23], v[18:21], off offset:1024
	global_store_dwordx4 v[22:23], v[18:21], off offset:1408
	global_store_dwordx4 v[22:23], v[18:21], off offset:1792
	global_store_dwordx4 v[22:23], v[18:21], off offset:2176
.LBB0_458:
	v_add_u32_e32 v22, 0xb0, v152
	s_nop 0
	v_mov_b64_e32 v[18:19], s[20:21]
	s_movk_i32 s34, 0x1e00
	v_mad_i64_i32 v[18:19], s[34:35], v22, s34, v[18:19]
	v_ashrrev_i32_e32 v23, 31, v22
	v_lshl_add_u64 v[24:25], v[150:151], 1, v[18:19]
	s_and_b64 vcc, exec, s[10:11]
	v_cvt_pk_bf16_f32 v18, v6, v7
	v_cvt_pk_bf16_f32 v19, v8, v9
	v_cvt_pk_bf16_f32 v20, v2, v3
	v_cvt_pk_bf16_f32 v21, v4, v5
	global_store_dwordx4 v[24:25], v[18:21], off
	v_cvt_pk_bf16_f32 v14, v14, v15
	v_cvt_pk_bf16_f32 v15, v16, v17
	v_cvt_pk_bf16_f32 v16, v10, v11
	v_cvt_pk_bf16_f32 v17, v12, v13
	global_store_dwordx4 v[24:25], v[14:17], off offset:256
	s_cbranch_vccnz .LBB0_462
	v_and_b32_e32 v10, 0xffff0000, v18
	v_lshlrev_b32_e32 v0, 16, v18
	v_mul_f32_e32 v10, v10, v10
	v_and_b32_e32 v11, 0xffff0000, v19
	v_fmac_f32_e32 v10, v0, v0
	v_lshlrev_b32_e32 v0, 16, v19
	v_mul_f32_e32 v11, v11, v11
	v_fmac_f32_e32 v11, v0, v0
	v_add_f32_e32 v0, v10, v11
	v_and_b32_e32 v11, 0xffff0000, v20
	v_lshlrev_b32_e32 v10, 16, v20
	v_mul_f32_e32 v11, v11, v11
	v_fmac_f32_e32 v11, v10, v10
	v_add_f32_e32 v0, v0, v11
	v_and_b32_e32 v11, 0xffff0000, v21
	v_lshlrev_b32_e32 v10, 16, v21
	v_mul_f32_e32 v11, v11, v11
	v_fmac_f32_e32 v11, v10, v10
	v_add_f32_e32 v0, v0, v11
	v_and_b32_e32 v11, 0xffff0000, v14
	v_lshlrev_b32_e32 v10, 16, v14
	v_mul_f32_e32 v11, v11, v11
	v_fmac_f32_e32 v11, v10, v10
	v_add_f32_e32 v0, v0, v11
	v_and_b32_e32 v11, 0xffff0000, v15
	v_lshlrev_b32_e32 v10, 16, v15
	v_mul_f32_e32 v11, v11, v11
	v_fmac_f32_e32 v11, v10, v10
	v_add_f32_e32 v0, v0, v11
	v_and_b32_e32 v11, 0xffff0000, v16
	v_lshlrev_b32_e32 v10, 16, v16
	v_mul_f32_e32 v11, v11, v11
	v_fmac_f32_e32 v11, v10, v10
	v_add_f32_e32 v0, v0, v11
	v_and_b32_e32 v11, 0xffff0000, v17
	v_lshlrev_b32_e32 v10, 16, v17
	v_mul_f32_e32 v11, v11, v11
	v_fmac_f32_e32 v11, v10, v10
	v_add_f32_e32 v0, v0, v11
	v_and_b32_e32 v11, 64, v221
	v_xor_b32_e32 v10, 16, v221
	v_add_u32_e32 v11, 64, v11
	v_cmp_lt_i32_e32 vcc, v10, v11
	s_nop 1
	v_cndmask_b32_e32 v10, v221, v10, vcc
	v_lshlrev_b32_e32 v10, 2, v10
	ds_bpermute_b32 v10, v10, v0
	s_waitcnt lgkmcnt(0)
	v_add_f32_e32 v0, v0, v10
	v_xor_b32_e32 v10, 32, v221
	v_cmp_lt_i32_e32 vcc, v10, v11
	s_nop 1
	v_cndmask_b32_e32 v10, v221, v10, vcc
	v_lshlrev_b32_e32 v10, 2, v10
	ds_bpermute_b32 v10, v10, v0
	s_and_saveexec_b64 s[10:11], s[4:5]
	s_cbranch_execz .LBB0_461
	s_waitcnt lgkmcnt(0)
	v_add_f32_e32 v12, v0, v10
	v_mov_b32_e32 v0, s68
	v_mad_i64_i32 v[10:11], s[34:35], v22, 3, v[0:1]
	v_lshl_add_u64 v[10:11], v[10:11], 4, s[28:29]
	global_store_dword v[10:11], v12, off

; __device__ __forceinline__ u32x4 pack8(const f32x4 v0, const f32x4 v1) { u32x4 w; w.x = cvt_pk_bf16(v0[0], v0[1]); w.y = cvt_pk_bf16(v0[2], v0[3]); w.z = cvt_pk_bf16(v1[0], v1[1]); w.w = cvt_pk_bf16(v1[2], v1[3]); return w; }
;     __device__ __forceinline__ void operator()(const f32x4 (&acc)[2][2][4][2], const Unit& u, int wr, int wc, int fr, int fq) const {
;     ...
;                 if (u.pn == 9 && wc < 2) { const int ib = wc * 16 + 4 * fq; const f32x4 v0 = acc[ai][0][m][0], v1 = acc[ai][0][m][1];
;                     const f32x4 c = *(const f32x4*)(rope + (size_t)row * 64 + ib), sn = *(const f32x4*)(rope + (size_t)row * 64 + 32 + ib);
;                     f32x4 a, b;
;                     a[0] = v0[0] * c[0] - v0[1] * sn[0]; a[1] = v0[1] * c[0] + v0[0] * sn[0];
;                     a[2] = v0[2] * c[1] - v0[3] * sn[1]; a[3] = v0[3] * c[1] + v0[2] * sn[1];
;                     b[0] = v1[0] * c[2] - v1[1] * sn[2]; b[1] = v1[1] * c[2] + v1[0] * sn[2];
;                     b[2] = v1[2] * c[3] - v1[3] * sn[3]; b[3] = v1[3] * c[3] + v1[2] * sn[3];
;                     const u32x4 w = pack8(a, b);
; #pragma unroll
;                     for (int h = 0; h < 6; ++h) *(u32x4*)(Kb + (size_t)row * ldk + 192 * h + 128 + wc * 32 + 8 * fq) = w; }
.LBB0_462:
	s_and_b64 vcc, exec, s[8:9]
	s_cbranch_vccnz .LBB0_464
	s_waitcnt lgkmcnt(0)
	v_lshlrev_b64 v[10:11], 8, v[22:23]
	v_lshl_add_u64 v[14:15], v[142:143], 0, v[10:11]
	flat_load_dwordx4 v[10:13], v[14:15]
	s_nop 0
	flat_load_dwordx4 v[14:17], v[14:15] offset:128
	s_waitcnt vmcnt(0) lgkmcnt(0)
	v_mov_b32_e32 v18, v10
	v_mov_b32_e32 v19, v14
	v_pk_mul_f32 v[18:19], v[6:7], v[18:19]
	s_nop 0
	v_sub_f32_e32 v0, v18, v19
	v_mov_b32_e32 v18, v14
	v_mov_b32_e32 v19, v10
	v_pk_mul_f32 v[6:7], v[6:7], v[18:19]
	v_mov_b32_e32 v14, v11
	v_add_f32_e32 v18, v7, v6
	v_pk_mul_f32 v[6:7], v[8:9], v[14:15]
	v_mov_b32_e32 v10, v15
	v_sub_f32_e32 v14, v6, v7
	v_pk_mul_f32 v[6:7], v[8:9], v[10:11]
	s_nop 0
	v_add_f32_e32 v8, v7, v6
	v_mov_b32_e32 v6, v12
	v_mov_b32_e32 v7, v16
	v_pk_mul_f32 v[6:7], v[2:3], v[6:7]
	s_nop 0
	v_sub_f32_e32 v9, v6, v7
	v_mov_b32_e32 v6, v16
	v_mov_b32_e32 v7, v12
	v_pk_mul_f32 v[2:3], v[2:3], v[6:7]
	v_mov_b32_e32 v16, v13
	v_add_f32_e32 v6, v3, v2
	v_pk_mul_f32 v[2:3], v[4:5], v[16:17]
	v_mov_b32_e32 v12, v17
	v_sub_f32_e32 v7, v2, v3
	v_pk_mul_f32 v[2:3], v[4:5], v[12:13]
	s_nop 0
	v_add_f32_e32 v5, v3, v2
	v_cvt_pk_bf16_f32 v2, v0, v18
	v_cvt_pk_bf16_f32 v3, v14, v8
	v_cvt_pk_bf16_f32 v4, v9, v6
	v_cvt_pk_bf16_f32 v5, v7, v5
	v_mad_i64_i32 v[6:7], s[8:9], v22, s87, v[144:145]
	global_store_dwordx4 v[6:7], v[2:5], off offset:256
	global_store_dwordx4 v[6:7], v[2:5], off offset:640
	global_store_dwordx4 v[6:7], v[2:5], off offset:1024
	global_store_dwordx4 v[6:7], v[2:5], off offset:1408
	global_store_dwordx4 v[6:7], v[2:5], off offset:1792
	global_store_dwordx4 v[6:7], v[2:5], off offset:2176

; __device__ __forceinline__ unsigned cvt_pk_bf16(float lo, float hi) { unsigned r; asm volatile("v_cvt_pk_bf16_f32 %0, %1, %2" : "=v"(r) : "v"(lo), "v"(hi)); return r; }
; template <int PERMT>
; __device__ __forceinline__ void transpose_job(const float* __restrict__ src, bf16_t* __restrict__ dst, int K, int N, int Npad, const float* __restrict__ kscale, unsigned char* lds_g, int first, int stride) {
;     ...
;         { const int n = tid >> 1, ks = tid & 1;
;           if (n0 + n < N) { bf16_t* dp = dst + (size_t)dst_row<PERMT>(n0 + n) * K + k0 + 32 * ks;
; #pragma unroll
;             for (int eb = 0; eb < 4; ++eb) { float v[8];
; #pragma unroll
;               for (int e = 0; e < 8; ++e) v[e] = T[(32 * ks + 8 * eb + e) * 257 + n];
;               u32x4 w; w.x = cvt_pk_bf16(v[0], v[1]); w.y = cvt_pk_bf16(v[2], v[3]); w.z = cvt_pk_bf16(v[4], v[5]); w.w = cvt_pk_bf16(v[6], v[7]);
;               *(u32x4*)(dp + 8 * eb) = w; } } }
.LBB0_472:
	s_or_b64 exec, exec, s[8:9]
	s_sub_i32 s8, 0, s18
	v_ashrrev_i32_e32 v3, 31, v2
	s_add_i32 s8, s16, s8
	v_lshlrev_b64 v[2:3], 10, v[2:3]
	v_lshl_add_u64 v[2:3], s[2:3], 0, v[2:3]
	s_ashr_i32 s9, s8, 31
	v_lshl_add_u64 v[2:3], s[8:9], 1, v[2:3]
	v_mov_b32_e32 v45, v1
	v_lshl_add_u64 v[6:7], v[2:3], 0, v[44:45]
	ds_read_b32 v0, v52 offset:1028
	ds_read_b32 v2, v52
	ds_read_b32 v3, v52 offset:3084
	ds_read_b32 v4, v52 offset:2056
	ds_read_b32 v5, v52 offset:5140
	ds_read_b32 v8, v52 offset:4112
	ds_read_b32 v9, v52 offset:7196
	ds_read_b32 v10, v52 offset:6168
	s_waitcnt lgkmcnt(6)
	v_cvt_pk_bf16_f32 v2, v2, v0
	s_waitcnt lgkmcnt(4)
	v_cvt_pk_bf16_f32 v3, v4, v3
	s_waitcnt lgkmcnt(2)
	v_cvt_pk_bf16_f32 v4, v8, v5
	s_waitcnt lgkmcnt(0)
	v_cvt_pk_bf16_f32 v5, v10, v9
	global_store_dwordx4 v[6:7], v[2:5], off
	ds_read_b32 v0, v52 offset:9252
	ds_read_b32 v2, v52 offset:8224
	ds_read_b32 v3, v52 offset:11308
	ds_read_b32 v4, v52 offset:10280
	ds_read_b32 v5, v52 offset:13364
	ds_read_b32 v8, v52 offset:12336
	ds_read_b32 v9, v52 offset:15420
	ds_read_b32 v10, v52 offset:14392
	s_waitcnt lgkmcnt(0)
	v_cvt_pk_bf16_f32 v2, v2, v0
	v_cvt_pk_bf16_f32 v3, v4, v3
	v_cvt_pk_bf16_f32 v4, v8, v5
	v_cvt_pk_bf16_f32 v5, v10, v9
	global_store_dwordx4 v[6:7], v[2:5], off offset:16
	ds_read_b32 v0, v52 offset:17476
	ds_read_b32 v2, v52 offset:16448
	ds_read_b32 v3, v52 offset:19532
	ds_read_b32 v4, v52 offset:18504
	ds_read_b32 v5, v52 offset:21588
	ds_read_b32 v8, v52 offset:20560
	ds_read_b32 v9, v52 offset:23644
	ds_read_b32 v10, v52 offset:22616
	s_waitcnt lgkmcnt(0)
	v_cvt_pk_bf16_f32 v2, v2, v0
	v_cvt_pk_bf16_f32 v3, v4, v3
	v_cvt_pk_bf16_f32 v4, v8, v5
	v_cvt_pk_bf16_f32 v5, v10, v9
	global_store_dwordx4 v[6:7], v[2:5], off offset:32
	ds_read_b32 v0, v52 offset:25700
	ds_read_b32 v2, v52 offset:24672
	ds_read_b32 v3, v52 offset:27756
	ds_read_b32 v4, v52 offset:26728
	ds_read_b32 v5, v52 offset:29812
	ds_read_b32 v8, v52 offset:28784
	ds_read_b32 v9, v52 offset:31868
	ds_read_b32 v10, v52 offset:30840
	s_waitcnt lgkmcnt(0)
	v_cvt_pk_bf16_f32 v2, v2, v0
	v_cvt_pk_bf16_f32 v3, v4, v3
	v_cvt_pk_bf16_f32 v4, v8, v5
	v_cvt_pk_bf16_f32 v5, v10, v9
	global_store_dwordx4 v[6:7], v[2:5], off offset:48

; template <int PERMT>
; __device__ __forceinline__ void transpose_job(const float* __restrict__ src, bf16_t* __restrict__ dst, int K, int N, int Npad, const float* __restrict__ kscale, unsigned char* lds_g, int first, int stride) {
;     ...
;     const size_t nz = (size_t)(Npad - N) * K / 8;
;     for (size_t i = (size_t)blockIdx.x * NTHREADS + tid; i < nz; i += (size_t)gridDim.x * NTHREADS) *(u32x4*)(dst + (size_t)N * K + i * 8) = (u32x4){0u, 0u, 0u, 0u};
.LBB0_511:
	v_lshl_add_u64 v[2:3], v[2:3], 0, s[78:79]
	s_mov_b64 s[4:5], 0x1fff
	v_cmp_lt_u64_e32 vcc, s[4:5], v[2:3]
	global_store_dwordx4 v[4:5], v[232:235], off
	s_or_b64 s[2:3], vcc, s[2:3]
	v_lshl_add_u64 v[4:5], v[4:5], 0, s[6:7]
	s_andn2_b64 exec, exec, s[2:3]
	s_cbranch_execnz .LBB0_511

; __device__ __forceinline__ unsigned cvt_pk_bf16(float lo, float hi) { unsigned r; asm volatile("v_cvt_pk_bf16_f32 %0, %1, %2" : "=v"(r) : "v"(lo), "v"(hi)); return r; }
; template <int PERMT>
; __device__ __forceinline__ void transpose_job(const float* __restrict__ src, bf16_t* __restrict__ dst, int K, int N, int Npad, const float* __restrict__ kscale, unsigned char* lds_g, int first, int stride) {
;     ...
;           for (int i = 0; i < 8; ++i) { const int k = k0 + kk + 8 * i; if (kscale) v[i] = v[i] * kscale[k];
;               float* tp = T + (kk + 8 * i) * 257 + 4 * n4; tp[0] = v[i][0]; tp[1] = v[i][1]; tp[2] = v[i][2]; tp[3] = v[i][3]; } }
;         __syncthreads();
;         { const int n = tid >> 1, ks = tid & 1;
;           if (n0 + n < N) { bf16_t* dp = dst + (size_t)dst_row<PERMT>(n0 + n) * K + k0 + 32 * ks;
; #pragma unroll
;             for (int eb = 0; eb < 4; ++eb) { float v[8];
; #pragma unroll
;               for (int e = 0; e < 8; ++e) v[e] = T[(32 * ks + 8 * eb + e) * 257 + n];
;               u32x4 w; w.x = cvt_pk_bf16(v[0], v[1]); w.y = cvt_pk_bf16(v[2], v[3]); w.z = cvt_pk_bf16(v[4], v[5]); w.w = cvt_pk_bf16(v[6], v[7]);
;               *(u32x4*)(dp + 8 * eb) = w; } } }
.LBB0_525:
	v_add_u32_e32 v2, 0xc0c0, v0
	ds_write2_b32 v2, v16, v17 offset1:1
	v_add_u32_e32 v2, 0xc0c8, v0
	v_ashrrev_i32_e32 v3, 1, v44
	ds_write2_b32 v2, v14, v15 offset1:1
	v_add_u32_e32 v2, 0xe0e0, v0
	ds_write2_b32 v2, v10, v11 offset1:1
	v_add_u32_e32 v2, s7, v3
	v_add_u32_e32 v0, 0xe0e8, v0
	v_cmp_gt_i32_e32 vcc, s33, v2
	ds_write2_b32 v0, v12, v13 offset1:1
	s_waitcnt lgkmcnt(0)
	s_barrier
	s_and_saveexec_b64 s[0:1], vcc
	s_cbranch_execz .LBB0_527
	v_lshlrev_b32_e32 v0, 5, v44
	v_and_b32_e32 v0, 32, v0
	v_lshlrev_b32_e32 v4, 2, v3
	v_mul_u32_u24_e32 v5, 0x404, v0
	v_add3_u32 v10, 0, v4, v5
	ds_read_b32 v4, v10 offset:1028
	ds_read_b32 v5, v10 offset:3084
	ds_read_b32 v8, v10 offset:5140
	ds_read_b32 v9, v10 offset:7196
	ds_read_b32 v11, v10 offset:6168
	ds_read_b32 v12, v10 offset:4112
	ds_read_b32 v13, v10 offset:2056
	ds_read_b32 v14, v10
	s_add_u32 s2, s4, s36
	v_ashrrev_i32_e32 v3, 31, v2
	s_addc_u32 s3, s5, 0
	v_lshlrev_b64 v[2:3], 9, v[2:3]
	v_lshl_add_u64 v[2:3], s[2:3], 0, v[2:3]
	s_lshl_b32 s90, s6, 1
	v_lshl_add_u64 v[2:3], v[2:3], 0, s[90:91]
	v_lshlrev_b32_e32 v0, 1, v0
	v_lshl_add_u64 v[6:7], v[2:3], 0, v[0:1]
	s_waitcnt lgkmcnt(0)
	v_cvt_pk_bf16_f32 v2, v14, v4
	v_cvt_pk_bf16_f32 v3, v13, v5
	v_cvt_pk_bf16_f32 v4, v12, v8
	v_cvt_pk_bf16_f32 v5, v11, v9
	ds_read_b32 v0, v10 offset:9252
	ds_read_b32 v11, v10 offset:11308
	ds_read_b32 v12, v10 offset:13364
	ds_read_b32 v13, v10 offset:15420
	ds_read_b32 v14, v10 offset:14392
	ds_read_b32 v15, v10 offset:12336
	ds_read_b32 v16, v10 offset:10280
	ds_read_b32 v17, v10 offset:8224
	s_mov_b32 s2, 0x1040000
	v_add_co_u32_e32 v8, vcc, s2, v6
	s_mov_b64 s[2:3], 0x1040000
	s_nop 0
	v_addc_co_u32_e32 v9, vcc, 0, v7, vcc
	global_store_dwordx4 v[8:9], v[2:5], off
	v_lshl_add_u64 v[6:7], v[6:7], 0, s[2:3]
	s_waitcnt lgkmcnt(0)
	v_cvt_pk_bf16_f32 v2, v17, v0
	v_cvt_pk_bf16_f32 v3, v16, v11
	v_cvt_pk_bf16_f32 v4, v15, v12
	v_cvt_pk_bf16_f32 v5, v14, v13
	ds_read_b32 v0, v10 offset:17476
	ds_read_b32 v8, v10 offset:20560
	ds_read_b32 v9, v10 offset:23644
	ds_read_b32 v11, v10 offset:21588
	ds_read_b32 v12, v10 offset:18504
	ds_read_b32 v13, v10 offset:16448
	ds_read_b32 v14, v10 offset:19532
	ds_read_b32 v15, v10 offset:22616
	global_store_dwordx4 v[6:7], v[2:5], off offset:16
	s_waitcnt lgkmcnt(0)
	s_nop 0
	v_cvt_pk_bf16_f32 v2, v13, v0
	v_cvt_pk_bf16_f32 v3, v12, v14
	v_cvt_pk_bf16_f32 v4, v8, v11
	v_cvt_pk_bf16_f32 v5, v15, v9
	ds_read_b32 v0, v10 offset:25700
	ds_read_b32 v8, v10 offset:26728
	ds_read_b32 v9, v10 offset:31868
	ds_read_b32 v11, v10 offset:29812
	ds_read_b32 v12, v10 offset:27756
	ds_read_b32 v13, v10 offset:24672
	ds_read_b32 v14, v10 offset:28784
	ds_read_b32 v10, v10 offset:30840
	global_store_dwordx4 v[6:7], v[2:5], off offset:32
	s_waitcnt lgkmcnt(0)
	s_nop 0
	v_cvt_pk_bf16_f32 v2, v13, v0
	v_cvt_pk_bf16_f32 v3, v8, v12
	v_cvt_pk_bf16_f32 v4, v14, v11
	v_cvt_pk_bf16_f32 v5, v10, v9
	global_store_dwordx4 v[6:7], v[2:5], off offset:48

; __device__ __forceinline__ unsigned cvt_pk_bf16(float lo, float hi) { unsigned r; asm volatile("v_cvt_pk_bf16_f32 %0, %1, %2" : "=v"(r) : "v"(lo), "v"(hi)); return r; }
; template <int PERMT>
; __device__ __forceinline__ void transpose_job(const float* __restrict__ src, bf16_t* __restrict__ dst, int K, int N, int Npad, const float* __restrict__ kscale, unsigned char* lds_g, int first, int stride) {
;     ...
;           for (int i = 0; i < 8; ++i) { const int k = k0 + kk + 8 * i; if (kscale) v[i] = v[i] * kscale[k];
;               float* tp = T + (kk + 8 * i) * 257 + 4 * n4; tp[0] = v[i][0]; tp[1] = v[i][1]; tp[2] = v[i][2]; tp[3] = v[i][3]; } }
;         __syncthreads();
;         { const int n = tid >> 1, ks = tid & 1;
;           if (n0 + n < N) { bf16_t* dp = dst + (size_t)dst_row<PERMT>(n0 + n) * K + k0 + 32 * ks;
; #pragma unroll
;             for (int eb = 0; eb < 4; ++eb) { float v[8];
; #pragma unroll
;               for (int e = 0; e < 8; ++e) v[e] = T[(32 * ks + 8 * eb + e) * 257 + n];
;               u32x4 w; w.x = cvt_pk_bf16(v[0], v[1]); w.y = cvt_pk_bf16(v[2], v[3]); w.z = cvt_pk_bf16(v[4], v[5]); w.w = cvt_pk_bf16(v[6], v[7]);
;               *(u32x4*)(dp + 8 * eb) = w; } } }
.LBB0_559:
	v_add_u32_e32 v0, 0xc0c0, v52
	ds_write2_b32 v0, v16, v17 offset1:1
	v_add_u32_e32 v0, 0xc0c8, v52
	ds_write2_b32 v0, v2, v3 offset1:1
	v_add_u32_e32 v0, 0xe0e0, v52
	v_add_u32_e32 v2, s8, v50
	s_movk_i32 s0, 0x800
	ds_write2_b32 v0, v8, v9 offset1:1
	v_add_u32_e32 v0, 0xe0e8, v52
	v_cmp_gt_i32_e32 vcc, s0, v2
	ds_write2_b32 v0, v10, v11 offset1:1
	s_waitcnt lgkmcnt(0)
	s_barrier
	s_and_saveexec_b64 s[0:1], vcc
	s_cbranch_execz .LBB0_530
	s_sub_i32 s8, 0, s14
	v_ashrrev_i32_e32 v3, 31, v2
	s_add_i32 s8, s13, s8
	v_lshlrev_b64 v[2:3], 12, v[2:3]
	v_lshl_add_u64 v[2:3], s[2:3], 0, v[2:3]
	s_ashr_i32 s9, s8, 31
	v_lshl_add_u64 v[2:3], s[8:9], 1, v[2:3]
	v_mov_b32_e32 v43, v1
	v_lshl_add_u64 v[6:7], v[2:3], 0, v[42:43]
	ds_read_b32 v0, v51 offset:1028
	ds_read_b32 v2, v51
	ds_read_b32 v3, v51 offset:3084
	ds_read_b32 v4, v51 offset:2056
	ds_read_b32 v5, v51 offset:5140
	ds_read_b32 v8, v51 offset:4112
	ds_read_b32 v9, v51 offset:7196
	ds_read_b32 v10, v51 offset:6168
	s_waitcnt lgkmcnt(6)
	v_cvt_pk_bf16_f32 v2, v2, v0
	s_waitcnt lgkmcnt(4)
	v_cvt_pk_bf16_f32 v3, v4, v3
	s_waitcnt lgkmcnt(2)
	v_cvt_pk_bf16_f32 v4, v8, v5
	s_waitcnt lgkmcnt(0)
	v_cvt_pk_bf16_f32 v5, v10, v9
	global_store_dwordx4 v[6:7], v[2:5], off
	ds_read_b32 v0, v51 offset:9252
	ds_read_b32 v2, v51 offset:8224
	ds_read_b32 v3, v51 offset:11308
	ds_read_b32 v4, v51 offset:10280
	ds_read_b32 v5, v51 offset:13364
	ds_read_b32 v8, v51 offset:12336
	ds_read_b32 v9, v51 offset:15420
	ds_read_b32 v10, v51 offset:14392
	s_waitcnt lgkmcnt(0)
	v_cvt_pk_bf16_f32 v2, v2, v0
	v_cvt_pk_bf16_f32 v3, v4, v3
	v_cvt_pk_bf16_f32 v4, v8, v5
	v_cvt_pk_bf16_f32 v5, v10, v9
	global_store_dwordx4 v[6:7], v[2:5], off offset:16
	ds_read_b32 v0, v51 offset:17476
	ds_read_b32 v2, v51 offset:16448
	ds_read_b32 v3, v51 offset:19532
	ds_read_b32 v4, v51 offset:18504
	ds_read_b32 v5, v51 offset:21588
	ds_read_b32 v8, v51 offset:20560
	ds_read_b32 v9, v51 offset:23644
	ds_read_b32 v10, v51 offset:22616
	s_waitcnt lgkmcnt(0)
	v_cvt_pk_bf16_f32 v2, v2, v0
	v_cvt_pk_bf16_f32 v3, v4, v3
	v_cvt_pk_bf16_f32 v4, v8, v5
	v_cvt_pk_bf16_f32 v5, v10, v9
	global_store_dwordx4 v[6:7], v[2:5], off offset:32
	ds_read_b32 v0, v51 offset:25700
	ds_read_b32 v2, v51 offset:24672
	ds_read_b32 v3, v51 offset:27756
	ds_read_b32 v4, v51 offset:26728
	ds_read_b32 v5, v51 offset:29812
	ds_read_b32 v8, v51 offset:28784
	ds_read_b32 v9, v51 offset:31868
	ds_read_b32 v10, v51 offset:30840
	s_waitcnt lgkmcnt(0)
	v_cvt_pk_bf16_f32 v2, v2, v0
	v_cvt_pk_bf16_f32 v3, v4, v3
	v_cvt_pk_bf16_f32 v4, v8, v5
	v_cvt_pk_bf16_f32 v5, v10, v9
	global_store_dwordx4 v[6:7], v[2:5], off offset:48
	s_branch .LBB0_530

; __device__ __forceinline__ u32x4 pack8(const f32x4 v0, const f32x4 v1) { u32x4 w; w.x = cvt_pk_bf16(v0[0], v0[1]); w.y = cvt_pk_bf16(v0[2], v0[3]); w.z = cvt_pk_bf16(v1[0], v1[1]); w.w = cvt_pk_bf16(v1[2], v1[3]); return w; }
;     __device__ __forceinline__ void operator()(const f32x4 (&acc)[2][2][4][2], const Unit& u, int wr, int wc, int fr, int fq) const {
;     ...
;             for (int m = 0; m < 4; ++m) { const f32x4 a = q0[ai][m], b = q1[ai][m];
;                 sc[ai][m] = 1.0f / sqrtf((((a[0] + a[1]) + (a[2] + a[3])) + ((b[0] + b[1]) + (b[2] + b[3]))) * (1.0f / 512.0f) + 1e-6f); } }
;     ...
;             for (int m = 0; m < 4; ++m) { const int row = row0 + ai * HALF + m * 16; const float s = sc[ai][m];
; #pragma unroll
;                 for (int bj = 0; bj < 2; ++bj) {
;                     const int cb = u.pn * BM + bj * HALF + wc * 32, hc = cb % 192;
;                     f32x4 v0 = acc[ai][bj][m][0] * s, v1 = acc[ai][bj][m][1] * s;
;                     if (hc >= 128) {
;                         const int ib = (hc - 128) / 2 + 4 * fq;
;                         const f32x4 c = *(const f32x4*)(rope + (size_t)row * 64 + ib), sn = *(const f32x4*)(rope + (size_t)row * 64 + 32 + ib);
;                         f32x4 a, b;
;                         a[0] = v0[0] * c[0] - v0[1] * sn[0]; a[1] = v0[1] * c[0] + v0[0] * sn[0];
;                         a[2] = v0[2] * c[1] - v0[3] * sn[1]; a[3] = v0[3] * c[1] + v0[2] * sn[1];
;                         b[0] = v1[0] * c[2] - v1[1] * sn[2]; b[1] = v1[1] * c[2] + v1[0] * sn[2];
;                         b[2] = v1[2] * c[3] - v1[3] * sn[3]; b[3] = v1[3] * c[3] + v1[2] * sn[3];
;                         v0 = a; v1 = b;
;                     }
;                     *(u32x4*)(O + (size_t)row * ldc + cb + 8 * fq) = pack8(v0, v1);
.LBB0_638:
	s_add_u32 s10, s17, 0x15428000
	s_addc_u32 s11, s18, 0
	v_cvt_pk_bf16_f32 v236, v164, v165
	v_cvt_pk_bf16_f32 v237, v214, v215
	v_cvt_pk_bf16_f32 v238, v162, v163
	v_mov_b64_e32 v[162:163], s[10:11]
	s_movk_i32 s1, 0xa00
	s_lshl_b32 s90, s0, 1
	s_bitset1_b32 s0, 7
	v_mad_i64_i32 v[162:163], s[4:5], v210, s1, v[162:163]
	s_mul_i32 s1, s0, 0xaaab
	s_lshr_b32 s1, s1, 23
	s_mulk_i32 s1, 0xc0
	s_sub_i32 s0, s0, s1
	s_and_b32 s15, s0, 0xffff
	v_mov_b32_e32 v213, v212
	v_cvt_pk_bf16_f32 v239, v168, v169
	v_lshl_add_u64 v[162:163], v[162:163], 0, s[90:91]
	v_mov_b32_e32 v203, v1
	v_mov_b32_e32 v168, v212
	v_mov_b32_e32 v169, v212
	s_cmpk_gt_u32 s15, 0x7f
	v_lshl_add_u64 v[162:163], v[162:163], 0, v[202:203]
	v_pk_mul_f32 v[164:165], v[152:153], v[168:169]
	v_pk_mul_f32 v[150:151], v[150:151], v[212:213]
	v_pk_mul_f32 v[152:153], v[148:149], v[168:169]
	s_cselect_b64 s[12:13], -1, 0
	s_cmpk_lt_u32 s15, 0x80
	v_pk_mul_f32 v[148:149], v[146:147], v[212:213]
	global_store_dwordx4 v[162:163], v[236:239], off
	s_cbranch_scc1 .LBB0_640
	s_add_i32 s0, s15, 0xffffff80
	s_lshr_b32 s0, s0, 1
	v_or_b32_e32 v0, s0, v231
	v_lshl_add_u64 v[146:147], v[0:1], 2, v[166:167]
	flat_load_dwordx4 v[166:169], v[146:147]
	flat_load_dwordx4 v[210:213], v[146:147] offset:128
	s_waitcnt vmcnt(0) lgkmcnt(0)
	v_pk_mul_f32 v[146:147], v[150:151], v[166:167]
	v_pk_mul_f32 v[202:203], v[150:151], v[210:211] op_sel:[1,0] op_sel_hi:[0,0]
	v_mov_b32_e32 v210, v167
	v_mul_f32_e32 v0, v165, v211
	v_pk_fma_f32 v[150:151], v[150:151], v[166:167], v[202:203] op_sel_hi:[1,0,1]
	v_pk_fma_f32 v[214:215], v[164:165], v[210:211], v[0:1] op_sel_hi:[1,1,0] neg_lo:[0,0,1] neg_hi:[0,0,1]
	v_mov_b32_e32 v166, v211
	v_mul_f32_e32 v0, v165, v167
	v_pk_fma_f32 v[166:167], v[164:165], v[166:167], v[0:1] op_sel_hi:[1,1,0]
	v_pk_mul_f32 v[210:211], v[148:149], v[212:213] op_sel:[1,0] op_sel_hi:[0,0]
	v_mov_b32_e32 v212, v169
	v_mul_f32_e32 v0, v153, v213
	v_pk_mul_f32 v[164:165], v[148:149], v[168:169]
	v_pk_fma_f32 v[148:149], v[148:149], v[168:169], v[210:211] op_sel_hi:[1,0,1]
	v_pk_fma_f32 v[236:237], v[152:153], v[212:213], v[0:1] op_sel_hi:[1,1,0] neg_lo:[0,0,1] neg_hi:[0,0,1]
	v_mov_b32_e32 v168, v213
	v_mul_f32_e32 v0, v153, v169
	v_pk_fma_f32 v[168:169], v[152:153], v[168:169], v[0:1] op_sel_hi:[1,1,0]
	v_sub_f32_e32 v150, v146, v202
	v_sub_f32_e32 v148, v164, v210
	v_mov_b32_e32 v164, v214
	v_mov_b32_e32 v165, v166
	v_mov_b32_e32 v152, v236
	v_mov_b32_e32 v153, v168
.LBB0_640:
	v_add_f32_e32 v0, v182, v183
	v_add_f32_e32 v146, v184, v185
	v_add_f32_e32 v0, v0, v146
	v_add_f32_e32 v146, v178, v179
	v_add_f32_e32 v147, v180, v181
	v_add_f32_e32 v146, v146, v147
	v_add_f32_e32 v0, v0, v146
	v_fmamk_f32 v0, v0, 0x3b000000, v218
	v_mul_f32_e32 v146, 0x4f800000, v0
	v_cmp_gt_f32_e32 vcc, s77, v0
	v_ashrrev_i32_e32 v209, 31, v208
	s_nop 0
	v_cndmask_b32_e32 v0, v0, v146, vcc
	v_sqrt_f32_e32 v146, v0
	s_nop 0
	v_add_u32_e32 v147, -1, v146
	v_fma_f32 v166, -v147, v146, v0
	v_cmp_ge_f32_e64 s[0:1], 0, v166
	v_add_u32_e32 v166, 1, v146
	s_nop 0
	v_cndmask_b32_e64 v147, v146, v147, s[0:1]
	v_fma_f32 v146, -v166, v146, v0
	v_cmp_lt_f32_e64 s[0:1], 0, v146
	s_nop 1
	v_cndmask_b32_e64 v146, v147, v166, s[0:1]
	v_mul_f32_e32 v147, 0x37800000, v146
	v_cndmask_b32_e32 v146, v146, v147, vcc
	v_cmp_class_f32_e32 vcc, v0, v219
	s_nop 1
	v_cndmask_b32_e32 v0, v146, v0, vcc
	v_div_scale_f32 v146, s[0:1], v0, v0, 1.0
	v_rcp_f32_e32 v147, v146
	s_nop 0
	v_fma_f32 v166, -v146, v147, 1.0
	v_fmac_f32_e32 v147, v166, v147
	v_div_scale_f32 v166, vcc, 1.0, v0, 1.0
	v_mul_f32_e32 v167, v166, v147
	v_fma_f32 v168, -v146, v167, v166
	v_fmac_f32_e32 v167, v168, v147
	v_fma_f32 v146, -v146, v167, v166
	v_div_fmas_f32 v146, v146, v147, v167
	v_div_fixup_f32 v146, v146, v0, 1.0
	v_cvt_pk_bf16_f32 v166, v150, v151
	v_lshlrev_b64 v[150:151], 8, v[208:209]
	v_cndmask_b32_e64 v0, 0, 1, s[2:3]
	v_cvt_pk_bf16_f32 v167, v164, v165
	v_cvt_pk_bf16_f32 v168, v148, v149
	v_pk_mul_f32 v[148:149], v[144:145], v[146:147] op_sel_hi:[1,0]
	v_pk_mul_f32 v[142:143], v[142:143], v[146:147] op_sel_hi:[1,0]
	v_pk_mul_f32 v[144:145], v[140:141], v[146:147] op_sel_hi:[1,0]
	v_pk_mul_f32 v[138:139], v[138:139], v[146:147] op_sel_hi:[1,0]
	v_cmp_ne_u32_e64 s[4:5], 1, v0
	s_andn2_b64 vcc, exec, s[2:3]
	v_lshl_add_u64 v[140:141], s[8:9], 0, v[150:151]
	v_cvt_pk_bf16_f32 v169, v152, v153
	global_store_dwordx4 v[162:163], v[166:169], off offset:256
	s_cbranch_vccnz .LBB0_642
	s_add_i32 s0, s14, 0xffffff80
	s_lshr_b32 s0, s0, 1
	v_or_b32_e32 v0, s0, v231
	v_lshl_add_u64 v[162:163], v[0:1], 2, v[140:141]
	flat_load_dwordx4 v[150:153], v[162:163]
	s_nop 0
	flat_load_dwordx4 v[162:165], v[162:163] offset:128
	s_waitcnt vmcnt(0) lgkmcnt(0)
	v_pk_mul_f32 v[166:167], v[142:143], v[150:151]
	v_pk_mul_f32 v[168:169], v[142:143], v[162:163] op_sel:[1,0] op_sel_hi:[0,0]
	v_mov_b32_e32 v162, v151
	v_mul_f32_e32 v0, v149, v163
	v_pk_fma_f32 v[142:143], v[142:143], v[150:151], v[168:169] op_sel_hi:[1,0,1]
	v_pk_fma_f32 v[178:179], v[148:149], v[162:163], v[0:1] op_sel_hi:[1,1,0] neg_lo:[0,0,1] neg_hi:[0,0,1]
	v_mov_b32_e32 v150, v163
	v_mul_f32_e32 v0, v149, v151
	v_pk_fma_f32 v[150:151], v[148:149], v[150:151], v[0:1] op_sel_hi:[1,1,0]
	v_pk_mul_f32 v[162:163], v[138:139], v[164:165] op_sel:[1,0] op_sel_hi:[0,0]
	v_mov_b32_e32 v164, v153
	v_mul_f32_e32 v0, v145, v165
	v_pk_mul_f32 v[148:149], v[138:139], v[152:153]
	v_pk_fma_f32 v[138:139], v[138:139], v[152:153], v[162:163] op_sel_hi:[1,0,1]
	v_pk_fma_f32 v[180:181], v[144:145], v[164:165], v[0:1] op_sel_hi:[1,1,0] neg_lo:[0,0,1] neg_hi:[0,0,1]
	v_mov_b32_e32 v152, v165
	v_mul_f32_e32 v0, v145, v153
	v_pk_fma_f32 v[152:153], v[144:145], v[152:153], v[0:1] op_sel_hi:[1,1,0]
	v_sub_f32_e32 v142, v166, v168
	v_sub_f32_e32 v138, v148, v162
	v_mov_b32_e32 v148, v178
	v_mov_b32_e32 v149, v150
	v_mov_b32_e32 v144, v180
	v_mov_b32_e32 v145, v152
; __device__ __forceinline__ u32x4 pack8(const f32x4 v0, const f32x4 v1) { u32x4 w; w.x = cvt_pk_bf16(v0[0], v0[1]); w.y = cvt_pk_bf16(v0[2], v0[3]); w.z = cvt_pk_bf16(v1[0], v1[1]); w.w = cvt_pk_bf16(v1[2], v1[3]); return w; }
;     __device__ __forceinline__ void operator()(const f32x4 (&acc)[2][2][4][2], const Unit& u, int wr, int wc, int fr, int fq) const {
;     ...
;             for (int m = 0; m < 4; ++m) { const f32x4 a = q0[ai][m], b = q1[ai][m];
;                 sc[ai][m] = 1.0f / sqrtf((((a[0] + a[1]) + (a[2] + a[3])) + ((b[0] + b[1]) + (b[2] + b[3]))) * (1.0f / 512.0f) + 1e-6f); } }
;     ...
;             for (int m = 0; m < 4; ++m) { const int row = row0 + ai * HALF + m * 16; const float s = sc[ai][m];
; #pragma unroll
;                 for (int bj = 0; bj < 2; ++bj) {
;                     const int cb = u.pn * BM + bj * HALF + wc * 32, hc = cb % 192;
;                     f32x4 v0 = acc[ai][bj][m][0] * s, v1 = acc[ai][bj][m][1] * s;
;                     if (hc >= 128) {
;                         const int ib = (hc - 128) / 2 + 4 * fq;
;                         const f32x4 c = *(const f32x4*)(rope + (size_t)row * 64 + ib), sn = *(const f32x4*)(rope + (size_t)row * 64 + 32 + ib);
;                         f32x4 a, b;
;                         a[0] = v0[0] * c[0] - v0[1] * sn[0]; a[1] = v0[1] * c[0] + v0[0] * sn[0];
;                         a[2] = v0[2] * c[1] - v0[3] * sn[1]; a[3] = v0[3] * c[1] + v0[2] * sn[1];
;                         b[0] = v1[0] * c[2] - v1[1] * sn[2]; b[1] = v1[1] * c[2] + v1[0] * sn[2];
;                         b[2] = v1[2] * c[3] - v1[3] * sn[3]; b[3] = v1[3] * c[3] + v1[2] * sn[3];
;                         v0 = a; v1 = b;
;                     }
;                     *(u32x4*)(O + (size_t)row * ldc + cb + 8 * fq) = pack8(v0, v1);
.LBB0_642:
	v_cvt_pk_bf16_f32 v150, v142, v143
	v_cvt_pk_bf16_f32 v151, v148, v149
	v_cvt_pk_bf16_f32 v152, v138, v139
	v_mov_b64_e32 v[138:139], s[10:11]
	s_movk_i32 s0, 0xa00
	v_lshlrev_b32_e32 v0, 3, v195
	v_cvt_pk_bf16_f32 v153, v144, v145
	v_mad_i64_i32 v[138:139], s[0:1], v208, s0, v[138:139]
	v_mov_b32_e32 v144, v146
	v_mov_b32_e32 v145, v146
	v_mov_b32_e32 v147, v146
	v_lshl_add_u64 v[138:139], v[138:139], 0, s[90:91]
	v_lshlrev_b32_e32 v0, 1, v0
	v_pk_mul_f32 v[142:143], v[128:129], v[144:145]
	v_pk_mul_f32 v[128:129], v[124:125], v[144:145]
	v_cndmask_b32_e64 v124, 0, 1, s[12:13]
	v_lshl_add_u64 v[138:139], v[138:139], 0, v[0:1]
	v_pk_mul_f32 v[126:127], v[126:127], v[146:147]
	v_cmp_ne_u32_e64 s[6:7], 1, v124
	s_andn2_b64 vcc, exec, s[12:13]
	v_pk_mul_f32 v[124:125], v[122:123], v[146:147]
	global_store_dwordx4 v[138:139], v[150:153], off
	s_cbranch_vccnz .LBB0_644
	s_add_i32 s0, s15, 0xffffff80
	s_lshr_b32 s0, s0, 1
	v_or_b32_e32 v122, s0, v231
	v_mov_b32_e32 v123, v1
	v_lshl_add_u64 v[122:123], v[122:123], 2, v[140:141]
	flat_load_dwordx4 v[144:147], v[122:123]
	flat_load_dwordx4 v[148:151], v[122:123] offset:128
	s_waitcnt vmcnt(0) lgkmcnt(0)
	v_pk_mul_f32 v[122:123], v[126:127], v[144:145]
	v_pk_mul_f32 v[140:141], v[126:127], v[148:149] op_sel:[1,0] op_sel_hi:[0,0]
	v_pk_fma_f32 v[126:127], v[126:127], v[144:145], v[140:141] op_sel_hi:[1,0,1]
	v_mov_b32_e32 v148, v145
	v_mul_f32_e32 v126, v143, v149
	v_pk_fma_f32 v[152:153], v[142:143], v[148:149], v[126:127] op_sel_hi:[1,1,0] neg_lo:[0,0,1] neg_hi:[0,0,1]
	v_mov_b32_e32 v144, v149
	v_mul_f32_e32 v126, v143, v145
	v_pk_mul_f32 v[148:149], v[124:125], v[150:151] op_sel:[1,0] op_sel_hi:[0,0]
	v_pk_fma_f32 v[144:145], v[142:143], v[144:145], v[126:127] op_sel_hi:[1,1,0]
	v_pk_mul_f32 v[142:143], v[124:125], v[146:147]
	v_pk_fma_f32 v[124:125], v[124:125], v[146:147], v[148:149] op_sel_hi:[1,0,1]
	v_mov_b32_e32 v150, v147
	v_mul_f32_e32 v124, v129, v151
	v_pk_fma_f32 v[162:163], v[128:129], v[150:151], v[124:125] op_sel_hi:[1,1,0] neg_lo:[0,0,1] neg_hi:[0,0,1]
	v_mov_b32_e32 v146, v151
	v_mul_f32_e32 v124, v129, v147
	v_pk_fma_f32 v[146:147], v[128:129], v[146:147], v[124:125] op_sel_hi:[1,1,0]
	v_sub_f32_e32 v126, v122, v140
	v_sub_f32_e32 v124, v142, v148
	v_mov_b32_e32 v142, v152
	v_mov_b32_e32 v143, v144
	v_mov_b32_e32 v128, v162
	v_mov_b32_e32 v129, v146
.LBB0_644:
	v_add_f32_e32 v122, v174, v175
	v_add_f32_e32 v123, v176, v177
	v_add_f32_e32 v122, v122, v123
	v_add_f32_e32 v123, v170, v171
	v_add_f32_e32 v140, v172, v173
	v_add_f32_e32 v123, v123, v140
	v_add_f32_e32 v122, v122, v123
	v_fmamk_f32 v122, v122, 0x3b000000, v218
	v_mul_f32_e32 v123, 0x4f800000, v122
	v_cmp_gt_f32_e32 vcc, s77, v122
	v_ashrrev_i32_e32 v207, 31, v206
	s_nop 0
	v_cndmask_b32_e32 v122, v122, v123, vcc
	v_sqrt_f32_e32 v123, v122
	s_nop 0
	v_add_u32_e32 v140, -1, v123
	v_fma_f32 v141, -v140, v123, v122
	v_cmp_ge_f32_e64 s[0:1], 0, v141
	v_add_u32_e32 v141, 1, v123
	s_nop 0
	v_cndmask_b32_e64 v140, v123, v140, s[0:1]
	v_fma_f32 v123, -v141, v123, v122
	v_cmp_lt_f32_e64 s[0:1], 0, v123
	s_nop 1
	v_cndmask_b32_e64 v123, v140, v141, s[0:1]
	v_mul_f32_e32 v140, 0x37800000, v123
	v_cndmask_b32_e32 v123, v123, v140, vcc
	v_cmp_class_f32_e32 vcc, v122, v219
	s_nop 1
	v_cndmask_b32_e32 v122, v123, v122, vcc
	v_div_scale_f32 v123, s[0:1], v122, v122, 1.0
	v_rcp_f32_e32 v140, v123
	s_nop 0
	v_fma_f32 v141, -v123, v140, 1.0
	v_fmac_f32_e32 v140, v141, v140
	v_div_scale_f32 v141, vcc, 1.0, v122, 1.0
	v_mul_f32_e32 v144, v141, v140
	v_fma_f32 v145, -v123, v144, v141
	v_fmac_f32_e32 v144, v145, v140
	v_fma_f32 v123, -v123, v144, v141
	v_div_fmas_f32 v123, v123, v140, v144
	v_div_fixup_f32 v122, v123, v122, 1.0
	v_cvt_pk_bf16_f32 v140, v126, v127
	v_lshlrev_b64 v[126:127], 8, v[206:207]
	v_cvt_pk_bf16_f32 v141, v142, v143
	v_cvt_pk_bf16_f32 v142, v124, v125
	v_pk_mul_f32 v[124:125], v[120:121], v[122:123] op_sel_hi:[1,0]
	v_pk_mul_f32 v[118:119], v[118:119], v[122:123] op_sel_hi:[1,0]
	v_pk_mul_f32 v[120:121], v[116:117], v[122:123] op_sel_hi:[1,0]
	v_pk_mul_f32 v[114:115], v[114:115], v[122:123] op_sel_hi:[1,0]
	s_and_b64 vcc, exec, s[4:5]
	v_lshl_add_u64 v[116:117], s[8:9], 0, v[126:127]
	v_cvt_pk_bf16_f32 v143, v128, v129
	global_store_dwordx4 v[138:139], v[140:143], off offset:256
	s_cbranch_vccnz .LBB0_646
	s_add_i32 s0, s14, 0xffffff80
	s_lshr_b32 s0, s0, 1
	v_or_b32_e32 v126, s0, v231
	v_mov_b32_e32 v127, v1
	v_lshl_add_u64 v[138:139], v[126:127], 2, v[116:117]
	flat_load_dwordx4 v[126:129], v[138:139]
	s_nop 0
	flat_load_dwordx4 v[138:141], v[138:139] offset:128
	s_waitcnt vmcnt(0) lgkmcnt(0)
	v_pk_mul_f32 v[142:143], v[118:119], v[126:127]
	v_pk_mul_f32 v[144:145], v[118:119], v[138:139] op_sel:[1,0] op_sel_hi:[0,0]
	v_pk_fma_f32 v[118:119], v[118:119], v[126:127], v[144:145] op_sel_hi:[1,0,1]
	v_mov_b32_e32 v138, v127
	v_mul_f32_e32 v118, v125, v139
	v_pk_fma_f32 v[146:147], v[124:125], v[138:139], v[118:119] op_sel_hi:[1,1,0] neg_lo:[0,0,1] neg_hi:[0,0,1]
	v_mov_b32_e32 v126, v139
	v_mul_f32_e32 v118, v125, v127
	v_pk_mul_f32 v[138:139], v[114:115], v[140:141] op_sel:[1,0] op_sel_hi:[0,0]
	v_pk_fma_f32 v[126:127], v[124:125], v[126:127], v[118:119] op_sel_hi:[1,1,0]
	v_pk_mul_f32 v[124:125], v[114:115], v[128:129]
	v_pk_fma_f32 v[114:115], v[114:115], v[128:129], v[138:139] op_sel_hi:[1,0,1]
	v_mov_b32_e32 v140, v129
	v_mul_f32_e32 v114, v121, v141
	v_pk_fma_f32 v[148:149], v[120:121], v[140:141], v[114:115] op_sel_hi:[1,1,0] neg_lo:[0,0,1] neg_hi:[0,0,1]
	v_mov_b32_e32 v128, v141
	v_mul_f32_e32 v114, v121, v129
	v_pk_fma_f32 v[128:129], v[120:121], v[128:129], v[114:115] op_sel_hi:[1,1,0]
	v_sub_f32_e32 v118, v142, v144
	v_sub_f32_e32 v114, v124, v138
	v_mov_b32_e32 v124, v146
	v_mov_b32_e32 v125, v126
	v_mov_b32_e32 v120, v148
	v_mov_b32_e32 v121, v128
; __device__ __forceinline__ u32x4 pack8(const f32x4 v0, const f32x4 v1) { u32x4 w; w.x = cvt_pk_bf16(v0[0], v0[1]); w.y = cvt_pk_bf16(v0[2], v0[3]); w.z = cvt_pk_bf16(v1[0], v1[1]); w.w = cvt_pk_bf16(v1[2], v1[3]); return w; }
;     __device__ __forceinline__ void operator()(const f32x4 (&acc)[2][2][4][2], const Unit& u, int wr, int wc, int fr, int fq) const {
;     ...
;             for (int m = 0; m < 4; ++m) { const f32x4 a = q0[ai][m], b = q1[ai][m];
;                 sc[ai][m] = 1.0f / sqrtf((((a[0] + a[1]) + (a[2] + a[3])) + ((b[0] + b[1]) + (b[2] + b[3]))) * (1.0f / 512.0f) + 1e-6f); } }
; #pragma unroll
;         for (int ai = 0; ai < 2; ++ai)
; #pragma unroll
;             for (int m = 0; m < 4; ++m) { const int row = row0 + ai * HALF + m * 16; const float s = sc[ai][m];
; #pragma unroll
;                 for (int bj = 0; bj < 2; ++bj) {
;                     const int cb = u.pn * BM + bj * HALF + wc * 32, hc = cb % 192;
;                     f32x4 v0 = acc[ai][bj][m][0] * s, v1 = acc[ai][bj][m][1] * s;
;                     if (hc >= 128) {
;                         const int ib = (hc - 128) / 2 + 4 * fq;
;                         const f32x4 c = *(const f32x4*)(rope + (size_t)row * 64 + ib), sn = *(const f32x4*)(rope + (size_t)row * 64 + 32 + ib);
;                         f32x4 a, b;
;                         a[0] = v0[0] * c[0] - v0[1] * sn[0]; a[1] = v0[1] * c[0] + v0[0] * sn[0];
;                         a[2] = v0[2] * c[1] - v0[3] * sn[1]; a[3] = v0[3] * c[1] + v0[2] * sn[1];
;                         b[0] = v1[0] * c[2] - v1[1] * sn[2]; b[1] = v1[1] * c[2] + v1[0] * sn[2];
;                         b[2] = v1[2] * c[3] - v1[3] * sn[3]; b[3] = v1[3] * c[3] + v1[2] * sn[3];
;                         v0 = a; v1 = b;
;                     }
;                     *(u32x4*)(O + (size_t)row * ldc + cb + 8 * fq) = pack8(v0, v1);
.LBB0_646:
	v_cvt_pk_bf16_f32 v126, v118, v119
	v_cvt_pk_bf16_f32 v127, v124, v125
	v_cvt_pk_bf16_f32 v128, v114, v115
	v_mov_b64_e32 v[114:115], s[10:11]
	s_movk_i32 s0, 0xa00
	v_mad_i64_i32 v[114:115], s[0:1], v206, s0, v[114:115]
	v_mov_b32_e32 v123, v122
	v_cvt_pk_bf16_f32 v129, v120, v121
	v_lshl_add_u64 v[114:115], v[114:115], 0, s[90:91]
	v_mov_b32_e32 v120, v122
	v_mov_b32_e32 v121, v122
	v_lshl_add_u64 v[114:115], v[114:115], 0, v[0:1]
	v_pk_mul_f32 v[118:119], v[104:105], v[120:121]
	v_pk_mul_f32 v[102:103], v[102:103], v[122:123]
	v_pk_mul_f32 v[104:105], v[100:101], v[120:121]
	s_and_b64 vcc, exec, s[6:7]
	v_pk_mul_f32 v[100:101], v[98:99], v[122:123]
	global_store_dwordx4 v[114:115], v[126:129], off
	s_cbranch_vccnz .LBB0_648
	s_add_i32 s0, s15, 0xffffff80
	s_lshr_b32 s0, s0, 1
	v_or_b32_e32 v98, s0, v231
	v_mov_b32_e32 v99, v1
	v_lshl_add_u64 v[98:99], v[98:99], 2, v[116:117]
	flat_load_dwordx4 v[120:123], v[98:99]
	flat_load_dwordx4 v[124:127], v[98:99] offset:128
	s_waitcnt vmcnt(0) lgkmcnt(0)
	v_pk_mul_f32 v[98:99], v[102:103], v[120:121]
	v_pk_mul_f32 v[116:117], v[102:103], v[124:125] op_sel:[1,0] op_sel_hi:[0,0]
	v_pk_fma_f32 v[102:103], v[102:103], v[120:121], v[116:117] op_sel_hi:[1,0,1]
	v_mov_b32_e32 v124, v121
	v_mul_f32_e32 v102, v119, v125
	v_pk_fma_f32 v[128:129], v[118:119], v[124:125], v[102:103] op_sel_hi:[1,1,0] neg_lo:[0,0,1] neg_hi:[0,0,1]
	v_mov_b32_e32 v120, v125
	v_mul_f32_e32 v102, v119, v121
	v_pk_mul_f32 v[124:125], v[100:101], v[126:127] op_sel:[1,0] op_sel_hi:[0,0]
	v_pk_fma_f32 v[120:121], v[118:119], v[120:121], v[102:103] op_sel_hi:[1,1,0]
	v_pk_mul_f32 v[118:119], v[100:101], v[122:123]
	v_pk_fma_f32 v[100:101], v[100:101], v[122:123], v[124:125] op_sel_hi:[1,0,1]
	v_mov_b32_e32 v126, v123
	v_mul_f32_e32 v100, v105, v127
	v_pk_fma_f32 v[138:139], v[104:105], v[126:127], v[100:101] op_sel_hi:[1,1,0] neg_lo:[0,0,1] neg_hi:[0,0,1]
	v_mov_b32_e32 v122, v127
	v_mul_f32_e32 v100, v105, v123
	v_pk_fma_f32 v[122:123], v[104:105], v[122:123], v[100:101] op_sel_hi:[1,1,0]
	v_sub_f32_e32 v102, v98, v116
	v_sub_f32_e32 v100, v118, v124
	v_mov_b32_e32 v118, v128
	v_mov_b32_e32 v119, v120
	v_mov_b32_e32 v104, v138
	v_mov_b32_e32 v105, v122
.LBB0_648:
	v_add_f32_e32 v98, v158, v159
	v_add_f32_e32 v99, v160, v161
	v_add_f32_e32 v98, v98, v99
	v_add_f32_e32 v99, v154, v155
	v_add_f32_e32 v116, v156, v157
	v_add_f32_e32 v99, v99, v116
	v_add_f32_e32 v98, v98, v99
	v_fmamk_f32 v98, v98, 0x3b000000, v218
	v_mul_f32_e32 v99, 0x4f800000, v98
	v_cmp_gt_f32_e32 vcc, s77, v98
	v_ashrrev_i32_e32 v205, 31, v204
	s_nop 0
	v_cndmask_b32_e32 v98, v98, v99, vcc
	v_sqrt_f32_e32 v99, v98
	s_nop 0
	v_add_u32_e32 v116, -1, v99
	v_fma_f32 v117, -v116, v99, v98
	v_cmp_ge_f32_e64 s[0:1], 0, v117
	v_add_u32_e32 v117, 1, v99
	s_nop 0
	v_cndmask_b32_e64 v116, v99, v116, s[0:1]
	v_fma_f32 v99, -v117, v99, v98
	v_cmp_lt_f32_e64 s[0:1], 0, v99
	s_nop 1
	v_cndmask_b32_e64 v99, v116, v117, s[0:1]
	v_mul_f32_e32 v116, 0x37800000, v99
	v_cndmask_b32_e32 v99, v99, v116, vcc
	v_cmp_class_f32_e32 vcc, v98, v219
	s_nop 1
	v_cndmask_b32_e32 v98, v99, v98, vcc
	v_div_scale_f32 v99, s[0:1], v98, v98, 1.0
	v_rcp_f32_e32 v116, v99
	s_nop 0
	v_fma_f32 v117, -v99, v116, 1.0
	v_fmac_f32_e32 v116, v117, v116
	v_div_scale_f32 v117, vcc, 1.0, v98, 1.0
	v_mul_f32_e32 v120, v117, v116
	v_fma_f32 v121, -v99, v120, v117
	v_fmac_f32_e32 v120, v121, v116
	v_fma_f32 v99, -v99, v120, v117
	v_div_fmas_f32 v99, v99, v116, v120
	v_div_fixup_f32 v98, v99, v98, 1.0
	v_cvt_pk_bf16_f32 v116, v102, v103
	v_lshlrev_b64 v[102:103], 8, v[204:205]
	v_cvt_pk_bf16_f32 v117, v118, v119
	v_cvt_pk_bf16_f32 v118, v100, v101
	v_pk_mul_f32 v[100:101], v[96:97], v[98:99] op_sel_hi:[1,0]
	v_pk_mul_f32 v[94:95], v[94:95], v[98:99] op_sel_hi:[1,0]
	v_pk_mul_f32 v[96:97], v[92:93], v[98:99] op_sel_hi:[1,0]
	v_pk_mul_f32 v[90:91], v[90:91], v[98:99] op_sel_hi:[1,0]
	s_and_b64 vcc, exec, s[4:5]
	v_lshl_add_u64 v[92:93], s[8:9], 0, v[102:103]
	v_cvt_pk_bf16_f32 v119, v104, v105
	global_store_dwordx4 v[114:115], v[116:119], off offset:256
	s_cbranch_vccnz .LBB0_650
	s_add_i32 s0, s14, 0xffffff80
	s_lshr_b32 s0, s0, 1
	v_or_b32_e32 v102, s0, v231
	v_mov_b32_e32 v103, v1
	v_lshl_add_u64 v[114:115], v[102:103], 2, v[92:93]
	flat_load_dwordx4 v[102:105], v[114:115]
	s_nop 0
	flat_load_dwordx4 v[114:117], v[114:115] offset:128
	s_waitcnt vmcnt(0) lgkmcnt(0)
	v_pk_mul_f32 v[118:119], v[94:95], v[102:103]
	v_pk_mul_f32 v[120:121], v[94:95], v[114:115] op_sel:[1,0] op_sel_hi:[0,0]
	v_pk_fma_f32 v[94:95], v[94:95], v[102:103], v[120:121] op_sel_hi:[1,0,1]
	v_mov_b32_e32 v114, v103
	v_mul_f32_e32 v94, v101, v115
	v_pk_fma_f32 v[122:123], v[100:101], v[114:115], v[94:95] op_sel_hi:[1,1,0] neg_lo:[0,0,1] neg_hi:[0,0,1]
	v_mov_b32_e32 v102, v115
	v_mul_f32_e32 v94, v101, v103
	v_pk_mul_f32 v[114:115], v[90:91], v[116:117] op_sel:[1,0] op_sel_hi:[0,0]
	v_pk_fma_f32 v[102:103], v[100:101], v[102:103], v[94:95] op_sel_hi:[1,1,0]
	v_pk_mul_f32 v[100:101], v[90:91], v[104:105]
	v_pk_fma_f32 v[90:91], v[90:91], v[104:105], v[114:115] op_sel_hi:[1,0,1]
	v_mov_b32_e32 v116, v105
	v_mul_f32_e32 v90, v97, v117
	v_pk_fma_f32 v[124:125], v[96:97], v[116:117], v[90:91] op_sel_hi:[1,1,0] neg_lo:[0,0,1] neg_hi:[0,0,1]
	v_mov_b32_e32 v104, v117
	v_mul_f32_e32 v90, v97, v105
	v_pk_fma_f32 v[104:105], v[96:97], v[104:105], v[90:91] op_sel_hi:[1,1,0]
	v_sub_f32_e32 v94, v118, v120
	v_sub_f32_e32 v90, v100, v114
	v_mov_b32_e32 v100, v122
	v_mov_b32_e32 v101, v102
	v_mov_b32_e32 v96, v124
	v_mov_b32_e32 v97, v104
; __device__ __forceinline__ u32x4 pack8(const f32x4 v0, const f32x4 v1) { u32x4 w; w.x = cvt_pk_bf16(v0[0], v0[1]); w.y = cvt_pk_bf16(v0[2], v0[3]); w.z = cvt_pk_bf16(v1[0], v1[1]); w.w = cvt_pk_bf16(v1[2], v1[3]); return w; }
;     __device__ __forceinline__ void operator()(const f32x4 (&acc)[2][2][4][2], const Unit& u, int wr, int wc, int fr, int fq) const {
;     ...
;             for (int m = 0; m < 4; ++m) { const f32x4 a = q0[ai][m], b = q1[ai][m];
;                 sc[ai][m] = 1.0f / sqrtf((((a[0] + a[1]) + (a[2] + a[3])) + ((b[0] + b[1]) + (b[2] + b[3]))) * (1.0f / 512.0f) + 1e-6f); } }
; #pragma unroll
;         for (int ai = 0; ai < 2; ++ai)
; #pragma unroll
;             for (int m = 0; m < 4; ++m) { const int row = row0 + ai * HALF + m * 16; const float s = sc[ai][m];
; #pragma unroll
;                 for (int bj = 0; bj < 2; ++bj) {
;                     const int cb = u.pn * BM + bj * HALF + wc * 32, hc = cb % 192;
;                     f32x4 v0 = acc[ai][bj][m][0] * s, v1 = acc[ai][bj][m][1] * s;
;                     if (hc >= 128) {
;                         const int ib = (hc - 128) / 2 + 4 * fq;
;                         const f32x4 c = *(const f32x4*)(rope + (size_t)row * 64 + ib), sn = *(const f32x4*)(rope + (size_t)row * 64 + 32 + ib);
;                         f32x4 a, b;
;                         a[0] = v0[0] * c[0] - v0[1] * sn[0]; a[1] = v0[1] * c[0] + v0[0] * sn[0];
;                         a[2] = v0[2] * c[1] - v0[3] * sn[1]; a[3] = v0[3] * c[1] + v0[2] * sn[1];
;                         b[0] = v1[0] * c[2] - v1[1] * sn[2]; b[1] = v1[1] * c[2] + v1[0] * sn[2];
;                         b[2] = v1[2] * c[3] - v1[3] * sn[3]; b[3] = v1[3] * c[3] + v1[2] * sn[3];
;                         v0 = a; v1 = b;
;                     }
;                     *(u32x4*)(O + (size_t)row * ldc + cb + 8 * fq) = pack8(v0, v1);
.LBB0_650:
	v_cvt_pk_bf16_f32 v102, v94, v95
	v_cvt_pk_bf16_f32 v103, v100, v101
	v_cvt_pk_bf16_f32 v104, v90, v91
	v_mov_b64_e32 v[90:91], s[10:11]
	s_movk_i32 s0, 0xa00
	v_mad_i64_i32 v[90:91], s[0:1], v204, s0, v[90:91]
	v_mov_b32_e32 v99, v98
	v_cvt_pk_bf16_f32 v105, v96, v97
	v_lshl_add_u64 v[90:91], v[90:91], 0, s[90:91]
	v_mov_b32_e32 v96, v98
	v_mov_b32_e32 v97, v98
	v_lshl_add_u64 v[90:91], v[90:91], 0, v[0:1]
	v_pk_mul_f32 v[94:95], v[80:81], v[96:97]
	v_pk_mul_f32 v[78:79], v[78:79], v[98:99]
	v_pk_mul_f32 v[80:81], v[76:77], v[96:97]
	s_and_b64 vcc, exec, s[6:7]
	v_pk_mul_f32 v[76:77], v[74:75], v[98:99]
	global_store_dwordx4 v[90:91], v[102:105], off
	s_cbranch_vccnz .LBB0_652
	s_add_i32 s0, s15, 0xffffff80
	s_lshr_b32 s0, s0, 1
	v_or_b32_e32 v74, s0, v231
	v_mov_b32_e32 v75, v1
	v_lshl_add_u64 v[74:75], v[74:75], 2, v[92:93]
	flat_load_dwordx4 v[96:99], v[74:75]
	flat_load_dwordx4 v[100:103], v[74:75] offset:128
	s_waitcnt vmcnt(0) lgkmcnt(0)
	v_pk_mul_f32 v[74:75], v[78:79], v[96:97]
	v_pk_mul_f32 v[92:93], v[78:79], v[100:101] op_sel:[1,0] op_sel_hi:[0,0]
	v_pk_fma_f32 v[78:79], v[78:79], v[96:97], v[92:93] op_sel_hi:[1,0,1]
	v_mov_b32_e32 v100, v97
	v_mul_f32_e32 v78, v95, v101
	v_pk_fma_f32 v[104:105], v[94:95], v[100:101], v[78:79] op_sel_hi:[1,1,0] neg_lo:[0,0,1] neg_hi:[0,0,1]
	v_mov_b32_e32 v96, v101
	v_mul_f32_e32 v78, v95, v97
	v_pk_mul_f32 v[100:101], v[76:77], v[102:103] op_sel:[1,0] op_sel_hi:[0,0]
	v_pk_fma_f32 v[96:97], v[94:95], v[96:97], v[78:79] op_sel_hi:[1,1,0]
	v_pk_mul_f32 v[94:95], v[76:77], v[98:99]
	v_pk_fma_f32 v[76:77], v[76:77], v[98:99], v[100:101] op_sel_hi:[1,0,1]
	v_mov_b32_e32 v102, v99
	v_mul_f32_e32 v76, v81, v103
	v_pk_fma_f32 v[114:115], v[80:81], v[102:103], v[76:77] op_sel_hi:[1,1,0] neg_lo:[0,0,1] neg_hi:[0,0,1]
	v_mov_b32_e32 v98, v103
	v_mul_f32_e32 v76, v81, v99
	v_pk_fma_f32 v[98:99], v[80:81], v[98:99], v[76:77] op_sel_hi:[1,1,0]
	v_sub_f32_e32 v78, v74, v92
	v_sub_f32_e32 v76, v94, v100
	v_mov_b32_e32 v94, v104
	v_mov_b32_e32 v95, v96
	v_mov_b32_e32 v80, v114
	v_mov_b32_e32 v81, v98
.LBB0_652:
	v_add_f32_e32 v74, v134, v135
	v_add_f32_e32 v75, v136, v137
	v_add_f32_e32 v74, v74, v75
	v_add_f32_e32 v75, v130, v131
	v_add_f32_e32 v92, v132, v133
	v_add_f32_e32 v75, v75, v92
	v_add_f32_e32 v74, v74, v75
	v_fmamk_f32 v74, v74, 0x3b000000, v218
	v_mul_f32_e32 v75, 0x4f800000, v74
	v_cmp_gt_f32_e32 vcc, s77, v74
	v_ashrrev_i32_e32 v201, 31, v200
	s_nop 0
	v_cndmask_b32_e32 v74, v74, v75, vcc
	v_sqrt_f32_e32 v75, v74
	s_nop 0
	v_add_u32_e32 v92, -1, v75
	v_fma_f32 v93, -v92, v75, v74
	v_cmp_ge_f32_e64 s[0:1], 0, v93
	v_add_u32_e32 v93, 1, v75
	s_nop 0
	v_cndmask_b32_e64 v92, v75, v92, s[0:1]
	v_fma_f32 v75, -v93, v75, v74
	v_cmp_lt_f32_e64 s[0:1], 0, v75
	s_nop 1
	v_cndmask_b32_e64 v75, v92, v93, s[0:1]
	v_mul_f32_e32 v92, 0x37800000, v75
	v_cndmask_b32_e32 v75, v75, v92, vcc
	v_cmp_class_f32_e32 vcc, v74, v219
	s_nop 1
	v_cndmask_b32_e32 v74, v75, v74, vcc
	v_div_scale_f32 v75, s[0:1], v74, v74, 1.0
	v_rcp_f32_e32 v92, v75
	s_nop 0
	v_fma_f32 v93, -v75, v92, 1.0
	v_fmac_f32_e32 v92, v93, v92
	v_div_scale_f32 v93, vcc, 1.0, v74, 1.0
	v_mul_f32_e32 v96, v93, v92
	v_fma_f32 v97, -v75, v96, v93
	v_fmac_f32_e32 v96, v97, v92
	v_fma_f32 v75, -v75, v96, v93
	v_div_fmas_f32 v75, v75, v92, v96
	v_cvt_pk_bf16_f32 v92, v78, v79
	v_cvt_pk_bf16_f32 v93, v94, v95
	v_cvt_pk_bf16_f32 v94, v76, v77
	v_cvt_pk_bf16_f32 v95, v80, v81
	global_store_dwordx4 v[90:91], v[92:95], off offset:256
	v_div_fixup_f32 v74, v75, v74, 1.0
	v_lshlrev_b64 v[78:79], 8, v[200:201]
	v_pk_mul_f32 v[76:77], v[64:65], v[74:75] op_sel_hi:[1,0]
	v_pk_mul_f32 v[62:63], v[62:63], v[74:75] op_sel_hi:[1,0]
	v_pk_mul_f32 v[64:65], v[60:61], v[74:75] op_sel_hi:[1,0]
	v_pk_mul_f32 v[58:59], v[58:59], v[74:75] op_sel_hi:[1,0]
	s_and_b64 vcc, exec, s[4:5]
	v_lshl_add_u64 v[60:61], s[8:9], 0, v[78:79]
	s_cbranch_vccnz .LBB0_654
	s_add_i32 s0, s14, 0xffffff80
	s_lshr_b32 s0, s0, 1
	v_or_b32_e32 v78, s0, v231
	v_mov_b32_e32 v79, v1
	v_lshl_add_u64 v[90:91], v[78:79], 2, v[60:61]
	flat_load_dwordx4 v[78:81], v[90:91]
	s_nop 0
	flat_load_dwordx4 v[90:93], v[90:91] offset:128
	s_waitcnt vmcnt(0) lgkmcnt(0)
	v_pk_mul_f32 v[94:95], v[62:63], v[78:79]
	v_pk_mul_f32 v[96:97], v[62:63], v[90:91] op_sel:[1,0] op_sel_hi:[0,0]
	v_pk_fma_f32 v[62:63], v[62:63], v[78:79], v[96:97] op_sel_hi:[1,0,1]
	v_mov_b32_e32 v90, v79
	v_mul_f32_e32 v62, v77, v91
	v_pk_fma_f32 v[98:99], v[76:77], v[90:91], v[62:63] op_sel_hi:[1,1,0] neg_lo:[0,0,1] neg_hi:[0,0,1]
	v_mov_b32_e32 v78, v91
	v_mul_f32_e32 v62, v77, v79
	v_pk_mul_f32 v[90:91], v[58:59], v[92:93] op_sel:[1,0] op_sel_hi:[0,0]
	v_pk_fma_f32 v[78:79], v[76:77], v[78:79], v[62:63] op_sel_hi:[1,1,0]
	v_pk_mul_f32 v[76:77], v[58:59], v[80:81]
	v_pk_fma_f32 v[58:59], v[58:59], v[80:81], v[90:91] op_sel_hi:[1,0,1]
	v_mov_b32_e32 v92, v81
	v_mul_f32_e32 v58, v65, v93
	v_pk_fma_f32 v[100:101], v[64:65], v[92:93], v[58:59] op_sel_hi:[1,1,0] neg_lo:[0,0,1] neg_hi:[0,0,1]
	v_mov_b32_e32 v80, v93
	v_mul_f32_e32 v58, v65, v81
	v_pk_fma_f32 v[80:81], v[64:65], v[80:81], v[58:59] op_sel_hi:[1,1,0]
	v_sub_f32_e32 v62, v94, v96
	v_sub_f32_e32 v58, v76, v90
	v_mov_b32_e32 v76, v98
	v_mov_b32_e32 v77, v78
	v_mov_b32_e32 v64, v100
	v_mov_b32_e32 v65, v80
; __device__ __forceinline__ u32x4 pack8(const f32x4 v0, const f32x4 v1) { u32x4 w; w.x = cvt_pk_bf16(v0[0], v0[1]); w.y = cvt_pk_bf16(v0[2], v0[3]); w.z = cvt_pk_bf16(v1[0], v1[1]); w.w = cvt_pk_bf16(v1[2], v1[3]); return w; }
;     __device__ __forceinline__ void operator()(const f32x4 (&acc)[2][2][4][2], const Unit& u, int wr, int wc, int fr, int fq) const {
;     ...
;             for (int m = 0; m < 4; ++m) { const f32x4 a = q0[ai][m], b = q1[ai][m];
;                 sc[ai][m] = 1.0f / sqrtf((((a[0] + a[1]) + (a[2] + a[3])) + ((b[0] + b[1]) + (b[2] + b[3]))) * (1.0f / 512.0f) + 1e-6f); } }
; #pragma unroll
;         for (int ai = 0; ai < 2; ++ai)
; #pragma unroll
;             for (int m = 0; m < 4; ++m) { const int row = row0 + ai * HALF + m * 16; const float s = sc[ai][m];
; #pragma unroll
;                 for (int bj = 0; bj < 2; ++bj) {
;                     const int cb = u.pn * BM + bj * HALF + wc * 32, hc = cb % 192;
;                     f32x4 v0 = acc[ai][bj][m][0] * s, v1 = acc[ai][bj][m][1] * s;
;                     if (hc >= 128) {
;                         const int ib = (hc - 128) / 2 + 4 * fq;
;                         const f32x4 c = *(const f32x4*)(rope + (size_t)row * 64 + ib), sn = *(const f32x4*)(rope + (size_t)row * 64 + 32 + ib);
;                         f32x4 a, b;
;                         a[0] = v0[0] * c[0] - v0[1] * sn[0]; a[1] = v0[1] * c[0] + v0[0] * sn[0];
;                         a[2] = v0[2] * c[1] - v0[3] * sn[1]; a[3] = v0[3] * c[1] + v0[2] * sn[1];
;                         b[0] = v1[0] * c[2] - v1[1] * sn[2]; b[1] = v1[1] * c[2] + v1[0] * sn[2];
;                         b[2] = v1[2] * c[3] - v1[3] * sn[3]; b[3] = v1[3] * c[3] + v1[2] * sn[3];
;                         v0 = a; v1 = b;
;                     }
;                     *(u32x4*)(O + (size_t)row * ldc + cb + 8 * fq) = pack8(v0, v1);
.LBB0_654:
	v_cvt_pk_bf16_f32 v78, v62, v63
	v_cvt_pk_bf16_f32 v79, v76, v77
	v_cvt_pk_bf16_f32 v80, v58, v59
	v_mov_b64_e32 v[58:59], s[10:11]
	s_movk_i32 s0, 0xa00
	v_mad_i64_i32 v[58:59], s[0:1], v200, s0, v[58:59]
	v_mov_b32_e32 v75, v74
	v_cvt_pk_bf16_f32 v81, v64, v65
	v_lshl_add_u64 v[58:59], v[58:59], 0, s[90:91]
	v_mov_b32_e32 v64, v74
	v_mov_b32_e32 v65, v74
	v_lshl_add_u64 v[58:59], v[58:59], 0, v[0:1]
	v_pk_mul_f32 v[62:63], v[56:57], v[64:65]
	v_pk_mul_f32 v[54:55], v[54:55], v[74:75]
	v_pk_mul_f32 v[56:57], v[52:53], v[64:65]
	s_and_b64 vcc, exec, s[6:7]
	v_pk_mul_f32 v[52:53], v[50:51], v[74:75]
	global_store_dwordx4 v[58:59], v[78:81], off
	s_cbranch_vccnz .LBB0_656
	s_add_i32 s0, s15, 0xffffff80
	s_lshr_b32 s0, s0, 1
	v_or_b32_e32 v50, s0, v231
	v_mov_b32_e32 v51, v1
	v_lshl_add_u64 v[50:51], v[50:51], 2, v[60:61]
	flat_load_dwordx4 v[74:77], v[50:51]
	flat_load_dwordx4 v[78:81], v[50:51] offset:128
	s_waitcnt vmcnt(0) lgkmcnt(0)
	v_pk_mul_f32 v[50:51], v[54:55], v[74:75]
	v_pk_mul_f32 v[60:61], v[54:55], v[78:79] op_sel:[1,0] op_sel_hi:[0,0]
	v_pk_fma_f32 v[54:55], v[54:55], v[74:75], v[60:61] op_sel_hi:[1,0,1]
	v_mov_b32_e32 v78, v75
	v_mul_f32_e32 v54, v63, v79
	v_pk_fma_f32 v[64:65], v[62:63], v[78:79], v[54:55] op_sel_hi:[1,1,0] neg_lo:[0,0,1] neg_hi:[0,0,1]
	v_mov_b32_e32 v74, v79
	v_mul_f32_e32 v54, v63, v75
	v_pk_mul_f32 v[78:79], v[52:53], v[80:81] op_sel:[1,0] op_sel_hi:[0,0]
	v_pk_fma_f32 v[74:75], v[62:63], v[74:75], v[54:55] op_sel_hi:[1,1,0]
	v_pk_mul_f32 v[62:63], v[52:53], v[76:77]
	v_pk_fma_f32 v[52:53], v[52:53], v[76:77], v[78:79] op_sel_hi:[1,0,1]
	v_mov_b32_e32 v80, v77
	v_mul_f32_e32 v52, v57, v81
	v_pk_fma_f32 v[90:91], v[56:57], v[80:81], v[52:53] op_sel_hi:[1,1,0] neg_lo:[0,0,1] neg_hi:[0,0,1]
	v_mov_b32_e32 v76, v81
	v_mul_f32_e32 v52, v57, v77
	v_pk_fma_f32 v[76:77], v[56:57], v[76:77], v[52:53] op_sel_hi:[1,1,0]
	v_sub_f32_e32 v54, v50, v60
	v_sub_f32_e32 v52, v62, v78
	v_mov_b32_e32 v62, v64
	v_mov_b32_e32 v63, v74
	v_mov_b32_e32 v56, v90
	v_mov_b32_e32 v57, v76
.LBB0_656:
	v_add_f32_e32 v50, v110, v111
	v_add_f32_e32 v51, v112, v113
	v_add_f32_e32 v50, v50, v51
	v_add_f32_e32 v51, v106, v107
	v_add_f32_e32 v60, v108, v109
	v_add_f32_e32 v51, v51, v60
	v_add_f32_e32 v50, v50, v51
	v_fmamk_f32 v50, v50, 0x3b000000, v218
	v_mul_f32_e32 v51, 0x4f800000, v50
	v_cmp_gt_f32_e32 vcc, s77, v50
	v_ashrrev_i32_e32 v199, 31, v198
	s_nop 0
	v_cndmask_b32_e32 v50, v50, v51, vcc
	v_sqrt_f32_e32 v51, v50
	s_nop 0
	v_add_u32_e32 v60, -1, v51
	v_fma_f32 v61, -v60, v51, v50
	v_cmp_ge_f32_e64 s[0:1], 0, v61
	v_add_u32_e32 v61, 1, v51
	s_nop 0
	v_cndmask_b32_e64 v60, v51, v60, s[0:1]
	v_fma_f32 v51, -v61, v51, v50
	v_cmp_lt_f32_e64 s[0:1], 0, v51
	s_nop 1
	v_cndmask_b32_e64 v51, v60, v61, s[0:1]
	v_mul_f32_e32 v60, 0x37800000, v51
	v_cndmask_b32_e32 v51, v51, v60, vcc
	v_cmp_class_f32_e32 vcc, v50, v219
	s_nop 1
	v_cndmask_b32_e32 v50, v51, v50, vcc
	v_div_scale_f32 v51, s[0:1], v50, v50, 1.0
	v_rcp_f32_e32 v60, v51
	s_nop 0
	v_fma_f32 v61, -v51, v60, 1.0
	v_fmac_f32_e32 v60, v61, v60
	v_div_scale_f32 v61, vcc, 1.0, v50, 1.0
	v_mul_f32_e32 v64, v61, v60
	v_fma_f32 v65, -v51, v64, v61
	v_fmac_f32_e32 v64, v65, v60
	v_fma_f32 v51, -v51, v64, v61
	v_div_fmas_f32 v51, v51, v60, v64
	v_div_fixup_f32 v50, v51, v50, 1.0
	v_cvt_pk_bf16_f32 v60, v54, v55
	v_lshlrev_b64 v[54:55], 8, v[198:199]
	v_cvt_pk_bf16_f32 v61, v62, v63
	v_cvt_pk_bf16_f32 v62, v52, v53
	v_pk_mul_f32 v[52:53], v[48:49], v[50:51] op_sel_hi:[1,0]
	v_pk_mul_f32 v[46:47], v[46:47], v[50:51] op_sel_hi:[1,0]
	v_pk_mul_f32 v[48:49], v[44:45], v[50:51] op_sel_hi:[1,0]
	v_pk_mul_f32 v[42:43], v[42:43], v[50:51] op_sel_hi:[1,0]
	s_and_b64 vcc, exec, s[4:5]
	v_lshl_add_u64 v[44:45], s[8:9], 0, v[54:55]
	v_cvt_pk_bf16_f32 v63, v56, v57
	global_store_dwordx4 v[58:59], v[60:63], off offset:256
	s_cbranch_vccnz .LBB0_658
	s_add_i32 s0, s14, 0xffffff80
	s_lshr_b32 s0, s0, 1
	v_or_b32_e32 v54, s0, v231
	v_mov_b32_e32 v55, v1
	v_lshl_add_u64 v[58:59], v[54:55], 2, v[44:45]
	flat_load_dwordx4 v[54:57], v[58:59]
	s_nop 0
	flat_load_dwordx4 v[58:61], v[58:59] offset:128
	s_waitcnt vmcnt(0) lgkmcnt(0)
	v_pk_mul_f32 v[62:63], v[46:47], v[54:55]
	v_pk_mul_f32 v[64:65], v[46:47], v[58:59] op_sel:[1,0] op_sel_hi:[0,0]
	v_pk_fma_f32 v[46:47], v[46:47], v[54:55], v[64:65] op_sel_hi:[1,0,1]
	v_mov_b32_e32 v58, v55
	v_mul_f32_e32 v46, v53, v59
	v_pk_fma_f32 v[74:75], v[52:53], v[58:59], v[46:47] op_sel_hi:[1,1,0] neg_lo:[0,0,1] neg_hi:[0,0,1]
	v_mov_b32_e32 v54, v59
	v_mul_f32_e32 v46, v53, v55
	v_pk_mul_f32 v[58:59], v[42:43], v[60:61] op_sel:[1,0] op_sel_hi:[0,0]
	v_pk_fma_f32 v[54:55], v[52:53], v[54:55], v[46:47] op_sel_hi:[1,1,0]
	v_pk_mul_f32 v[52:53], v[42:43], v[56:57]
	v_pk_fma_f32 v[42:43], v[42:43], v[56:57], v[58:59] op_sel_hi:[1,0,1]
	v_mov_b32_e32 v60, v57
	v_mul_f32_e32 v42, v49, v61
	v_pk_fma_f32 v[76:77], v[48:49], v[60:61], v[42:43] op_sel_hi:[1,1,0] neg_lo:[0,0,1] neg_hi:[0,0,1]
	v_mov_b32_e32 v56, v61
	v_mul_f32_e32 v42, v49, v57
	v_pk_fma_f32 v[56:57], v[48:49], v[56:57], v[42:43] op_sel_hi:[1,1,0]
	v_sub_f32_e32 v46, v62, v64
	v_sub_f32_e32 v42, v52, v58
	v_mov_b32_e32 v52, v74
	v_mov_b32_e32 v53, v54
	v_mov_b32_e32 v48, v76
	v_mov_b32_e32 v49, v56
; __device__ __forceinline__ u32x4 pack8(const f32x4 v0, const f32x4 v1) { u32x4 w; w.x = cvt_pk_bf16(v0[0], v0[1]); w.y = cvt_pk_bf16(v0[2], v0[3]); w.z = cvt_pk_bf16(v1[0], v1[1]); w.w = cvt_pk_bf16(v1[2], v1[3]); return w; }
;     __device__ __forceinline__ void operator()(const f32x4 (&acc)[2][2][4][2], const Unit& u, int wr, int wc, int fr, int fq) const {
;     ...
;             for (int m = 0; m < 4; ++m) { const f32x4 a = q0[ai][m], b = q1[ai][m];
;                 sc[ai][m] = 1.0f / sqrtf((((a[0] + a[1]) + (a[2] + a[3])) + ((b[0] + b[1]) + (b[2] + b[3]))) * (1.0f / 512.0f) + 1e-6f); } }
; #pragma unroll
;         for (int ai = 0; ai < 2; ++ai)
; #pragma unroll
;             for (int m = 0; m < 4; ++m) { const int row = row0 + ai * HALF + m * 16; const float s = sc[ai][m];
; #pragma unroll
;                 for (int bj = 0; bj < 2; ++bj) {
;                     const int cb = u.pn * BM + bj * HALF + wc * 32, hc = cb % 192;
;                     f32x4 v0 = acc[ai][bj][m][0] * s, v1 = acc[ai][bj][m][1] * s;
;                     if (hc >= 128) {
;                         const int ib = (hc - 128) / 2 + 4 * fq;
;                         const f32x4 c = *(const f32x4*)(rope + (size_t)row * 64 + ib), sn = *(const f32x4*)(rope + (size_t)row * 64 + 32 + ib);
;                         f32x4 a, b;
;                         a[0] = v0[0] * c[0] - v0[1] * sn[0]; a[1] = v0[1] * c[0] + v0[0] * sn[0];
;                         a[2] = v0[2] * c[1] - v0[3] * sn[1]; a[3] = v0[3] * c[1] + v0[2] * sn[1];
;                         b[0] = v1[0] * c[2] - v1[1] * sn[2]; b[1] = v1[1] * c[2] + v1[0] * sn[2];
;                         b[2] = v1[2] * c[3] - v1[3] * sn[3]; b[3] = v1[3] * c[3] + v1[2] * sn[3];
;                         v0 = a; v1 = b;
;                     }
;                     *(u32x4*)(O + (size_t)row * ldc + cb + 8 * fq) = pack8(v0, v1);
.LBB0_658:
	v_cvt_pk_bf16_f32 v54, v46, v47
	v_cvt_pk_bf16_f32 v55, v52, v53
	v_cvt_pk_bf16_f32 v56, v42, v43
	v_mov_b64_e32 v[42:43], s[10:11]
	s_movk_i32 s0, 0xa00
	v_mad_i64_i32 v[42:43], s[0:1], v198, s0, v[42:43]
	v_mov_b32_e32 v51, v50
	v_cvt_pk_bf16_f32 v57, v48, v49
	v_lshl_add_u64 v[42:43], v[42:43], 0, s[90:91]
	v_mov_b32_e32 v48, v50
	v_mov_b32_e32 v49, v50
	v_lshl_add_u64 v[42:43], v[42:43], 0, v[0:1]
	v_pk_mul_f32 v[46:47], v[40:41], v[48:49]
	v_pk_mul_f32 v[38:39], v[38:39], v[50:51]
	v_pk_mul_f32 v[40:41], v[36:37], v[48:49]
	s_and_b64 vcc, exec, s[6:7]
	v_pk_mul_f32 v[36:37], v[34:35], v[50:51]
	global_store_dwordx4 v[42:43], v[54:57], off
	s_cbranch_vccnz .LBB0_660
	s_add_i32 s0, s15, 0xffffff80
	s_lshr_b32 s0, s0, 1
	v_or_b32_e32 v34, s0, v231
	v_mov_b32_e32 v35, v1
	v_lshl_add_u64 v[34:35], v[34:35], 2, v[44:45]
	flat_load_dwordx4 v[48:51], v[34:35]
	flat_load_dwordx4 v[52:55], v[34:35] offset:128
	s_waitcnt vmcnt(0) lgkmcnt(0)
	v_pk_mul_f32 v[34:35], v[38:39], v[48:49]
	v_pk_mul_f32 v[44:45], v[38:39], v[52:53] op_sel:[1,0] op_sel_hi:[0,0]
	v_pk_fma_f32 v[38:39], v[38:39], v[48:49], v[44:45] op_sel_hi:[1,0,1]
	v_mov_b32_e32 v52, v49
	v_mul_f32_e32 v38, v47, v53
	v_pk_fma_f32 v[56:57], v[46:47], v[52:53], v[38:39] op_sel_hi:[1,1,0] neg_lo:[0,0,1] neg_hi:[0,0,1]
	v_mov_b32_e32 v48, v53
	v_mul_f32_e32 v38, v47, v49
	v_pk_mul_f32 v[52:53], v[36:37], v[54:55] op_sel:[1,0] op_sel_hi:[0,0]
	v_pk_fma_f32 v[48:49], v[46:47], v[48:49], v[38:39] op_sel_hi:[1,1,0]
	v_pk_mul_f32 v[46:47], v[36:37], v[50:51]
	v_pk_fma_f32 v[36:37], v[36:37], v[50:51], v[52:53] op_sel_hi:[1,0,1]
	v_mov_b32_e32 v54, v51
	v_mul_f32_e32 v36, v41, v55
	v_pk_fma_f32 v[58:59], v[40:41], v[54:55], v[36:37] op_sel_hi:[1,1,0] neg_lo:[0,0,1] neg_hi:[0,0,1]
	v_mov_b32_e32 v50, v55
	v_mul_f32_e32 v36, v41, v51
	v_pk_fma_f32 v[50:51], v[40:41], v[50:51], v[36:37] op_sel_hi:[1,1,0]
	v_sub_f32_e32 v38, v34, v44
	v_sub_f32_e32 v36, v46, v52
	v_mov_b32_e32 v46, v56
	v_mov_b32_e32 v47, v48
	v_mov_b32_e32 v40, v58
	v_mov_b32_e32 v41, v50
.LBB0_660:
	v_add_f32_e32 v34, v86, v87
	v_add_f32_e32 v35, v88, v89
	v_add_f32_e32 v34, v34, v35
	v_add_f32_e32 v35, v82, v83
	v_add_f32_e32 v44, v84, v85
	v_add_f32_e32 v35, v35, v44
	v_add_f32_e32 v34, v34, v35
	v_fmamk_f32 v34, v34, 0x3b000000, v218
	v_mul_f32_e32 v35, 0x4f800000, v34
	v_cmp_gt_f32_e32 vcc, s77, v34
	v_ashrrev_i32_e32 v197, 31, v196
	s_nop 0
	v_cndmask_b32_e32 v34, v34, v35, vcc
	v_sqrt_f32_e32 v35, v34
	s_nop 0
	v_add_u32_e32 v44, -1, v35
	v_fma_f32 v45, -v44, v35, v34
	v_cmp_ge_f32_e64 s[0:1], 0, v45
	v_add_u32_e32 v45, 1, v35
	s_nop 0
	v_cndmask_b32_e64 v44, v35, v44, s[0:1]
	v_fma_f32 v35, -v45, v35, v34
	v_cmp_lt_f32_e64 s[0:1], 0, v35
	s_nop 1
	v_cndmask_b32_e64 v35, v44, v45, s[0:1]
	v_mul_f32_e32 v44, 0x37800000, v35
	v_cndmask_b32_e32 v35, v35, v44, vcc
	v_cmp_class_f32_e32 vcc, v34, v219
	s_nop 1
	v_cndmask_b32_e32 v34, v35, v34, vcc
	v_div_scale_f32 v35, s[0:1], v34, v34, 1.0
	v_rcp_f32_e32 v44, v35
	s_nop 0
	v_fma_f32 v45, -v35, v44, 1.0
	v_fmac_f32_e32 v44, v45, v44
	v_div_scale_f32 v45, vcc, 1.0, v34, 1.0
	v_mul_f32_e32 v48, v45, v44
	v_fma_f32 v49, -v35, v48, v45
	v_fmac_f32_e32 v48, v49, v44
	v_fma_f32 v35, -v35, v48, v45
	v_div_fmas_f32 v35, v35, v44, v48
	v_div_fixup_f32 v34, v35, v34, 1.0
	v_cvt_pk_bf16_f32 v44, v38, v39
	v_lshlrev_b64 v[38:39], 8, v[196:197]
	v_cvt_pk_bf16_f32 v45, v46, v47
	v_cvt_pk_bf16_f32 v46, v36, v37
	v_pk_mul_f32 v[36:37], v[32:33], v[34:35] op_sel_hi:[1,0]
	v_pk_mul_f32 v[30:31], v[30:31], v[34:35] op_sel_hi:[1,0]
	v_pk_mul_f32 v[32:33], v[28:29], v[34:35] op_sel_hi:[1,0]
	v_pk_mul_f32 v[26:27], v[26:27], v[34:35] op_sel_hi:[1,0]
	s_and_b64 vcc, exec, s[4:5]
	v_lshl_add_u64 v[28:29], s[8:9], 0, v[38:39]
	v_cvt_pk_bf16_f32 v47, v40, v41
	global_store_dwordx4 v[42:43], v[44:47], off offset:256
	s_cbranch_vccnz .LBB0_662
	s_add_i32 s0, s14, 0xffffff80
	s_lshr_b32 s0, s0, 1
	v_or_b32_e32 v38, s0, v231
	v_mov_b32_e32 v39, v1
	v_lshl_add_u64 v[42:43], v[38:39], 2, v[28:29]
	flat_load_dwordx4 v[38:41], v[42:43]
	s_nop 0
	flat_load_dwordx4 v[42:45], v[42:43] offset:128
	s_waitcnt vmcnt(0) lgkmcnt(0)
	v_pk_mul_f32 v[46:47], v[30:31], v[38:39]
	v_pk_mul_f32 v[48:49], v[30:31], v[42:43] op_sel:[1,0] op_sel_hi:[0,0]
	v_pk_fma_f32 v[30:31], v[30:31], v[38:39], v[48:49] op_sel_hi:[1,0,1]
	v_mov_b32_e32 v42, v39
	v_mul_f32_e32 v30, v37, v43
	v_pk_fma_f32 v[50:51], v[36:37], v[42:43], v[30:31] op_sel_hi:[1,1,0] neg_lo:[0,0,1] neg_hi:[0,0,1]
	v_mov_b32_e32 v38, v43
	v_mul_f32_e32 v30, v37, v39
	v_pk_mul_f32 v[42:43], v[26:27], v[44:45] op_sel:[1,0] op_sel_hi:[0,0]
	v_pk_fma_f32 v[38:39], v[36:37], v[38:39], v[30:31] op_sel_hi:[1,1,0]
	v_pk_mul_f32 v[36:37], v[26:27], v[40:41]
	v_pk_fma_f32 v[26:27], v[26:27], v[40:41], v[42:43] op_sel_hi:[1,0,1]
	v_mov_b32_e32 v44, v41
	v_mul_f32_e32 v26, v33, v45
	v_pk_fma_f32 v[52:53], v[32:33], v[44:45], v[26:27] op_sel_hi:[1,1,0] neg_lo:[0,0,1] neg_hi:[0,0,1]
	v_mov_b32_e32 v40, v45
	v_mul_f32_e32 v26, v33, v41
	v_pk_fma_f32 v[40:41], v[32:33], v[40:41], v[26:27] op_sel_hi:[1,1,0]
	v_sub_f32_e32 v30, v46, v48
	v_sub_f32_e32 v26, v36, v42
	v_mov_b32_e32 v36, v50
	v_mov_b32_e32 v37, v38
	v_mov_b32_e32 v32, v52
	v_mov_b32_e32 v33, v40
; __device__ __forceinline__ u32x4 pack8(const f32x4 v0, const f32x4 v1) { u32x4 w; w.x = cvt_pk_bf16(v0[0], v0[1]); w.y = cvt_pk_bf16(v0[2], v0[3]); w.z = cvt_pk_bf16(v1[0], v1[1]); w.w = cvt_pk_bf16(v1[2], v1[3]); return w; }
;     __device__ __forceinline__ void operator()(const f32x4 (&acc)[2][2][4][2], const Unit& u, int wr, int wc, int fr, int fq) const {
;     ...
;             for (int m = 0; m < 4; ++m) { const f32x4 a = q0[ai][m], b = q1[ai][m];
;                 sc[ai][m] = 1.0f / sqrtf((((a[0] + a[1]) + (a[2] + a[3])) + ((b[0] + b[1]) + (b[2] + b[3]))) * (1.0f / 512.0f) + 1e-6f); } }
; #pragma unroll
;         for (int ai = 0; ai < 2; ++ai)
; #pragma unroll
;             for (int m = 0; m < 4; ++m) { const int row = row0 + ai * HALF + m * 16; const float s = sc[ai][m];
; #pragma unroll
;                 for (int bj = 0; bj < 2; ++bj) {
;                     const int cb = u.pn * BM + bj * HALF + wc * 32, hc = cb % 192;
;                     f32x4 v0 = acc[ai][bj][m][0] * s, v1 = acc[ai][bj][m][1] * s;
;                     if (hc >= 128) {
;                         const int ib = (hc - 128) / 2 + 4 * fq;
;                         const f32x4 c = *(const f32x4*)(rope + (size_t)row * 64 + ib), sn = *(const f32x4*)(rope + (size_t)row * 64 + 32 + ib);
;                         f32x4 a, b;
;                         a[0] = v0[0] * c[0] - v0[1] * sn[0]; a[1] = v0[1] * c[0] + v0[0] * sn[0];
;                         a[2] = v0[2] * c[1] - v0[3] * sn[1]; a[3] = v0[3] * c[1] + v0[2] * sn[1];
;                         b[0] = v1[0] * c[2] - v1[1] * sn[2]; b[1] = v1[1] * c[2] + v1[0] * sn[2];
;                         b[2] = v1[2] * c[3] - v1[3] * sn[3]; b[3] = v1[3] * c[3] + v1[2] * sn[3];
;                         v0 = a; v1 = b;
;                     }
;                     *(u32x4*)(O + (size_t)row * ldc + cb + 8 * fq) = pack8(v0, v1);
.LBB0_662:
	v_cvt_pk_bf16_f32 v38, v30, v31
	v_cvt_pk_bf16_f32 v39, v36, v37
	v_cvt_pk_bf16_f32 v40, v26, v27
	v_mov_b64_e32 v[26:27], s[10:11]
	s_movk_i32 s0, 0xa00
	v_mad_i64_i32 v[26:27], s[0:1], v196, s0, v[26:27]
	v_mov_b32_e32 v35, v34
	v_cvt_pk_bf16_f32 v41, v32, v33
	v_lshl_add_u64 v[26:27], v[26:27], 0, s[90:91]
	v_mov_b32_e32 v32, v34
	v_mov_b32_e32 v33, v34
	v_lshl_add_u64 v[26:27], v[26:27], 0, v[0:1]
	v_pk_mul_f32 v[30:31], v[24:25], v[32:33]
	v_pk_mul_f32 v[22:23], v[22:23], v[34:35]
	v_pk_mul_f32 v[24:25], v[20:21], v[32:33]
	s_and_b64 vcc, exec, s[6:7]
	v_pk_mul_f32 v[20:21], v[18:19], v[34:35]
	global_store_dwordx4 v[26:27], v[38:41], off
	s_cbranch_vccnz .LBB0_664
	s_add_i32 s0, s15, 0xffffff80
	s_lshr_b32 s0, s0, 1
	v_or_b32_e32 v18, s0, v231
	v_mov_b32_e32 v19, v1
	v_lshl_add_u64 v[18:19], v[18:19], 2, v[28:29]
	flat_load_dwordx4 v[32:35], v[18:19]
	flat_load_dwordx4 v[36:39], v[18:19] offset:128
	s_waitcnt vmcnt(0) lgkmcnt(0)
	v_pk_mul_f32 v[18:19], v[22:23], v[32:33]
	v_pk_mul_f32 v[28:29], v[22:23], v[36:37] op_sel:[1,0] op_sel_hi:[0,0]
	v_pk_fma_f32 v[22:23], v[22:23], v[32:33], v[28:29] op_sel_hi:[1,0,1]
	v_mov_b32_e32 v36, v33
	v_mul_f32_e32 v22, v31, v37
	v_pk_fma_f32 v[40:41], v[30:31], v[36:37], v[22:23] op_sel_hi:[1,1,0] neg_lo:[0,0,1] neg_hi:[0,0,1]
	v_mov_b32_e32 v32, v37
	v_mul_f32_e32 v22, v31, v33
	v_pk_mul_f32 v[36:37], v[20:21], v[38:39] op_sel:[1,0] op_sel_hi:[0,0]
	v_pk_fma_f32 v[32:33], v[30:31], v[32:33], v[22:23] op_sel_hi:[1,1,0]
	v_pk_mul_f32 v[30:31], v[20:21], v[34:35]
	v_pk_fma_f32 v[20:21], v[20:21], v[34:35], v[36:37] op_sel_hi:[1,0,1]
	v_mov_b32_e32 v38, v35
	v_mul_f32_e32 v20, v25, v39
	v_pk_fma_f32 v[42:43], v[24:25], v[38:39], v[20:21] op_sel_hi:[1,1,0] neg_lo:[0,0,1] neg_hi:[0,0,1]
	v_mov_b32_e32 v34, v39
	v_mul_f32_e32 v20, v25, v35
	v_pk_fma_f32 v[34:35], v[24:25], v[34:35], v[20:21] op_sel_hi:[1,1,0]
	v_sub_f32_e32 v22, v18, v28
	v_sub_f32_e32 v20, v30, v36
	v_mov_b32_e32 v30, v40
	v_mov_b32_e32 v31, v32
	v_mov_b32_e32 v24, v42
	v_mov_b32_e32 v25, v34
.LBB0_664:
	v_add_f32_e32 v18, v70, v71
	v_add_f32_e32 v19, v72, v73
	v_add_f32_e32 v18, v18, v19
	v_add_f32_e32 v19, v66, v67
	v_add_f32_e32 v28, v68, v69
	v_add_f32_e32 v19, v19, v28
	v_add_f32_e32 v18, v18, v19
	v_fmamk_f32 v18, v18, 0x3b000000, v218
	v_mul_f32_e32 v19, 0x4f800000, v18
	v_cmp_gt_f32_e32 vcc, s77, v18
	v_ashrrev_i32_e32 v195, 31, v194
	s_nop 0
	v_cndmask_b32_e32 v18, v18, v19, vcc
	v_sqrt_f32_e32 v19, v18
	s_nop 0
	v_add_u32_e32 v28, -1, v19
	v_fma_f32 v29, -v28, v19, v18
	v_cmp_ge_f32_e64 s[0:1], 0, v29
	v_add_u32_e32 v29, 1, v19
	s_nop 0
	v_cndmask_b32_e64 v28, v19, v28, s[0:1]
	v_fma_f32 v19, -v29, v19, v18
	v_cmp_lt_f32_e64 s[0:1], 0, v19
	s_nop 1
	v_cndmask_b32_e64 v19, v28, v29, s[0:1]
	v_mul_f32_e32 v28, 0x37800000, v19
	v_cndmask_b32_e32 v19, v19, v28, vcc
	v_cmp_class_f32_e32 vcc, v18, v219
	s_nop 1
	v_cndmask_b32_e32 v18, v19, v18, vcc
	v_div_scale_f32 v19, s[0:1], v18, v18, 1.0
	v_rcp_f32_e32 v28, v19
	s_nop 0
	v_fma_f32 v29, -v19, v28, 1.0
	v_fmac_f32_e32 v28, v29, v28
	v_div_scale_f32 v29, vcc, 1.0, v18, 1.0
	v_mul_f32_e32 v32, v29, v28
	v_fma_f32 v33, -v19, v32, v29
	v_fmac_f32_e32 v32, v33, v28
	v_fma_f32 v19, -v19, v32, v29
	v_div_fmas_f32 v19, v19, v28, v32
	v_div_fixup_f32 v18, v19, v18, 1.0
	v_cvt_pk_bf16_f32 v28, v22, v23
	v_lshlrev_b64 v[22:23], 8, v[194:195]
	v_cvt_pk_bf16_f32 v29, v30, v31
	v_cvt_pk_bf16_f32 v30, v20, v21
	v_pk_mul_f32 v[20:21], v[16:17], v[18:19] op_sel_hi:[1,0]
	v_pk_mul_f32 v[14:15], v[14:15], v[18:19] op_sel_hi:[1,0]
	v_pk_mul_f32 v[16:17], v[12:13], v[18:19] op_sel_hi:[1,0]
	v_pk_mul_f32 v[12:13], v[10:11], v[18:19] op_sel_hi:[1,0]
	s_and_b64 vcc, exec, s[4:5]
	v_lshl_add_u64 v[10:11], s[8:9], 0, v[22:23]
	v_cvt_pk_bf16_f32 v31, v24, v25
	global_store_dwordx4 v[26:27], v[28:31], off offset:256
	s_cbranch_vccnz .LBB0_666
	s_addk_i32 s14, 0xff80
	s_lshr_b32 s0, s14, 1
	v_or_b32_e32 v22, s0, v231
	v_mov_b32_e32 v23, v1
	v_lshl_add_u64 v[26:27], v[22:23], 2, v[10:11]
	flat_load_dwordx4 v[22:25], v[26:27]
	s_nop 0
	flat_load_dwordx4 v[26:29], v[26:27] offset:128
	s_waitcnt vmcnt(0) lgkmcnt(0)
	v_pk_mul_f32 v[30:31], v[14:15], v[22:23]
	v_pk_mul_f32 v[32:33], v[14:15], v[26:27] op_sel:[1,0] op_sel_hi:[0,0]
	v_pk_fma_f32 v[14:15], v[14:15], v[22:23], v[32:33] op_sel_hi:[1,0,1]
	v_mov_b32_e32 v26, v23
	v_mul_f32_e32 v14, v21, v27
	v_pk_fma_f32 v[34:35], v[20:21], v[26:27], v[14:15] op_sel_hi:[1,1,0] neg_lo:[0,0,1] neg_hi:[0,0,1]
	v_mov_b32_e32 v22, v27
	v_mul_f32_e32 v14, v21, v23
	v_pk_mul_f32 v[26:27], v[12:13], v[28:29] op_sel:[1,0] op_sel_hi:[0,0]
	v_pk_fma_f32 v[22:23], v[20:21], v[22:23], v[14:15] op_sel_hi:[1,1,0]
	v_pk_mul_f32 v[20:21], v[12:13], v[24:25]
	v_pk_fma_f32 v[12:13], v[12:13], v[24:25], v[26:27] op_sel_hi:[1,0,1]
	v_mov_b32_e32 v28, v25
	v_mul_f32_e32 v12, v17, v29
	v_pk_fma_f32 v[36:37], v[16:17], v[28:29], v[12:13] op_sel_hi:[1,1,0] neg_lo:[0,0,1] neg_hi:[0,0,1]
	v_mov_b32_e32 v24, v29
	v_mul_f32_e32 v12, v17, v25
	v_pk_fma_f32 v[24:25], v[16:17], v[24:25], v[12:13] op_sel_hi:[1,1,0]
	v_sub_f32_e32 v14, v30, v32
	v_sub_f32_e32 v12, v20, v26
	v_mov_b32_e32 v20, v34
	v_mov_b32_e32 v21, v22
	v_mov_b32_e32 v16, v36
	v_mov_b32_e32 v17, v24
; __device__ __forceinline__ u32x4 pack8(const f32x4 v0, const f32x4 v1) { u32x4 w; w.x = cvt_pk_bf16(v0[0], v0[1]); w.y = cvt_pk_bf16(v0[2], v0[3]); w.z = cvt_pk_bf16(v1[0], v1[1]); w.w = cvt_pk_bf16(v1[2], v1[3]); return w; }
; #define PG8_WAIT_V(n) asm volatile("s_waitcnt vmcnt(" #n ")" ::: "memory")
; #define PG8_BAR __builtin_amdgcn_s_barrier()
;     __device__ __forceinline__ void operator()(const f32x4 (&acc)[2][2][4][2], const Unit& u, int wr, int wc, int fr, int fq) const {
;     ...
;                     const int cb = u.pn * BM + bj * HALF + wc * 32, hc = cb % 192;
;                     f32x4 v0 = acc[ai][bj][m][0] * s, v1 = acc[ai][bj][m][1] * s;
;                     if (hc >= 128) {
;                         const int ib = (hc - 128) / 2 + 4 * fq;
;                         const f32x4 c = *(const f32x4*)(rope + (size_t)row * 64 + ib), sn = *(const f32x4*)(rope + (size_t)row * 64 + 32 + ib);
;                         f32x4 a, b;
;                         a[0] = v0[0] * c[0] - v0[1] * sn[0]; a[1] = v0[1] * c[0] + v0[0] * sn[0];
;                         a[2] = v0[2] * c[1] - v0[3] * sn[1]; a[3] = v0[3] * c[1] + v0[2] * sn[1];
;                         b[0] = v1[0] * c[2] - v1[1] * sn[2]; b[1] = v1[1] * c[2] + v1[0] * sn[2];
;                         b[2] = v1[2] * c[3] - v1[3] * sn[3]; b[3] = v1[3] * c[3] + v1[2] * sn[3];
;                         v0 = a; v1 = b;
;                     }
;                     *(u32x4*)(O + (size_t)row * ldc + cb + 8 * fq) = pack8(v0, v1);
; template <class Epi, class Sched, bool ALIGN_EPI = false, bool SP2 = false>
; __device__ __forceinline__ void gemm_phase(PG8_LAS unsigned char* lds, const Gemm g, const Sched& S, const Epi& E) {
;     ...
;     PG8_WAIT_V(0);
;     if constexpr (!ALIGN_EPI) { if (wr == 0) PG8_BAR; }
;     PG8_BAR;
.LBB0_666:
	v_cvt_pk_bf16_f32 v22, v14, v15
	v_cvt_pk_bf16_f32 v23, v20, v21
	v_cvt_pk_bf16_f32 v24, v12, v13
	v_mov_b64_e32 v[12:13], s[10:11]
	s_movk_i32 s0, 0xa00
	v_mad_i64_i32 v[12:13], s[0:1], v194, s0, v[12:13]
	v_mov_b32_e32 v19, v18
	v_lshl_add_u64 v[12:13], v[12:13], 0, s[90:91]
	v_mov_b32_e32 v14, v18
	v_mov_b32_e32 v15, v18
	v_lshl_add_u64 v[12:13], v[12:13], 0, v[0:1]
	v_pk_mul_f32 v[8:9], v[8:9], v[14:15]
	v_pk_mul_f32 v[6:7], v[6:7], v[18:19]
	v_pk_mul_f32 v[4:5], v[4:5], v[14:15]
	s_and_b64 vcc, exec, s[6:7]
	v_pk_mul_f32 v[2:3], v[2:3], v[18:19]
	v_cvt_pk_bf16_f32 v25, v16, v17
	global_store_dwordx4 v[12:13], v[22:25], off
	s_cbranch_vccnz .LBB0_668
	s_addk_i32 s15, 0xff80
	s_lshr_b32 s0, s15, 1
	v_or_b32_e32 v0, s0, v231
	v_lshl_add_u64 v[10:11], v[0:1], 2, v[10:11]
	flat_load_dwordx4 v[14:17], v[10:11]
	flat_load_dwordx4 v[18:21], v[10:11] offset:128
	s_waitcnt vmcnt(0) lgkmcnt(0)
	v_pk_mul_f32 v[10:11], v[6:7], v[14:15]
	v_pk_mul_f32 v[22:23], v[6:7], v[18:19] op_sel:[1,0] op_sel_hi:[0,0]
	v_mov_b32_e32 v18, v15
	v_mul_f32_e32 v0, v9, v19
	v_pk_fma_f32 v[6:7], v[6:7], v[14:15], v[22:23] op_sel_hi:[1,0,1]
	v_pk_fma_f32 v[24:25], v[8:9], v[18:19], v[0:1] op_sel_hi:[1,1,0] neg_lo:[0,0,1] neg_hi:[0,0,1]
	v_mov_b32_e32 v14, v19
	v_mul_f32_e32 v0, v9, v15
	v_pk_fma_f32 v[14:15], v[8:9], v[14:15], v[0:1] op_sel_hi:[1,1,0]
	v_pk_mul_f32 v[18:19], v[2:3], v[20:21] op_sel:[1,0] op_sel_hi:[0,0]
	v_mov_b32_e32 v20, v17
	v_mul_f32_e32 v0, v5, v21
	v_pk_mul_f32 v[8:9], v[2:3], v[16:17]
	v_pk_fma_f32 v[2:3], v[2:3], v[16:17], v[18:19] op_sel_hi:[1,0,1]
	v_pk_fma_f32 v[26:27], v[4:5], v[20:21], v[0:1] op_sel_hi:[1,1,0] neg_lo:[0,0,1] neg_hi:[0,0,1]
	v_mov_b32_e32 v16, v21
	v_mul_f32_e32 v0, v5, v17
	v_pk_fma_f32 v[16:17], v[4:5], v[16:17], v[0:1] op_sel_hi:[1,1,0]
	v_sub_f32_e32 v6, v10, v22
	v_sub_f32_e32 v2, v8, v18
	v_mov_b32_e32 v8, v24
	v_mov_b32_e32 v9, v14
	v_mov_b32_e32 v4, v26
	v_mov_b32_e32 v5, v16
.LBB0_668:
	v_cvt_pk_bf16_f32 v6, v6, v7
	v_cvt_pk_bf16_f32 v7, v8, v9
	v_cvt_pk_bf16_f32 v8, v2, v3
	v_cvt_pk_bf16_f32 v9, v4, v5
	global_store_dwordx4 v[12:13], v[6:9], off offset:256
	s_waitcnt vmcnt(0)
	s_barrier

; __device__ __forceinline__ u32x4 pack8(const f32x4 v0, const f32x4 v1) { u32x4 w; w.x = cvt_pk_bf16(v0[0], v0[1]); w.y = cvt_pk_bf16(v0[2], v0[3]); w.z = cvt_pk_bf16(v1[0], v1[1]); w.w = cvt_pk_bf16(v1[2], v1[3]); return w; }
;     __device__ __forceinline__ void operator()(const f32x4 (&acc)[2][2][4][2], const Unit& u, int wr, int wc, int fr, int fq) const {
;         const int row0 = u.pm * BM + wr * 64 + fr, cin = wc * 32 + 8 * fq;
;         f32x4 q2[2][4];
; #pragma unroll
;         for (int ai = 0; ai < 2; ++ai)
; #pragma unroll
;             for (int m = 0; m < 4; ++m) q2[ai][m] = *(const f32x4*)(ssq + (size_t)(row0 + ai * HALF + m * 16) * 12 + 8);
; #pragma unroll
;         for (int ai = 0; ai < 2; ++ai)
; #pragma unroll
;             for (int m = 0; m < 4; ++m) { const int row = row0 + ai * HALF + m * 16; const f32x4 a = q2[ai][m];
;                 const float s = 1.0f / sqrtf(((a[0] + a[1]) + (a[2] + a[3])) * (1.0f / 256.0f) + 1e-6f);
;                 *(u32x4*)(Kb + (size_t)row * ldk + 192 * u.pn + cin) = pack8(acc[ai][0][m][0] * s, acc[ai][0][m][1] * s);
;                 *(u32x4*)(Vb + (size_t)row * ldv + 128 * u.pn + cin) = pack8(acc[ai][1][m][0] * s, acc[ai][1][m][1] * s); }
.LBB0_680:
	v_lshl_add_u32 v194, s28, 8, v170
	v_mad_i64_i32 v[114:115], s[0:1], v194, 48, s[16:17]
	flat_load_dwordx4 v[180:183], v[114:115] offset:32
	v_or_b32_e32 v179, 16, v194
	v_mad_i64_i32 v[114:115], s[0:1], v179, 48, s[16:17]
	flat_load_dwordx4 v[154:157], v[114:115] offset:32
	v_or_b32_e32 v178, 32, v194
	v_mad_i64_i32 v[114:115], s[0:1], v178, 48, s[16:17]
	flat_load_dwordx4 v[150:153], v[114:115] offset:32
	v_or_b32_e32 v177, 48, v194
	v_mad_i64_i32 v[114:115], s[0:1], v177, 48, s[16:17]
	v_add_u32_e32 v176, 0x80, v194
	flat_load_dwordx4 v[146:149], v[114:115] offset:32
	v_mad_i64_i32 v[114:115], s[0:1], v176, 48, s[16:17]
	v_add_u32_e32 v175, 0x90, v194
	flat_load_dwordx4 v[142:145], v[114:115] offset:32
	v_mad_i64_i32 v[114:115], s[0:1], v175, 48, s[16:17]
	v_add_u32_e32 v174, 0xa0, v194
	flat_load_dwordx4 v[130:133], v[114:115] offset:32
	v_mad_i64_i32 v[114:115], s[0:1], v174, 48, s[16:17]
	v_add_u32_e32 v173, 0xb0, v194
	flat_load_dwordx4 v[118:121], v[114:115] offset:32
	v_mad_i64_i32 v[114:115], s[0:1], v173, 48, s[16:17]
	flat_load_dwordx4 v[114:117], v[114:115] offset:32
	s_mul_i32 s90, s48, 0xc0
	s_lshl_b64 s[28:29], s[90:91], 1
	s_lshl_b32 s90, s48, 8
	s_waitcnt vmcnt(0) lgkmcnt(0)
	v_mov_b32_e32 v184, v181
	v_mov_b32_e32 v185, v182
	v_mov_b32_e32 v181, v183
	v_pk_add_f32 v[180:181], v[184:185], v[180:181]
	s_nop 0
	v_add_f32_e32 v180, v180, v181
	v_fmamk_f32 v180, v180, 0x3b800000, v218
	v_cmp_gt_f32_e32 vcc, s77, v180
	v_mul_f32_e32 v181, 0x4f800000, v180
	s_nop 0
	v_cndmask_b32_e32 v180, v180, v181, vcc
	v_sqrt_f32_e32 v181, v180
	s_nop 0
	v_add_u32_e32 v182, -1, v181
	v_fma_f32 v183, -v182, v181, v180
	v_cmp_ge_f32_e64 s[0:1], 0, v183
	v_add_u32_e32 v183, 1, v181
	s_nop 0
	v_cndmask_b32_e64 v182, v181, v182, s[0:1]
	v_fma_f32 v181, -v183, v181, v180
	v_cmp_lt_f32_e64 s[0:1], 0, v181
	s_nop 1
	v_cndmask_b32_e64 v181, v182, v183, s[0:1]
	v_mul_f32_e32 v182, 0x37800000, v181
	v_cndmask_b32_e32 v181, v181, v182, vcc
	v_cmp_class_f32_e32 vcc, v180, v219
	s_nop 1
	v_cndmask_b32_e32 v180, v181, v180, vcc
	v_div_scale_f32 v181, s[0:1], v180, v180, 1.0
	v_rcp_f32_e32 v182, v181
	s_nop 0
	v_fma_f32 v183, -v181, v182, 1.0
	v_fmac_f32_e32 v182, v183, v182
	v_div_scale_f32 v183, vcc, 1.0, v180, 1.0
	v_mul_f32_e32 v184, v183, v182
	v_fma_f32 v185, -v181, v184, v183
	v_fmac_f32_e32 v184, v185, v182
	v_fma_f32 v181, -v181, v184, v183
	v_div_fmas_f32 v181, v181, v182, v184
	v_div_fixup_f32 v180, v181, v180, 1.0
	v_pk_mul_f32 v[134:135], v[134:135], v[180:181] op_sel_hi:[1,0]
	v_pk_mul_f32 v[182:183], v[136:137], v[180:181] op_sel_hi:[1,0]
	v_pk_mul_f32 v[140:141], v[140:141], v[180:181] op_sel_hi:[1,0]
	v_pk_mul_f32 v[138:139], v[138:139], v[180:181] op_sel_hi:[1,0]
	v_cvt_pk_bf16_f32 v136, v134, v135
	v_mov_b64_e32 v[134:135], s[12:13]
	v_cvt_pk_bf16_f32 v137, v182, v183
	v_cvt_pk_bf16_f32 v138, v138, v139
	v_cvt_pk_bf16_f32 v139, v140, v141
	v_mad_i64_i32 v[140:141], s[0:1], v194, s87, v[134:135]
	v_lshl_add_u64 v[140:141], v[140:141], 0, s[28:29]
	v_lshl_add_u64 v[140:141], v[140:141], 0, v[0:1]
	v_pk_mul_f32 v[126:127], v[126:127], v[180:181] op_sel_hi:[1,0]
	v_pk_mul_f32 v[122:123], v[122:123], v[180:181] op_sel_hi:[1,0]
	global_store_dwordx4 v[140:141], v[136:139], off
	v_pk_mul_f32 v[128:129], v[128:129], v[180:181] op_sel_hi:[1,0]
	s_nop 0
	v_pk_mul_f32 v[136:137], v[124:125], v[180:181] op_sel_hi:[1,0]
	v_cvt_pk_bf16_f32 v124, v126, v127
	v_cvt_pk_bf16_f32 v125, v128, v129
	v_cvt_pk_bf16_f32 v126, v122, v123
	v_mov_b64_e32 v[122:123], s[14:15]
	v_mad_i64_i32 v[128:129], s[0:1], v194, s33, v[122:123]
	v_lshl_add_u64 v[128:129], v[128:129], 0, s[90:91]
	v_lshl_add_u64 v[128:129], v[128:129], 0, v[0:1]
	v_cvt_pk_bf16_f32 v127, v136, v137
	global_store_dwordx4 v[128:129], v[124:127], off
	s_nop 1
	v_mov_b32_e32 v124, v155
	v_mov_b32_e32 v125, v156
	v_mov_b32_e32 v155, v157
	v_pk_add_f32 v[124:125], v[124:125], v[154:155]
	s_nop 0
	v_add_f32_e32 v124, v124, v125
	v_fmamk_f32 v124, v124, 0x3b800000, v218
	v_cmp_gt_f32_e32 vcc, s77, v124
	v_mul_f32_e32 v125, 0x4f800000, v124
	s_nop 0
	v_cndmask_b32_e32 v124, v124, v125, vcc
	v_sqrt_f32_e32 v125, v124
	s_nop 0
	v_add_u32_e32 v126, -1, v125
	v_fma_f32 v127, -v126, v125, v124
	v_cmp_ge_f32_e64 s[0:1], 0, v127
	v_add_u32_e32 v127, 1, v125
	s_nop 0
	v_cndmask_b32_e64 v126, v125, v126, s[0:1]
	v_fma_f32 v125, -v127, v125, v124
	v_cmp_lt_f32_e64 s[0:1], 0, v125
	s_nop 1
	v_cndmask_b32_e64 v125, v126, v127, s[0:1]
	v_mul_f32_e32 v126, 0x37800000, v125
	v_cndmask_b32_e32 v125, v125, v126, vcc
	v_cmp_class_f32_e32 vcc, v124, v219
	s_nop 1
	v_cndmask_b32_e32 v124, v125, v124, vcc
	v_div_scale_f32 v125, s[0:1], v124, v124, 1.0
	v_rcp_f32_e32 v126, v125
	s_nop 0
	v_fma_f32 v127, -v125, v126, 1.0
	v_fmac_f32_e32 v126, v127, v126
	v_div_scale_f32 v127, vcc, 1.0, v124, 1.0
	v_mul_f32_e32 v128, v127, v126
	v_fma_f32 v129, -v125, v128, v127
	v_fmac_f32_e32 v128, v129, v126
	v_fma_f32 v125, -v125, v128, v127
	v_div_fmas_f32 v125, v125, v126, v128
	v_div_fixup_f32 v124, v125, v124, 1.0
	v_pk_mul_f32 v[110:111], v[110:111], v[124:125] op_sel_hi:[1,0]
	v_pk_mul_f32 v[126:127], v[108:109], v[124:125] op_sel_hi:[1,0]
	v_pk_mul_f32 v[108:109], v[106:107], v[124:125] op_sel_hi:[1,0]
	v_cvt_pk_bf16_f32 v106, v110, v111
	v_mad_i64_i32 v[110:111], s[0:1], v179, s87, v[134:135]
	v_lshl_add_u64 v[110:111], v[110:111], 0, s[28:29]
	v_pk_mul_f32 v[112:113], v[112:113], v[124:125] op_sel_hi:[1,0]
	v_lshl_add_u64 v[110:111], v[110:111], 0, v[0:1]
	v_cvt_pk_bf16_f32 v107, v112, v113
	v_pk_mul_f32 v[102:103], v[102:103], v[124:125] op_sel_hi:[1,0]
	v_cvt_pk_bf16_f32 v108, v108, v109
	v_cvt_pk_bf16_f32 v109, v126, v127
; __device__ __forceinline__ u32x4 pack8(const f32x4 v0, const f32x4 v1) { u32x4 w; w.x = cvt_pk_bf16(v0[0], v0[1]); w.y = cvt_pk_bf16(v0[2], v0[3]); w.z = cvt_pk_bf16(v1[0], v1[1]); w.w = cvt_pk_bf16(v1[2], v1[3]); return w; }
;     __device__ __forceinline__ void operator()(const f32x4 (&acc)[2][2][4][2], const Unit& u, int wr, int wc, int fr, int fq) const {
;     ...
;             for (int m = 0; m < 4; ++m) { const int row = row0 + ai * HALF + m * 16; const f32x4 a = q2[ai][m];
;                 const float s = 1.0f / sqrtf(((a[0] + a[1]) + (a[2] + a[3])) * (1.0f / 256.0f) + 1e-6f);
;                 *(u32x4*)(Kb + (size_t)row * ldk + 192 * u.pn + cin) = pack8(acc[ai][0][m][0] * s, acc[ai][0][m][1] * s);
;                 *(u32x4*)(Vb + (size_t)row * ldv + 128 * u.pn + cin) = pack8(acc[ai][1][m][0] * s, acc[ai][1][m][1] * s); }
	global_store_dwordx4 v[110:111], v[106:109], off
	v_pk_mul_f32 v[104:105], v[104:105], v[124:125] op_sel_hi:[1,0]
	s_nop 0
	v_pk_mul_f32 v[106:107], v[100:101], v[124:125] op_sel_hi:[1,0]
	v_pk_mul_f32 v[100:101], v[98:99], v[124:125] op_sel_hi:[1,0]
	v_cvt_pk_bf16_f32 v98, v102, v103
	v_mad_i64_i32 v[102:103], s[0:1], v179, s33, v[122:123]
	v_lshl_add_u64 v[102:103], v[102:103], 0, s[90:91]
	v_cvt_pk_bf16_f32 v99, v104, v105
	v_lshl_add_u64 v[102:103], v[102:103], 0, v[0:1]
	v_cvt_pk_bf16_f32 v100, v100, v101
	v_cvt_pk_bf16_f32 v101, v106, v107
	global_store_dwordx4 v[102:103], v[98:101], off
	s_nop 1
	v_mov_b32_e32 v98, v151
	v_mov_b32_e32 v99, v152
	v_mov_b32_e32 v151, v153
	v_pk_add_f32 v[98:99], v[98:99], v[150:151]
	s_nop 0
	v_add_f32_e32 v98, v98, v99
	v_fmamk_f32 v98, v98, 0x3b800000, v218
	v_cmp_gt_f32_e32 vcc, s77, v98
	v_mul_f32_e32 v99, 0x4f800000, v98
	s_nop 0
	v_cndmask_b32_e32 v98, v98, v99, vcc
	v_sqrt_f32_e32 v99, v98
	s_nop 0
	v_add_u32_e32 v100, -1, v99
	v_fma_f32 v101, -v100, v99, v98
	v_cmp_ge_f32_e64 s[0:1], 0, v101
	v_add_u32_e32 v101, 1, v99
	s_nop 0
	v_cndmask_b32_e64 v100, v99, v100, s[0:1]
	v_fma_f32 v99, -v101, v99, v98
	v_cmp_lt_f32_e64 s[0:1], 0, v99
	s_nop 1
	v_cndmask_b32_e64 v99, v100, v101, s[0:1]
	v_mul_f32_e32 v100, 0x37800000, v99
	v_cndmask_b32_e32 v99, v99, v100, vcc
	v_cmp_class_f32_e32 vcc, v98, v219
	s_nop 1
	v_cndmask_b32_e32 v98, v99, v98, vcc
	v_div_scale_f32 v99, s[0:1], v98, v98, 1.0
	v_rcp_f32_e32 v100, v99
	s_nop 0
	v_fma_f32 v101, -v99, v100, 1.0
	v_fmac_f32_e32 v100, v101, v100
	v_div_scale_f32 v101, vcc, 1.0, v98, 1.0
	v_mul_f32_e32 v102, v101, v100
	v_fma_f32 v103, -v99, v102, v101
	v_fmac_f32_e32 v102, v103, v100
	v_fma_f32 v99, -v99, v102, v101
	v_div_fmas_f32 v99, v99, v100, v102
	v_div_fixup_f32 v98, v99, v98, 1.0
	v_pk_mul_f32 v[94:95], v[94:95], v[98:99] op_sel_hi:[1,0]
	v_pk_mul_f32 v[100:101], v[92:93], v[98:99] op_sel_hi:[1,0]
	v_pk_mul_f32 v[92:93], v[90:91], v[98:99] op_sel_hi:[1,0]
	v_cvt_pk_bf16_f32 v90, v94, v95
	v_mad_i64_i32 v[94:95], s[0:1], v178, s87, v[134:135]
	v_lshl_add_u64 v[94:95], v[94:95], 0, s[28:29]
	v_pk_mul_f32 v[96:97], v[96:97], v[98:99] op_sel_hi:[1,0]
	v_lshl_add_u64 v[94:95], v[94:95], 0, v[0:1]
	v_cvt_pk_bf16_f32 v91, v96, v97
	v_pk_mul_f32 v[86:87], v[86:87], v[98:99] op_sel_hi:[1,0]
	v_cvt_pk_bf16_f32 v92, v92, v93
	v_cvt_pk_bf16_f32 v93, v100, v101
	global_store_dwordx4 v[94:95], v[90:93], off
	v_pk_mul_f32 v[88:89], v[88:89], v[98:99] op_sel_hi:[1,0]
	s_nop 0
	v_pk_mul_f32 v[90:91], v[84:85], v[98:99] op_sel_hi:[1,0]
	v_pk_mul_f32 v[84:85], v[82:83], v[98:99] op_sel_hi:[1,0]
	v_cvt_pk_bf16_f32 v82, v86, v87
	v_mad_i64_i32 v[86:87], s[0:1], v178, s33, v[122:123]
	v_lshl_add_u64 v[86:87], v[86:87], 0, s[90:91]
	v_cvt_pk_bf16_f32 v83, v88, v89
	v_lshl_add_u64 v[86:87], v[86:87], 0, v[0:1]
	v_cvt_pk_bf16_f32 v84, v84, v85
	v_cvt_pk_bf16_f32 v85, v90, v91
	global_store_dwordx4 v[86:87], v[82:85], off
	s_nop 1
	v_mov_b32_e32 v82, v147
	v_mov_b32_e32 v83, v148
	v_mov_b32_e32 v147, v149
	v_pk_add_f32 v[82:83], v[82:83], v[146:147]
	s_nop 0
	v_add_f32_e32 v82, v82, v83
	v_fmamk_f32 v82, v82, 0x3b800000, v218
	v_cmp_gt_f32_e32 vcc, s77, v82
	v_mul_f32_e32 v83, 0x4f800000, v82
	s_nop 0
	v_cndmask_b32_e32 v82, v82, v83, vcc
	v_sqrt_f32_e32 v83, v82
	s_nop 0
	v_add_u32_e32 v84, -1, v83
	v_fma_f32 v85, -v84, v83, v82
	v_cmp_ge_f32_e64 s[0:1], 0, v85
	v_add_u32_e32 v85, 1, v83
	s_nop 0
	v_cndmask_b32_e64 v84, v83, v84, s[0:1]
	v_fma_f32 v83, -v85, v83, v82
	v_cmp_lt_f32_e64 s[0:1], 0, v83
	s_nop 1
	v_cndmask_b32_e64 v83, v84, v85, s[0:1]
	v_mul_f32_e32 v84, 0x37800000, v83
	v_cndmask_b32_e32 v83, v83, v84, vcc
	v_cmp_class_f32_e32 vcc, v82, v219
	s_nop 1
	v_cndmask_b32_e32 v82, v83, v82, vcc
	v_div_scale_f32 v83, s[0:1], v82, v82, 1.0
	v_rcp_f32_e32 v84, v83
	s_nop 0
	v_fma_f32 v85, -v83, v84, 1.0
	v_fmac_f32_e32 v84, v85, v84
	v_div_scale_f32 v85, vcc, 1.0, v82, 1.0
	v_mul_f32_e32 v86, v85, v84
	v_fma_f32 v87, -v83, v86, v85
	v_fmac_f32_e32 v86, v87, v84
	v_fma_f32 v83, -v83, v86, v85
	v_div_fmas_f32 v83, v83, v84, v86
	v_div_fixup_f32 v82, v83, v82, 1.0
	v_pk_mul_f32 v[78:79], v[78:79], v[82:83] op_sel_hi:[1,0]
	v_pk_mul_f32 v[84:85], v[76:77], v[82:83] op_sel_hi:[1,0]
	v_pk_mul_f32 v[76:77], v[74:75], v[82:83] op_sel_hi:[1,0]
	v_cvt_pk_bf16_f32 v74, v78, v79
	v_mad_i64_i32 v[78:79], s[0:1], v177, s87, v[134:135]
	v_lshl_add_u64 v[78:79], v[78:79], 0, s[28:29]
	v_pk_mul_f32 v[80:81], v[80:81], v[82:83] op_sel_hi:[1,0]
	v_lshl_add_u64 v[78:79], v[78:79], 0, v[0:1]
	v_cvt_pk_bf16_f32 v75, v80, v81
	v_pk_mul_f32 v[70:71], v[70:71], v[82:83] op_sel_hi:[1,0]
	v_cvt_pk_bf16_f32 v76, v76, v77
	v_cvt_pk_bf16_f32 v77, v84, v85
	global_store_dwordx4 v[78:79], v[74:77], off
	v_pk_mul_f32 v[72:73], v[72:73], v[82:83] op_sel_hi:[1,0]
	s_nop 0
	v_pk_mul_f32 v[74:75], v[68:69], v[82:83] op_sel_hi:[1,0]
	v_pk_mul_f32 v[68:69], v[66:67], v[82:83] op_sel_hi:[1,0]
	v_cvt_pk_bf16_f32 v66, v70, v71
	v_mad_i64_i32 v[70:71], s[0:1], v177, s33, v[122:123]
	v_lshl_add_u64 v[70:71], v[70:71], 0, s[90:91]
	v_cvt_pk_bf16_f32 v67, v72, v73
	v_lshl_add_u64 v[70:71], v[70:71], 0, v[0:1]
	v_cvt_pk_bf16_f32 v68, v68, v69
	v_cvt_pk_bf16_f32 v69, v74, v75
	global_store_dwordx4 v[70:71], v[66:69], off
	s_nop 1
	v_mov_b32_e32 v66, v143
	v_mov_b32_e32 v67, v144
	v_mov_b32_e32 v143, v145
	v_pk_add_f32 v[66:67], v[66:67], v[142:143]
	s_nop 0
	v_add_f32_e32 v66, v66, v67
	v_fmamk_f32 v66, v66, 0x3b800000, v218
	v_cmp_gt_f32_e32 vcc, s77, v66
	v_mul_f32_e32 v67, 0x4f800000, v66
	s_nop 0
	v_cndmask_b32_e32 v66, v66, v67, vcc
	v_sqrt_f32_e32 v67, v66
	s_nop 0
	v_add_u32_e32 v68, -1, v67
; __device__ __forceinline__ u32x4 pack8(const f32x4 v0, const f32x4 v1) { u32x4 w; w.x = cvt_pk_bf16(v0[0], v0[1]); w.y = cvt_pk_bf16(v0[2], v0[3]); w.z = cvt_pk_bf16(v1[0], v1[1]); w.w = cvt_pk_bf16(v1[2], v1[3]); return w; }
;     __device__ __forceinline__ void operator()(const f32x4 (&acc)[2][2][4][2], const Unit& u, int wr, int wc, int fr, int fq) const {
;     ...
;             for (int m = 0; m < 4; ++m) { const int row = row0 + ai * HALF + m * 16; const f32x4 a = q2[ai][m];
;                 const float s = 1.0f / sqrtf(((a[0] + a[1]) + (a[2] + a[3])) * (1.0f / 256.0f) + 1e-6f);
;                 *(u32x4*)(Kb + (size_t)row * ldk + 192 * u.pn + cin) = pack8(acc[ai][0][m][0] * s, acc[ai][0][m][1] * s);
;                 *(u32x4*)(Vb + (size_t)row * ldv + 128 * u.pn + cin) = pack8(acc[ai][1][m][0] * s, acc[ai][1][m][1] * s); }
	v_fma_f32 v69, -v68, v67, v66
	v_cmp_ge_f32_e64 s[0:1], 0, v69
	v_add_u32_e32 v69, 1, v67
	s_nop 0
	v_cndmask_b32_e64 v68, v67, v68, s[0:1]
	v_fma_f32 v67, -v69, v67, v66
	v_cmp_lt_f32_e64 s[0:1], 0, v67
	s_nop 1
	v_cndmask_b32_e64 v67, v68, v69, s[0:1]
	v_mul_f32_e32 v68, 0x37800000, v67
	v_cndmask_b32_e32 v67, v67, v68, vcc
	v_cmp_class_f32_e32 vcc, v66, v219
	s_nop 1
	v_cndmask_b32_e32 v66, v67, v66, vcc
	v_div_scale_f32 v67, s[0:1], v66, v66, 1.0
	v_rcp_f32_e32 v68, v67
	s_nop 0
	v_fma_f32 v69, -v67, v68, 1.0
	v_fmac_f32_e32 v68, v69, v68
	v_div_scale_f32 v69, vcc, 1.0, v66, 1.0
	v_mul_f32_e32 v70, v69, v68
	v_fma_f32 v71, -v67, v70, v69
	v_fmac_f32_e32 v70, v71, v68
	v_fma_f32 v67, -v67, v70, v69
	v_div_fmas_f32 v67, v67, v68, v70
	v_div_fixup_f32 v66, v67, v66, 1.0
	v_pk_mul_f32 v[62:63], v[62:63], v[66:67] op_sel_hi:[1,0]
	v_pk_mul_f32 v[68:69], v[60:61], v[66:67] op_sel_hi:[1,0]
	v_pk_mul_f32 v[60:61], v[58:59], v[66:67] op_sel_hi:[1,0]
	v_cvt_pk_bf16_f32 v58, v62, v63
	v_mad_i64_i32 v[62:63], s[0:1], v176, s87, v[134:135]
	v_lshl_add_u64 v[62:63], v[62:63], 0, s[28:29]
	v_pk_mul_f32 v[64:65], v[64:65], v[66:67] op_sel_hi:[1,0]
	v_lshl_add_u64 v[62:63], v[62:63], 0, v[0:1]
	v_cvt_pk_bf16_f32 v59, v64, v65
	v_pk_mul_f32 v[54:55], v[54:55], v[66:67] op_sel_hi:[1,0]
	v_cvt_pk_bf16_f32 v60, v60, v61
	v_cvt_pk_bf16_f32 v61, v68, v69
	global_store_dwordx4 v[62:63], v[58:61], off
	v_pk_mul_f32 v[56:57], v[56:57], v[66:67] op_sel_hi:[1,0]
	s_nop 0
	v_pk_mul_f32 v[58:59], v[52:53], v[66:67] op_sel_hi:[1,0]
	v_pk_mul_f32 v[52:53], v[50:51], v[66:67] op_sel_hi:[1,0]
	v_cvt_pk_bf16_f32 v50, v54, v55
	v_mad_i64_i32 v[54:55], s[0:1], v176, s33, v[122:123]
	v_lshl_add_u64 v[54:55], v[54:55], 0, s[90:91]
	v_cvt_pk_bf16_f32 v51, v56, v57
	v_lshl_add_u64 v[54:55], v[54:55], 0, v[0:1]
	v_cvt_pk_bf16_f32 v52, v52, v53
	v_cvt_pk_bf16_f32 v53, v58, v59
	global_store_dwordx4 v[54:55], v[50:53], off
	s_nop 1
	v_mov_b32_e32 v50, v131
	v_mov_b32_e32 v51, v132
	v_mov_b32_e32 v131, v133
	v_pk_add_f32 v[50:51], v[50:51], v[130:131]
	s_nop 0
	v_add_f32_e32 v50, v50, v51
	v_fmamk_f32 v50, v50, 0x3b800000, v218
	v_cmp_gt_f32_e32 vcc, s77, v50
	v_mul_f32_e32 v51, 0x4f800000, v50
	s_nop 0
	v_cndmask_b32_e32 v50, v50, v51, vcc
	v_sqrt_f32_e32 v51, v50
	s_nop 0
	v_add_u32_e32 v52, -1, v51
	v_fma_f32 v53, -v52, v51, v50
	v_cmp_ge_f32_e64 s[0:1], 0, v53
	v_add_u32_e32 v53, 1, v51
	s_nop 0
	v_cndmask_b32_e64 v52, v51, v52, s[0:1]
	v_fma_f32 v51, -v53, v51, v50
	v_cmp_lt_f32_e64 s[0:1], 0, v51
	s_nop 1
	v_cndmask_b32_e64 v51, v52, v53, s[0:1]
	v_mul_f32_e32 v52, 0x37800000, v51
	v_cndmask_b32_e32 v51, v51, v52, vcc
	v_cmp_class_f32_e32 vcc, v50, v219
	s_nop 1
	v_cndmask_b32_e32 v50, v51, v50, vcc
	v_div_scale_f32 v51, s[0:1], v50, v50, 1.0
	v_rcp_f32_e32 v52, v51
	s_nop 0
	v_fma_f32 v53, -v51, v52, 1.0
	v_fmac_f32_e32 v52, v53, v52
	v_div_scale_f32 v53, vcc, 1.0, v50, 1.0
	v_mul_f32_e32 v54, v53, v52
	v_fma_f32 v55, -v51, v54, v53
	v_fmac_f32_e32 v54, v55, v52
	v_fma_f32 v51, -v51, v54, v53
	v_div_fmas_f32 v51, v51, v52, v54
	v_div_fixup_f32 v50, v51, v50, 1.0
	v_pk_mul_f32 v[46:47], v[46:47], v[50:51] op_sel_hi:[1,0]
	v_pk_mul_f32 v[52:53], v[44:45], v[50:51] op_sel_hi:[1,0]
	v_pk_mul_f32 v[44:45], v[42:43], v[50:51] op_sel_hi:[1,0]
	v_cvt_pk_bf16_f32 v42, v46, v47
	v_mad_i64_i32 v[46:47], s[0:1], v175, s87, v[134:135]
	v_lshl_add_u64 v[46:47], v[46:47], 0, s[28:29]
	v_pk_mul_f32 v[48:49], v[48:49], v[50:51] op_sel_hi:[1,0]
	v_lshl_add_u64 v[46:47], v[46:47], 0, v[0:1]
	v_cvt_pk_bf16_f32 v43, v48, v49
	v_pk_mul_f32 v[38:39], v[38:39], v[50:51] op_sel_hi:[1,0]
	v_cvt_pk_bf16_f32 v44, v44, v45
	v_cvt_pk_bf16_f32 v45, v52, v53
	global_store_dwordx4 v[46:47], v[42:45], off
	v_pk_mul_f32 v[40:41], v[40:41], v[50:51] op_sel_hi:[1,0]
	s_nop 0
	v_pk_mul_f32 v[42:43], v[36:37], v[50:51] op_sel_hi:[1,0]
	v_pk_mul_f32 v[36:37], v[34:35], v[50:51] op_sel_hi:[1,0]
	v_cvt_pk_bf16_f32 v34, v38, v39
	v_mad_i64_i32 v[38:39], s[0:1], v175, s33, v[122:123]
	v_lshl_add_u64 v[38:39], v[38:39], 0, s[90:91]
	v_cvt_pk_bf16_f32 v35, v40, v41
	v_lshl_add_u64 v[38:39], v[38:39], 0, v[0:1]
	v_cvt_pk_bf16_f32 v36, v36, v37
	v_cvt_pk_bf16_f32 v37, v42, v43
	global_store_dwordx4 v[38:39], v[34:37], off
	s_nop 1
	v_mov_b32_e32 v34, v119
	v_mov_b32_e32 v35, v120
	v_mov_b32_e32 v119, v121
	v_pk_add_f32 v[34:35], v[34:35], v[118:119]
	s_nop 0
	v_add_f32_e32 v34, v34, v35
	v_fmamk_f32 v34, v34, 0x3b800000, v218
	v_cmp_gt_f32_e32 vcc, s77, v34
; __device__ __forceinline__ u32x4 pack8(const f32x4 v0, const f32x4 v1) { u32x4 w; w.x = cvt_pk_bf16(v0[0], v0[1]); w.y = cvt_pk_bf16(v0[2], v0[3]); w.z = cvt_pk_bf16(v1[0], v1[1]); w.w = cvt_pk_bf16(v1[2], v1[3]); return w; }
; #define PG8_BAR __builtin_amdgcn_s_barrier()
;     __device__ __forceinline__ void operator()(const f32x4 (&acc)[2][2][4][2], const Unit& u, int wr, int wc, int fr, int fq) const {
;     ...
;             for (int m = 0; m < 4; ++m) { const int row = row0 + ai * HALF + m * 16; const f32x4 a = q2[ai][m];
;                 const float s = 1.0f / sqrtf(((a[0] + a[1]) + (a[2] + a[3])) * (1.0f / 256.0f) + 1e-6f);
;                 *(u32x4*)(Kb + (size_t)row * ldk + 192 * u.pn + cin) = pack8(acc[ai][0][m][0] * s, acc[ai][0][m][1] * s);
;                 *(u32x4*)(Vb + (size_t)row * ldv + 128 * u.pn + cin) = pack8(acc[ai][1][m][0] * s, acc[ai][1][m][1] * s); }
; template <class Epi, class Sched, bool ALIGN_EPI = false, bool SP2 = false>
; __device__ __forceinline__ void gemm_phase(PG8_LAS unsigned char* lds, const Gemm g, const Sched& S, const Epi& E) {
;     ...
;         if (!has_next) break;
; #pragma unroll
;         for (int a = 0; a < 2; ++a)
; #pragma unroll
;             for (int b = 0; b < 2; ++b)
; #pragma unroll
;                 for (int m = 0; m < 4; ++m)
; #pragma unroll
;                     for (int n = 0; n < 2; ++n) acc[a][b][m][n] = (f32x4){0.f, 0.f, 0.f, 0.f};
;         cur = nxt; cA = nA; cB = nB; ++ui;
;         if constexpr (ALIGN_EPI) { if (wr == 1) PG8_BAR; }
	v_mul_f32_e32 v35, 0x4f800000, v34
	s_nop 0
	v_cndmask_b32_e32 v34, v34, v35, vcc
	v_sqrt_f32_e32 v35, v34
	s_nop 0
	v_add_u32_e32 v36, -1, v35
	v_fma_f32 v37, -v36, v35, v34
	v_cmp_ge_f32_e64 s[0:1], 0, v37
	v_add_u32_e32 v37, 1, v35
	s_nop 0
	v_cndmask_b32_e64 v36, v35, v36, s[0:1]
	v_fma_f32 v35, -v37, v35, v34
	v_cmp_lt_f32_e64 s[0:1], 0, v35
	s_nop 1
	v_cndmask_b32_e64 v35, v36, v37, s[0:1]
	v_mul_f32_e32 v36, 0x37800000, v35
	v_cndmask_b32_e32 v35, v35, v36, vcc
	v_cmp_class_f32_e32 vcc, v34, v219
	s_nop 1
	v_cndmask_b32_e32 v34, v35, v34, vcc
	v_div_scale_f32 v35, s[0:1], v34, v34, 1.0
	v_rcp_f32_e32 v36, v35
	s_nop 0
	v_fma_f32 v37, -v35, v36, 1.0
	v_fmac_f32_e32 v36, v37, v36
	v_div_scale_f32 v37, vcc, 1.0, v34, 1.0
	v_mul_f32_e32 v38, v37, v36
	v_fma_f32 v39, -v35, v38, v37
	v_fmac_f32_e32 v38, v39, v36
	v_fma_f32 v35, -v35, v38, v37
	v_div_fmas_f32 v35, v35, v36, v38
	v_div_fixup_f32 v34, v35, v34, 1.0
	v_pk_mul_f32 v[30:31], v[30:31], v[34:35] op_sel_hi:[1,0]
	v_pk_mul_f32 v[36:37], v[28:29], v[34:35] op_sel_hi:[1,0]
	v_pk_mul_f32 v[28:29], v[26:27], v[34:35] op_sel_hi:[1,0]
	v_cvt_pk_bf16_f32 v26, v30, v31
	v_mad_i64_i32 v[30:31], s[0:1], v174, s87, v[134:135]
	v_lshl_add_u64 v[30:31], v[30:31], 0, s[28:29]
	v_pk_mul_f32 v[32:33], v[32:33], v[34:35] op_sel_hi:[1,0]
	v_lshl_add_u64 v[30:31], v[30:31], 0, v[0:1]
	v_cvt_pk_bf16_f32 v27, v32, v33
	v_pk_mul_f32 v[22:23], v[22:23], v[34:35] op_sel_hi:[1,0]
	v_cvt_pk_bf16_f32 v28, v28, v29
	v_cvt_pk_bf16_f32 v29, v36, v37
	global_store_dwordx4 v[30:31], v[26:29], off
	v_pk_mul_f32 v[24:25], v[24:25], v[34:35] op_sel_hi:[1,0]
	s_nop 0
	v_pk_mul_f32 v[26:27], v[20:21], v[34:35] op_sel_hi:[1,0]
	v_pk_mul_f32 v[20:21], v[18:19], v[34:35] op_sel_hi:[1,0]
	v_cvt_pk_bf16_f32 v18, v22, v23
	v_mad_i64_i32 v[22:23], s[0:1], v174, s33, v[122:123]
	v_lshl_add_u64 v[22:23], v[22:23], 0, s[90:91]
	v_cvt_pk_bf16_f32 v19, v24, v25
	v_lshl_add_u64 v[22:23], v[22:23], 0, v[0:1]
	v_cvt_pk_bf16_f32 v20, v20, v21
	v_cvt_pk_bf16_f32 v21, v26, v27
	global_store_dwordx4 v[22:23], v[18:21], off
	s_nop 1
	v_mov_b32_e32 v18, v115
	v_mov_b32_e32 v19, v116
	v_mov_b32_e32 v115, v117
	v_pk_add_f32 v[18:19], v[18:19], v[114:115]
	s_nop 0
	v_add_f32_e32 v18, v18, v19
	v_fmamk_f32 v18, v18, 0x3b800000, v218
	v_cmp_gt_f32_e32 vcc, s77, v18
	v_mul_f32_e32 v19, 0x4f800000, v18
	s_nop 0
	v_cndmask_b32_e32 v18, v18, v19, vcc
	v_sqrt_f32_e32 v19, v18
	s_nop 0
	v_add_u32_e32 v20, -1, v19
	v_fma_f32 v21, -v20, v19, v18
	v_cmp_ge_f32_e64 s[0:1], 0, v21
	v_add_u32_e32 v21, 1, v19
	s_nop 0
	v_cndmask_b32_e64 v20, v19, v20, s[0:1]
	v_fma_f32 v19, -v21, v19, v18
	v_cmp_lt_f32_e64 s[0:1], 0, v19
	s_nop 1
	v_cndmask_b32_e64 v19, v20, v21, s[0:1]
	v_mul_f32_e32 v20, 0x37800000, v19
	v_cndmask_b32_e32 v19, v19, v20, vcc
	v_cmp_class_f32_e32 vcc, v18, v219
	s_nop 1
	v_cndmask_b32_e32 v18, v19, v18, vcc
	v_div_scale_f32 v19, s[0:1], v18, v18, 1.0
	v_rcp_f32_e32 v20, v19
	s_nop 0
	v_fma_f32 v21, -v19, v20, 1.0
	v_fmac_f32_e32 v20, v21, v20
	v_div_scale_f32 v21, vcc, 1.0, v18, 1.0
	v_mul_f32_e32 v22, v21, v20
	v_fma_f32 v23, -v19, v22, v21
	v_fmac_f32_e32 v22, v23, v20
	v_fma_f32 v19, -v19, v22, v21
	v_div_fmas_f32 v19, v19, v20, v22
	v_div_fixup_f32 v18, v19, v18, 1.0
	v_pk_mul_f32 v[14:15], v[14:15], v[18:19] op_sel_hi:[1,0]
	v_pk_mul_f32 v[20:21], v[12:13], v[18:19] op_sel_hi:[1,0]
	v_pk_mul_f32 v[12:13], v[10:11], v[18:19] op_sel_hi:[1,0]
	v_cvt_pk_bf16_f32 v10, v14, v15
	v_mad_i64_i32 v[14:15], s[0:1], v173, s87, v[134:135]
	v_lshl_add_u64 v[14:15], v[14:15], 0, s[28:29]
	v_pk_mul_f32 v[16:17], v[16:17], v[18:19] op_sel_hi:[1,0]
	v_lshl_add_u64 v[14:15], v[14:15], 0, v[0:1]
	v_cvt_pk_bf16_f32 v11, v16, v17
	v_pk_mul_f32 v[6:7], v[6:7], v[18:19] op_sel_hi:[1,0]
	v_cvt_pk_bf16_f32 v12, v12, v13
	v_cvt_pk_bf16_f32 v13, v20, v21
	global_store_dwordx4 v[14:15], v[10:13], off
	s_andn2_b64 vcc, exec, s[26:27]
	v_pk_mul_f32 v[8:9], v[8:9], v[18:19] op_sel_hi:[1,0]
	v_pk_mul_f32 v[10:11], v[4:5], v[18:19] op_sel_hi:[1,0]
	v_pk_mul_f32 v[4:5], v[2:3], v[18:19] op_sel_hi:[1,0]
	v_cvt_pk_bf16_f32 v2, v6, v7
	v_mad_i64_i32 v[6:7], s[0:1], v173, s33, v[122:123]
	v_lshl_add_u64 v[6:7], v[6:7], 0, s[90:91]
	v_lshl_add_u64 v[6:7], v[6:7], 0, v[0:1]
	s_mov_b64 s[0:1], -1
	v_cvt_pk_bf16_f32 v3, v8, v9
	v_cvt_pk_bf16_f32 v4, v4, v5
	v_cvt_pk_bf16_f32 v5, v10, v11
	global_store_dwordx4 v[6:7], v[2:5], off
	s_cbranch_vccnz .LBB0_674
	s_andn2_b64 vcc, exec, s[8:9]
	s_cbranch_vccnz .LBB0_673
	s_barrier
	s_branch .LBB0_673

; __device__ __forceinline__ int crow(int r, int hi) { return (r & 3) + 8 * (r >> 2) + 4 * hi; }
; __device__ __forceinline__ unsigned cvtpk(float lo, float hi) { unsigned r; asm volatile("v_cvt_pk_bf16_f32 %0, %1, %2" : "=v"(r) : "v"(lo), "v"(hi)); return r; }
; template <int MODE>
; __device__ __forceinline__ void attn_unit(unsigned char* ws_, const float* rpb, const float* sink, int l, int h, int qb, int kvq, unsigned char* lds_g) {
;     ...
;   { auto rr = __builtin_amdgcn_permlane32_swap(__float_as_uint(l_reg), __float_as_uint(l_reg), false, false); l_reg = __uint_as_float(rr[0]) + __uint_as_float(rr[1]); }
;   if (hi == 0) li_l[r32] = l_reg; asm volatile("s_waitcnt lgkmcnt(0)" ::: "memory");
;   bf16_t* Ow; int ldo;
;   if (MODE == 1) { Ow = (bf16_t*)(ws_ + WS_PART) + ((size_t)kvq * S + q0 + wid * 32) * VLD + 128 * h + r32; ldo = VLD;
;     if (hi == 0) { float* st = (float*)(ws_ + WS_STAT) + ((size_t)(kvq * 6 + h) * S + qi) * 2; st[0] = m_reg; st[1] = l_reg; } }
;   else { Ow = (bf16_t*)(ws_ + WS_Y) + (size_t)(q0 + wid * 32) * DM + ycol + r32; ldo = DM; }
; #pragma unroll
;   for (int r = 0; r < 16; ++r) { const int orow = crow(r, hi); const float rl = __builtin_amdgcn_rcpf(li_l[orow]);
; #pragma unroll
;     for (int d0 = 0; d0 < 4; ++d0) Ow[(size_t)orow * ldo + d0 * 32] = (bf16_t)(cvtpk(o[d0][r] * rl, 0.f) & 0xffffu); }
.LBB0_774:
	v_mov_b32_e32 v0, v174
	s_nop 1
	v_permlane32_swap_b32_e32 v174, v0
	v_cmp_gt_u32_e32 vcc, 32, v145
	s_and_saveexec_b64 s[0:1], vcc
	v_add_f32_e32 v0, v174, v0
	v_lshl_add_u32 v2, v159, 2, v147
	ds_write_b32 v2, v0
	s_or_b64 exec, exec, s[0:1]
	s_waitcnt lgkmcnt(0)
	v_lshl_add_u32 v6, v158, 4, v147
	ds_read_b32 v4, v6
	v_ashrrev_i32_e32 v145, 31, v144
	v_lshlrev_b64 v[2:3], 12, v[144:145]
	v_lshl_add_u64 v[2:3], s[94:95], 0, v[2:3]
	v_lshl_add_u64 v[2:3], s[90:91], 1, v[2:3]
	s_waitcnt lgkmcnt(0)
	v_rcp_f32_e32 v7, v4
	v_lshlrev_b32_e32 v0, 1, v159
	v_lshl_add_u64 v[2:3], v[2:3], 0, v[0:1]
	s_mov_b64 s[0:1], 0x18628000
	v_lshl_add_u64 v[2:3], v[2:3], 0, s[0:1]
	v_lshlrev_b32_e32 v0, 14, v158
	v_mul_f32_e32 v8, v64, v7
	v_lshl_add_u64 v[4:5], v[2:3], 0, v[0:1]
	v_cvt_pk_bf16_f32 v8, v8, v1
	global_store_short v[4:5], v8, off
	v_mul_f32_e32 v8, v48, v7
	v_cvt_pk_bf16_f32 v8, v8, v1
	global_store_short v[4:5], v8, off offset:64
	v_mul_f32_e32 v8, v32, v7
	v_cvt_pk_bf16_f32 v8, v8, v1
	v_mul_f32_e32 v7, v16, v7
	global_store_short v[4:5], v8, off offset:128
	v_cvt_pk_bf16_f32 v7, v7, v1
	ds_read_b32 v8, v6 offset:4
	global_store_short v[4:5], v7, off offset:192
	v_or_b32_e32 v4, 0x1000, v0
	v_mov_b32_e32 v5, v1
	v_lshl_add_u64 v[4:5], v[2:3], 0, v[4:5]
	s_waitcnt lgkmcnt(0)
	v_rcp_f32_e32 v7, v8
	s_nop 0
	v_mul_f32_e32 v8, v65, v7
	v_cvt_pk_bf16_f32 v8, v8, v1
	global_store_short v[4:5], v8, off
	v_mul_f32_e32 v8, v49, v7
	v_cvt_pk_bf16_f32 v8, v8, v1
	global_store_short v[4:5], v8, off offset:64
	v_mul_f32_e32 v8, v33, v7
	v_cvt_pk_bf16_f32 v8, v8, v1
	v_mul_f32_e32 v7, v17, v7
	global_store_short v[4:5], v8, off offset:128
	v_cvt_pk_bf16_f32 v7, v7, v1
	ds_read_b32 v8, v6 offset:8
	global_store_short v[4:5], v7, off offset:192
	v_or_b32_e32 v4, 0x2000, v0
	v_mov_b32_e32 v5, v1
	v_lshl_add_u64 v[4:5], v[2:3], 0, v[4:5]
	s_waitcnt lgkmcnt(0)
	v_rcp_f32_e32 v7, v8
	s_nop 0
	v_mul_f32_e32 v8, v66, v7
	v_cvt_pk_bf16_f32 v8, v8, v1
	global_store_short v[4:5], v8, off
	v_mul_f32_e32 v8, v50, v7
	v_cvt_pk_bf16_f32 v8, v8, v1
	global_store_short v[4:5], v8, off offset:64
	v_mul_f32_e32 v8, v34, v7
	v_cvt_pk_bf16_f32 v8, v8, v1
	v_mul_f32_e32 v7, v18, v7
	global_store_short v[4:5], v8, off offset:128
	v_cvt_pk_bf16_f32 v7, v7, v1
	ds_read_b32 v8, v6 offset:12
	global_store_short v[4:5], v7, off offset:192
	v_or_b32_e32 v4, 0x3000, v0
	v_mov_b32_e32 v5, v1
	v_lshl_add_u64 v[4:5], v[2:3], 0, v[4:5]
	s_waitcnt lgkmcnt(0)
	v_rcp_f32_e32 v7, v8
	s_nop 0
	v_mul_f32_e32 v8, v67, v7
	v_cvt_pk_bf16_f32 v8, v8, v1
	global_store_short v[4:5], v8, off
	v_mul_f32_e32 v8, v51, v7
	v_cvt_pk_bf16_f32 v8, v8, v1
	global_store_short v[4:5], v8, off offset:64
	v_mul_f32_e32 v8, v35, v7
	v_cvt_pk_bf16_f32 v8, v8, v1
	v_mul_f32_e32 v7, v19, v7
	global_store_short v[4:5], v8, off offset:128
	v_cvt_pk_bf16_f32 v7, v7, v1
	ds_read_b32 v8, v6 offset:32
	global_store_short v[4:5], v7, off offset:192
	v_or_b32_e32 v4, 0x8000, v0
	v_mov_b32_e32 v5, v1
	v_lshl_add_u64 v[4:5], v[2:3], 0, v[4:5]
	s_waitcnt lgkmcnt(0)
	v_rcp_f32_e32 v7, v8
	s_nop 0
	v_mul_f32_e32 v8, v68, v7
	v_cvt_pk_bf16_f32 v8, v8, v1
	global_store_short v[4:5], v8, off
	v_mul_f32_e32 v8, v52, v7
	v_cvt_pk_bf16_f32 v8, v8, v1
	global_store_short v[4:5], v8, off offset:64
	v_mul_f32_e32 v8, v36, v7
	v_cvt_pk_bf16_f32 v8, v8, v1
	v_mul_f32_e32 v7, v20, v7
	global_store_short v[4:5], v8, off offset:128
	v_cvt_pk_bf16_f32 v7, v7, v1
	ds_read_b32 v8, v6 offset:36
	global_store_short v[4:5], v7, off offset:192
	v_or_b32_e32 v4, 0x9000, v0
	v_mov_b32_e32 v5, v1
	v_lshl_add_u64 v[4:5], v[2:3], 0, v[4:5]
	s_waitcnt lgkmcnt(0)
	v_rcp_f32_e32 v7, v8
	s_nop 0
	v_mul_f32_e32 v8, v69, v7
	v_cvt_pk_bf16_f32 v8, v8, v1
	global_store_short v[4:5], v8, off
	v_mul_f32_e32 v8, v53, v7
	v_cvt_pk_bf16_f32 v8, v8, v1
	global_store_short v[4:5], v8, off offset:64
	v_mul_f32_e32 v8, v37, v7
	v_cvt_pk_bf16_f32 v8, v8, v1
	v_mul_f32_e32 v7, v21, v7
	global_store_short v[4:5], v8, off offset:128
	v_cvt_pk_bf16_f32 v7, v7, v1
	ds_read_b32 v8, v6 offset:40
	global_store_short v[4:5], v7, off offset:192
	v_or_b32_e32 v4, 0xa000, v0
	v_mov_b32_e32 v5, v1
	v_lshl_add_u64 v[4:5], v[2:3], 0, v[4:5]
	s_waitcnt lgkmcnt(0)
	v_rcp_f32_e32 v7, v8
	s_nop 0
	v_mul_f32_e32 v8, v70, v7
	v_cvt_pk_bf16_f32 v8, v8, v1
	global_store_short v[4:5], v8, off
	v_mul_f32_e32 v8, v54, v7
	v_cvt_pk_bf16_f32 v8, v8, v1
	global_store_short v[4:5], v8, off offset:64
	v_mul_f32_e32 v8, v38, v7
	v_cvt_pk_bf16_f32 v8, v8, v1
	v_mul_f32_e32 v7, v22, v7
	global_store_short v[4:5], v8, off offset:128
	v_cvt_pk_bf16_f32 v7, v7, v1
	ds_read_b32 v8, v6 offset:44
	global_store_short v[4:5], v7, off offset:192
	v_or_b32_e32 v4, 0xb000, v0
	v_mov_b32_e32 v5, v1
	v_lshl_add_u64 v[4:5], v[2:3], 0, v[4:5]
	s_waitcnt lgkmcnt(0)
; __device__ __forceinline__ int crow(int r, int hi) { return (r & 3) + 8 * (r >> 2) + 4 * hi; }
; __device__ __forceinline__ unsigned cvtpk(float lo, float hi) { unsigned r; asm volatile("v_cvt_pk_bf16_f32 %0, %1, %2" : "=v"(r) : "v"(lo), "v"(hi)); return r; }
; template <int MODE>
; __device__ __forceinline__ void attn_unit(unsigned char* ws_, const float* rpb, const float* sink, int l, int h, int qb, int kvq, unsigned char* lds_g) {
;     ...
;   { auto rr = __builtin_amdgcn_permlane32_swap(__float_as_uint(l_reg), __float_as_uint(l_reg), false, false); l_reg = __uint_as_float(rr[0]) + __uint_as_float(rr[1]); }
;   if (hi == 0) li_l[r32] = l_reg; asm volatile("s_waitcnt lgkmcnt(0)" ::: "memory");
;   bf16_t* Ow; int ldo;
;   if (MODE == 1) { Ow = (bf16_t*)(ws_ + WS_PART) + ((size_t)kvq * S + q0 + wid * 32) * VLD + 128 * h + r32; ldo = VLD;
;     if (hi == 0) { float* st = (float*)(ws_ + WS_STAT) + ((size_t)(kvq * 6 + h) * S + qi) * 2; st[0] = m_reg; st[1] = l_reg; } }
;   else { Ow = (bf16_t*)(ws_ + WS_Y) + (size_t)(q0 + wid * 32) * DM + ycol + r32; ldo = DM; }
; #pragma unroll
;   for (int r = 0; r < 16; ++r) { const int orow = crow(r, hi); const float rl = __builtin_amdgcn_rcpf(li_l[orow]);
; #pragma unroll
;     for (int d0 = 0; d0 < 4; ++d0) Ow[(size_t)orow * ldo + d0 * 32] = (bf16_t)(cvtpk(o[d0][r] * rl, 0.f) & 0xffffu); }
;   asm volatile("s_waitcnt lgkmcnt(0)" ::: "memory");
;   __syncthreads();
	v_rcp_f32_e32 v7, v8
	s_nop 0
	v_mul_f32_e32 v8, v71, v7
	v_cvt_pk_bf16_f32 v8, v8, v1
	global_store_short v[4:5], v8, off
	v_mul_f32_e32 v8, v55, v7
	v_cvt_pk_bf16_f32 v8, v8, v1
	global_store_short v[4:5], v8, off offset:64
	v_mul_f32_e32 v8, v39, v7
	v_cvt_pk_bf16_f32 v8, v8, v1
	v_mul_f32_e32 v7, v23, v7
	global_store_short v[4:5], v8, off offset:128
	v_cvt_pk_bf16_f32 v7, v7, v1
	ds_read_b32 v8, v6 offset:64
	global_store_short v[4:5], v7, off offset:192
	v_or_b32_e32 v4, 0x10000, v0
	v_mov_b32_e32 v5, v1
	v_lshl_add_u64 v[4:5], v[2:3], 0, v[4:5]
	s_waitcnt lgkmcnt(0)
	v_rcp_f32_e32 v7, v8
	s_nop 0
	v_mul_f32_e32 v8, v72, v7
	v_cvt_pk_bf16_f32 v8, v8, v1
	global_store_short v[4:5], v8, off
	v_mul_f32_e32 v8, v56, v7
	v_cvt_pk_bf16_f32 v8, v8, v1
	global_store_short v[4:5], v8, off offset:64
	v_mul_f32_e32 v8, v40, v7
	v_cvt_pk_bf16_f32 v8, v8, v1
	v_mul_f32_e32 v7, v24, v7
	global_store_short v[4:5], v8, off offset:128
	v_cvt_pk_bf16_f32 v7, v7, v1
	ds_read_b32 v8, v6 offset:68
	global_store_short v[4:5], v7, off offset:192
	v_or_b32_e32 v4, 0x11000, v0
	v_mov_b32_e32 v5, v1
	v_lshl_add_u64 v[4:5], v[2:3], 0, v[4:5]
	s_waitcnt lgkmcnt(0)
	v_rcp_f32_e32 v7, v8
	s_nop 0
	v_mul_f32_e32 v8, v73, v7
	v_cvt_pk_bf16_f32 v8, v8, v1
	global_store_short v[4:5], v8, off
	v_mul_f32_e32 v8, v57, v7
	v_cvt_pk_bf16_f32 v8, v8, v1
	global_store_short v[4:5], v8, off offset:64
	v_mul_f32_e32 v8, v41, v7
	v_cvt_pk_bf16_f32 v8, v8, v1
	v_mul_f32_e32 v7, v25, v7
	global_store_short v[4:5], v8, off offset:128
	v_cvt_pk_bf16_f32 v7, v7, v1
	ds_read_b32 v8, v6 offset:72
	global_store_short v[4:5], v7, off offset:192
	v_or_b32_e32 v4, 0x12000, v0
	v_mov_b32_e32 v5, v1
	v_lshl_add_u64 v[4:5], v[2:3], 0, v[4:5]
	s_waitcnt lgkmcnt(0)
	v_rcp_f32_e32 v7, v8
	s_nop 0
	v_mul_f32_e32 v8, v74, v7
	v_cvt_pk_bf16_f32 v8, v8, v1
	global_store_short v[4:5], v8, off
	v_mul_f32_e32 v8, v58, v7
	v_cvt_pk_bf16_f32 v8, v8, v1
	global_store_short v[4:5], v8, off offset:64
	v_mul_f32_e32 v8, v42, v7
	v_cvt_pk_bf16_f32 v8, v8, v1
	v_mul_f32_e32 v7, v26, v7
	global_store_short v[4:5], v8, off offset:128
	v_cvt_pk_bf16_f32 v7, v7, v1
	ds_read_b32 v8, v6 offset:76
	global_store_short v[4:5], v7, off offset:192
	v_or_b32_e32 v4, 0x13000, v0
	v_mov_b32_e32 v5, v1
	v_lshl_add_u64 v[4:5], v[2:3], 0, v[4:5]
	s_waitcnt lgkmcnt(0)
	v_rcp_f32_e32 v7, v8
	s_nop 0
	v_mul_f32_e32 v8, v75, v7
	v_cvt_pk_bf16_f32 v8, v8, v1
	global_store_short v[4:5], v8, off
	v_mul_f32_e32 v8, v59, v7
	v_cvt_pk_bf16_f32 v8, v8, v1
	global_store_short v[4:5], v8, off offset:64
	v_mul_f32_e32 v8, v43, v7
	v_cvt_pk_bf16_f32 v8, v8, v1
	v_mul_f32_e32 v7, v27, v7
	global_store_short v[4:5], v8, off offset:128
	v_cvt_pk_bf16_f32 v7, v7, v1
	ds_read_b32 v8, v6 offset:96
	global_store_short v[4:5], v7, off offset:192
	v_or_b32_e32 v4, 0x18000, v0
	v_mov_b32_e32 v5, v1
	v_lshl_add_u64 v[4:5], v[2:3], 0, v[4:5]
	s_waitcnt lgkmcnt(0)
	v_rcp_f32_e32 v7, v8
	s_nop 0
	v_mul_f32_e32 v8, v76, v7
	v_cvt_pk_bf16_f32 v8, v8, v1
	global_store_short v[4:5], v8, off
	v_mul_f32_e32 v8, v60, v7
	v_cvt_pk_bf16_f32 v8, v8, v1
	global_store_short v[4:5], v8, off offset:64
	v_mul_f32_e32 v8, v44, v7
	v_cvt_pk_bf16_f32 v8, v8, v1
	v_mul_f32_e32 v7, v28, v7
	global_store_short v[4:5], v8, off offset:128
	v_cvt_pk_bf16_f32 v7, v7, v1
	ds_read_b32 v8, v6 offset:100
	global_store_short v[4:5], v7, off offset:192
	v_or_b32_e32 v4, 0x19000, v0
	v_mov_b32_e32 v5, v1
	v_lshl_add_u64 v[4:5], v[2:3], 0, v[4:5]
	s_waitcnt lgkmcnt(0)
	v_rcp_f32_e32 v7, v8
	s_nop 0
	v_mul_f32_e32 v8, v77, v7
	v_cvt_pk_bf16_f32 v8, v8, v1
	global_store_short v[4:5], v8, off
	v_mul_f32_e32 v8, v61, v7
	v_cvt_pk_bf16_f32 v8, v8, v1
	global_store_short v[4:5], v8, off offset:64
	v_mul_f32_e32 v8, v45, v7
	v_cvt_pk_bf16_f32 v8, v8, v1
	v_mul_f32_e32 v7, v29, v7
	global_store_short v[4:5], v8, off offset:128
	v_cvt_pk_bf16_f32 v7, v7, v1
	ds_read_b32 v8, v6 offset:104
	global_store_short v[4:5], v7, off offset:192
	v_or_b32_e32 v4, 0x1a000, v0
	v_mov_b32_e32 v5, v1
	v_lshl_add_u64 v[4:5], v[2:3], 0, v[4:5]
	s_waitcnt lgkmcnt(0)
	v_rcp_f32_e32 v7, v8
	v_or_b32_e32 v0, 0x1b000, v0
	v_lshl_add_u64 v[2:3], v[2:3], 0, v[0:1]
	v_mul_f32_e32 v8, v78, v7
	v_cvt_pk_bf16_f32 v8, v8, v1
	global_store_short v[4:5], v8, off
	v_mul_f32_e32 v8, v62, v7
	v_cvt_pk_bf16_f32 v8, v8, v1
	global_store_short v[4:5], v8, off offset:64
	v_mul_f32_e32 v8, v46, v7
	v_mul_f32_e32 v7, v30, v7
	v_cvt_pk_bf16_f32 v8, v8, v1
	global_store_short v[4:5], v8, off offset:128
	v_cvt_pk_bf16_f32 v7, v7, v1
	ds_read_b32 v6, v6 offset:108
	global_store_short v[4:5], v7, off offset:192
	s_waitcnt lgkmcnt(0)
	v_rcp_f32_e32 v6, v6
	s_nop 0
	v_mul_f32_e32 v0, v79, v6
	v_cvt_pk_bf16_f32 v0, v0, v1
	global_store_short v[2:3], v0, off
	v_mul_f32_e32 v0, v63, v6
	v_cvt_pk_bf16_f32 v0, v0, v1
	global_store_short v[2:3], v0, off offset:64
	v_mul_f32_e32 v0, v47, v6
	v_cvt_pk_bf16_f32 v0, v0, v1
	global_store_short v[2:3], v0, off offset:128
	v_mul_f32_e32 v0, v31, v6
	v_cvt_pk_bf16_f32 v0, v0, v1
	global_store_short v[2:3], v0, off offset:192
	s_waitcnt lgkmcnt(0)
	s_barrier

; __device__ __forceinline__ int crow(int r, int hi) { return (r & 3) + 8 * (r >> 2) + 4 * hi; }
; __device__ __forceinline__ unsigned cvtpk(float lo, float hi) { unsigned r; asm volatile("v_cvt_pk_bf16_f32 %0, %1, %2" : "=v"(r) : "v"(lo), "v"(hi)); return r; }
; template <int MODE>
; __device__ __forceinline__ void attn_unit(unsigned char* ws_, const float* rpb, const float* sink, int l, int h, int qb, int kvq, unsigned char* lds_g) {
;     ...
;   { auto rr = __builtin_amdgcn_permlane32_swap(__float_as_uint(l_reg), __float_as_uint(l_reg), false, false); l_reg = __uint_as_float(rr[0]) + __uint_as_float(rr[1]); }
;   if (hi == 0) li_l[r32] = l_reg; asm volatile("s_waitcnt lgkmcnt(0)" ::: "memory");
;   bf16_t* Ow; int ldo;
;   if (MODE == 1) { Ow = (bf16_t*)(ws_ + WS_PART) + ((size_t)kvq * S + q0 + wid * 32) * VLD + 128 * h + r32; ldo = VLD;
;     if (hi == 0) { float* st = (float*)(ws_ + WS_STAT) + ((size_t)(kvq * 6 + h) * S + qi) * 2; st[0] = m_reg; st[1] = l_reg; } }
;   else { Ow = (bf16_t*)(ws_ + WS_Y) + (size_t)(q0 + wid * 32) * DM + ycol + r32; ldo = DM; }
; #pragma unroll
;   for (int r = 0; r < 16; ++r) { const int orow = crow(r, hi); const float rl = __builtin_amdgcn_rcpf(li_l[orow]);
; #pragma unroll
;     for (int d0 = 0; d0 < 4; ++d0) Ow[(size_t)orow * ldo + d0 * 32] = (bf16_t)(cvtpk(o[d0][r] * rl, 0.f) & 0xffffu); }
.LBB0_778:
	s_or_b64 exec, exec, s[0:1]
	s_waitcnt lgkmcnt(0)
	v_lshl_add_u32 v6, v198, 4, v200
	ds_read_b32 v4, v6
	v_ashrrev_i32_e32 v177, 31, v176
	v_lshlrev_b64 v[2:3], 12, v[176:177]
	v_lshl_add_u64 v[2:3], s[8:9], 0, v[2:3]
	s_lshl_b32 s90, s2, 1
	s_waitcnt lgkmcnt(0)
	v_rcp_f32_e32 v7, v4
	v_lshl_add_u64 v[2:3], v[2:3], 0, s[90:91]
	v_lshlrev_b32_e32 v0, 1, v199
	v_lshl_add_u64 v[2:3], v[2:3], 0, v[0:1]
	s_mov_b64 s[0:1], 0x18628a00
	v_lshl_add_u64 v[2:3], v[2:3], 0, s[0:1]
	v_lshlrev_b32_e32 v0, 14, v198
	v_mul_f32_e32 v8, v64, v7
	v_lshl_add_u64 v[4:5], v[2:3], 0, v[0:1]
	v_cvt_pk_bf16_f32 v8, v8, v1
	global_store_short v[4:5], v8, off
	v_mul_f32_e32 v8, v48, v7
	v_cvt_pk_bf16_f32 v8, v8, v1
	global_store_short v[4:5], v8, off offset:64
	v_mul_f32_e32 v8, v32, v7
	v_cvt_pk_bf16_f32 v8, v8, v1
	v_mul_f32_e32 v7, v16, v7
	global_store_short v[4:5], v8, off offset:128
	v_cvt_pk_bf16_f32 v7, v7, v1
	ds_read_b32 v8, v6 offset:4
	global_store_short v[4:5], v7, off offset:192
	v_or_b32_e32 v4, 0x1000, v0
	v_mov_b32_e32 v5, v1
	v_lshl_add_u64 v[4:5], v[2:3], 0, v[4:5]
	s_waitcnt lgkmcnt(0)
	v_rcp_f32_e32 v7, v8
	s_nop 0
	v_mul_f32_e32 v8, v65, v7
	v_cvt_pk_bf16_f32 v8, v8, v1
	global_store_short v[4:5], v8, off
	v_mul_f32_e32 v8, v49, v7
	v_cvt_pk_bf16_f32 v8, v8, v1
	global_store_short v[4:5], v8, off offset:64
	v_mul_f32_e32 v8, v33, v7
	v_cvt_pk_bf16_f32 v8, v8, v1
	v_mul_f32_e32 v7, v17, v7
	global_store_short v[4:5], v8, off offset:128
	v_cvt_pk_bf16_f32 v7, v7, v1
	ds_read_b32 v8, v6 offset:8
	global_store_short v[4:5], v7, off offset:192
	v_or_b32_e32 v4, 0x2000, v0
	v_mov_b32_e32 v5, v1
	v_lshl_add_u64 v[4:5], v[2:3], 0, v[4:5]
	s_waitcnt lgkmcnt(0)
	v_rcp_f32_e32 v7, v8
	s_nop 0
	v_mul_f32_e32 v8, v66, v7
	v_cvt_pk_bf16_f32 v8, v8, v1
	global_store_short v[4:5], v8, off
	v_mul_f32_e32 v8, v50, v7
	v_cvt_pk_bf16_f32 v8, v8, v1
	global_store_short v[4:5], v8, off offset:64
	v_mul_f32_e32 v8, v34, v7
	v_cvt_pk_bf16_f32 v8, v8, v1
	v_mul_f32_e32 v7, v18, v7
	global_store_short v[4:5], v8, off offset:128
	v_cvt_pk_bf16_f32 v7, v7, v1
	ds_read_b32 v8, v6 offset:12
	global_store_short v[4:5], v7, off offset:192
	v_or_b32_e32 v4, 0x3000, v0
	v_mov_b32_e32 v5, v1
	v_lshl_add_u64 v[4:5], v[2:3], 0, v[4:5]
	s_waitcnt lgkmcnt(0)
	v_rcp_f32_e32 v7, v8
	s_nop 0
	v_mul_f32_e32 v8, v67, v7
	v_cvt_pk_bf16_f32 v8, v8, v1
	global_store_short v[4:5], v8, off
	v_mul_f32_e32 v8, v51, v7
	v_cvt_pk_bf16_f32 v8, v8, v1
	global_store_short v[4:5], v8, off offset:64
	v_mul_f32_e32 v8, v35, v7
	v_cvt_pk_bf16_f32 v8, v8, v1
	v_mul_f32_e32 v7, v19, v7
	global_store_short v[4:5], v8, off offset:128
	v_cvt_pk_bf16_f32 v7, v7, v1
	ds_read_b32 v8, v6 offset:32
	global_store_short v[4:5], v7, off offset:192
	v_or_b32_e32 v4, 0x8000, v0
	v_mov_b32_e32 v5, v1
	v_lshl_add_u64 v[4:5], v[2:3], 0, v[4:5]
	s_waitcnt lgkmcnt(0)
	v_rcp_f32_e32 v7, v8
	s_nop 0
	v_mul_f32_e32 v8, v68, v7
	v_cvt_pk_bf16_f32 v8, v8, v1
	global_store_short v[4:5], v8, off
	v_mul_f32_e32 v8, v52, v7
	v_cvt_pk_bf16_f32 v8, v8, v1
	global_store_short v[4:5], v8, off offset:64
	v_mul_f32_e32 v8, v36, v7
	v_cvt_pk_bf16_f32 v8, v8, v1
	v_mul_f32_e32 v7, v20, v7
	global_store_short v[4:5], v8, off offset:128
	v_cvt_pk_bf16_f32 v7, v7, v1
	ds_read_b32 v8, v6 offset:36
	global_store_short v[4:5], v7, off offset:192
	v_or_b32_e32 v4, 0x9000, v0
	v_mov_b32_e32 v5, v1
	v_lshl_add_u64 v[4:5], v[2:3], 0, v[4:5]
	s_waitcnt lgkmcnt(0)
	v_rcp_f32_e32 v7, v8
	s_nop 0
	v_mul_f32_e32 v8, v69, v7
	v_cvt_pk_bf16_f32 v8, v8, v1
	global_store_short v[4:5], v8, off
	v_mul_f32_e32 v8, v53, v7
	v_cvt_pk_bf16_f32 v8, v8, v1
	global_store_short v[4:5], v8, off offset:64
	v_mul_f32_e32 v8, v37, v7
	v_cvt_pk_bf16_f32 v8, v8, v1
	v_mul_f32_e32 v7, v21, v7
	global_store_short v[4:5], v8, off offset:128
	v_cvt_pk_bf16_f32 v7, v7, v1
	ds_read_b32 v8, v6 offset:40
	global_store_short v[4:5], v7, off offset:192
	v_or_b32_e32 v4, 0xa000, v0
	v_mov_b32_e32 v5, v1
	v_lshl_add_u64 v[4:5], v[2:3], 0, v[4:5]
	s_waitcnt lgkmcnt(0)
	v_rcp_f32_e32 v7, v8
	s_nop 0
	v_mul_f32_e32 v8, v70, v7
	v_cvt_pk_bf16_f32 v8, v8, v1
	global_store_short v[4:5], v8, off
	v_mul_f32_e32 v8, v54, v7
	v_cvt_pk_bf16_f32 v8, v8, v1
	global_store_short v[4:5], v8, off offset:64
	v_mul_f32_e32 v8, v38, v7
	v_cvt_pk_bf16_f32 v8, v8, v1
	v_mul_f32_e32 v7, v22, v7
	global_store_short v[4:5], v8, off offset:128
	v_cvt_pk_bf16_f32 v7, v7, v1
	ds_read_b32 v8, v6 offset:44
	global_store_short v[4:5], v7, off offset:192
	v_or_b32_e32 v4, 0xb000, v0
	v_mov_b32_e32 v5, v1
	v_lshl_add_u64 v[4:5], v[2:3], 0, v[4:5]
	s_waitcnt lgkmcnt(0)
; __device__ __forceinline__ int crow(int r, int hi) { return (r & 3) + 8 * (r >> 2) + 4 * hi; }
; __device__ __forceinline__ unsigned cvtpk(float lo, float hi) { unsigned r; asm volatile("v_cvt_pk_bf16_f32 %0, %1, %2" : "=v"(r) : "v"(lo), "v"(hi)); return r; }
; template <int MODE>
; __device__ __forceinline__ void attn_unit(unsigned char* ws_, const float* rpb, const float* sink, int l, int h, int qb, int kvq, unsigned char* lds_g) {
;     ...
;   { auto rr = __builtin_amdgcn_permlane32_swap(__float_as_uint(l_reg), __float_as_uint(l_reg), false, false); l_reg = __uint_as_float(rr[0]) + __uint_as_float(rr[1]); }
;   if (hi == 0) li_l[r32] = l_reg; asm volatile("s_waitcnt lgkmcnt(0)" ::: "memory");
;   bf16_t* Ow; int ldo;
;   if (MODE == 1) { Ow = (bf16_t*)(ws_ + WS_PART) + ((size_t)kvq * S + q0 + wid * 32) * VLD + 128 * h + r32; ldo = VLD;
;     if (hi == 0) { float* st = (float*)(ws_ + WS_STAT) + ((size_t)(kvq * 6 + h) * S + qi) * 2; st[0] = m_reg; st[1] = l_reg; } }
;   else { Ow = (bf16_t*)(ws_ + WS_Y) + (size_t)(q0 + wid * 32) * DM + ycol + r32; ldo = DM; }
; #pragma unroll
;   for (int r = 0; r < 16; ++r) { const int orow = crow(r, hi); const float rl = __builtin_amdgcn_rcpf(li_l[orow]);
; #pragma unroll
;     for (int d0 = 0; d0 < 4; ++d0) Ow[(size_t)orow * ldo + d0 * 32] = (bf16_t)(cvtpk(o[d0][r] * rl, 0.f) & 0xffffu); }
;   asm volatile("s_waitcnt lgkmcnt(0)" ::: "memory");
;   __syncthreads();
	v_rcp_f32_e32 v7, v8
	s_nop 0
	v_mul_f32_e32 v8, v71, v7
	v_cvt_pk_bf16_f32 v8, v8, v1
	global_store_short v[4:5], v8, off
	v_mul_f32_e32 v8, v55, v7
	v_cvt_pk_bf16_f32 v8, v8, v1
	global_store_short v[4:5], v8, off offset:64
	v_mul_f32_e32 v8, v39, v7
	v_cvt_pk_bf16_f32 v8, v8, v1
	v_mul_f32_e32 v7, v23, v7
	global_store_short v[4:5], v8, off offset:128
	v_cvt_pk_bf16_f32 v7, v7, v1
	ds_read_b32 v8, v6 offset:64
	global_store_short v[4:5], v7, off offset:192
	v_or_b32_e32 v4, 0x10000, v0
	v_mov_b32_e32 v5, v1
	v_lshl_add_u64 v[4:5], v[2:3], 0, v[4:5]
	s_waitcnt lgkmcnt(0)
	v_rcp_f32_e32 v7, v8
	s_nop 0
	v_mul_f32_e32 v8, v72, v7
	v_cvt_pk_bf16_f32 v8, v8, v1
	global_store_short v[4:5], v8, off
	v_mul_f32_e32 v8, v56, v7
	v_cvt_pk_bf16_f32 v8, v8, v1
	global_store_short v[4:5], v8, off offset:64
	v_mul_f32_e32 v8, v40, v7
	v_cvt_pk_bf16_f32 v8, v8, v1
	v_mul_f32_e32 v7, v24, v7
	global_store_short v[4:5], v8, off offset:128
	v_cvt_pk_bf16_f32 v7, v7, v1
	ds_read_b32 v8, v6 offset:68
	global_store_short v[4:5], v7, off offset:192
	v_or_b32_e32 v4, 0x11000, v0
	v_mov_b32_e32 v5, v1
	v_lshl_add_u64 v[4:5], v[2:3], 0, v[4:5]
	s_waitcnt lgkmcnt(0)
	v_rcp_f32_e32 v7, v8
	s_nop 0
	v_mul_f32_e32 v8, v73, v7
	v_cvt_pk_bf16_f32 v8, v8, v1
	global_store_short v[4:5], v8, off
	v_mul_f32_e32 v8, v57, v7
	v_cvt_pk_bf16_f32 v8, v8, v1
	global_store_short v[4:5], v8, off offset:64
	v_mul_f32_e32 v8, v41, v7
	v_cvt_pk_bf16_f32 v8, v8, v1
	v_mul_f32_e32 v7, v25, v7
	global_store_short v[4:5], v8, off offset:128
	v_cvt_pk_bf16_f32 v7, v7, v1
	ds_read_b32 v8, v6 offset:72
	global_store_short v[4:5], v7, off offset:192
	v_or_b32_e32 v4, 0x12000, v0
	v_mov_b32_e32 v5, v1
	v_lshl_add_u64 v[4:5], v[2:3], 0, v[4:5]
	s_waitcnt lgkmcnt(0)
	v_rcp_f32_e32 v7, v8
	s_nop 0
	v_mul_f32_e32 v8, v74, v7
	v_cvt_pk_bf16_f32 v8, v8, v1
	global_store_short v[4:5], v8, off
	v_mul_f32_e32 v8, v58, v7
	v_cvt_pk_bf16_f32 v8, v8, v1
	global_store_short v[4:5], v8, off offset:64
	v_mul_f32_e32 v8, v42, v7
	v_cvt_pk_bf16_f32 v8, v8, v1
	v_mul_f32_e32 v7, v26, v7
	global_store_short v[4:5], v8, off offset:128
	v_cvt_pk_bf16_f32 v7, v7, v1
	ds_read_b32 v8, v6 offset:76
	global_store_short v[4:5], v7, off offset:192
	v_or_b32_e32 v4, 0x13000, v0
	v_mov_b32_e32 v5, v1
	v_lshl_add_u64 v[4:5], v[2:3], 0, v[4:5]
	s_waitcnt lgkmcnt(0)
	v_rcp_f32_e32 v7, v8
	s_nop 0
	v_mul_f32_e32 v8, v75, v7
	v_cvt_pk_bf16_f32 v8, v8, v1
	global_store_short v[4:5], v8, off
	v_mul_f32_e32 v8, v59, v7
	v_cvt_pk_bf16_f32 v8, v8, v1
	global_store_short v[4:5], v8, off offset:64
	v_mul_f32_e32 v8, v43, v7
	v_cvt_pk_bf16_f32 v8, v8, v1
	v_mul_f32_e32 v7, v27, v7
	global_store_short v[4:5], v8, off offset:128
	v_cvt_pk_bf16_f32 v7, v7, v1
	ds_read_b32 v8, v6 offset:96
	global_store_short v[4:5], v7, off offset:192
	v_or_b32_e32 v4, 0x18000, v0
	v_mov_b32_e32 v5, v1
	v_lshl_add_u64 v[4:5], v[2:3], 0, v[4:5]
	s_waitcnt lgkmcnt(0)
	v_rcp_f32_e32 v7, v8
	s_nop 0
	v_mul_f32_e32 v8, v76, v7
	v_cvt_pk_bf16_f32 v8, v8, v1
	global_store_short v[4:5], v8, off
	v_mul_f32_e32 v8, v60, v7
	v_cvt_pk_bf16_f32 v8, v8, v1
	global_store_short v[4:5], v8, off offset:64
	v_mul_f32_e32 v8, v44, v7
	v_cvt_pk_bf16_f32 v8, v8, v1
	v_mul_f32_e32 v7, v28, v7
	global_store_short v[4:5], v8, off offset:128
	v_cvt_pk_bf16_f32 v7, v7, v1
	ds_read_b32 v8, v6 offset:100
	global_store_short v[4:5], v7, off offset:192
	v_or_b32_e32 v4, 0x19000, v0
	v_mov_b32_e32 v5, v1
	v_lshl_add_u64 v[4:5], v[2:3], 0, v[4:5]
	s_waitcnt lgkmcnt(0)
	v_rcp_f32_e32 v7, v8
	s_nop 0
	v_mul_f32_e32 v8, v77, v7
	v_cvt_pk_bf16_f32 v8, v8, v1
	global_store_short v[4:5], v8, off
	v_mul_f32_e32 v8, v61, v7
	v_cvt_pk_bf16_f32 v8, v8, v1
	global_store_short v[4:5], v8, off offset:64
	v_mul_f32_e32 v8, v45, v7
	v_cvt_pk_bf16_f32 v8, v8, v1
	v_mul_f32_e32 v7, v29, v7
	global_store_short v[4:5], v8, off offset:128
	v_cvt_pk_bf16_f32 v7, v7, v1
	ds_read_b32 v8, v6 offset:104
	global_store_short v[4:5], v7, off offset:192
	v_or_b32_e32 v4, 0x1a000, v0
	v_mov_b32_e32 v5, v1
	v_lshl_add_u64 v[4:5], v[2:3], 0, v[4:5]
	s_waitcnt lgkmcnt(0)
	v_rcp_f32_e32 v7, v8
	v_or_b32_e32 v0, 0x1b000, v0
	v_lshl_add_u64 v[2:3], v[2:3], 0, v[0:1]
	v_mul_f32_e32 v8, v78, v7
	v_cvt_pk_bf16_f32 v8, v8, v1
	global_store_short v[4:5], v8, off
	v_mul_f32_e32 v8, v62, v7
	v_cvt_pk_bf16_f32 v8, v8, v1
	global_store_short v[4:5], v8, off offset:64
	v_mul_f32_e32 v8, v46, v7
	v_mul_f32_e32 v7, v30, v7
	v_cvt_pk_bf16_f32 v8, v8, v1
	global_store_short v[4:5], v8, off offset:128
	v_cvt_pk_bf16_f32 v7, v7, v1
	ds_read_b32 v6, v6 offset:108
	global_store_short v[4:5], v7, off offset:192
	s_waitcnt lgkmcnt(0)
	v_rcp_f32_e32 v6, v6
	s_nop 0
	v_mul_f32_e32 v0, v79, v6
	v_cvt_pk_bf16_f32 v0, v0, v1
	global_store_short v[2:3], v0, off
	v_mul_f32_e32 v0, v63, v6
	v_cvt_pk_bf16_f32 v0, v0, v1
	global_store_short v[2:3], v0, off offset:64
	v_mul_f32_e32 v0, v47, v6
	v_cvt_pk_bf16_f32 v0, v0, v1
	global_store_short v[2:3], v0, off offset:128
	v_mul_f32_e32 v0, v31, v6
	v_cvt_pk_bf16_f32 v0, v0, v1
	global_store_short v[2:3], v0, off offset:192
	s_waitcnt lgkmcnt(0)
	s_barrier

; __device__ __forceinline__ int crow(int r, int hi) { return (r & 3) + 8 * (r >> 2) + 4 * hi; }
; __device__ __forceinline__ unsigned cvtpk(float lo, float hi) { unsigned r; asm volatile("v_cvt_pk_bf16_f32 %0, %1, %2" : "=v"(r) : "v"(lo), "v"(hi)); return r; }
; template <int MODE>
; __device__ __forceinline__ void attn_unit(unsigned char* ws_, const float* rpb, const float* sink, int l, int h, int qb, int kvq, unsigned char* lds_g) {
;     ...
;   if (MODE == 1) { Ow = (bf16_t*)(ws_ + WS_PART) + ((size_t)kvq * S + q0 + wid * 32) * VLD + 128 * h + r32; ldo = VLD;
;     if (hi == 0) { float* st = (float*)(ws_ + WS_STAT) + ((size_t)(kvq * 6 + h) * S + qi) * 2; st[0] = m_reg; st[1] = l_reg; } }
;   else { Ow = (bf16_t*)(ws_ + WS_Y) + (size_t)(q0 + wid * 32) * DM + ycol + r32; ldo = DM; }
; #pragma unroll
;   for (int r = 0; r < 16; ++r) { const int orow = crow(r, hi); const float rl = __builtin_amdgcn_rcpf(li_l[orow]);
; #pragma unroll
;     for (int d0 = 0; d0 < 4; ++d0) Ow[(size_t)orow * ldo + d0 * 32] = (bf16_t)(cvtpk(o[d0][r] * rl, 0.f) & 0xffffu); }
.LBB0_859:
	s_or_b64 exec, exec, s[8:9]
	s_lshl_b32 s4, s14, 13
	s_or_b32 s4, s4, s16
	v_add_u32_e32 v0, s4, v179
	v_mov_b64_e32 v[66:67], s[2:3]
	v_mad_i64_i32 v[66:67], s[2:3], v0, s33, v[66:67]
	v_lshl_add_u64 v[66:67], s[6:7], 1, v[66:67]
	v_lshlrev_b32_e32 v0, 1, v177
	v_lshl_add_u32 v70, v176, 4, v178
	v_lshl_add_u64 v[66:67], v[66:67], 0, v[0:1]
	ds_read_b32 v0, v70
	s_mov_b64 s[2:3], 0x1fe28000
	v_lshl_add_u64 v[66:67], v[66:67], 0, s[2:3]
	s_add_i32 s13, s13, s12
	s_cmpk_gt_i32 s13, 0x2ff
	s_waitcnt lgkmcnt(0)
	v_rcp_f32_e32 v71, v0
	v_mul_u32_u24_e32 v0, 0x1800, v176
	v_lshl_add_u64 v[68:69], v[66:67], 0, v[0:1]
	v_mul_f32_e32 v0, v2, v71
	v_cvt_pk_bf16_f32 v0, v0, v1
	global_store_short v[68:69], v0, off
	v_mul_f32_e32 v0, v50, v71
	v_cvt_pk_bf16_f32 v0, v0, v1
	global_store_short v[68:69], v0, off offset:64
	v_mul_f32_e32 v0, v34, v71
	v_cvt_pk_bf16_f32 v0, v0, v1
	global_store_short v[68:69], v0, off offset:128
	v_mul_f32_e32 v0, v18, v71
	v_cvt_pk_bf16_f32 v0, v0, v1
	global_store_short v[68:69], v0, off offset:192
	ds_read_b32 v0, v70 offset:4
	v_lshl_or_b32 v18, v176, 2, 1
	s_waitcnt lgkmcnt(0)
	v_rcp_f32_e32 v2, v0
	v_mul_u32_u24_e32 v0, 0x600, v18
	v_lshl_add_u64 v[68:69], v[66:67], 0, v[0:1]
	v_mul_f32_e32 v0, v3, v2
	v_cvt_pk_bf16_f32 v0, v0, v1
	global_store_short v[68:69], v0, off
	v_mul_f32_e32 v0, v51, v2
	v_cvt_pk_bf16_f32 v0, v0, v1
	global_store_short v[68:69], v0, off offset:64
	v_mul_f32_e32 v0, v35, v2
	v_cvt_pk_bf16_f32 v0, v0, v1
	global_store_short v[68:69], v0, off offset:128
	v_mul_f32_e32 v0, v19, v2
	v_cvt_pk_bf16_f32 v0, v0, v1
	global_store_short v[68:69], v0, off offset:192
	ds_read_b32 v0, v70 offset:8
	s_waitcnt lgkmcnt(0)
	v_rcp_f32_e32 v19, v0
	v_mad_u32_u24 v0, v18, s33, s33
	v_lshl_add_u64 v[2:3], v[66:67], 0, v[0:1]
	v_mul_f32_e32 v0, v4, v19
	v_cvt_pk_bf16_f32 v0, v0, v1
	global_store_short v[2:3], v0, off
	v_mul_f32_e32 v0, v52, v19
	v_cvt_pk_bf16_f32 v0, v0, v1
	global_store_short v[2:3], v0, off offset:64
	v_mul_f32_e32 v0, v36, v19
	v_cvt_pk_bf16_f32 v0, v0, v1
	global_store_short v[2:3], v0, off offset:128
	v_mul_f32_e32 v0, v20, v19
	v_cvt_pk_bf16_f32 v0, v0, v1
	global_store_short v[2:3], v0, off offset:192
	ds_read_b32 v0, v70 offset:12
	s_waitcnt lgkmcnt(0)
	v_rcp_f32_e32 v4, v0
	v_mov_b32_e32 v0, 0xc00
	v_mad_u32_u24 v0, v18, s33, v0
	v_lshl_add_u64 v[2:3], v[66:67], 0, v[0:1]
	v_mul_f32_e32 v0, v5, v4
	v_cvt_pk_bf16_f32 v0, v0, v1
	global_store_short v[2:3], v0, off
	v_mul_f32_e32 v0, v53, v4
	v_cvt_pk_bf16_f32 v0, v0, v1
	global_store_short v[2:3], v0, off offset:64
	v_mul_f32_e32 v0, v37, v4
	v_cvt_pk_bf16_f32 v0, v0, v1
	global_store_short v[2:3], v0, off offset:128
	v_mul_f32_e32 v0, v21, v4
	v_cvt_pk_bf16_f32 v0, v0, v1
	global_store_short v[2:3], v0, off offset:192
	ds_read_b32 v0, v70 offset:32
	s_waitcnt lgkmcnt(0)
	v_rcp_f32_e32 v4, v0
	v_mov_b32_e32 v0, 0x2a00
	v_mad_u32_u24 v0, v18, s33, v0
	v_lshl_add_u64 v[2:3], v[66:67], 0, v[0:1]
	v_mul_f32_e32 v0, v6, v4
	v_cvt_pk_bf16_f32 v0, v0, v1
	global_store_short v[2:3], v0, off
	v_mul_f32_e32 v0, v54, v4
	v_cvt_pk_bf16_f32 v0, v0, v1
	global_store_short v[2:3], v0, off offset:64
	v_mul_f32_e32 v0, v38, v4
	v_cvt_pk_bf16_f32 v0, v0, v1
	global_store_short v[2:3], v0, off offset:128
	v_mul_f32_e32 v0, v22, v4
	v_cvt_pk_bf16_f32 v0, v0, v1
	global_store_short v[2:3], v0, off offset:192
	ds_read_b32 v0, v70 offset:36
	s_waitcnt lgkmcnt(0)
	v_rcp_f32_e32 v4, v0
	v_mov_b32_e32 v0, 0x3000
	v_mad_u32_u24 v0, v18, s33, v0
	v_lshl_add_u64 v[2:3], v[66:67], 0, v[0:1]
	v_mul_f32_e32 v0, v7, v4
	v_cvt_pk_bf16_f32 v0, v0, v1
	global_store_short v[2:3], v0, off
	v_mul_f32_e32 v0, v55, v4
	v_cvt_pk_bf16_f32 v0, v0, v1
	global_store_short v[2:3], v0, off offset:64
	v_mul_f32_e32 v0, v39, v4
	v_cvt_pk_bf16_f32 v0, v0, v1
	global_store_short v[2:3], v0, off offset:128
	v_mul_f32_e32 v0, v23, v4
	v_cvt_pk_bf16_f32 v0, v0, v1
	global_store_short v[2:3], v0, off offset:192
	ds_read_b32 v0, v70 offset:40
	s_waitcnt lgkmcnt(0)
	v_rcp_f32_e32 v4, v0
	v_mov_b32_e32 v0, 0x3600
	v_mad_u32_u24 v0, v18, s33, v0
	v_lshl_add_u64 v[2:3], v[66:67], 0, v[0:1]
	v_mul_f32_e32 v0, v8, v4
	v_cvt_pk_bf16_f32 v0, v0, v1
	global_store_short v[2:3], v0, off
	v_mul_f32_e32 v0, v56, v4
	v_cvt_pk_bf16_f32 v0, v0, v1
	global_store_short v[2:3], v0, off offset:64
	v_mul_f32_e32 v0, v40, v4
	v_cvt_pk_bf16_f32 v0, v0, v1
	global_store_short v[2:3], v0, off offset:128
	v_mul_f32_e32 v0, v24, v4
	v_cvt_pk_bf16_f32 v0, v0, v1
	global_store_short v[2:3], v0, off offset:192
	ds_read_b32 v0, v70 offset:44
	s_waitcnt lgkmcnt(0)
; __device__ __forceinline__ int crow(int r, int hi) { return (r & 3) + 8 * (r >> 2) + 4 * hi; }
; __device__ __forceinline__ unsigned cvtpk(float lo, float hi) { unsigned r; asm volatile("v_cvt_pk_bf16_f32 %0, %1, %2" : "=v"(r) : "v"(lo), "v"(hi)); return r; }
; __device__ __forceinline__ int opq(int v) { asm volatile("" : "+s"(v)); return v; }
; template <int MODE>
; __device__ __forceinline__ void attn_unit(unsigned char* ws_, const float* rpb, const float* sink, int l, int h, int qb, int kvq, unsigned char* lds_g) {
;     ...
;   if (MODE == 1) { Ow = (bf16_t*)(ws_ + WS_PART) + ((size_t)kvq * S + q0 + wid * 32) * VLD + 128 * h + r32; ldo = VLD;
;     if (hi == 0) { float* st = (float*)(ws_ + WS_STAT) + ((size_t)(kvq * 6 + h) * S + qi) * 2; st[0] = m_reg; st[1] = l_reg; } }
;   else { Ow = (bf16_t*)(ws_ + WS_Y) + (size_t)(q0 + wid * 32) * DM + ycol + r32; ldo = DM; }
; #pragma unroll
;   for (int r = 0; r < 16; ++r) { const int orow = crow(r, hi); const float rl = __builtin_amdgcn_rcpf(li_l[orow]);
; #pragma unroll
;     for (int d0 = 0; d0 < 4; ++d0) Ow[(size_t)orow * ldo + d0 * 32] = (bf16_t)(cvtpk(o[d0][r] * rl, 0.f) & 0xffffu); }
;   asm volatile("s_waitcnt lgkmcnt(0)" ::: "memory");
;   __syncthreads();
; __global__ void __launch_bounds__(NTHREADS) fwd_megakernel(Args a) {
;     ...
;             for (int su = opq((int)blockIdx.x); su < 192 * att::KVSPLIT; su += Gq) {
	v_rcp_f32_e32 v4, v0
	v_mov_b32_e32 v0, 0x3c00
	v_mad_u32_u24 v0, v18, s33, v0
	v_lshl_add_u64 v[2:3], v[66:67], 0, v[0:1]
	v_mul_f32_e32 v0, v9, v4
	v_cvt_pk_bf16_f32 v0, v0, v1
	global_store_short v[2:3], v0, off
	v_mul_f32_e32 v0, v57, v4
	v_cvt_pk_bf16_f32 v0, v0, v1
	global_store_short v[2:3], v0, off offset:64
	v_mul_f32_e32 v0, v41, v4
	v_cvt_pk_bf16_f32 v0, v0, v1
	global_store_short v[2:3], v0, off offset:128
	v_mul_f32_e32 v0, v25, v4
	v_cvt_pk_bf16_f32 v0, v0, v1
	global_store_short v[2:3], v0, off offset:192
	ds_read_b32 v0, v70 offset:64
	s_waitcnt lgkmcnt(0)
	v_rcp_f32_e32 v4, v0
	v_mov_b32_e32 v0, 0x5a00
	v_mad_u32_u24 v0, v18, s33, v0
	v_lshl_add_u64 v[2:3], v[66:67], 0, v[0:1]
	v_mul_f32_e32 v0, v10, v4
	v_cvt_pk_bf16_f32 v0, v0, v1
	global_store_short v[2:3], v0, off
	v_mul_f32_e32 v0, v58, v4
	v_cvt_pk_bf16_f32 v0, v0, v1
	global_store_short v[2:3], v0, off offset:64
	v_mul_f32_e32 v0, v42, v4
	v_cvt_pk_bf16_f32 v0, v0, v1
	global_store_short v[2:3], v0, off offset:128
	v_mul_f32_e32 v0, v26, v4
	v_cvt_pk_bf16_f32 v0, v0, v1
	global_store_short v[2:3], v0, off offset:192
	ds_read_b32 v0, v70 offset:68
	s_waitcnt lgkmcnt(0)
	v_rcp_f32_e32 v4, v0
	v_mad_u32_u24 v0, v18, s33, v223
	v_lshl_add_u64 v[2:3], v[66:67], 0, v[0:1]
	v_mul_f32_e32 v0, v11, v4
	v_cvt_pk_bf16_f32 v0, v0, v1
	global_store_short v[2:3], v0, off
	v_mul_f32_e32 v0, v59, v4
	v_cvt_pk_bf16_f32 v0, v0, v1
	global_store_short v[2:3], v0, off offset:64
	v_mul_f32_e32 v0, v43, v4
	v_cvt_pk_bf16_f32 v0, v0, v1
	global_store_short v[2:3], v0, off offset:128
	v_mul_f32_e32 v0, v27, v4
	v_cvt_pk_bf16_f32 v0, v0, v1
	global_store_short v[2:3], v0, off offset:192
	ds_read_b32 v0, v70 offset:72
	s_waitcnt lgkmcnt(0)
	v_rcp_f32_e32 v4, v0
	v_mad_u32_u24 v0, v18, s33, v224
	v_lshl_add_u64 v[2:3], v[66:67], 0, v[0:1]
	v_mul_f32_e32 v0, v12, v4
	v_cvt_pk_bf16_f32 v0, v0, v1
	global_store_short v[2:3], v0, off
	v_mul_f32_e32 v0, v60, v4
	v_cvt_pk_bf16_f32 v0, v0, v1
	global_store_short v[2:3], v0, off offset:64
	v_mul_f32_e32 v0, v44, v4
	v_cvt_pk_bf16_f32 v0, v0, v1
	global_store_short v[2:3], v0, off offset:128
	v_mul_f32_e32 v0, v28, v4
	v_cvt_pk_bf16_f32 v0, v0, v1
	global_store_short v[2:3], v0, off offset:192
	ds_read_b32 v0, v70 offset:76
	s_waitcnt lgkmcnt(0)
	v_rcp_f32_e32 v4, v0
	v_mad_u32_u24 v0, v18, s33, v225
	v_lshl_add_u64 v[2:3], v[66:67], 0, v[0:1]
	v_mul_f32_e32 v0, v13, v4
	v_cvt_pk_bf16_f32 v0, v0, v1
	global_store_short v[2:3], v0, off
	v_mul_f32_e32 v0, v61, v4
	v_cvt_pk_bf16_f32 v0, v0, v1
	global_store_short v[2:3], v0, off offset:64
	v_mul_f32_e32 v0, v45, v4
	v_cvt_pk_bf16_f32 v0, v0, v1
	global_store_short v[2:3], v0, off offset:128
	v_mul_f32_e32 v0, v29, v4
	v_cvt_pk_bf16_f32 v0, v0, v1
	global_store_short v[2:3], v0, off offset:192
	ds_read_b32 v0, v70 offset:96
	s_waitcnt lgkmcnt(0)
	v_rcp_f32_e32 v4, v0
	v_mad_u32_u24 v0, v18, s33, v226
	v_lshl_add_u64 v[2:3], v[66:67], 0, v[0:1]
	v_mul_f32_e32 v0, v14, v4
	v_cvt_pk_bf16_f32 v0, v0, v1
	global_store_short v[2:3], v0, off
	v_mul_f32_e32 v0, v62, v4
	v_cvt_pk_bf16_f32 v0, v0, v1
	global_store_short v[2:3], v0, off offset:64
	v_mul_f32_e32 v0, v46, v4
	v_cvt_pk_bf16_f32 v0, v0, v1
	global_store_short v[2:3], v0, off offset:128
	v_mul_f32_e32 v0, v30, v4
	v_cvt_pk_bf16_f32 v0, v0, v1
	global_store_short v[2:3], v0, off offset:192
	ds_read_b32 v0, v70 offset:100
	s_waitcnt lgkmcnt(0)
	v_rcp_f32_e32 v4, v0
	v_mad_u32_u24 v0, v18, s33, v227
	v_lshl_add_u64 v[2:3], v[66:67], 0, v[0:1]
	v_mul_f32_e32 v0, v15, v4
	v_cvt_pk_bf16_f32 v0, v0, v1
	global_store_short v[2:3], v0, off
	v_mul_f32_e32 v0, v63, v4
	v_cvt_pk_bf16_f32 v0, v0, v1
	global_store_short v[2:3], v0, off offset:64
	v_mul_f32_e32 v0, v47, v4
	v_cvt_pk_bf16_f32 v0, v0, v1
	global_store_short v[2:3], v0, off offset:128
	v_mul_f32_e32 v0, v31, v4
	v_cvt_pk_bf16_f32 v0, v0, v1
	global_store_short v[2:3], v0, off offset:192
	ds_read_b32 v0, v70 offset:104
	s_waitcnt lgkmcnt(0)
	v_rcp_f32_e32 v4, v0
	v_mad_u32_u24 v0, v18, s33, v228
	v_lshl_add_u64 v[2:3], v[66:67], 0, v[0:1]
	v_mul_f32_e32 v0, v16, v4
	v_cvt_pk_bf16_f32 v0, v0, v1
	global_store_short v[2:3], v0, off
	v_mul_f32_e32 v0, v64, v4
	v_cvt_pk_bf16_f32 v0, v0, v1
	global_store_short v[2:3], v0, off offset:64
	v_mul_f32_e32 v0, v48, v4
	v_cvt_pk_bf16_f32 v0, v0, v1
	global_store_short v[2:3], v0, off offset:128
	v_mul_f32_e32 v0, v32, v4
	v_cvt_pk_bf16_f32 v0, v0, v1
	global_store_short v[2:3], v0, off offset:192
	ds_read_b32 v0, v70 offset:108
	s_waitcnt lgkmcnt(0)
	v_rcp_f32_e32 v4, v0
	v_mad_u32_u24 v0, v18, s33, v229
	v_lshl_add_u64 v[2:3], v[66:67], 0, v[0:1]
	v_mul_f32_e32 v0, v17, v4
	v_cvt_pk_bf16_f32 v0, v0, v1
	global_store_short v[2:3], v0, off
	v_mul_f32_e32 v0, v65, v4
	v_cvt_pk_bf16_f32 v0, v0, v1
	global_store_short v[2:3], v0, off offset:64
	v_mul_f32_e32 v0, v49, v4
	v_cvt_pk_bf16_f32 v0, v0, v1
	global_store_short v[2:3], v0, off offset:128
	v_mul_f32_e32 v0, v33, v4
	v_cvt_pk_bf16_f32 v0, v0, v1
	global_store_short v[2:3], v0, off offset:192
	s_waitcnt lgkmcnt(0)
	s_barrier
	s_cbranch_scc1 .LBB0_882

; template <int MODE>
; __device__ __forceinline__ void attn_unit(unsigned char* ws_, const float* rpb, const float* sink, int l, int h, int qb, int kvq, unsigned char* lds_g) {
;     ...
;   { auto rr = __builtin_amdgcn_permlane32_swap(__float_as_uint(l_reg), __float_as_uint(l_reg), false, false); l_reg = __uint_as_float(rr[0]) + __uint_as_float(rr[1]); }
;   if (hi == 0) li_l[r32] = l_reg; asm volatile("s_waitcnt lgkmcnt(0)" ::: "memory");
;   bf16_t* Ow; int ldo;
;   if (MODE == 1) { Ow = (bf16_t*)(ws_ + WS_PART) + ((size_t)kvq * S + q0 + wid * 32) * VLD + 128 * h + r32; ldo = VLD;
;     if (hi == 0) { float* st = (float*)(ws_ + WS_STAT) + ((size_t)(kvq * 6 + h) * S + qi) * 2; st[0] = m_reg; st[1] = l_reg; } }
.LBB0_878:
	v_mov_b32_e32 v0, v202
	s_nop 1
	v_permlane32_swap_b32_e32 v202, v0
	v_add_f32_e32 v149, v202, v0
	s_and_saveexec_b64 s[8:9], s[4:5]
	ds_write_b32 v182, v149
	s_or_b64 exec, exec, s[8:9]
	s_waitcnt lgkmcnt(0)
	s_and_saveexec_b64 s[8:9], s[4:5]
	s_cbranch_execz .LBB0_859
	s_mul_i32 s4, s14, 6
	s_add_i32 s4, s4, s15
	s_ashr_i32 s5, s4, 31
	s_lshl_b64 s[4:5], s[4:5], 16
	s_add_u32 s4, s2, s4
	s_addc_u32 s5, s3, s5
	v_lshl_add_u64 v[66:67], v[146:147], 3, s[4:5]
	v_add_co_u32_e32 v66, vcc, 0x22e28000, v66
	s_nop 1
	v_addc_co_u32_e32 v67, vcc, 0, v67, vcc
	global_store_dwordx2 v[66:67], v[148:149], off
	s_branch .LBB0_859

; __device__ __forceinline__ void phase_ynorm(unsigned char* ws_) {
;     ...
;     for (int r = blockIdx.x * 8 + wave; r < S; r += gridDim.x * 8) {
;         bf16_t* yr = y + (size_t)r * DM;
;         float v[4][8]; float ss[4];
; #pragma unroll
;         for (int j = 0; j < 4; ++j) {
;             const bool fromPart = (j == 1) || (j == 2 && lowhalf);
;             if (!fromPart) { const u32x4 w = *(const u32x4*)(yr + j * 512 + 8 * lane);
; #pragma unroll
;                 for (int e = 0; e < 4; ++e) { v[j][2 * e] = __uint_as_float(w[e] << 16); v[j][2 * e + 1] = __uint_as_float(w[e] & 0xffff0000u); } }
;             else { const int yb = j * 512 + 8 * lane - 512, h = yb >> 7; float m[4], lw[4];
; #pragma unroll
;                 for (int i = 0; i < 4; ++i) { const float* st = stat + ((size_t)(i * 6 + h) * S + r) * 2; m[i] = st[0]; lw[i] = st[1]; }
;                 const float M = fmaxf(fmaxf(m[0], m[1]), fmaxf(m[2], m[3])); float W = 0.f;
; #pragma unroll
;                 for (int i = 0; i < 4; ++i) { lw[i] *= __builtin_amdgcn_exp2f(m[i] - M); W += lw[i]; }
;                 const float rW = 1.0f / W;
; #pragma unroll
;                 for (int e = 0; e < 8; ++e) v[j][e] = 0.f;
; #pragma unroll
;                 for (int i = 0; i < 4; ++i) { const u32x4 w = *(const u32x4*)(part + ((size_t)i * S + r) * VLD + yb); const float wi = lw[i] * rW;
; #pragma unroll
;                     for (int e = 0; e < 4; ++e) { v[j][2 * e] += wi * __uint_as_float(w[e] << 16); v[j][2 * e + 1] += wi * __uint_as_float(w[e] & 0xffff0000u); } } }
;             float sq = 0.f;
; #pragma unroll
;             for (int e = 0; e < 8; ++e) sq += v[j][e] * v[j][e];
;             ss[j] = sq;
;         }
.LBB0_933:
	s_or_b64 exec, exec, s[0:1]
	s_waitcnt vmcnt(0) lgkmcnt(0)
	v_lshlrev_b32_e32 v31, 16, v18
	v_and_b32_e32 v32, 0xffff0000, v18
	v_lshlrev_b32_e32 v29, 16, v19
	v_and_b32_e32 v30, 0xffff0000, v19
	v_lshlrev_b32_e32 v18, 16, v21
	v_and_b32_e32 v19, 0xffff0000, v21
	v_max_f32_e32 v21, v52, v52
	v_max_f32_e32 v33, v54, v54
	v_max_f32_e32 v21, v33, v21
	v_max3_f32 v21, v58, v56, v21
	v_sub_f32_e32 v33, v58, v21
	v_exp_f32_e32 v33, v33
	v_sub_f32_e32 v35, v56, v21
	v_exp_f32_e32 v35, v35
	v_mul_f32_e32 v36, v32, v32
	v_mul_f32_e32 v34, v59, v33
	v_fma_f32 v33, v59, v33, 0
	v_mul_f32_e32 v37, v57, v35
	v_fmac_f32_e32 v33, v57, v35
	v_sub_f32_e32 v35, v54, v21
	v_exp_f32_e32 v35, v35
	v_sub_f32_e32 v21, v52, v21
	v_exp_f32_e32 v21, v21
	v_fmac_f32_e32 v36, v31, v31
	v_fmac_f32_e32 v33, v55, v35
	v_mul_f32_e32 v39, v55, v35
	v_fmac_f32_e32 v33, v53, v21
	v_mul_f32_e32 v52, v53, v21
	v_div_scale_f32 v21, s[0:1], v33, v33, 1.0
	v_rcp_f32_e32 v35, v21
	v_fmac_f32_e32 v36, v29, v29
	v_lshlrev_b32_e32 v28, 16, v20
	v_fmac_f32_e32 v36, v30, v30
	v_fma_f32 v53, -v21, v35, 1.0
	v_fmac_f32_e32 v35, v53, v35
	v_div_scale_f32 v53, vcc, 1.0, v33, 1.0
	v_mul_f32_e32 v54, v53, v35
	v_fma_f32 v55, -v21, v54, v53
	v_fmac_f32_e32 v54, v55, v35
	v_fma_f32 v21, -v21, v54, v53
	v_div_fmas_f32 v21, v21, v35, v54
	v_div_fixup_f32 v53, v21, v33, 1.0
	v_mul_f32_e32 v54, v34, v53
	v_lshlrev_b32_e32 v21, 16, v14
	v_and_b32_e32 v14, 0xffff0000, v14
	v_lshlrev_b32_e32 v33, 16, v15
	v_and_b32_e32 v15, 0xffff0000, v15
	v_lshlrev_b32_e32 v34, 16, v16
	v_and_b32_e32 v16, 0xffff0000, v16
	v_lshlrev_b32_e32 v35, 16, v17
	v_and_b32_e32 v17, 0xffff0000, v17
	v_fma_f32 v21, v54, v21, 0
	v_fma_f32 v14, v54, v14, 0
	v_fma_f32 v33, v54, v33, 0
	v_fma_f32 v15, v54, v15, 0
	v_fma_f32 v34, v54, v34, 0
	v_fma_f32 v16, v54, v16, 0
	v_fma_f32 v35, v54, v35, 0
	v_fma_f32 v17, v54, v17, 0
	v_mul_f32_e32 v37, v37, v53
	v_lshlrev_b32_e32 v54, 16, v10
	v_and_b32_e32 v10, 0xffff0000, v10
	v_fmac_f32_e32 v14, v37, v10
	v_lshlrev_b32_e32 v10, 16, v11
	v_fmac_f32_e32 v33, v37, v10
	v_and_b32_e32 v10, 0xffff0000, v11
	v_fmac_f32_e32 v15, v37, v10
	v_lshlrev_b32_e32 v10, 16, v12
	v_fmac_f32_e32 v34, v37, v10
	v_and_b32_e32 v10, 0xffff0000, v12
	v_fmac_f32_e32 v16, v37, v10
	v_lshlrev_b32_e32 v10, 16, v13
	v_fmac_f32_e32 v35, v37, v10
	v_and_b32_e32 v10, 0xffff0000, v13
	v_fmac_f32_e32 v17, v37, v10
	v_mul_f32_e32 v10, v39, v53
	v_lshlrev_b32_e32 v11, 16, v6
	v_and_b32_e32 v6, 0xffff0000, v6
	v_fmac_f32_e32 v14, v10, v6
	v_lshlrev_b32_e32 v6, 16, v7
	v_fmac_f32_e32 v33, v10, v6
	v_and_b32_e32 v6, 0xffff0000, v7
	v_fmac_f32_e32 v15, v10, v6
	v_lshlrev_b32_e32 v6, 16, v8
	v_fmac_f32_e32 v34, v10, v6
	v_and_b32_e32 v6, 0xffff0000, v8
	v_fmac_f32_e32 v16, v10, v6
	v_lshlrev_b32_e32 v6, 16, v9
	v_fmac_f32_e32 v35, v10, v6
	v_and_b32_e32 v6, 0xffff0000, v9
	v_fmac_f32_e32 v17, v10, v6
	v_mul_f32_e32 v6, v52, v53
	v_lshlrev_b32_e32 v7, 16, v2
	v_and_b32_e32 v2, 0xffff0000, v2
	v_fmac_f32_e32 v14, v6, v2
	v_lshlrev_b32_e32 v2, 16, v3
	v_fmac_f32_e32 v33, v6, v2
	v_and_b32_e32 v2, 0xffff0000, v3
	v_fmac_f32_e32 v15, v6, v2
	v_lshlrev_b32_e32 v2, 16, v4
	v_fmac_f32_e32 v34, v6, v2
	v_and_b32_e32 v2, 0xffff0000, v4
	v_fmac_f32_e32 v16, v6, v2
	v_lshlrev_b32_e32 v2, 16, v5
	v_fmac_f32_e32 v35, v6, v2
	v_and_b32_e32 v2, 0xffff0000, v5
	v_fmac_f32_e32 v17, v6, v2
	v_pk_mul_f32 v[2:3], v[50:51], v[50:51]
	v_pk_mul_f32 v[4:5], v[22:23], v[22:23]
	v_add_f32_e32 v2, v2, v3
	v_add_f32_e32 v2, v5, v2
	v_pk_mul_f32 v[8:9], v[26:27], v[26:27]
	v_add_f32_e32 v2, v4, v2
	v_fmac_f32_e32 v21, v37, v54
	v_add_f32_e32 v2, v9, v2
	v_fmac_f32_e32 v21, v10, v11
	v_pk_mul_f32 v[10:11], v[24:25], v[24:25]
	v_add_f32_e32 v2, v8, v2
	v_add_f32_e32 v2, v11, v2
	v_fmac_f32_e32 v21, v6, v7
	v_add_f32_e32 v7, v10, v2
	flat_load_dwordx4 v[2:5], v[48:49] offset:3072
	v_mul_f32_e32 v6, v14, v14
	v_fmac_f32_e32 v6, v21, v21
	v_fmac_f32_e32 v6, v33, v33
	v_fmac_f32_e32 v6, v15, v15
	v_fmac_f32_e32 v6, v34, v34
	v_fmac_f32_e32 v6, v16, v16
	v_fmac_f32_e32 v6, v35, v35
	v_fmac_f32_e32 v6, v17, v17
	v_and_b32_e32 v20, 0xffff0000, v20
	v_fmac_f32_e32 v36, v28, v28
	v_fmac_f32_e32 v36, v20, v20
	v_fmac_f32_e32 v36, v18, v18
	v_fmac_f32_e32 v36, v19, v19
	v_add_u32_e32 v38, s14, v38
	s_waitcnt vmcnt(0) lgkmcnt(0)
; __device__ __forceinline__ unsigned cvt_pk_bf16(float lo, float hi) { unsigned r; asm volatile("v_cvt_pk_bf16_f32 %0, %1, %2" : "=v"(r) : "v"(lo), "v"(hi)); return r; }
; __device__ __forceinline__ void phase_ynorm(unsigned char* ws_) {
;     ...
;         const float sA = wave_sum(ss[0]);
;         const float sB = wave_sum(ss[1] + (lowhalf ? ss[2] : 0.f));
;         const float sC = wave_sum(ss[3] + (lowhalf ? 0.f : ss[2]));
;         const float rA = 1.0f / sqrtf(sA * (1.0f / 512.0f) + 1e-6f), rB = 1.0f / sqrtf(sB * (1.0f / 768.0f) + 1e-6f), rC = 1.0f / sqrtf(sC * (1.0f / 768.0f) + 1e-6f);
; #pragma unroll
;         for (int j = 0; j < 4; ++j) { const float sc = j == 0 ? rA : (j == 1 ? rB : (j == 2 ? (lowhalf ? rB : rC) : rC)); u32x4 o;
; #pragma unroll
;             for (int e = 0; e < 4; ++e) o[e] = cvt_pk_bf16(v[j][2 * e] * sc, v[j][2 * e + 1] * sc);
;             *(u32x4*)(yr + j * 512 + 8 * lane) = o; }
	v_lshlrev_b32_e32 v37, 16, v5
	v_and_b32_e32 v39, 0xffff0000, v5
	v_cndmask_b32_e64 v5, 0, v7, s[4:5]
	v_add_f32_e32 v5, v6, v5
	v_and_b32_e32 v9, 0xffff0000, v2
	v_lshlrev_b32_e32 v8, 16, v2
	v_add_f32_dpp v5, v5, v5 quad_perm:[1,0,3,2] row_mask:0xf bank_mask:0xf bound_ctrl:1
	v_mul_f32_e32 v2, v9, v9
	v_lshlrev_b32_e32 v10, 16, v3
	v_add_f32_dpp v5, v5, v5 quad_perm:[2,3,0,1] row_mask:0xf bank_mask:0xf bound_ctrl:1
	v_fmac_f32_e32 v2, v8, v8
	v_and_b32_e32 v11, 0xffff0000, v3
	v_add_f32_dpp v5, v5, v5 row_half_mirror row_mask:0xf bank_mask:0xf bound_ctrl:1
	v_fmac_f32_e32 v2, v10, v10
	v_lshlrev_b32_e32 v12, 16, v4
	v_add_f32_dpp v5, v5, v5 row_mirror row_mask:0xf bank_mask:0xf bound_ctrl:1
	v_mov_b32_e32 v6, v5
	v_fmac_f32_e32 v2, v11, v11
	s_nop 0
	v_permlane16_swap_b32_e32 v5, v6
	v_and_b32_e32 v13, 0xffff0000, v4
	v_fmac_f32_e32 v2, v12, v12
	v_add_f32_e32 v5, v5, v6
	v_fmac_f32_e32 v2, v13, v13
	v_mov_b32_e32 v6, v5
	v_fmac_f32_e32 v2, v37, v37
	s_nop 0
	v_permlane32_swap_b32_e32 v5, v6
	v_fmac_f32_e32 v2, v39, v39
	v_add_f32_e32 v5, v5, v6
	v_cndmask_b32_e64 v6, v7, 0, s[4:5]
	v_add_f32_e32 v2, v6, v2
	v_fmamk_f32 v5, v5, 0x3aaaaaab, v218
	v_cmp_gt_f32_e32 vcc, s77, v5
	v_add_f32_dpp v2, v2, v2 quad_perm:[1,0,3,2] row_mask:0xf bank_mask:0xf bound_ctrl:1
	v_add_f32_dpp v3, v36, v36 quad_perm:[1,0,3,2] row_mask:0xf bank_mask:0xf bound_ctrl:1
	s_nop 0
	v_add_f32_dpp v2, v2, v2 quad_perm:[2,3,0,1] row_mask:0xf bank_mask:0xf bound_ctrl:1
	v_add_f32_dpp v3, v3, v3 quad_perm:[2,3,0,1] row_mask:0xf bank_mask:0xf bound_ctrl:1
	s_nop 0
	v_add_f32_dpp v2, v2, v2 row_half_mirror row_mask:0xf bank_mask:0xf bound_ctrl:1
	v_add_f32_dpp v3, v3, v3 row_half_mirror row_mask:0xf bank_mask:0xf bound_ctrl:1
	s_nop 0
	v_add_f32_dpp v2, v2, v2 row_mirror row_mask:0xf bank_mask:0xf bound_ctrl:1
	v_mov_b32_e32 v6, v2
	s_nop 1
	v_permlane16_swap_b32_e32 v2, v6
	v_add_f32_e32 v2, v2, v6
	v_mov_b32_e32 v6, v2
	s_nop 1
	v_permlane32_swap_b32_e32 v2, v6
	v_add_f32_e32 v2, v2, v6
	v_mul_f32_e32 v6, 0x4f800000, v5
	v_cndmask_b32_e32 v5, v5, v6, vcc
	v_sqrt_f32_e32 v6, v5
	v_fmamk_f32 v2, v2, 0x3aaaaaab, v218
	v_add_f32_dpp v3, v3, v3 row_mirror row_mask:0xf bank_mask:0xf bound_ctrl:1
	v_mov_b32_e32 v4, v3
	v_add_u32_e32 v7, -1, v6
	v_fma_f32 v36, -v7, v6, v5
	v_cmp_ge_f32_e64 s[0:1], 0, v36
	v_add_u32_e32 v36, 1, v6
	v_permlane16_swap_b32_e32 v3, v4
	v_cndmask_b32_e64 v7, v6, v7, s[0:1]
	v_fma_f32 v6, -v36, v6, v5
	v_cmp_lt_f32_e64 s[0:1], 0, v6
	v_add_f32_e32 v3, v3, v4
	v_mov_b32_e32 v4, v3
	v_cndmask_b32_e64 v6, v7, v36, s[0:1]
	v_mul_f32_e32 v7, 0x37800000, v6
	v_cndmask_b32_e32 v6, v6, v7, vcc
	v_cmp_class_f32_e32 vcc, v5, v219
	v_permlane32_swap_b32_e32 v3, v4
	s_nop 0
	v_cndmask_b32_e32 v5, v6, v5, vcc
	v_div_scale_f32 v6, s[0:1], v5, v5, 1.0
	v_rcp_f32_e32 v7, v6
	s_nop 0
	v_fma_f32 v36, -v6, v7, 1.0
	v_fmac_f32_e32 v7, v36, v7
	v_div_scale_f32 v36, vcc, 1.0, v5, 1.0
	v_mul_f32_e32 v52, v36, v7
	v_fma_f32 v53, -v6, v52, v36
	v_fmac_f32_e32 v52, v53, v7
	v_fma_f32 v6, -v6, v52, v36
	v_div_fmas_f32 v6, v6, v7, v52
	v_div_fixup_f32 v6, v6, v5, 1.0
	v_cmp_gt_f32_e32 vcc, s77, v2
	v_mul_f32_e32 v5, 0x4f800000, v2
	s_nop 0
	v_cndmask_b32_e32 v2, v2, v5, vcc
	v_sqrt_f32_e32 v5, v2
	s_nop 0
	v_add_u32_e32 v7, -1, v5
	v_fma_f32 v36, -v7, v5, v2
	v_cmp_ge_f32_e64 s[0:1], 0, v36
	v_add_u32_e32 v36, 1, v5
	s_nop 0
	v_cndmask_b32_e64 v7, v5, v7, s[0:1]
	v_fma_f32 v5, -v36, v5, v2
	v_cmp_lt_f32_e64 s[0:1], 0, v5
	s_nop 1
	v_cndmask_b32_e64 v5, v7, v36, s[0:1]
	v_mul_f32_e32 v7, 0x37800000, v5
	v_cndmask_b32_e32 v5, v5, v7, vcc
	v_cmp_class_f32_e32 vcc, v2, v219
	s_nop 1
	v_cndmask_b32_e32 v2, v5, v2, vcc
	v_div_scale_f32 v5, s[0:1], v2, v2, 1.0
	v_rcp_f32_e32 v7, v5
	s_nop 0
	v_fma_f32 v36, -v5, v7, 1.0
	v_fmac_f32_e32 v7, v36, v7
	v_div_scale_f32 v36, vcc, 1.0, v2, 1.0
	v_mul_f32_e32 v52, v36, v7
	v_fma_f32 v53, -v5, v52, v36
	v_fmac_f32_e32 v52, v53, v7
	v_fma_f32 v5, -v5, v52, v36
	v_div_fmas_f32 v5, v5, v7, v52
	v_div_fixup_f32 v7, v5, v2, 1.0
	v_add_f32_e32 v2, v3, v4
	v_fmamk_f32 v2, v2, 0x3b000000, v218
	v_cmp_gt_f32_e32 vcc, s77, v2
	v_mul_f32_e32 v3, 0x4f800000, v2
	v_cndmask_b32_e64 v36, v7, v6, s[4:5]
	v_cndmask_b32_e32 v2, v2, v3, vcc
	v_sqrt_f32_e32 v3, v2
	s_nop 0
	v_add_u32_e32 v4, -1, v3
	v_fma_f32 v5, -v4, v3, v2
	v_cmp_ge_f32_e64 s[0:1], 0, v5
	v_add_u32_e32 v5, 1, v3
	s_nop 0
	v_cndmask_b32_e64 v4, v3, v4, s[0:1]
	v_fma_f32 v3, -v5, v3, v2
	v_cmp_lt_f32_e64 s[0:1], 0, v3
	s_nop 1
	v_cndmask_b32_e64 v3, v4, v5, s[0:1]
	v_mul_f32_e32 v4, 0x37800000, v3
	v_cndmask_b32_e32 v3, v3, v4, vcc
	v_cmp_class_f32_e32 vcc, v2, v219
	s_nop 1
	v_cndmask_b32_e32 v2, v3, v2, vcc
	v_div_scale_f32 v3, s[0:1], v2, v2, 1.0
	v_rcp_f32_e32 v4, v3
	s_nop 0
	v_fma_f32 v5, -v3, v4, 1.0
	v_fmac_f32_e32 v4, v5, v4
	v_div_scale_f32 v5, vcc, 1.0, v2, 1.0
	v_mul_f32_e32 v52, v5, v4
	v_fma_f32 v53, -v3, v52, v5
	v_fmac_f32_e32 v52, v53, v4
	v_fma_f32 v3, -v3, v52, v5
	v_div_fmas_f32 v3, v3, v4, v52
	v_div_fixup_f32 v5, v3, v2, 1.0
	v_mul_f32_e32 v2, v5, v31
	v_mul_f32_e32 v3, v5, v32
	v_cvt_pk_bf16_f32 v2, v2, v3
	v_mul_f32_e32 v3, v5, v29
	v_mul_f32_e32 v4, v5, v30
	v_cvt_pk_bf16_f32 v3, v3, v4
	v_mul_f32_e32 v4, v5, v28
	v_mul_f32_e32 v20, v5, v20
	v_mul_f32_e32 v18, v5, v18
	v_mul_f32_e32 v5, v5, v19
	v_cvt_pk_bf16_f32 v4, v4, v20
	v_cvt_pk_bf16_f32 v5, v18, v5
	global_store_dwordx4 v[48:49], v[2:5], off
	v_cmp_lt_i32_e32 vcc, s15, v38
	s_or_b64 s[10:11], vcc, s[10:11]
	v_mul_f32_e32 v2, v21, v6
	v_mul_f32_e32 v3, v14, v6
	v_cvt_pk_bf16_f32 v2, v2, v3
	v_mul_f32_e32 v3, v33, v6
	v_mul_f32_e32 v4, v15, v6
	v_cvt_pk_bf16_f32 v3, v3, v4
	v_mul_f32_e32 v4, v34, v6
	v_mul_f32_e32 v5, v16, v6
	v_cvt_pk_bf16_f32 v4, v4, v5
	v_mul_f32_e32 v5, v35, v6
	v_mul_f32_e32 v6, v17, v6
	v_cvt_pk_bf16_f32 v5, v5, v6
	global_store_dwordx4 v[48:49], v[2:5], off offset:1024
	v_mul_f32_e32 v6, v24, v36
	s_nop 0
	v_mul_f32_e32 v2, v51, v36
	v_mul_f32_e32 v3, v50, v36
	v_cvt_pk_bf16_f32 v2, v2, v3
	v_mul_f32_e32 v3, v23, v36
	v_mul_f32_e32 v4, v22, v36
	v_cvt_pk_bf16_f32 v3, v3, v4
	v_mul_f32_e32 v4, v27, v36
	v_mul_f32_e32 v5, v26, v36
	v_cvt_pk_bf16_f32 v4, v4, v5
	v_mul_f32_e32 v5, v25, v36
	v_cvt_pk_bf16_f32 v5, v5, v6
	global_store_dwordx4 v[48:49], v[2:5], off offset:2048
	v_mul_f32_e32 v6, v7, v39
	s_nop 0
	v_mul_f32_e32 v2, v7, v8
	v_mul_f32_e32 v3, v7, v9
	v_cvt_pk_bf16_f32 v2, v2, v3
	v_mul_f32_e32 v3, v7, v10
	v_mul_f32_e32 v4, v7, v11
	v_cvt_pk_bf16_f32 v3, v3, v4
	v_mul_f32_e32 v4, v7, v12
	v_mul_f32_e32 v5, v7, v13
	v_cvt_pk_bf16_f32 v4, v4, v5
	v_mul_f32_e32 v5, v7, v37
	v_cvt_pk_bf16_f32 v5, v5, v6
	global_store_dwordx4 v[48:49], v[2:5], off offset:3072
	s_andn2_b64 exec, exec, s[10:11]
	s_cbranch_execz .LBB0_938

;     __device__ __forceinline__ void operator()(const f32x4 (&acc)[2][2][4][2], const Unit& u, int wr, int wc, int fr, int fq) const {
;         const int row0 = u.pm * BM + wr * 64 + fr, col0 = u.pn * BM + wc * 32 + 4 * fq;
;         f32x4 gv[2][2];
; #pragma unroll
;         for (int bj = 0; bj < 2; ++bj)
; #pragma unroll
;             for (int n = 0; n < 2; ++n) gv[bj][n] = *(const f32x4*)(gate + col0 + bj * HALF + n * 16) + 1.0f;
; #pragma unroll
;         for (int ai = 0; ai < 2; ++ai)
; #pragma unroll
;             for (int m = 0; m < 4; ++m) { const size_t off = (size_t)(row0 + ai * HALF + m * 16) * ldc + col0;
; #pragma unroll
;                 for (int bj = 0; bj < 2; ++bj)
; #pragma unroll
;                     for (int n = 0; n < 2; ++n) { const f32x4 xr = *(const f32x4*)(xres + off + bj * HALF + n * 16);
;                         *(f32x4*)(z + off + bj * HALF + n * 16) = xr * alpha + gv[bj][n] * acc[ai][bj][m][n]; }
.LBB0_1017:
	v_lshl_or_b32 v158, s68, 8, v164
	v_ashrrev_i32_e32 v159, 31, v158
	v_lshl_add_u64 v[156:157], v[158:159], 2, s[18:19]
	flat_load_dwordx4 v[140:143], v[156:157]
	v_lshl_add_u32 v160, s59, 8, v162
	v_ashrrev_i32_e32 v161, 31, v160
	s_mov_b32 s26, 0x3fb504f3
	s_mov_b64 s[28:29], 0x100000
	s_and_b64 vcc, exec, s[4:5]
	s_waitcnt vmcnt(0) lgkmcnt(0)
	v_pk_add_f32 v[152:153], v[142:143], 1.0 op_sel_hi:[1,0]
	v_pk_add_f32 v[154:155], v[140:141], 1.0 op_sel_hi:[1,0]
	flat_load_dwordx4 v[140:143], v[156:157] offset:64
	s_waitcnt vmcnt(0) lgkmcnt(0)
	v_pk_add_f32 v[150:151], v[142:143], 1.0 op_sel_hi:[1,0]
	v_pk_add_f32 v[148:149], v[140:141], 1.0 op_sel_hi:[1,0]
	flat_load_dwordx4 v[140:143], v[156:157] offset:512
	s_waitcnt vmcnt(0) lgkmcnt(0)
	v_pk_add_f32 v[146:147], v[142:143], 1.0 op_sel_hi:[1,0]
	v_pk_add_f32 v[144:145], v[140:141], 1.0 op_sel_hi:[1,0]
	flat_load_dwordx4 v[140:143], v[156:157] offset:576
	v_lshlrev_b64 v[156:157], 11, v[160:161]
	v_lshl_add_u64 v[156:157], v[156:157], 0, v[158:159]
	v_lshlrev_b64 v[156:157], 2, v[156:157]
	v_lshl_add_u64 v[170:171], s[2:3], 0, v[156:157]
	flat_load_dwordx4 v[166:169], v[170:171]
	s_waitcnt vmcnt(0) lgkmcnt(0)
	v_pk_add_f32 v[142:143], v[142:143], 1.0 op_sel_hi:[1,0]
	v_pk_add_f32 v[140:141], v[140:141], 1.0 op_sel_hi:[1,0]
	v_pk_mul_f32 v[168:169], v[168:169], s[26:27] op_sel_hi:[1,0]
	v_pk_mul_f32 v[166:167], v[166:167], s[26:27] op_sel_hi:[1,0]
	v_pk_fma_f32 v[128:129], v[128:129], v[152:153], v[168:169]
	v_pk_fma_f32 v[126:127], v[126:127], v[154:155], v[166:167]
	v_lshl_add_u64 v[166:167], s[16:17], 0, v[156:157]
	global_store_dwordx4 v[166:167], v[126:129], off
	flat_load_dwordx4 v[126:129], v[170:171] offset:64
	s_waitcnt vmcnt(0) lgkmcnt(0)
	v_pk_mul_f32 v[128:129], v[128:129], s[26:27] op_sel_hi:[1,0]
	v_pk_mul_f32 v[126:127], v[126:127], s[26:27] op_sel_hi:[1,0]
	v_pk_fma_f32 v[124:125], v[124:125], v[150:151], v[128:129]
	v_pk_fma_f32 v[122:123], v[122:123], v[148:149], v[126:127]
	global_store_dwordx4 v[166:167], v[122:125], off offset:64
	flat_load_dwordx4 v[122:125], v[170:171] offset:512
	s_waitcnt vmcnt(0) lgkmcnt(0)
	v_pk_mul_f32 v[124:125], v[124:125], s[26:27] op_sel_hi:[1,0]
	v_pk_mul_f32 v[122:123], v[122:123], s[26:27] op_sel_hi:[1,0]
	v_pk_fma_f32 v[120:121], v[120:121], v[146:147], v[124:125]
	v_pk_fma_f32 v[118:119], v[118:119], v[144:145], v[122:123]
	global_store_dwordx4 v[166:167], v[118:121], off offset:512
	flat_load_dwordx4 v[118:121], v[170:171] offset:576
	s_waitcnt vmcnt(0) lgkmcnt(0)
	v_pk_mul_f32 v[120:121], v[120:121], s[26:27] op_sel_hi:[1,0]
	v_pk_mul_f32 v[118:119], v[118:119], s[26:27] op_sel_hi:[1,0]
	v_pk_fma_f32 v[116:117], v[116:117], v[142:143], v[120:121]
	v_pk_fma_f32 v[114:115], v[114:115], v[140:141], v[118:119]
	global_store_dwordx4 v[166:167], v[114:117], off offset:576
	s_nop 1
	v_or_b32_e32 v114, 16, v160
	v_ashrrev_i32_e32 v115, 31, v114
	v_lshlrev_b64 v[114:115], 11, v[114:115]
	v_lshl_add_u64 v[114:115], v[114:115], 0, v[158:159]
	v_lshlrev_b64 v[118:119], 2, v[114:115]
	v_lshl_add_u64 v[120:121], s[2:3], 0, v[118:119]
	flat_load_dwordx4 v[114:117], v[120:121]
	s_waitcnt vmcnt(0) lgkmcnt(0)
	v_pk_mul_f32 v[116:117], v[116:117], s[26:27] op_sel_hi:[1,0]
	v_pk_mul_f32 v[114:115], v[114:115], s[26:27] op_sel_hi:[1,0]
	v_pk_fma_f32 v[112:113], v[112:113], v[152:153], v[116:117]
	v_pk_fma_f32 v[110:111], v[110:111], v[154:155], v[114:115]
	v_lshl_add_u64 v[114:115], s[16:17], 0, v[118:119]
	global_store_dwordx4 v[114:115], v[110:113], off
	flat_load_dwordx4 v[110:113], v[120:121] offset:64
	s_waitcnt vmcnt(0) lgkmcnt(0)
	v_pk_mul_f32 v[112:113], v[112:113], s[26:27] op_sel_hi:[1,0]
	v_pk_mul_f32 v[110:111], v[110:111], s[26:27] op_sel_hi:[1,0]
	v_pk_fma_f32 v[108:109], v[108:109], v[150:151], v[112:113]
	v_pk_fma_f32 v[106:107], v[106:107], v[148:149], v[110:111]
	global_store_dwordx4 v[114:115], v[106:109], off offset:64
	flat_load_dwordx4 v[106:109], v[120:121] offset:512
	s_waitcnt vmcnt(0) lgkmcnt(0)
	v_pk_mul_f32 v[108:109], v[108:109], s[26:27] op_sel_hi:[1,0]
	v_pk_mul_f32 v[106:107], v[106:107], s[26:27] op_sel_hi:[1,0]
	v_pk_fma_f32 v[104:105], v[104:105], v[146:147], v[108:109]
	v_pk_fma_f32 v[102:103], v[102:103], v[144:145], v[106:107]
	global_store_dwordx4 v[114:115], v[102:105], off offset:512
	flat_load_dwordx4 v[102:105], v[120:121] offset:576
	s_waitcnt vmcnt(0) lgkmcnt(0)
	v_pk_mul_f32 v[104:105], v[104:105], s[26:27] op_sel_hi:[1,0]
	v_pk_mul_f32 v[102:103], v[102:103], s[26:27] op_sel_hi:[1,0]
	v_pk_fma_f32 v[100:101], v[100:101], v[142:143], v[104:105]
	v_pk_fma_f32 v[98:99], v[98:99], v[140:141], v[102:103]
	global_store_dwordx4 v[114:115], v[98:101], off offset:576
	s_nop 1
	v_or_b32_e32 v98, 32, v160
	v_ashrrev_i32_e32 v99, 31, v98
	v_lshlrev_b64 v[98:99], 11, v[98:99]
	v_lshl_add_u64 v[98:99], v[98:99], 0, v[158:159]
	v_lshlrev_b64 v[102:103], 2, v[98:99]
	v_lshl_add_u64 v[104:105], s[2:3], 0, v[102:103]
	flat_load_dwordx4 v[98:101], v[104:105]
	s_waitcnt vmcnt(0) lgkmcnt(0)
	v_pk_mul_f32 v[100:101], v[100:101], s[26:27] op_sel_hi:[1,0]
	v_pk_mul_f32 v[98:99], v[98:99], s[26:27] op_sel_hi:[1,0]
	v_pk_fma_f32 v[96:97], v[96:97], v[152:153], v[100:101]
	v_pk_fma_f32 v[94:95], v[94:95], v[154:155], v[98:99]
	v_lshl_add_u64 v[98:99], s[16:17], 0, v[102:103]
	global_store_dwordx4 v[98:99], v[94:97], off
	flat_load_dwordx4 v[94:97], v[104:105] offset:64
	s_waitcnt vmcnt(0) lgkmcnt(0)
	v_pk_mul_f32 v[96:97], v[96:97], s[26:27] op_sel_hi:[1,0]
	v_pk_mul_f32 v[94:95], v[94:95], s[26:27] op_sel_hi:[1,0]
	v_pk_fma_f32 v[92:93], v[92:93], v[150:151], v[96:97]
	v_pk_fma_f32 v[90:91], v[90:91], v[148:149], v[94:95]
	global_store_dwordx4 v[98:99], v[90:93], off offset:64
	flat_load_dwordx4 v[90:93], v[104:105] offset:512
	s_waitcnt vmcnt(0) lgkmcnt(0)
;     __device__ __forceinline__ void operator()(const f32x4 (&acc)[2][2][4][2], const Unit& u, int wr, int wc, int fr, int fq) const {
;     ...
;         for (int ai = 0; ai < 2; ++ai)
; #pragma unroll
;             for (int m = 0; m < 4; ++m) { const size_t off = (size_t)(row0 + ai * HALF + m * 16) * ldc + col0;
; #pragma unroll
;                 for (int bj = 0; bj < 2; ++bj)
; #pragma unroll
;                     for (int n = 0; n < 2; ++n) { const f32x4 xr = *(const f32x4*)(xres + off + bj * HALF + n * 16);
;                         *(f32x4*)(z + off + bj * HALF + n * 16) = xr * alpha + gv[bj][n] * acc[ai][bj][m][n]; }
	v_pk_mul_f32 v[92:93], v[92:93], s[26:27] op_sel_hi:[1,0]
	v_pk_mul_f32 v[90:91], v[90:91], s[26:27] op_sel_hi:[1,0]
	v_pk_fma_f32 v[88:89], v[88:89], v[146:147], v[92:93]
	v_pk_fma_f32 v[86:87], v[86:87], v[144:145], v[90:91]
	global_store_dwordx4 v[98:99], v[86:89], off offset:512
	flat_load_dwordx4 v[86:89], v[104:105] offset:576
	s_waitcnt vmcnt(0) lgkmcnt(0)
	v_pk_mul_f32 v[88:89], v[88:89], s[26:27] op_sel_hi:[1,0]
	v_pk_mul_f32 v[86:87], v[86:87], s[26:27] op_sel_hi:[1,0]
	v_pk_fma_f32 v[84:85], v[84:85], v[142:143], v[88:89]
	v_pk_fma_f32 v[82:83], v[82:83], v[140:141], v[86:87]
	global_store_dwordx4 v[98:99], v[82:85], off offset:576
	s_nop 1
	v_or_b32_e32 v82, 48, v160
	v_ashrrev_i32_e32 v83, 31, v82
	v_lshlrev_b64 v[82:83], 11, v[82:83]
	v_lshl_add_u64 v[82:83], v[82:83], 0, v[158:159]
	v_lshlrev_b64 v[86:87], 2, v[82:83]
	v_lshl_add_u64 v[88:89], s[2:3], 0, v[86:87]
	flat_load_dwordx4 v[82:85], v[88:89]
	s_waitcnt vmcnt(0) lgkmcnt(0)
	v_pk_mul_f32 v[84:85], v[84:85], s[26:27] op_sel_hi:[1,0]
	v_pk_mul_f32 v[82:83], v[82:83], s[26:27] op_sel_hi:[1,0]
	v_pk_fma_f32 v[80:81], v[80:81], v[152:153], v[84:85]
	v_pk_fma_f32 v[78:79], v[78:79], v[154:155], v[82:83]
	v_lshl_add_u64 v[82:83], s[16:17], 0, v[86:87]
	global_store_dwordx4 v[82:83], v[78:81], off
	flat_load_dwordx4 v[78:81], v[88:89] offset:64
	s_waitcnt vmcnt(0) lgkmcnt(0)
	v_pk_mul_f32 v[80:81], v[80:81], s[26:27] op_sel_hi:[1,0]
	v_pk_mul_f32 v[78:79], v[78:79], s[26:27] op_sel_hi:[1,0]
	v_pk_fma_f32 v[76:77], v[76:77], v[150:151], v[80:81]
	v_pk_fma_f32 v[74:75], v[74:75], v[148:149], v[78:79]
	global_store_dwordx4 v[82:83], v[74:77], off offset:64
	flat_load_dwordx4 v[74:77], v[88:89] offset:512
	s_waitcnt vmcnt(0) lgkmcnt(0)
	v_pk_mul_f32 v[76:77], v[76:77], s[26:27] op_sel_hi:[1,0]
	v_pk_mul_f32 v[74:75], v[74:75], s[26:27] op_sel_hi:[1,0]
	v_pk_fma_f32 v[72:73], v[72:73], v[146:147], v[76:77]
	v_pk_fma_f32 v[70:71], v[70:71], v[144:145], v[74:75]
	global_store_dwordx4 v[82:83], v[70:73], off offset:512
	flat_load_dwordx4 v[70:73], v[88:89] offset:576
	s_waitcnt vmcnt(0) lgkmcnt(0)
	v_pk_mul_f32 v[72:73], v[72:73], s[26:27] op_sel_hi:[1,0]
	v_pk_mul_f32 v[70:71], v[70:71], s[26:27] op_sel_hi:[1,0]
	v_pk_fma_f32 v[68:69], v[68:69], v[142:143], v[72:73]
	v_pk_fma_f32 v[66:67], v[66:67], v[140:141], v[70:71]
	global_store_dwordx4 v[82:83], v[66:69], off offset:576
	v_lshl_add_u64 v[70:71], v[156:157], 0, s[28:29]
	v_lshl_add_u64 v[72:73], s[2:3], 0, v[70:71]
	flat_load_dwordx4 v[66:69], v[72:73]
	s_mov_b64 s[28:29], 0x120000
	s_waitcnt vmcnt(0) lgkmcnt(0)
	v_pk_mul_f32 v[68:69], v[68:69], s[26:27] op_sel_hi:[1,0]
	v_pk_mul_f32 v[66:67], v[66:67], s[26:27] op_sel_hi:[1,0]
	v_pk_fma_f32 v[64:65], v[64:65], v[152:153], v[68:69]
	v_pk_fma_f32 v[62:63], v[62:63], v[154:155], v[66:67]
	v_lshl_add_u64 v[66:67], s[16:17], 0, v[70:71]
	global_store_dwordx4 v[66:67], v[62:65], off
	flat_load_dwordx4 v[62:65], v[72:73] offset:64
	s_waitcnt vmcnt(0) lgkmcnt(0)
	v_pk_mul_f32 v[64:65], v[64:65], s[26:27] op_sel_hi:[1,0]
	v_pk_mul_f32 v[62:63], v[62:63], s[26:27] op_sel_hi:[1,0]
	v_pk_fma_f32 v[60:61], v[60:61], v[150:151], v[64:65]
	v_pk_fma_f32 v[58:59], v[58:59], v[148:149], v[62:63]
	global_store_dwordx4 v[66:67], v[58:61], off offset:64
	flat_load_dwordx4 v[58:61], v[72:73] offset:512
	s_waitcnt vmcnt(0) lgkmcnt(0)
	v_pk_mul_f32 v[60:61], v[60:61], s[26:27] op_sel_hi:[1,0]
	v_pk_mul_f32 v[58:59], v[58:59], s[26:27] op_sel_hi:[1,0]
	v_pk_fma_f32 v[56:57], v[56:57], v[146:147], v[60:61]
	v_pk_fma_f32 v[54:55], v[54:55], v[144:145], v[58:59]
	global_store_dwordx4 v[66:67], v[54:57], off offset:512
	flat_load_dwordx4 v[54:57], v[72:73] offset:576
	s_waitcnt vmcnt(0) lgkmcnt(0)
	v_pk_mul_f32 v[56:57], v[56:57], s[26:27] op_sel_hi:[1,0]
	v_pk_mul_f32 v[54:55], v[54:55], s[26:27] op_sel_hi:[1,0]
	v_pk_fma_f32 v[52:53], v[52:53], v[142:143], v[56:57]
	v_pk_fma_f32 v[50:51], v[50:51], v[140:141], v[54:55]
	v_lshl_add_u64 v[54:55], v[156:157], 0, s[28:29]
	global_store_dwordx4 v[66:67], v[50:53], off offset:576
	v_lshl_add_u64 v[56:57], s[2:3], 0, v[54:55]
	flat_load_dwordx4 v[50:53], v[56:57]
	s_mov_b64 s[28:29], 0x140000
	s_waitcnt vmcnt(0) lgkmcnt(0)
	v_pk_mul_f32 v[52:53], v[52:53], s[26:27] op_sel_hi:[1,0]
	v_pk_mul_f32 v[50:51], v[50:51], s[26:27] op_sel_hi:[1,0]
	v_pk_fma_f32 v[48:49], v[48:49], v[152:153], v[52:53]
	v_pk_fma_f32 v[46:47], v[46:47], v[154:155], v[50:51]
	v_lshl_add_u64 v[50:51], s[16:17], 0, v[54:55]
	global_store_dwordx4 v[50:51], v[46:49], off
	flat_load_dwordx4 v[46:49], v[56:57] offset:64
	s_waitcnt vmcnt(0) lgkmcnt(0)
; #define PG8_BAR __builtin_amdgcn_s_barrier()
;     __device__ __forceinline__ void operator()(const f32x4 (&acc)[2][2][4][2], const Unit& u, int wr, int wc, int fr, int fq) const {
;     ...
;         for (int ai = 0; ai < 2; ++ai)
; #pragma unroll
;             for (int m = 0; m < 4; ++m) { const size_t off = (size_t)(row0 + ai * HALF + m * 16) * ldc + col0;
; #pragma unroll
;                 for (int bj = 0; bj < 2; ++bj)
; #pragma unroll
;                     for (int n = 0; n < 2; ++n) { const f32x4 xr = *(const f32x4*)(xres + off + bj * HALF + n * 16);
;                         *(f32x4*)(z + off + bj * HALF + n * 16) = xr * alpha + gv[bj][n] * acc[ai][bj][m][n]; }
; template <class Epi, class Sched, bool ALIGN_EPI = false, bool SP2 = false>
; __device__ __forceinline__ void gemm_phase(PG8_LAS unsigned char* lds, const Gemm g, const Sched& S, const Epi& E) {
;     ...
;         if (!has_next) break;
; #pragma unroll
;         for (int a = 0; a < 2; ++a)
; #pragma unroll
;             for (int b = 0; b < 2; ++b)
; #pragma unroll
;                 for (int m = 0; m < 4; ++m)
; #pragma unroll
;                     for (int n = 0; n < 2; ++n) acc[a][b][m][n] = (f32x4){0.f, 0.f, 0.f, 0.f};
;         cur = nxt; cA = nA; cB = nB; ++ui;
;         if constexpr (ALIGN_EPI) { if (wr == 1) PG8_BAR; }
	v_pk_mul_f32 v[48:49], v[48:49], s[26:27] op_sel_hi:[1,0]
	v_pk_mul_f32 v[46:47], v[46:47], s[26:27] op_sel_hi:[1,0]
	v_pk_fma_f32 v[44:45], v[44:45], v[150:151], v[48:49]
	v_pk_fma_f32 v[42:43], v[42:43], v[148:149], v[46:47]
	global_store_dwordx4 v[50:51], v[42:45], off offset:64
	flat_load_dwordx4 v[42:45], v[56:57] offset:512
	s_waitcnt vmcnt(0) lgkmcnt(0)
	v_pk_mul_f32 v[44:45], v[44:45], s[26:27] op_sel_hi:[1,0]
	v_pk_mul_f32 v[42:43], v[42:43], s[26:27] op_sel_hi:[1,0]
	v_pk_fma_f32 v[40:41], v[40:41], v[146:147], v[44:45]
	v_pk_fma_f32 v[38:39], v[38:39], v[144:145], v[42:43]
	global_store_dwordx4 v[50:51], v[38:41], off offset:512
	flat_load_dwordx4 v[38:41], v[56:57] offset:576
	s_waitcnt vmcnt(0) lgkmcnt(0)
	v_pk_mul_f32 v[40:41], v[40:41], s[26:27] op_sel_hi:[1,0]
	v_pk_mul_f32 v[38:39], v[38:39], s[26:27] op_sel_hi:[1,0]
	v_pk_fma_f32 v[36:37], v[36:37], v[142:143], v[40:41]
	v_pk_fma_f32 v[34:35], v[34:35], v[140:141], v[38:39]
	v_lshl_add_u64 v[38:39], v[156:157], 0, s[28:29]
	global_store_dwordx4 v[50:51], v[34:37], off offset:576
	v_lshl_add_u64 v[40:41], s[2:3], 0, v[38:39]
	flat_load_dwordx4 v[34:37], v[40:41]
	s_mov_b64 s[28:29], 0x160000
	s_waitcnt vmcnt(0) lgkmcnt(0)
	v_pk_mul_f32 v[36:37], v[36:37], s[26:27] op_sel_hi:[1,0]
	v_pk_mul_f32 v[34:35], v[34:35], s[26:27] op_sel_hi:[1,0]
	v_pk_fma_f32 v[32:33], v[32:33], v[152:153], v[36:37]
	v_pk_fma_f32 v[30:31], v[30:31], v[154:155], v[34:35]
	v_lshl_add_u64 v[34:35], s[16:17], 0, v[38:39]
	global_store_dwordx4 v[34:35], v[30:33], off
	flat_load_dwordx4 v[30:33], v[40:41] offset:64
	s_waitcnt vmcnt(0) lgkmcnt(0)
	v_pk_mul_f32 v[32:33], v[32:33], s[26:27] op_sel_hi:[1,0]
	v_pk_mul_f32 v[30:31], v[30:31], s[26:27] op_sel_hi:[1,0]
	v_pk_fma_f32 v[28:29], v[28:29], v[150:151], v[32:33]
	v_pk_fma_f32 v[26:27], v[26:27], v[148:149], v[30:31]
	global_store_dwordx4 v[34:35], v[26:29], off offset:64
	flat_load_dwordx4 v[26:29], v[40:41] offset:512
	s_waitcnt vmcnt(0) lgkmcnt(0)
	v_pk_mul_f32 v[28:29], v[28:29], s[26:27] op_sel_hi:[1,0]
	v_pk_mul_f32 v[26:27], v[26:27], s[26:27] op_sel_hi:[1,0]
	v_pk_fma_f32 v[24:25], v[24:25], v[146:147], v[28:29]
	v_pk_fma_f32 v[22:23], v[22:23], v[144:145], v[26:27]
	global_store_dwordx4 v[34:35], v[22:25], off offset:512
	flat_load_dwordx4 v[22:25], v[40:41] offset:576
	s_waitcnt vmcnt(0) lgkmcnt(0)
	v_pk_mul_f32 v[24:25], v[24:25], s[26:27] op_sel_hi:[1,0]
	v_pk_mul_f32 v[22:23], v[22:23], s[26:27] op_sel_hi:[1,0]
	v_pk_fma_f32 v[20:21], v[20:21], v[142:143], v[24:25]
	v_pk_fma_f32 v[18:19], v[18:19], v[140:141], v[22:23]
	v_lshl_add_u64 v[22:23], v[156:157], 0, s[28:29]
	global_store_dwordx4 v[34:35], v[18:21], off offset:576
	v_lshl_add_u64 v[24:25], s[2:3], 0, v[22:23]
	flat_load_dwordx4 v[18:21], v[24:25]
	s_waitcnt vmcnt(0) lgkmcnt(0)
	v_pk_mul_f32 v[20:21], v[20:21], s[26:27] op_sel_hi:[1,0]
	v_pk_mul_f32 v[18:19], v[18:19], s[26:27] op_sel_hi:[1,0]
	v_pk_fma_f32 v[16:17], v[16:17], v[152:153], v[20:21]
	v_pk_fma_f32 v[14:15], v[14:15], v[154:155], v[18:19]
	v_lshl_add_u64 v[18:19], s[16:17], 0, v[22:23]
	global_store_dwordx4 v[18:19], v[14:17], off
	flat_load_dwordx4 v[14:17], v[24:25] offset:64
	s_waitcnt vmcnt(0) lgkmcnt(0)
	v_pk_mul_f32 v[16:17], v[16:17], s[26:27] op_sel_hi:[1,0]
	v_pk_mul_f32 v[14:15], v[14:15], s[26:27] op_sel_hi:[1,0]
	v_pk_fma_f32 v[12:13], v[12:13], v[150:151], v[16:17]
	v_pk_fma_f32 v[10:11], v[10:11], v[148:149], v[14:15]
	global_store_dwordx4 v[18:19], v[10:13], off offset:64
	flat_load_dwordx4 v[10:13], v[24:25] offset:512
	s_waitcnt vmcnt(0) lgkmcnt(0)
	v_pk_mul_f32 v[12:13], v[12:13], s[26:27] op_sel_hi:[1,0]
	v_pk_mul_f32 v[10:11], v[10:11], s[26:27] op_sel_hi:[1,0]
	v_pk_fma_f32 v[8:9], v[8:9], v[146:147], v[12:13]
	v_pk_fma_f32 v[6:7], v[6:7], v[144:145], v[10:11]
	global_store_dwordx4 v[18:19], v[6:9], off offset:512
	flat_load_dwordx4 v[6:9], v[24:25] offset:576
	s_waitcnt vmcnt(0) lgkmcnt(0)
	v_pk_mul_f32 v[8:9], v[8:9], s[26:27] op_sel_hi:[1,0]
	v_pk_mul_f32 v[6:7], v[6:7], s[26:27] op_sel_hi:[1,0]
	v_pk_fma_f32 v[4:5], v[4:5], v[142:143], v[8:9]
	v_pk_fma_f32 v[2:3], v[2:3], v[140:141], v[6:7]
	global_store_dwordx4 v[18:19], v[2:5], off offset:576
	s_mov_b64 s[26:27], -1
	s_cbranch_vccnz .LBB0_1001
	s_andn2_b64 vcc, exec, s[14:15]
	s_cbranch_vccnz .LBB0_1000
	s_barrier
	s_branch .LBB0_1000

; __device__ __forceinline__ u32x4 pack8(const f32x4 v0, const f32x4 v1) { u32x4 w; w.x = cvt_pk_bf16(v0[0], v0[1]); w.y = cvt_pk_bf16(v0[2], v0[3]); w.z = cvt_pk_bf16(v1[0], v1[1]); w.w = cvt_pk_bf16(v1[2], v1[3]); return w; }
;     __device__ __forceinline__ void operator()(const f32x4 (&acc)[2][2][4][2], const Unit& u, int wr, int wc, int fr, int fq) const {
;         const int row0 = u.pm * BM + wr * 64 + fr, col0 = u.pn * HALF + wc * 32 + 8 * fq;
; #pragma unroll
;         for (int ai = 0; ai < 2; ++ai)
; #pragma unroll
;             for (int m = 0; m < 4; ++m) { f32x4 h[2];
; #pragma unroll
;                 for (int n = 0; n < 2; ++n) { const f32x4 g = acc[ai][0][m][n], up = acc[ai][1][m][n];
; #pragma unroll
;                     for (int j = 0; j < 4; ++j) h[n][j] = g[j] * __builtin_amdgcn_rcpf(1.0f + __builtin_amdgcn_exp2f(-1.4426950408889634f * g[j])) * up[j]; }
;                 *(u32x4*)(H + (size_t)(row0 + ai * HALF + m * 16) * ldc + col0) = pack8(h[0], h[1]); }
.LBB0_1156:
	v_mul_f32_e32 v145, 0xbfb8aa3b, v122
	v_exp_f32_e32 v145, v145
	v_lshl_or_b32 v146, s53, 7, v142
	v_lshl_add_u32 v144, s52, 8, v140
	v_ashrrev_i32_e32 v147, 31, v146
	v_add_f32_e32 v145, 1.0, v145
	v_rcp_f32_e32 v145, v145
	s_movk_i32 s24, 0x2c00
	s_and_b64 vcc, exec, s[4:5]
	v_mul_f32_e32 v122, v122, v145
	v_mul_f32_e32 v122, v126, v122
	v_mul_f32_e32 v126, 0xbfb8aa3b, v123
	v_exp_f32_e32 v126, v126
	s_nop 0
	v_add_f32_e32 v126, 1.0, v126
	v_rcp_f32_e32 v126, v126
	s_nop 0
	v_mul_f32_e32 v123, v123, v126
	v_mul_f32_e32 v126, 0xbfb8aa3b, v124
	v_exp_f32_e32 v126, v126
	v_mul_f32_e32 v123, v127, v123
	v_add_f32_e32 v126, 1.0, v126
	v_rcp_f32_e32 v126, v126
	s_nop 0
	v_mul_f32_e32 v124, v124, v126
	v_mul_f32_e32 v126, 0xbfb8aa3b, v125
	v_exp_f32_e32 v126, v126
	v_mul_f32_e32 v124, v128, v124
	v_add_f32_e32 v126, 1.0, v126
	v_rcp_f32_e32 v126, v126
	s_nop 0
	v_mul_f32_e32 v125, v125, v126
	v_mul_f32_e32 v126, 0xbfb8aa3b, v118
	v_exp_f32_e32 v126, v126
	v_mul_f32_e32 v125, v129, v125
	v_add_f32_e32 v126, 1.0, v126
	v_rcp_f32_e32 v126, v126
	s_nop 0
	v_mul_f32_e32 v118, v118, v126
	v_mul_f32_e32 v114, v114, v118
	v_mul_f32_e32 v118, 0xbfb8aa3b, v119
	v_exp_f32_e32 v118, v118
	s_nop 0
	v_add_f32_e32 v118, 1.0, v118
	v_rcp_f32_e32 v118, v118
	s_nop 0
	v_mul_f32_e32 v118, v119, v118
	v_mul_f32_e32 v115, v115, v118
	v_mul_f32_e32 v118, 0xbfb8aa3b, v120
	v_exp_f32_e32 v118, v118
	s_nop 0
	v_add_f32_e32 v118, 1.0, v118
	v_rcp_f32_e32 v118, v118
	s_nop 0
	v_mul_f32_e32 v118, v120, v118
	v_mul_f32_e32 v116, v116, v118
	v_mul_f32_e32 v118, 0xbfb8aa3b, v121
	v_exp_f32_e32 v118, v118
	s_nop 0
	v_add_f32_e32 v118, 1.0, v118
	v_rcp_f32_e32 v118, v118
	s_nop 0
	v_mul_f32_e32 v118, v121, v118
	v_mul_f32_e32 v117, v117, v118
	v_cvt_pk_bf16_f32 v118, v122, v123
	v_cvt_pk_bf16_f32 v119, v124, v125
	v_cvt_pk_bf16_f32 v120, v114, v115
	v_mov_b64_e32 v[114:115], s[14:15]
	v_cvt_pk_bf16_f32 v121, v116, v117
	v_mad_i64_i32 v[122:123], s[22:23], v144, s24, v[114:115]
	v_lshlrev_b64 v[116:117], 1, v[146:147]
	v_lshl_add_u64 v[122:123], v[122:123], 0, v[116:117]
	global_store_dwordx4 v[122:123], v[118:121], off
	s_nop 1
	v_mul_f32_e32 v118, 0xbfb8aa3b, v110
	v_exp_f32_e32 v118, v118
	s_nop 0
	v_add_f32_e32 v118, 1.0, v118
	v_rcp_f32_e32 v118, v118
	s_nop 0
	v_mul_f32_e32 v110, v110, v118
	v_mul_f32_e32 v106, v106, v110
	v_mul_f32_e32 v110, 0xbfb8aa3b, v111
	v_exp_f32_e32 v110, v110
	s_nop 0
	v_add_f32_e32 v110, 1.0, v110
	v_rcp_f32_e32 v110, v110
	s_nop 0
	v_mul_f32_e32 v110, v111, v110
	v_mul_f32_e32 v107, v107, v110
	v_mul_f32_e32 v110, 0xbfb8aa3b, v112
	v_exp_f32_e32 v110, v110
	s_nop 0
	v_add_f32_e32 v110, 1.0, v110
	v_rcp_f32_e32 v110, v110
	s_nop 0
	v_mul_f32_e32 v110, v112, v110
	v_mul_f32_e32 v108, v108, v110
	v_mul_f32_e32 v110, 0xbfb8aa3b, v113
	v_exp_f32_e32 v110, v110
	s_nop 0
	v_add_f32_e32 v110, 1.0, v110
	v_rcp_f32_e32 v110, v110
	s_nop 0
	v_mul_f32_e32 v110, v113, v110
	v_mul_f32_e32 v109, v109, v110
	v_mul_f32_e32 v110, 0xbfb8aa3b, v102
	v_exp_f32_e32 v110, v110
	s_nop 0
	v_add_f32_e32 v110, 1.0, v110
	v_rcp_f32_e32 v110, v110
	s_nop 0
	v_mul_f32_e32 v102, v102, v110
	v_mul_f32_e32 v102, v98, v102
	v_mul_f32_e32 v98, 0xbfb8aa3b, v103
	v_exp_f32_e32 v98, v98
	s_nop 0
	v_add_f32_e32 v98, 1.0, v98
	v_rcp_f32_e32 v98, v98
	s_nop 0
	v_mul_f32_e32 v98, v103, v98
	v_mul_f32_e32 v103, v99, v98
	v_mul_f32_e32 v98, 0xbfb8aa3b, v104
	v_exp_f32_e32 v98, v98
	s_nop 0
	v_add_f32_e32 v98, 1.0, v98
	v_rcp_f32_e32 v98, v98
	s_nop 0
	v_mul_f32_e32 v98, v104, v98
	v_mul_f32_e32 v104, v100, v98
	v_mul_f32_e32 v98, 0xbfb8aa3b, v105
	v_exp_f32_e32 v98, v98
	s_nop 0
	v_add_f32_e32 v98, 1.0, v98
	v_rcp_f32_e32 v98, v98
	s_nop 0
	v_mul_f32_e32 v98, v105, v98
	v_mul_f32_e32 v101, v101, v98
	v_cvt_pk_bf16_f32 v98, v106, v107
	v_cvt_pk_bf16_f32 v99, v108, v109
	v_cvt_pk_bf16_f32 v100, v102, v103
	v_or_b32_e32 v102, 16, v144
	v_mad_i64_i32 v[102:103], s[22:23], v102, s24, v[114:115]
	v_lshl_add_u64 v[102:103], v[102:103], 0, v[116:117]
	v_cvt_pk_bf16_f32 v101, v104, v101
	global_store_dwordx4 v[102:103], v[98:101], off
	s_nop 1
	v_mul_f32_e32 v98, 0xbfb8aa3b, v94
	v_exp_f32_e32 v98, v98
	s_nop 0
	v_add_f32_e32 v98, 1.0, v98
	v_rcp_f32_e32 v98, v98
	s_nop 0
	v_mul_f32_e32 v94, v94, v98
	v_mul_f32_e32 v90, v90, v94
	v_mul_f32_e32 v94, 0xbfb8aa3b, v95
	v_exp_f32_e32 v94, v94
	s_nop 0
	v_add_f32_e32 v94, 1.0, v94
	v_rcp_f32_e32 v94, v94
	s_nop 0
	v_mul_f32_e32 v94, v95, v94
	v_mul_f32_e32 v91, v91, v94
	v_mul_f32_e32 v94, 0xbfb8aa3b, v96
	v_exp_f32_e32 v94, v94
	s_nop 0
	v_add_f32_e32 v94, 1.0, v94
	v_rcp_f32_e32 v94, v94
	s_nop 0
	v_mul_f32_e32 v94, v96, v94
	v_mul_f32_e32 v92, v92, v94
	v_mul_f32_e32 v94, 0xbfb8aa3b, v97
	v_exp_f32_e32 v94, v94
	s_nop 0
	v_add_f32_e32 v94, 1.0, v94
	v_rcp_f32_e32 v94, v94
	s_nop 0
	v_mul_f32_e32 v94, v97, v94
	v_mul_f32_e32 v93, v93, v94
	v_mul_f32_e32 v94, 0xbfb8aa3b, v86
	v_exp_f32_e32 v94, v94
	s_nop 0
	v_add_f32_e32 v94, 1.0, v94
	v_rcp_f32_e32 v94, v94
	s_nop 0
	v_mul_f32_e32 v86, v86, v94
	v_mul_f32_e32 v86, v82, v86
	v_mul_f32_e32 v82, 0xbfb8aa3b, v87
	v_exp_f32_e32 v82, v82
	s_nop 0
	v_add_f32_e32 v82, 1.0, v82
	v_rcp_f32_e32 v82, v82
	s_nop 0
	v_mul_f32_e32 v82, v87, v82
	v_mul_f32_e32 v87, v83, v82
	v_mul_f32_e32 v82, 0xbfb8aa3b, v88
	v_exp_f32_e32 v82, v82
	s_nop 0
	v_add_f32_e32 v82, 1.0, v82
	v_rcp_f32_e32 v82, v82
	s_nop 0
	v_mul_f32_e32 v82, v88, v82
	v_mul_f32_e32 v88, v84, v82
	v_mul_f32_e32 v82, 0xbfb8aa3b, v89
	v_exp_f32_e32 v82, v82
	s_nop 0
	v_add_f32_e32 v82, 1.0, v82
	v_rcp_f32_e32 v82, v82
	s_nop 0
	v_mul_f32_e32 v82, v89, v82
	v_mul_f32_e32 v85, v85, v82
	v_cvt_pk_bf16_f32 v82, v90, v91
	v_cvt_pk_bf16_f32 v83, v92, v93
; __device__ __forceinline__ u32x4 pack8(const f32x4 v0, const f32x4 v1) { u32x4 w; w.x = cvt_pk_bf16(v0[0], v0[1]); w.y = cvt_pk_bf16(v0[2], v0[3]); w.z = cvt_pk_bf16(v1[0], v1[1]); w.w = cvt_pk_bf16(v1[2], v1[3]); return w; }
;     __device__ __forceinline__ void operator()(const f32x4 (&acc)[2][2][4][2], const Unit& u, int wr, int wc, int fr, int fq) const {
;     ...
;             for (int m = 0; m < 4; ++m) { f32x4 h[2];
; #pragma unroll
;                 for (int n = 0; n < 2; ++n) { const f32x4 g = acc[ai][0][m][n], up = acc[ai][1][m][n];
; #pragma unroll
;                     for (int j = 0; j < 4; ++j) h[n][j] = g[j] * __builtin_amdgcn_rcpf(1.0f + __builtin_amdgcn_exp2f(-1.4426950408889634f * g[j])) * up[j]; }
;                 *(u32x4*)(H + (size_t)(row0 + ai * HALF + m * 16) * ldc + col0) = pack8(h[0], h[1]); }
	v_cvt_pk_bf16_f32 v84, v86, v87
	v_or_b32_e32 v86, 32, v144
	v_mad_i64_i32 v[86:87], s[22:23], v86, s24, v[114:115]
	v_lshl_add_u64 v[86:87], v[86:87], 0, v[116:117]
	v_cvt_pk_bf16_f32 v85, v88, v85
	global_store_dwordx4 v[86:87], v[82:85], off
	s_nop 1
	v_mul_f32_e32 v82, 0xbfb8aa3b, v78
	v_exp_f32_e32 v82, v82
	s_nop 0
	v_add_f32_e32 v82, 1.0, v82
	v_rcp_f32_e32 v82, v82
	s_nop 0
	v_mul_f32_e32 v78, v78, v82
	v_mul_f32_e32 v74, v74, v78
	v_mul_f32_e32 v78, 0xbfb8aa3b, v79
	v_exp_f32_e32 v78, v78
	s_nop 0
	v_add_f32_e32 v78, 1.0, v78
	v_rcp_f32_e32 v78, v78
	s_nop 0
	v_mul_f32_e32 v78, v79, v78
	v_mul_f32_e32 v75, v75, v78
	v_mul_f32_e32 v78, 0xbfb8aa3b, v80
	v_exp_f32_e32 v78, v78
	s_nop 0
	v_add_f32_e32 v78, 1.0, v78
	v_rcp_f32_e32 v78, v78
	s_nop 0
	v_mul_f32_e32 v78, v80, v78
	v_mul_f32_e32 v76, v76, v78
	v_mul_f32_e32 v78, 0xbfb8aa3b, v81
	v_exp_f32_e32 v78, v78
	s_nop 0
	v_add_f32_e32 v78, 1.0, v78
	v_rcp_f32_e32 v78, v78
	s_nop 0
	v_mul_f32_e32 v78, v81, v78
	v_mul_f32_e32 v77, v77, v78
	v_mul_f32_e32 v78, 0xbfb8aa3b, v70
	v_exp_f32_e32 v78, v78
	s_nop 0
	v_add_f32_e32 v78, 1.0, v78
	v_rcp_f32_e32 v78, v78
	s_nop 0
	v_mul_f32_e32 v70, v70, v78
	v_mul_f32_e32 v70, v66, v70
	v_mul_f32_e32 v66, 0xbfb8aa3b, v71
	v_exp_f32_e32 v66, v66
	s_nop 0
	v_add_f32_e32 v66, 1.0, v66
	v_rcp_f32_e32 v66, v66
	s_nop 0
	v_mul_f32_e32 v66, v71, v66
	v_mul_f32_e32 v71, v67, v66
	v_mul_f32_e32 v66, 0xbfb8aa3b, v72
	v_exp_f32_e32 v66, v66
	s_nop 0
	v_add_f32_e32 v66, 1.0, v66
	v_rcp_f32_e32 v66, v66
	s_nop 0
	v_mul_f32_e32 v66, v72, v66
	v_mul_f32_e32 v72, v68, v66
	v_mul_f32_e32 v66, 0xbfb8aa3b, v73
	v_exp_f32_e32 v66, v66
	s_nop 0
	v_add_f32_e32 v66, 1.0, v66
	v_rcp_f32_e32 v66, v66
	s_nop 0
	v_mul_f32_e32 v66, v73, v66
	v_mul_f32_e32 v69, v69, v66
	v_cvt_pk_bf16_f32 v66, v74, v75
	v_cvt_pk_bf16_f32 v67, v76, v77
	v_cvt_pk_bf16_f32 v68, v70, v71
	v_or_b32_e32 v70, 48, v144
	v_mad_i64_i32 v[70:71], s[22:23], v70, s24, v[114:115]
	v_lshl_add_u64 v[70:71], v[70:71], 0, v[116:117]
	v_cvt_pk_bf16_f32 v69, v72, v69
	global_store_dwordx4 v[70:71], v[66:69], off
	s_nop 1
	v_mul_f32_e32 v67, 0xbfb8aa3b, v62
	v_exp_f32_e32 v67, v67
	v_add_u32_e32 v66, 0x80, v144
	v_add_f32_e32 v67, 1.0, v67
	v_rcp_f32_e32 v67, v67
	s_nop 0
	v_mul_f32_e32 v62, v62, v67
	v_mul_f32_e32 v58, v58, v62
	v_mul_f32_e32 v62, 0xbfb8aa3b, v63
	v_exp_f32_e32 v62, v62
	s_nop 0
	v_add_f32_e32 v62, 1.0, v62
	v_rcp_f32_e32 v62, v62
	s_nop 0
	v_mul_f32_e32 v62, v63, v62
	v_mul_f32_e32 v59, v59, v62
	v_mul_f32_e32 v62, 0xbfb8aa3b, v64
	v_exp_f32_e32 v62, v62
	s_nop 0
	v_add_f32_e32 v62, 1.0, v62
	v_rcp_f32_e32 v62, v62
	s_nop 0
	v_mul_f32_e32 v62, v64, v62
	v_mul_f32_e32 v60, v60, v62
	v_mul_f32_e32 v62, 0xbfb8aa3b, v65
	v_exp_f32_e32 v62, v62
	s_nop 0
	v_add_f32_e32 v62, 1.0, v62
	v_rcp_f32_e32 v62, v62
	s_nop 0
	v_mul_f32_e32 v62, v65, v62
	v_mul_f32_e32 v61, v61, v62
	v_mul_f32_e32 v62, 0xbfb8aa3b, v54
	v_exp_f32_e32 v62, v62
	s_nop 0
	v_add_f32_e32 v62, 1.0, v62
	v_rcp_f32_e32 v62, v62
	s_nop 0
	v_mul_f32_e32 v54, v54, v62
	v_mul_f32_e32 v54, v50, v54
	v_mul_f32_e32 v50, 0xbfb8aa3b, v55
	v_exp_f32_e32 v50, v50
	s_nop 0
	v_add_f32_e32 v50, 1.0, v50
	v_rcp_f32_e32 v50, v50
	s_nop 0
	v_mul_f32_e32 v50, v55, v50
	v_mul_f32_e32 v55, v51, v50
	v_mul_f32_e32 v50, 0xbfb8aa3b, v56
	v_exp_f32_e32 v50, v50
	s_nop 0
	v_add_f32_e32 v50, 1.0, v50
	v_rcp_f32_e32 v50, v50
	s_nop 0
	v_mul_f32_e32 v50, v56, v50
	v_mul_f32_e32 v56, v52, v50
	v_mul_f32_e32 v50, 0xbfb8aa3b, v57
	v_exp_f32_e32 v50, v50
	s_nop 0
	v_add_f32_e32 v50, 1.0, v50
	v_rcp_f32_e32 v50, v50
	s_nop 0
	v_mul_f32_e32 v50, v57, v50
	v_mul_f32_e32 v53, v53, v50
	v_cvt_pk_bf16_f32 v50, v58, v59
	v_cvt_pk_bf16_f32 v51, v60, v61
	v_cvt_pk_bf16_f32 v52, v54, v55
	v_mad_i64_i32 v[54:55], s[22:23], v66, s24, v[114:115]
	v_lshl_add_u64 v[54:55], v[54:55], 0, v[116:117]
	v_cvt_pk_bf16_f32 v53, v56, v53
	global_store_dwordx4 v[54:55], v[50:53], off
	s_nop 1
	v_mul_f32_e32 v50, 0xbfb8aa3b, v46
	v_exp_f32_e32 v50, v50
	s_nop 0
	v_add_f32_e32 v50, 1.0, v50
	v_rcp_f32_e32 v50, v50
	s_nop 0
	v_mul_f32_e32 v46, v46, v50
	v_mul_f32_e32 v42, v42, v46
	v_mul_f32_e32 v46, 0xbfb8aa3b, v47
	v_exp_f32_e32 v46, v46
	s_nop 0
	v_add_f32_e32 v46, 1.0, v46
	v_rcp_f32_e32 v46, v46
	s_nop 0
	v_mul_f32_e32 v46, v47, v46
	v_mul_f32_e32 v43, v43, v46
	v_mul_f32_e32 v46, 0xbfb8aa3b, v48
	v_exp_f32_e32 v46, v46
	s_nop 0
	v_add_f32_e32 v46, 1.0, v46
	v_rcp_f32_e32 v46, v46
	s_nop 0
	v_mul_f32_e32 v46, v48, v46
	v_mul_f32_e32 v44, v44, v46
	v_mul_f32_e32 v46, 0xbfb8aa3b, v49
	v_exp_f32_e32 v46, v46
	s_nop 0
	v_add_f32_e32 v46, 1.0, v46
	v_rcp_f32_e32 v46, v46
	s_nop 0
	v_mul_f32_e32 v46, v49, v46
	v_mul_f32_e32 v45, v45, v46
	v_mul_f32_e32 v46, 0xbfb8aa3b, v38
	v_exp_f32_e32 v46, v46
	s_nop 0
; __device__ __forceinline__ u32x4 pack8(const f32x4 v0, const f32x4 v1) { u32x4 w; w.x = cvt_pk_bf16(v0[0], v0[1]); w.y = cvt_pk_bf16(v0[2], v0[3]); w.z = cvt_pk_bf16(v1[0], v1[1]); w.w = cvt_pk_bf16(v1[2], v1[3]); return w; }
; #define PG8_BAR __builtin_amdgcn_s_barrier()
;     __device__ __forceinline__ void operator()(const f32x4 (&acc)[2][2][4][2], const Unit& u, int wr, int wc, int fr, int fq) const {
;     ...
;             for (int m = 0; m < 4; ++m) { f32x4 h[2];
; #pragma unroll
;                 for (int n = 0; n < 2; ++n) { const f32x4 g = acc[ai][0][m][n], up = acc[ai][1][m][n];
; #pragma unroll
;                     for (int j = 0; j < 4; ++j) h[n][j] = g[j] * __builtin_amdgcn_rcpf(1.0f + __builtin_amdgcn_exp2f(-1.4426950408889634f * g[j])) * up[j]; }
;                 *(u32x4*)(H + (size_t)(row0 + ai * HALF + m * 16) * ldc + col0) = pack8(h[0], h[1]); }
; template <class Epi, class Sched, bool ALIGN_EPI = false, bool SP2 = false>
; __device__ __forceinline__ void gemm_phase(PG8_LAS unsigned char* lds, const Gemm g, const Sched& S, const Epi& E) {
;     ...
;         if constexpr (ALIGN_EPI) { if (wr == 0) PG8_BAR; }
;         if constexpr (!Epi::AFTER_DRAIN) { E(acc, cur, wr, wc, fr, fq); S.done(cur); }
;         if (!has_next) break;
; #pragma unroll
;         for (int a = 0; a < 2; ++a)
; #pragma unroll
;             for (int b = 0; b < 2; ++b)
; #pragma unroll
;                 for (int m = 0; m < 4; ++m)
; #pragma unroll
;                     for (int n = 0; n < 2; ++n) acc[a][b][m][n] = (f32x4){0.f, 0.f, 0.f, 0.f};
;         cur = nxt; cA = nA; cB = nB; ++ui;
;         if constexpr (ALIGN_EPI) { if (wr == 1) PG8_BAR; }
	v_add_f32_e32 v46, 1.0, v46
	v_rcp_f32_e32 v46, v46
	s_nop 0
	v_mul_f32_e32 v38, v38, v46
	v_mul_f32_e32 v38, v34, v38
	v_mul_f32_e32 v34, 0xbfb8aa3b, v39
	v_exp_f32_e32 v34, v34
	s_nop 0
	v_add_f32_e32 v34, 1.0, v34
	v_rcp_f32_e32 v34, v34
	s_nop 0
	v_mul_f32_e32 v34, v39, v34
	v_mul_f32_e32 v39, v35, v34
	v_mul_f32_e32 v34, 0xbfb8aa3b, v40
	v_exp_f32_e32 v34, v34
	s_nop 0
	v_add_f32_e32 v34, 1.0, v34
	v_rcp_f32_e32 v34, v34
	s_nop 0
	v_mul_f32_e32 v34, v40, v34
	v_mul_f32_e32 v40, v36, v34
	v_mul_f32_e32 v34, 0xbfb8aa3b, v41
	v_exp_f32_e32 v34, v34
	s_nop 0
	v_add_f32_e32 v34, 1.0, v34
	v_rcp_f32_e32 v34, v34
	s_nop 0
	v_mul_f32_e32 v34, v41, v34
	v_mul_f32_e32 v37, v37, v34
	v_cvt_pk_bf16_f32 v34, v42, v43
	v_cvt_pk_bf16_f32 v35, v44, v45
	v_cvt_pk_bf16_f32 v36, v38, v39
	v_add_u32_e32 v38, 0x90, v144
	v_mad_i64_i32 v[38:39], s[22:23], v38, s24, v[114:115]
	v_lshl_add_u64 v[38:39], v[38:39], 0, v[116:117]
	v_cvt_pk_bf16_f32 v37, v40, v37
	global_store_dwordx4 v[38:39], v[34:37], off
	s_nop 1
	v_mul_f32_e32 v34, 0xbfb8aa3b, v30
	v_exp_f32_e32 v34, v34
	s_nop 0
	v_add_f32_e32 v34, 1.0, v34
	v_rcp_f32_e32 v34, v34
	s_nop 0
	v_mul_f32_e32 v30, v30, v34
	v_mul_f32_e32 v26, v26, v30
	v_mul_f32_e32 v30, 0xbfb8aa3b, v31
	v_exp_f32_e32 v30, v30
	s_nop 0
	v_add_f32_e32 v30, 1.0, v30
	v_rcp_f32_e32 v30, v30
	s_nop 0
	v_mul_f32_e32 v30, v31, v30
	v_mul_f32_e32 v27, v27, v30
	v_mul_f32_e32 v30, 0xbfb8aa3b, v32
	v_exp_f32_e32 v30, v30
	s_nop 0
	v_add_f32_e32 v30, 1.0, v30
	v_rcp_f32_e32 v30, v30
	s_nop 0
	v_mul_f32_e32 v30, v32, v30
	v_mul_f32_e32 v28, v28, v30
	v_mul_f32_e32 v30, 0xbfb8aa3b, v33
	v_exp_f32_e32 v30, v30
	s_nop 0
	v_add_f32_e32 v30, 1.0, v30
	v_rcp_f32_e32 v30, v30
	s_nop 0
	v_mul_f32_e32 v30, v33, v30
	v_mul_f32_e32 v29, v29, v30
	v_mul_f32_e32 v30, 0xbfb8aa3b, v22
	v_exp_f32_e32 v30, v30
	s_nop 0
	v_add_f32_e32 v30, 1.0, v30
	v_rcp_f32_e32 v30, v30
	s_nop 0
	v_mul_f32_e32 v22, v22, v30
	v_mul_f32_e32 v22, v18, v22
	v_mul_f32_e32 v18, 0xbfb8aa3b, v23
	v_exp_f32_e32 v18, v18
	s_nop 0
	v_add_f32_e32 v18, 1.0, v18
	v_rcp_f32_e32 v18, v18
	s_nop 0
	v_mul_f32_e32 v18, v23, v18
	v_mul_f32_e32 v23, v19, v18
	v_mul_f32_e32 v18, 0xbfb8aa3b, v24
	v_exp_f32_e32 v18, v18
	s_nop 0
	v_add_f32_e32 v18, 1.0, v18
	v_rcp_f32_e32 v18, v18
	s_nop 0
	v_mul_f32_e32 v18, v24, v18
	v_mul_f32_e32 v24, v20, v18
	v_mul_f32_e32 v18, 0xbfb8aa3b, v25
	v_exp_f32_e32 v18, v18
	s_nop 0
	v_add_f32_e32 v18, 1.0, v18
	v_rcp_f32_e32 v18, v18
	s_nop 0
	v_mul_f32_e32 v18, v25, v18
	v_mul_f32_e32 v21, v21, v18
	v_cvt_pk_bf16_f32 v18, v26, v27
	v_cvt_pk_bf16_f32 v19, v28, v29
	v_cvt_pk_bf16_f32 v20, v22, v23
	v_add_u32_e32 v22, 0xa0, v144
	v_mad_i64_i32 v[22:23], s[22:23], v22, s24, v[114:115]
	v_lshl_add_u64 v[22:23], v[22:23], 0, v[116:117]
	v_cvt_pk_bf16_f32 v21, v24, v21
	global_store_dwordx4 v[22:23], v[18:21], off
	s_nop 1
	v_mul_f32_e32 v18, 0xbfb8aa3b, v14
	v_exp_f32_e32 v18, v18
	s_nop 0
	v_add_f32_e32 v18, 1.0, v18
	v_rcp_f32_e32 v18, v18
	s_nop 0
	v_mul_f32_e32 v14, v14, v18
	v_mul_f32_e32 v10, v10, v14
	v_mul_f32_e32 v14, 0xbfb8aa3b, v15
	v_exp_f32_e32 v14, v14
	s_nop 0
	v_add_f32_e32 v14, 1.0, v14
	v_rcp_f32_e32 v14, v14
	s_nop 0
	v_mul_f32_e32 v14, v15, v14
	v_mul_f32_e32 v11, v11, v14
	v_mul_f32_e32 v14, 0xbfb8aa3b, v16
	v_exp_f32_e32 v14, v14
	s_nop 0
	v_add_f32_e32 v14, 1.0, v14
	v_rcp_f32_e32 v14, v14
	s_nop 0
	v_mul_f32_e32 v14, v16, v14
	v_mul_f32_e32 v12, v12, v14
	v_mul_f32_e32 v14, 0xbfb8aa3b, v17
	v_exp_f32_e32 v14, v14
	s_nop 0
	v_add_f32_e32 v14, 1.0, v14
	v_rcp_f32_e32 v14, v14
	s_nop 0
	v_mul_f32_e32 v14, v17, v14
	v_mul_f32_e32 v13, v13, v14
	v_mul_f32_e32 v14, 0xbfb8aa3b, v6
	v_exp_f32_e32 v14, v14
	s_nop 0
	v_add_f32_e32 v14, 1.0, v14
	v_rcp_f32_e32 v14, v14
	s_nop 0
	v_mul_f32_e32 v6, v6, v14
	v_mul_f32_e32 v6, v2, v6
	v_mul_f32_e32 v2, 0xbfb8aa3b, v7
	v_exp_f32_e32 v2, v2
	s_nop 0
	v_add_f32_e32 v2, 1.0, v2
	v_rcp_f32_e32 v2, v2
	s_nop 0
	v_mul_f32_e32 v2, v7, v2
	v_mul_f32_e32 v7, v3, v2
	v_mul_f32_e32 v2, 0xbfb8aa3b, v8
	v_exp_f32_e32 v2, v2
	s_nop 0
	v_add_f32_e32 v2, 1.0, v2
	v_rcp_f32_e32 v2, v2
	s_nop 0
	v_mul_f32_e32 v2, v8, v2
	v_mul_f32_e32 v8, v4, v2
	v_mul_f32_e32 v2, 0xbfb8aa3b, v9
	v_exp_f32_e32 v2, v2
	s_nop 0
	v_add_f32_e32 v2, 1.0, v2
	v_rcp_f32_e32 v2, v2
	s_nop 0
	v_mul_f32_e32 v2, v9, v2
	v_mul_f32_e32 v5, v5, v2
	v_cvt_pk_bf16_f32 v2, v10, v11
	v_cvt_pk_bf16_f32 v3, v12, v13
	v_cvt_pk_bf16_f32 v4, v6, v7
	v_add_u32_e32 v6, 0xb0, v144
	v_mad_i64_i32 v[6:7], s[22:23], v6, s24, v[114:115]
	v_lshl_add_u64 v[6:7], v[6:7], 0, v[116:117]
	s_mov_b64 s[22:23], -1
	v_cvt_pk_bf16_f32 v5, v8, v5
	global_store_dwordx4 v[6:7], v[2:5], off
	s_cbranch_vccnz .LBB0_1143
	s_andn2_b64 vcc, exec, s[12:13]
	s_cbranch_vccnz .LBB0_1142
	s_barrier
	s_branch .LBB0_1142

; __device__ __forceinline__ unsigned cvt_pk_bf16(float lo, float hi) { unsigned r; asm volatile("v_cvt_pk_bf16_f32 %0, %1, %2" : "=v"(r) : "v"(lo), "v"(hi)); return r; }
; template <int PERMT>
; __device__ __forceinline__ void transpose_job(const float* __restrict__ src, bf16_t* __restrict__ dst, int K, int N, int Npad, const float* __restrict__ kscale, unsigned char* lds_g, int first, int stride) {
;     ...
;         { const int n = tid >> 1, ks = tid & 1;
;           if (n0 + n < N) { bf16_t* dp = dst + (size_t)dst_row<PERMT>(n0 + n) * K + k0 + 32 * ks;
; #pragma unroll
;             for (int eb = 0; eb < 4; ++eb) { float v[8];
; #pragma unroll
;               for (int e = 0; e < 8; ++e) v[e] = T[(32 * ks + 8 * eb + e) * 257 + n];
;               u32x4 w; w.x = cvt_pk_bf16(v[0], v[1]); w.y = cvt_pk_bf16(v[2], v[3]); w.z = cvt_pk_bf16(v[4], v[5]); w.w = cvt_pk_bf16(v[6], v[7]);
;               *(u32x4*)(dp + 8 * eb) = w; } } }
.LBB0_1165:
	s_or_b64 exec, exec, s[4:5]
	s_sub_i32 s4, 0, s8
	v_ashrrev_i32_e32 v5, 31, v4
	ds_read_b32 v12, v11 offset:1028
	ds_read_b32 v13, v11
	ds_read_b32 v14, v11 offset:3084
	ds_read_b32 v15, v11 offset:2056
	ds_read_b32 v16, v11 offset:5140
	ds_read_b32 v17, v11 offset:4112
	ds_read_b32 v18, v11 offset:7196
	ds_read_b32 v19, v11 offset:6168
	s_add_i32 s4, s7, s4
	v_lshlrev_b64 v[4:5], 12, v[4:5]
	v_lshl_add_u64 v[4:5], s[0:1], 0, v[4:5]
	s_ashr_i32 s5, s4, 31
	v_lshl_add_u64 v[4:5], s[4:5], 1, v[4:5]
	v_lshl_add_u64 v[4:5], v[4:5], 0, v[0:1]
	s_waitcnt lgkmcnt(6)
	v_cvt_pk_bf16_f32 v12, v13, v12
	s_waitcnt lgkmcnt(4)
	v_cvt_pk_bf16_f32 v13, v15, v14
	s_waitcnt lgkmcnt(2)
	v_cvt_pk_bf16_f32 v14, v17, v16
	s_waitcnt lgkmcnt(0)
	v_cvt_pk_bf16_f32 v15, v19, v18
	global_store_dwordx4 v[4:5], v[12:15], off
	ds_read_b32 v12, v11 offset:9252
	ds_read_b32 v13, v11 offset:8224
	ds_read_b32 v14, v11 offset:11308
	ds_read_b32 v15, v11 offset:10280
	ds_read_b32 v16, v11 offset:13364
	ds_read_b32 v17, v11 offset:12336
	ds_read_b32 v18, v11 offset:15420
	ds_read_b32 v19, v11 offset:14392
	s_waitcnt lgkmcnt(0)
	v_cvt_pk_bf16_f32 v12, v13, v12
	v_cvt_pk_bf16_f32 v13, v15, v14
	v_cvt_pk_bf16_f32 v14, v17, v16
	v_cvt_pk_bf16_f32 v15, v19, v18
	global_store_dwordx4 v[4:5], v[12:15], off offset:16
	ds_read_b32 v12, v11 offset:17476
	ds_read_b32 v13, v11 offset:16448
	ds_read_b32 v14, v11 offset:19532
	ds_read_b32 v15, v11 offset:18504
	ds_read_b32 v16, v11 offset:21588
	ds_read_b32 v17, v11 offset:20560
	ds_read_b32 v18, v11 offset:23644
	ds_read_b32 v19, v11 offset:22616
	s_waitcnt lgkmcnt(0)
	v_cvt_pk_bf16_f32 v12, v13, v12
	v_cvt_pk_bf16_f32 v13, v15, v14
	v_cvt_pk_bf16_f32 v14, v17, v16
	v_cvt_pk_bf16_f32 v15, v19, v18
	global_store_dwordx4 v[4:5], v[12:15], off offset:32
	ds_read_b32 v12, v11 offset:25700
	ds_read_b32 v13, v11 offset:24672
	ds_read_b32 v14, v11 offset:27756
	ds_read_b32 v15, v11 offset:26728
	ds_read_b32 v16, v11 offset:29812
	ds_read_b32 v17, v11 offset:28784
	ds_read_b32 v18, v11 offset:31868
	ds_read_b32 v19, v11 offset:30840
	s_waitcnt lgkmcnt(0)
	v_cvt_pk_bf16_f32 v12, v13, v12
	v_cvt_pk_bf16_f32 v13, v15, v14
	v_cvt_pk_bf16_f32 v14, v17, v16
	v_cvt_pk_bf16_f32 v15, v19, v18
	global_store_dwordx4 v[4:5], v[12:15], off offset:48

; __device__ __forceinline__ unsigned cvt_pk_bf16(float lo, float hi) { unsigned r; asm volatile("v_cvt_pk_bf16_f32 %0, %1, %2" : "=v"(r) : "v"(lo), "v"(hi)); return r; }
; template <int PERMT>
; __device__ __forceinline__ void transpose_job(const float* __restrict__ src, bf16_t* __restrict__ dst, int K, int N, int Npad, const float* __restrict__ kscale, unsigned char* lds_g, int first, int stride) {
;     ...
;         { const int kk = tid >> 6, n4 = tid & 63; const bool ok = n0 + 4 * n4 < N; f32x4 v[8];
; #pragma unroll
;           for (int i = 0; i < 8; ++i) { const int k = k0 + kk + 8 * i; v[i] = ok ? __builtin_nontemporal_load((const f32x4*)(src + (size_t)k * N + n0 + 4 * n4)) : (f32x4){0.f, 0.f, 0.f, 0.f}; }
; #pragma unroll
;           for (int i = 0; i < 8; ++i) { const int k = k0 + kk + 8 * i; if (kscale) v[i] = v[i] * kscale[k];
;               float* tp = T + (kk + 8 * i) * 257 + 4 * n4; tp[0] = v[i][0]; tp[1] = v[i][1]; tp[2] = v[i][2]; tp[3] = v[i][3]; } }
;         __syncthreads();
;         { const int n = tid >> 1, ks = tid & 1;
;           if (n0 + n < N) { bf16_t* dp = dst + (size_t)dst_row<PERMT>(n0 + n) * K + k0 + 32 * ks;
; #pragma unroll
;             for (int eb = 0; eb < 4; ++eb) { float v[8];
; #pragma unroll
;               for (int e = 0; e < 8; ++e) v[e] = T[(32 * ks + 8 * eb + e) * 257 + n];
;               u32x4 w; w.x = cvt_pk_bf16(v[0], v[1]); w.y = cvt_pk_bf16(v[2], v[3]); w.z = cvt_pk_bf16(v[4], v[5]); w.w = cvt_pk_bf16(v[6], v[7]);
;               *(u32x4*)(dp + 8 * eb) = w; } } }
.LBB0_1195:
	s_or_b64 exec, exec, s[6:7]
	s_waitcnt vmcnt(0) lgkmcnt(0)
	ds_write2_b32 v43, v6, v7 offset1:1
	ds_write2_b32 v43, v8, v9 offset0:2 offset1:3
	v_add_u32_e32 v6, 0x2020, v43
	ds_write2_b32 v6, v2, v3 offset1:1
	v_add_u32_e32 v2, 0x2028, v43
	ds_write2_b32 v2, v4, v5 offset1:1
	v_add_u32_e32 v2, 0x4040, v43
	ds_write2_b32 v2, v14, v15 offset1:1
	v_add_u32_e32 v2, 0x4048, v43
	ds_write2_b32 v2, v16, v17 offset1:1
	v_add_u32_e32 v2, 0x6060, v43
	ds_write2_b32 v2, v10, v11 offset1:1
	v_add_u32_e32 v2, 0x6068, v43
	ds_write2_b32 v2, v12, v13 offset1:1
	v_add_u32_e32 v2, 0x8080, v43
	ds_write2_b32 v2, v22, v23 offset1:1
	v_add_u32_e32 v2, 0x8088, v43
	ds_write2_b32 v2, v24, v25 offset1:1
	v_add_u32_e32 v2, 0xa0a0, v43
	ds_write2_b32 v2, v18, v19 offset1:1
	v_add_u32_e32 v2, 0xa0a8, v43
	ds_write2_b32 v2, v20, v21 offset1:1
	v_add_u32_e32 v2, 0xc0c0, v43
	ds_write2_b32 v2, v30, v31 offset1:1
	v_add_u32_e32 v2, 0xc0c8, v43
	ds_write2_b32 v2, v32, v33 offset1:1
	v_add_u32_e32 v2, 0xe0e0, v43
	ds_write2_b32 v2, v26, v27 offset1:1
	v_add_u32_e32 v2, 0xe0e8, v43
	ds_write2_b32 v2, v28, v29 offset1:1
	v_add_u32_e32 v2, s4, v42
	s_movk_i32 s3, 0x800
	v_cmp_gt_i32_e32 vcc, s3, v2
	s_waitcnt lgkmcnt(0)
	s_barrier
	s_and_saveexec_b64 s[4:5], vcc
	s_cbranch_execz .LBB0_1178
	v_mov_b64_e32 v[4:5], s[0:1]
	s_movk_i32 s3, 0x2c00
	v_mad_i64_i32 v[2:3], s[6:7], v2, s3, v[4:5]
	s_ashr_i32 s3, s2, 31
	v_lshl_add_u64 v[2:3], s[2:3], 1, v[2:3]
	v_lshl_add_u64 v[6:7], v[2:3], 0, v[0:1]
	ds_read_b32 v2, v44 offset:1028
	ds_read_b32 v3, v44
	ds_read_b32 v4, v44 offset:3084
	ds_read_b32 v5, v44 offset:2056
	ds_read_b32 v8, v44 offset:5140
	ds_read_b32 v9, v44 offset:4112
	ds_read_b32 v10, v44 offset:7196
	ds_read_b32 v11, v44 offset:6168
	s_waitcnt lgkmcnt(6)
	v_cvt_pk_bf16_f32 v2, v3, v2
	s_waitcnt lgkmcnt(4)
	v_cvt_pk_bf16_f32 v3, v5, v4
	s_waitcnt lgkmcnt(2)
	v_cvt_pk_bf16_f32 v4, v9, v8
	s_waitcnt lgkmcnt(0)
	v_cvt_pk_bf16_f32 v5, v11, v10
	global_store_dwordx4 v[6:7], v[2:5], off
	ds_read_b32 v2, v44 offset:9252
	ds_read_b32 v3, v44 offset:8224
	ds_read_b32 v4, v44 offset:11308
	ds_read_b32 v5, v44 offset:10280
	ds_read_b32 v8, v44 offset:13364
	ds_read_b32 v9, v44 offset:12336
	ds_read_b32 v10, v44 offset:15420
	ds_read_b32 v11, v44 offset:14392
	s_waitcnt lgkmcnt(0)
	v_cvt_pk_bf16_f32 v2, v3, v2
	v_cvt_pk_bf16_f32 v3, v5, v4
	v_cvt_pk_bf16_f32 v4, v9, v8
	v_cvt_pk_bf16_f32 v5, v11, v10
	global_store_dwordx4 v[6:7], v[2:5], off offset:16
	ds_read_b32 v2, v44 offset:17476
	ds_read_b32 v3, v44 offset:16448
	ds_read_b32 v4, v44 offset:19532
	ds_read_b32 v5, v44 offset:18504
	ds_read_b32 v8, v44 offset:21588
	ds_read_b32 v9, v44 offset:20560
	ds_read_b32 v10, v44 offset:23644
	ds_read_b32 v11, v44 offset:22616
	s_waitcnt lgkmcnt(0)
	v_cvt_pk_bf16_f32 v2, v3, v2
	v_cvt_pk_bf16_f32 v3, v5, v4
	v_cvt_pk_bf16_f32 v4, v9, v8
	v_cvt_pk_bf16_f32 v5, v11, v10
	global_store_dwordx4 v[6:7], v[2:5], off offset:32
	ds_read_b32 v2, v44 offset:25700
	ds_read_b32 v3, v44 offset:24672
	ds_read_b32 v4, v44 offset:27756
	ds_read_b32 v5, v44 offset:26728
	ds_read_b32 v8, v44 offset:29812
	ds_read_b32 v9, v44 offset:28784
	ds_read_b32 v10, v44 offset:31868
	ds_read_b32 v11, v44 offset:30840
	s_waitcnt lgkmcnt(0)
	v_cvt_pk_bf16_f32 v2, v3, v2
	v_cvt_pk_bf16_f32 v3, v5, v4
	v_cvt_pk_bf16_f32 v4, v9, v8
	v_cvt_pk_bf16_f32 v5, v11, v10
	global_store_dwordx4 v[6:7], v[2:5], off offset:48
	s_branch .LBB0_1178
